# baseline (speedup 1.0000x reference)
; DI unsigned pack2(float a, float b) { v2f f = {a, b}; return __builtin_bit_cast(unsigned, __builtin_convertvector(f, v2bf)); }
; DI void wprep_tile(const float* __restrict__ src, int Nsrc, u16* __restrict__ dst, int K, int kt, int nt, int remap, char* smem) {
;     ...
;   const int n2 = tid >> 2, k0 = (tid & 3) * 16;
;   unsigned w[8];
; #pragma unroll
;   for (int j = 0; j < 8; ++j) w[j] = pack2(tile[n2 * 65 + k0 + 2 * j], tile[n2 * 65 + k0 + 2 * j + 1]);
;   u16* d = dst + (long)(nt * 64 + n2) * K + kt * 64 + k0;
;   *(u32x4*)d = (u32x4){w[0], w[1], w[2], w[3]};
;   *(u32x4*)(d + 8) = (u32x4){w[4], w[5], w[6], w[7]};
.LBB0_74:
	v_ashrrev_i32_e32 v0, 2, v4
	v_lshlrev_b32_e32 v2, 4, v4
	v_and_b32_e32 v16, 48, v2
	v_mul_lo_u32 v2, v0, s13
	v_lshl_add_u32 v14, v16, 2, v2
	s_waitcnt lgkmcnt(0)
	s_barrier
	ds_read2_b32 v[2:3], v14 offset1:1
	ds_read2_b32 v[4:5], v14 offset0:2 offset1:3
	ds_read2_b32 v[6:7], v14 offset0:4 offset1:5
	ds_read2_b32 v[8:9], v14 offset0:6 offset1:7
	s_ashr_i32 s1, s0, 31
	s_waitcnt lgkmcnt(3)
	v_cvt_pk_bf16_f32 v2, v2, v3
	s_waitcnt lgkmcnt(2)
	v_cvt_pk_bf16_f32 v3, v4, v5
	s_waitcnt lgkmcnt(1)
	v_cvt_pk_bf16_f32 v4, v6, v7
	ds_read2_b32 v[6:7], v14 offset0:8 offset1:9
	ds_read2_b32 v[10:11], v14 offset0:10 offset1:11
	ds_read2_b32 v[12:13], v14 offset0:12 offset1:13
	ds_read2_b32 v[14:15], v14 offset0:14 offset1:15
	s_add_i32 s10, s10, s14
	s_waitcnt lgkmcnt(3)
	v_cvt_pk_bf16_f32 v6, v6, v7
	s_waitcnt lgkmcnt(2)
	v_cvt_pk_bf16_f32 v7, v10, v11
	v_add_u32_e32 v10, s16, v0
	v_ashrrev_i32_e32 v11, 31, v10
	v_lshlrev_b64 v[10:11], 11, v[10:11]
	v_lshl_add_u64 v[10:11], s[6:7], 0, v[10:11]
	v_lshl_add_u64 v[10:11], s[0:1], 1, v[10:11]
	v_lshlrev_b32_e32 v0, 1, v16
	v_cvt_pk_bf16_f32 v5, v8, v9
	s_waitcnt lgkmcnt(1)
	v_cvt_pk_bf16_f32 v8, v12, v13
	s_waitcnt lgkmcnt(0)
	v_cvt_pk_bf16_f32 v9, v14, v15
	v_lshl_add_u64 v[10:11], v[10:11], 0, v[0:1]
	s_cmpk_gt_i32 s10, 0x39f
	global_store_dwordx4 v[10:11], v[2:5], off sc0 sc1
	global_store_dwordx4 v[10:11], v[6:9], off offset:16 sc0 sc1
	s_cbranch_scc1 .LBB0_91

; DI unsigned pack2(float a, float b) { v2f f = {a, b}; return __builtin_bit_cast(unsigned, __builtin_convertvector(f, v2bf)); }
; DI void wprep_tile(const float* __restrict__ src, int Nsrc, u16* __restrict__ dst, int K, int kt, int nt, int remap, char* smem) {
;     ...
;   const int n2 = tid >> 2, k0 = (tid & 3) * 16;
;   unsigned w[8];
; #pragma unroll
;   for (int j = 0; j < 8; ++j) w[j] = pack2(tile[n2 * 65 + k0 + 2 * j], tile[n2 * 65 + k0 + 2 * j + 1]);
;   u16* d = dst + (long)(nt * 64 + n2) * K + kt * 64 + k0;
;   *(u32x4*)d = (u32x4){w[0], w[1], w[2], w[3]};
;   *(u32x4*)(d + 8) = (u32x4){w[4], w[5], w[6], w[7]};
.LBB0_93:
	v_ashrrev_i32_e32 v0, 2, v4
	v_lshlrev_b32_e32 v2, 4, v4
	v_and_b32_e32 v16, 48, v2
	v_mul_lo_u32 v2, v0, s15
	v_lshl_add_u32 v14, v16, 2, v2
	s_waitcnt lgkmcnt(0)
	s_barrier
	ds_read2_b32 v[2:3], v14 offset1:1
	ds_read2_b32 v[4:5], v14 offset0:2 offset1:3
	ds_read2_b32 v[6:7], v14 offset0:4 offset1:5
	ds_read2_b32 v[8:9], v14 offset0:6 offset1:7
	s_add_i32 s12, s12, s14
	s_waitcnt lgkmcnt(3)
	v_cvt_pk_bf16_f32 v2, v2, v3
	s_waitcnt lgkmcnt(2)
	v_cvt_pk_bf16_f32 v3, v4, v5
	s_waitcnt lgkmcnt(1)
	v_cvt_pk_bf16_f32 v4, v6, v7
	ds_read2_b32 v[6:7], v14 offset0:8 offset1:9
	ds_read2_b32 v[10:11], v14 offset0:10 offset1:11
	ds_read2_b32 v[12:13], v14 offset0:12 offset1:13
	ds_read2_b32 v[14:15], v14 offset0:14 offset1:15
	s_waitcnt lgkmcnt(4)
	v_cvt_pk_bf16_f32 v5, v8, v9
	s_waitcnt lgkmcnt(3)
	v_cvt_pk_bf16_f32 v6, v6, v7
	s_waitcnt lgkmcnt(2)
	v_cvt_pk_bf16_f32 v7, v10, v11
	v_add_u32_e32 v10, s1, v0
	v_ashrrev_i32_e32 v11, 31, v10
	v_lshlrev_b64 v[10:11], 11, v[10:11]
	v_lshl_add_u64 v[10:11], s[6:7], 0, v[10:11]
	s_ashr_i32 s1, s0, 31
	v_lshl_add_u64 v[10:11], s[0:1], 1, v[10:11]
	v_lshlrev_b32_e32 v0, 1, v16
	s_waitcnt lgkmcnt(1)
	v_cvt_pk_bf16_f32 v8, v12, v13
	s_waitcnt lgkmcnt(0)
	v_cvt_pk_bf16_f32 v9, v14, v15
	v_lshl_add_u64 v[10:11], v[10:11], 0, v[0:1]
	s_cmpk_gt_i32 s12, 0xff
	global_store_dwordx4 v[10:11], v[2:5], off sc0 sc1
	global_store_dwordx4 v[10:11], v[6:9], off offset:16 sc0 sc1
	s_cbranch_scc1 .LBB0_104

; DI unsigned pack2(float a, float b) { v2f f = {a, b}; return __builtin_bit_cast(unsigned, __builtin_convertvector(f, v2bf)); }
; DI void wprep_tile(const float* __restrict__ src, int Nsrc, u16* __restrict__ dst, int K, int kt, int nt, int remap, char* smem) {
;     ...
;   const int n2 = tid >> 2, k0 = (tid & 3) * 16;
;   unsigned w[8];
; #pragma unroll
;   for (int j = 0; j < 8; ++j) w[j] = pack2(tile[n2 * 65 + k0 + 2 * j], tile[n2 * 65 + k0 + 2 * j + 1]);
;   u16* d = dst + (long)(nt * 64 + n2) * K + kt * 64 + k0;
;   *(u32x4*)d = (u32x4){w[0], w[1], w[2], w[3]};
;   *(u32x4*)(d + 8) = (u32x4){w[4], w[5], w[6], w[7]};
.LBB0_106:
	v_ashrrev_i32_e32 v0, 2, v4
	v_lshlrev_b32_e32 v2, 4, v4
	v_and_b32_e32 v16, 48, v2
	v_mul_lo_u32 v2, v0, s15
	v_lshl_add_u32 v14, v16, 2, v2
	s_waitcnt lgkmcnt(0)
	s_barrier
	ds_read2_b32 v[2:3], v14 offset1:1
	ds_read2_b32 v[4:5], v14 offset0:2 offset1:3
	ds_read2_b32 v[6:7], v14 offset0:4 offset1:5
	ds_read2_b32 v[8:9], v14 offset0:6 offset1:7
	s_add_i32 s12, s12, s14
	s_waitcnt lgkmcnt(3)
	v_cvt_pk_bf16_f32 v2, v2, v3
	s_waitcnt lgkmcnt(2)
	v_cvt_pk_bf16_f32 v3, v4, v5
	s_waitcnt lgkmcnt(1)
	v_cvt_pk_bf16_f32 v4, v6, v7
	ds_read2_b32 v[6:7], v14 offset0:8 offset1:9
	ds_read2_b32 v[10:11], v14 offset0:10 offset1:11
	ds_read2_b32 v[12:13], v14 offset0:12 offset1:13
	ds_read2_b32 v[14:15], v14 offset0:14 offset1:15
	s_waitcnt lgkmcnt(4)
	v_cvt_pk_bf16_f32 v5, v8, v9
	s_waitcnt lgkmcnt(3)
	v_cvt_pk_bf16_f32 v6, v6, v7
	s_waitcnt lgkmcnt(2)
	v_cvt_pk_bf16_f32 v7, v10, v11
	v_add_u32_e32 v10, s1, v0
	v_ashrrev_i32_e32 v11, 31, v10
	v_lshlrev_b64 v[10:11], 12, v[10:11]
	v_lshl_add_u64 v[10:11], s[6:7], 0, v[10:11]
	s_ashr_i32 s1, s0, 31
	v_lshl_add_u64 v[10:11], s[0:1], 1, v[10:11]
	v_lshlrev_b32_e32 v0, 1, v16
	s_waitcnt lgkmcnt(1)
	v_cvt_pk_bf16_f32 v8, v12, v13
	s_waitcnt lgkmcnt(0)
	v_cvt_pk_bf16_f32 v9, v14, v15
	v_lshl_add_u64 v[10:11], v[10:11], 0, v[0:1]
	s_cmpk_gt_i32 s12, 0x7f
	global_store_dwordx4 v[10:11], v[2:5], off sc0 sc1
	global_store_dwordx4 v[10:11], v[6:9], off offset:16 sc0 sc1
	s_cbranch_scc1 .LBB0_117

; DI unsigned pack2(float a, float b) { v2f f = {a, b}; return __builtin_bit_cast(unsigned, __builtin_convertvector(f, v2bf)); }
; DI void wprep_tile(const float* __restrict__ src, int Nsrc, u16* __restrict__ dst, int K, int kt, int nt, int remap, char* smem) {
;     ...
;   const int n2 = tid >> 2, k0 = (tid & 3) * 16;
;   unsigned w[8];
; #pragma unroll
;   for (int j = 0; j < 8; ++j) w[j] = pack2(tile[n2 * 65 + k0 + 2 * j], tile[n2 * 65 + k0 + 2 * j + 1]);
;   u16* d = dst + (long)(nt * 64 + n2) * K + kt * 64 + k0;
;   *(u32x4*)d = (u32x4){w[0], w[1], w[2], w[3]};
;   *(u32x4*)(d + 8) = (u32x4){w[4], w[5], w[6], w[7]};
.LBB0_119:
	v_ashrrev_i32_e32 v0, 2, v4
	v_lshlrev_b32_e32 v2, 4, v4
	v_and_b32_e32 v16, 48, v2
	v_mul_lo_u32 v2, v0, s12
	v_lshl_add_u32 v14, v16, 2, v2
	s_waitcnt lgkmcnt(0)
	s_barrier
	ds_read2_b32 v[2:3], v14 offset1:1
	ds_read2_b32 v[4:5], v14 offset0:2 offset1:3
	ds_read2_b32 v[6:7], v14 offset0:4 offset1:5
	ds_read2_b32 v[8:9], v14 offset0:6 offset1:7
	s_add_i32 s10, s10, s14
	s_waitcnt lgkmcnt(3)
	v_cvt_pk_bf16_f32 v2, v2, v3
	s_waitcnt lgkmcnt(2)
	v_cvt_pk_bf16_f32 v3, v4, v5
	s_waitcnt lgkmcnt(1)
	v_cvt_pk_bf16_f32 v4, v6, v7
	ds_read2_b32 v[6:7], v14 offset0:8 offset1:9
	ds_read2_b32 v[10:11], v14 offset0:10 offset1:11
	ds_read2_b32 v[12:13], v14 offset0:12 offset1:13
	ds_read2_b32 v[14:15], v14 offset0:14 offset1:15
	s_waitcnt lgkmcnt(4)
	v_cvt_pk_bf16_f32 v5, v8, v9
	s_waitcnt lgkmcnt(3)
	v_cvt_pk_bf16_f32 v6, v6, v7
	s_waitcnt lgkmcnt(2)
	v_cvt_pk_bf16_f32 v7, v10, v11
	v_add_u32_e32 v10, s1, v0
	v_ashrrev_i32_e32 v11, 31, v10
	v_lshlrev_b64 v[10:11], 12, v[10:11]
	v_lshl_add_u64 v[10:11], s[6:7], 0, v[10:11]
	s_ashr_i32 s1, s0, 31
	v_lshl_add_u64 v[10:11], s[0:1], 1, v[10:11]
	v_lshlrev_b32_e32 v0, 1, v16
	s_waitcnt lgkmcnt(1)
	v_cvt_pk_bf16_f32 v8, v12, v13
	s_waitcnt lgkmcnt(0)
	v_cvt_pk_bf16_f32 v9, v14, v15
	v_lshl_add_u64 v[10:11], v[10:11], 0, v[0:1]
	s_cmpk_gt_i32 s10, 0x7f
	global_store_dwordx4 v[10:11], v[2:5], off sc0 sc1
	global_store_dwordx4 v[10:11], v[6:9], off offset:16 sc0 sc1
	s_cbranch_scc1 .LBB0_130

; template <class ARow, class Epi>
; DI void gemm_tile(const ARow& arow, long a_kstride, const u16* __restrict__ Bt, long ldb, int K, int m0, int n0,
;                   const Epi& epi, char* smem) {
;     ...
;       u16* rp = epi.rowp(m) + nh;
; #pragma unroll
;       for (int pp = 0; pp < 2; ++pp) {
;         u32x2 a = pk[2 * pp], b = pk[2 * pp + 1];
;         const u32x2 rx = __builtin_amdgcn_permlane16_swap(a.x, b.x, false, false);
;         const u32x2 ry = __builtin_amdgcn_permlane16_swap(a.y, b.y, false, false);
;         const int nst = (fq & 1) ? ((2 * pp + 1) * 16 + (fq - 1) * 4) : ((2 * pp) * 16 + fq * 4);
;         *(u32x4*)(rp + nst) = (u32x4){rx[0], ry[0], rx[1], ry[1]};
;       }
.LBB0_214:
	v_or_b32_e32 v20, 48, v74
	v_cvt_pk_bf16_f32 v16, v4, v5
	v_mov_b64_e32 v[4:5], s[18:19]
	v_mad_i64_i32 v[4:5], s[0:1], v20, s40, v[4:5]
	v_cvt_pk_bf16_f32 v18, v0, v1
	v_cvt_pk_bf16_f32 v19, v2, v3
	v_cvt_pk_bf16_f32 v2, v8, v9
	v_cvt_pk_bf16_f32 v3, v10, v11
	v_cvt_pk_bf16_f32 v0, v12, v13
	v_cvt_pk_bf16_f32 v1, v14, v15
	v_lshl_add_u64 v[4:5], v[66:67], 1, v[4:5]
	s_waitcnt lgkmcnt(0)
	v_cvt_pk_bf16_f32 v17, v6, v7
	v_permlane16_swap_b32_e32 v0, v2
	v_permlane16_swap_b32_e32 v1, v3
	v_lshl_add_u64 v[6:7], v[4:5], 0, v[64:65]
	v_mov_b32_e32 v49, v65
	global_store_dwordx4 v[6:7], v[0:3], off sc0 sc1
	v_permlane16_swap_b32_e32 v16, v18
	v_permlane16_swap_b32_e32 v17, v19
	v_lshl_add_u64 v[0:1], v[4:5], 0, v[48:49]
	global_store_dwordx4 v[0:1], v[16:19], off sc0 sc1

; template <class ARow, class Epi>
; DI void gemm_tile(const ARow& arow, long a_kstride, const u16* __restrict__ Bt, long ldb, int K, int m0, int n0,
;                   const Epi& epi, char* smem) {
;     ...
;   const int fr = lane & 15, fq = lane >> 4;
;   int foff[2];
; #pragma unroll
;   for (int ks = 0; ks < 2; ++ks) foff[ks] = fr * 128 + ((((4 * ks + fq) ^ ((fr >> 1) & 7))) << 4);
;   f32x4 acc[4][4];
; #pragma unroll
;   for (int a = 0; a < 4; ++a)
; #pragma unroll
;     for (int b = 0; b < 4; ++b) acc[a][b] = (f32x4){0.f, 0.f, 0.f, 0.f};
;   const int KT = K >> 6;
;   GEMM_STAGE(0, 0);
;   asm volatile("s_waitcnt vmcnt(0)" ::: "memory");
;   __syncthreads();
;   for (int kt = 0; kt < KT; ++kt) {
;     const int cur = kt & 1;
;     if (kt + 1 < KT) GEMM_STAGE(cur ^ 1, kt + 1);
;     const char* sa = smem + cur * 32768 + wm * 64 * 128;
;     const char* sb = smem + cur * 32768 + 16384 + wn * 64 * 128;
; #pragma unroll
;     for (int ks = 0; ks < 2; ++ks) {
;       bf16x8 wf[4], af[4];
; #pragma unroll
;       for (int j = 0; j < 4; ++j) {
;         wf[j] = *(const bf16x8*)(sb + j * 2048 + foff[ks]);
;         af[j] = *(const bf16x8*)(sa + j * 2048 + foff[ks]);
;       }
; #pragma unroll
;       for (int ni = 0; ni < 4; ++ni)
; #pragma unroll
;         for (int mi = 0; mi < 4; ++mi) acc[ni][mi] = __builtin_amdgcn_mfma_f32_16x16x32_bf16(wf[ni], af[mi], acc[ni][mi], 0, 0, 0);
;     }
;     asm volatile("s_waitcnt vmcnt(0)" ::: "memory");
;     __syncthreads();
;   }
.LBB0_217:
	s_and_b32 s6, s1, 0x8000
	s_xor_b32 s7, s6, 0x8000
	v_add_u32_e32 v108, s7, v91
	v_add_u32_e32 v116, s6, v89
	v_or_b32_e32 v117, s6, v90
	v_readfirstlane_b32 s6, v108
	v_add_u32_e32 v109, 0x4000, v108
	v_lshl_add_u64 v[92:93], v[66:67], 0, s[4:5]
	v_add_u32_e32 v110, 0x400, v108
	v_readfirstlane_b32 s7, v109
	s_mov_b32 m0, s6
	v_lshl_add_u64 v[94:95], v[68:69], 0, s[4:5]
	v_add_u32_e32 v111, 0x4400, v108
	v_readfirstlane_b32 s8, v110
	global_load_lds_dwordx4 v[92:93], off
	s_mov_b32 m0, s7
	v_lshl_add_u64 v[96:97], v[70:71], 0, s[4:5]
	v_add_u32_e32 v113, 0x800, v108
	v_readfirstlane_b32 s9, v111
	global_load_lds_dwordx4 v[94:95], off
	s_mov_b32 m0, s8
	v_lshl_add_u64 v[98:99], v[72:73], 0, s[4:5]
	v_add_u32_e32 v114, 0x4800, v108
	v_readfirstlane_b32 s10, v113
	global_load_lds_dwordx4 v[96:97], off
	s_mov_b32 m0, s9
	v_lshl_add_u64 v[100:101], v[74:75], 0, s[4:5]
	v_add_u32_e32 v115, 0xc00, v108
	v_readfirstlane_b32 s11, v114
	global_load_lds_dwordx4 v[98:99], off
	s_mov_b32 m0, s10
	v_lshl_add_u64 v[102:103], v[76:77], 0, s[4:5]
	v_add_u32_e32 v108, 0x4c00, v108
	v_readfirstlane_b32 s12, v115
	global_load_lds_dwordx4 v[100:101], off
	s_mov_b32 m0, s11
	v_lshl_add_u64 v[104:105], v[78:79], 0, s[4:5]
	v_readfirstlane_b32 s13, v108
	global_load_lds_dwordx4 v[102:103], off
	s_mov_b32 m0, s12
	v_lshl_add_u64 v[106:107], v[80:81], 0, s[4:5]
	global_load_lds_dwordx4 v[104:105], off
	s_mov_b32 m0, s13
	v_add_u32_e32 v118, v117, v88
	global_load_lds_dwordx4 v[106:107], off
	v_add_u32_e32 v112, v116, v88
	ds_read_b128 v[92:95], v118 offset:16384
	ds_read_b128 v[96:99], v112
	ds_read_b128 v[100:103], v118 offset:18432
	ds_read_b128 v[104:107], v112 offset:2048
	ds_read_b128 v[108:111], v112 offset:4096
	ds_read_b128 v[112:115], v112 offset:6144
	s_waitcnt lgkmcnt(0)
	v_mfma_f32_16x16x32_bf16 v[60:63], v[92:95], v[96:99], v[60:63]
	v_add_u32_e32 v117, v117, v87
	v_add_u32_e32 v116, v116, v87
	s_add_i32 s1, s1, 0x8000
	v_mfma_f32_16x16x32_bf16 v[56:59], v[92:95], v[104:107], v[56:59]
	s_add_u32 s4, s4, 0x80
	s_addc_u32 s5, s5, 0
	s_cmpk_eq_i32 s4, 0x780
	v_mfma_f32_16x16x32_bf16 v[48:51], v[92:95], v[108:111], v[48:51]
	v_mfma_f32_16x16x32_bf16 v[40:43], v[92:95], v[112:115], v[40:43]
	v_mfma_f32_16x16x32_bf16 v[36:39], v[100:103], v[96:99], v[36:39]
	v_mfma_f32_16x16x32_bf16 v[32:35], v[100:103], v[104:107], v[32:35]
	v_mfma_f32_16x16x32_bf16 v[28:31], v[100:103], v[108:111], v[28:31]
	v_mfma_f32_16x16x32_bf16 v[24:27], v[100:103], v[112:115], v[24:27]
	ds_read_b128 v[92:95], v118 offset:20480
	ds_read_b128 v[100:103], v118 offset:22528
	s_waitcnt lgkmcnt(0)
	v_mfma_f32_16x16x32_bf16 v[20:23], v[92:95], v[96:99], v[20:23]
	v_mfma_f32_16x16x32_bf16 v[16:19], v[92:95], v[104:107], v[16:19]
	v_mfma_f32_16x16x32_bf16 v[12:15], v[92:95], v[108:111], v[12:15]
	v_mfma_f32_16x16x32_bf16 v[8:11], v[92:95], v[112:115], v[8:11]
	ds_read_b128 v[92:95], v117 offset:16384
	v_mfma_f32_16x16x32_bf16 v[4:7], v[100:103], v[96:99], v[4:7]
	v_mfma_f32_16x16x32_bf16 v[0:3], v[100:103], v[104:107], v[0:3]
	v_mfma_f32_16x16x32_bf16 v[52:55], v[100:103], v[108:111], v[52:55]
	v_mfma_f32_16x16x32_bf16 v[44:47], v[100:103], v[112:115], v[44:47]
	ds_read_b128 v[96:99], v116
	ds_read_b128 v[100:103], v117 offset:18432
	ds_read_b128 v[104:107], v116 offset:2048
	ds_read_b128 v[108:111], v116 offset:4096
	ds_read_b128 v[112:115], v116 offset:6144
	s_waitcnt lgkmcnt(0)
	v_mfma_f32_16x16x32_bf16 v[60:63], v[92:95], v[96:99], v[60:63]
	v_mfma_f32_16x16x32_bf16 v[56:59], v[92:95], v[104:107], v[56:59]
	v_mfma_f32_16x16x32_bf16 v[48:51], v[92:95], v[108:111], v[48:51]
	v_mfma_f32_16x16x32_bf16 v[40:43], v[92:95], v[112:115], v[40:43]
	v_mfma_f32_16x16x32_bf16 v[36:39], v[100:103], v[96:99], v[36:39]
	v_mfma_f32_16x16x32_bf16 v[32:35], v[100:103], v[104:107], v[32:35]
	v_mfma_f32_16x16x32_bf16 v[28:31], v[100:103], v[108:111], v[28:31]
	v_mfma_f32_16x16x32_bf16 v[24:27], v[100:103], v[112:115], v[24:27]
	ds_read_b128 v[92:95], v117 offset:20480
	ds_read_b128 v[100:103], v117 offset:22528
	s_waitcnt vmcnt(0)
	s_waitcnt vmcnt(0) lgkmcnt(0)
	v_mfma_f32_16x16x32_bf16 v[20:23], v[92:95], v[96:99], v[20:23]
	s_barrier
	v_mfma_f32_16x16x32_bf16 v[16:19], v[92:95], v[104:107], v[16:19]
	v_mfma_f32_16x16x32_bf16 v[12:15], v[92:95], v[108:111], v[12:15]
	v_mfma_f32_16x16x32_bf16 v[8:11], v[92:95], v[112:115], v[8:11]
	v_mfma_f32_16x16x32_bf16 v[4:7], v[100:103], v[96:99], v[4:7]
	v_mfma_f32_16x16x32_bf16 v[0:3], v[100:103], v[104:107], v[0:3]
	v_mfma_f32_16x16x32_bf16 v[52:55], v[100:103], v[108:111], v[52:55]
	v_mfma_f32_16x16x32_bf16 v[44:47], v[100:103], v[112:115], v[44:47]
	s_cbranch_scc0 .LBB0_217
; DI unsigned pack2(float a, float b) { v2f f = {a, b}; return __builtin_bit_cast(unsigned, __builtin_convertvector(f, v2bf)); }
; DI float silu_f(float v) { return v / (1.f + fexp(-v)); }
;   DI u32x2 pack(int, int, float a, float b, float c, float d, float&) const { u32x2 v; v.x = pack2(a, b); v.y = pack2(c, d); return v; }
; template <class ARow, class Epi>
; DI void gemm_tile(const ARow& arow, long a_kstride, const u16* __restrict__ Bt, long ldb, int K, int m0, int n0,
;                   const Epi& epi, char* smem) {
;     ...
;     for (int ks = 0; ks < 2; ++ks) {
;       bf16x8 wf[4], af[4];
; #pragma unroll
;       for (int j = 0; j < 4; ++j) {
;         wf[j] = *(const bf16x8*)(sb + j * 2048 + foff[ks]);
;         af[j] = *(const bf16x8*)(sa + j * 2048 + foff[ks]);
;       }
; #pragma unroll
;       for (int ni = 0; ni < 4; ++ni)
; #pragma unroll
;         for (int mi = 0; mi < 4; ++mi) acc[ni][mi] = __builtin_amdgcn_mfma_f32_16x16x32_bf16(wf[ni], af[mi], acc[ni][mi], 0, 0, 0);
;     }
;   DI u32x2 pack(int m, int n, float a, float b, float c, float d, float& ss) const {
;     if (n < q_end) { a *= qscale; b *= qscale; c *= qscale; d *= qscale; }
;     else if (n >= z_start) { a = silu_f(a); b = silu_f(b); c = silu_f(c); d = silu_f(d); }
;     ss += a * a + b * b + c * c + d * d;
;     u32x2 v; v.x = pack2(a, b); v.y = pack2(c, d);
;     return v;
	v_add_u32_e32 v91, v90, v88
	ds_read_b128 v[66:69], v91 offset:49152
	v_add_u32_e32 v88, v89, v88
	ds_read_b128 v[70:73], v88 offset:32768
	ds_read_b128 v[74:77], v88 offset:34816
	ds_read_b128 v[78:81], v88 offset:36864
	ds_read_b128 v[92:95], v88 offset:38912
	v_add_u32_e32 v116, v90, v87
	s_waitcnt lgkmcnt(3)
	v_mfma_f32_16x16x32_bf16 v[60:63], v[66:69], v[70:73], v[60:63]
	s_waitcnt lgkmcnt(2)
	v_mfma_f32_16x16x32_bf16 v[56:59], v[66:69], v[74:77], v[56:59]
	s_waitcnt lgkmcnt(1)
	v_mfma_f32_16x16x32_bf16 v[48:51], v[66:69], v[78:81], v[48:51]
	s_waitcnt lgkmcnt(0)
	v_mfma_f32_16x16x32_bf16 v[40:43], v[66:69], v[92:95], v[40:43]
	ds_read_b128 v[66:69], v91 offset:51200
	s_waitcnt lgkmcnt(0)
	v_mfma_f32_16x16x32_bf16 v[36:39], v[66:69], v[70:73], v[36:39]
	v_mfma_f32_16x16x32_bf16 v[32:35], v[66:69], v[74:77], v[32:35]
	v_mfma_f32_16x16x32_bf16 v[96:99], v[66:69], v[78:81], v[28:31]
	v_mfma_f32_16x16x32_bf16 v[66:69], v[66:69], v[92:95], v[24:27]
	s_nop 2
	ds_read_b128 v[24:27], v91 offset:53248
	s_waitcnt lgkmcnt(0)
	v_mfma_f32_16x16x32_bf16 v[104:107], v[24:27], v[92:95], v[8:11]
	s_nop 2
	ds_read_b128 v[8:11], v91 offset:55296
	v_mfma_f32_16x16x32_bf16 v[20:23], v[24:27], v[70:73], v[20:23]
	s_waitcnt lgkmcnt(0)
	v_mfma_f32_16x16x32_bf16 v[70:73], v[8:11], v[70:73], v[4:7]
	s_nop 2
	ds_read_b128 v[4:7], v116 offset:49152
	v_mfma_f32_16x16x32_bf16 v[100:103], v[24:27], v[78:81], v[12:15]
	s_nop 2
	v_add_u32_e32 v12, v89, v87
	v_mfma_f32_16x16x32_bf16 v[16:19], v[24:27], v[74:77], v[16:19]
	ds_read_b128 v[88:91], v12 offset:32768
	ds_read_b128 v[108:111], v12 offset:36864
	ds_read_b128 v[112:115], v12 offset:38912
	v_mfma_f32_16x16x32_bf16 v[0:3], v[8:11], v[74:77], v[0:3]
	v_mfma_f32_16x16x32_bf16 v[74:77], v[8:11], v[78:81], v[52:55]
	v_mfma_f32_16x16x32_bf16 v[78:81], v[8:11], v[92:95], v[44:47]
	ds_read_b128 v[92:95], v12 offset:34816
	s_waitcnt lgkmcnt(3)
	v_mfma_f32_16x16x32_bf16 v[60:63], v[4:7], v[88:91], v[60:63]
	s_waitcnt lgkmcnt(0)
	v_mfma_f32_16x16x32_bf16 v[44:47], v[4:7], v[92:95], v[56:59]
	v_mfma_f32_16x16x32_bf16 v[28:31], v[4:7], v[108:111], v[48:51]
	v_mfma_f32_16x16x32_bf16 v[12:15], v[4:7], v[112:115], v[40:43]
	ds_read_b128 v[4:7], v116 offset:51200
	s_waitcnt lgkmcnt(0)
	v_mfma_f32_16x16x32_bf16 v[56:59], v[4:7], v[88:91], v[36:39]
	v_mfma_f32_16x16x32_bf16 v[40:43], v[4:7], v[92:95], v[32:35]
	v_mfma_f32_16x16x32_bf16 v[24:27], v[4:7], v[108:111], v[96:99]
	v_mfma_f32_16x16x32_bf16 v[8:11], v[4:7], v[112:115], v[66:69]
	ds_read_b128 v[4:7], v116 offset:53248
	s_nop 0
	ds_read_b128 v[96:99], v116 offset:55296
	s_waitcnt vmcnt(0)
	s_waitcnt lgkmcnt(0)
	v_mfma_f32_16x16x32_bf16 v[32:35], v[96:99], v[92:95], v[0:3]
	s_nop 2
	v_or_b32_e32 v0, s0, v64
	v_lshl_or_b32 v66, v85, 6, s42
	v_cmp_lt_i32_e32 vcc, s33, v66
	v_mfma_f32_16x16x32_bf16 v[52:55], v[4:7], v[88:91], v[20:23]
	s_barrier
	v_mfma_f32_16x16x32_bf16 v[36:39], v[4:7], v[92:95], v[16:19]
	v_mfma_f32_16x16x32_bf16 v[20:23], v[4:7], v[108:111], v[100:103]
	v_mfma_f32_16x16x32_bf16 v[4:7], v[4:7], v[112:115], v[104:107]
	v_mfma_f32_16x16x32_bf16 v[48:51], v[96:99], v[88:91], v[70:73]
	v_mfma_f32_16x16x32_bf16 v[16:19], v[96:99], v[108:111], v[74:77]
	s_nop 1
	v_lshlrev_b32_e32 v70, 2, v84
	v_or_b32_e32 v64, v66, v70
	v_lshl_add_u32 v74, v86, 6, v0
	v_mfma_f32_16x16x32_bf16 v[0:3], v[96:99], v[112:115], v[78:81]
	s_nop 7
	v_readfirstlane_b32 s99, v66
	s_cmpk_lt_u32 s99, 0x400
	s_cbranch_scc0 .Lfe_A_not_q
	s_load_dwordx2 s[100:101], s[56:57], 0x130
	v_and_b32_e32 v152, 1, v84
	v_mul_u32_u24_e32 v152, 12, v152
	v_lshl_add_u32 v152, v84, 2, v152
	v_add_u32_e32 v152, v152, v66
	v_mul_u32_u24_e32 v153, 0xe00, v74
	v_add_u32_e32 v152, v152, v153
	v_lshlrev_b32_e32 v152, 1, v152
	v_add_u32_e32 v153, 0x1c000, v152
	v_add_u32_e32 v154, 0x38000, v152
	v_add_u32_e32 v155, 0x54000, v152
	s_mov_b32 s98, 0x3e38aa3b
	s_nop 3
	v_pk_mul_f32 v[60:61], v[60:61], s[98:99] op_sel_hi:[1,0]
	v_pk_mul_f32 v[62:63], v[62:63], s[98:99] op_sel_hi:[1,0]
	v_pk_mul_f32 v[56:57], v[56:57], s[98:99] op_sel_hi:[1,0]
	v_pk_mul_f32 v[58:59], v[58:59], s[98:99] op_sel_hi:[1,0]
	v_pk_mul_f32 v[52:53], v[52:53], s[98:99] op_sel_hi:[1,0]
	v_pk_mul_f32 v[54:55], v[54:55], s[98:99] op_sel_hi:[1,0]
	v_pk_mul_f32 v[48:49], v[48:49], s[98:99] op_sel_hi:[1,0]
	v_pk_mul_f32 v[50:51], v[50:51], s[98:99] op_sel_hi:[1,0]
	v_cvt_pk_bf16_f32 v120, v60, v61
	v_cvt_pk_bf16_f32 v121, v62, v63
	v_cvt_pk_bf16_f32 v122, v56, v57
	v_cvt_pk_bf16_f32 v123, v58, v59
	v_cvt_pk_bf16_f32 v124, v52, v53
	v_cvt_pk_bf16_f32 v125, v54, v55
	v_cvt_pk_bf16_f32 v126, v48, v49
	v_cvt_pk_bf16_f32 v127, v50, v51
	s_nop 1
	v_permlane16_swap_b32_e32 v120, v122
	v_permlane16_swap_b32_e32 v121, v123
	v_permlane16_swap_b32_e32 v124, v126
	v_permlane16_swap_b32_e32 v125, v127
	s_waitcnt lgkmcnt(0)
; DI unsigned pack2(float a, float b) { v2f f = {a, b}; return __builtin_bit_cast(unsigned, __builtin_convertvector(f, v2bf)); }
; DI float silu_f(float v) { return v / (1.f + fexp(-v)); }
;   DI u32x2 pack(int, int, float a, float b, float c, float d, float&) const { u32x2 v; v.x = pack2(a, b); v.y = pack2(c, d); return v; }
; template <class ARow, class Epi>
; DI void gemm_tile(const ARow& arow, long a_kstride, const u16* __restrict__ Bt, long ldb, int K, int m0, int n0,
;                   const Epi& epi, char* smem) {
;     ...
;       u16* rp = epi.rowp(m) + nh;
; #pragma unroll
;       for (int pp = 0; pp < 2; ++pp) {
;         u32x2 a = pk[2 * pp], b = pk[2 * pp + 1];
;         const u32x2 rx = __builtin_amdgcn_permlane16_swap(a.x, b.x, false, false);
;         const u32x2 ry = __builtin_amdgcn_permlane16_swap(a.y, b.y, false, false);
;         const int nst = (fq & 1) ? ((2 * pp + 1) * 16 + (fq - 1) * 4) : ((2 * pp) * 16 + fq * 4);
;         *(u32x4*)(rp + nst) = (u32x4){rx[0], ry[0], rx[1], ry[1]};
;       }
;   DI u32x2 pack(int m, int n, float a, float b, float c, float d, float& ss) const {
;     if (n < q_end) { a *= qscale; b *= qscale; c *= qscale; d *= qscale; }
;     else if (n >= z_start) { a = silu_f(a); b = silu_f(b); c = silu_f(c); d = silu_f(d); }
;     ss += a * a + b * b + c * c + d * d;
;     u32x2 v; v.x = pack2(a, b); v.y = pack2(c, d);
;     return v;
	global_store_dwordx4 v152, v[120:123], s[100:101] sc0 sc1
	global_store_dwordx4 v152, v[124:127], s[100:101] offset:64 sc0 sc1
	v_pk_mul_f32 v[44:45], v[44:45], s[98:99] op_sel_hi:[1,0]
	v_pk_mul_f32 v[46:47], v[46:47], s[98:99] op_sel_hi:[1,0]
	v_pk_mul_f32 v[40:41], v[40:41], s[98:99] op_sel_hi:[1,0]
	v_pk_mul_f32 v[42:43], v[42:43], s[98:99] op_sel_hi:[1,0]
	v_pk_mul_f32 v[36:37], v[36:37], s[98:99] op_sel_hi:[1,0]
	v_pk_mul_f32 v[38:39], v[38:39], s[98:99] op_sel_hi:[1,0]
	v_pk_mul_f32 v[32:33], v[32:33], s[98:99] op_sel_hi:[1,0]
	v_pk_mul_f32 v[34:35], v[34:35], s[98:99] op_sel_hi:[1,0]
	v_cvt_pk_bf16_f32 v128, v44, v45
	v_cvt_pk_bf16_f32 v129, v46, v47
	v_cvt_pk_bf16_f32 v130, v40, v41
	v_cvt_pk_bf16_f32 v131, v42, v43
	v_cvt_pk_bf16_f32 v132, v36, v37
	v_cvt_pk_bf16_f32 v133, v38, v39
	v_cvt_pk_bf16_f32 v134, v32, v33
	v_cvt_pk_bf16_f32 v135, v34, v35
	s_nop 1
	v_permlane16_swap_b32_e32 v128, v130
	v_permlane16_swap_b32_e32 v129, v131
	v_permlane16_swap_b32_e32 v132, v134
	v_permlane16_swap_b32_e32 v133, v135
	global_store_dwordx4 v153, v[128:131], s[100:101] sc0 sc1
	global_store_dwordx4 v153, v[132:135], s[100:101] offset:64 sc0 sc1
	v_pk_mul_f32 v[28:29], v[28:29], s[98:99] op_sel_hi:[1,0]
	v_pk_mul_f32 v[30:31], v[30:31], s[98:99] op_sel_hi:[1,0]
	v_pk_mul_f32 v[24:25], v[24:25], s[98:99] op_sel_hi:[1,0]
	v_pk_mul_f32 v[26:27], v[26:27], s[98:99] op_sel_hi:[1,0]
	v_pk_mul_f32 v[20:21], v[20:21], s[98:99] op_sel_hi:[1,0]
	v_pk_mul_f32 v[22:23], v[22:23], s[98:99] op_sel_hi:[1,0]
	v_pk_mul_f32 v[16:17], v[16:17], s[98:99] op_sel_hi:[1,0]
	v_pk_mul_f32 v[18:19], v[18:19], s[98:99] op_sel_hi:[1,0]
	v_cvt_pk_bf16_f32 v136, v28, v29
	v_cvt_pk_bf16_f32 v137, v30, v31
	v_cvt_pk_bf16_f32 v138, v24, v25
	v_cvt_pk_bf16_f32 v139, v26, v27
	v_cvt_pk_bf16_f32 v140, v20, v21
	v_cvt_pk_bf16_f32 v141, v22, v23
	v_cvt_pk_bf16_f32 v142, v16, v17
	v_cvt_pk_bf16_f32 v143, v18, v19
	s_nop 1
	v_permlane16_swap_b32_e32 v136, v138
	v_permlane16_swap_b32_e32 v137, v139
	v_permlane16_swap_b32_e32 v140, v142
	v_permlane16_swap_b32_e32 v141, v143
	global_store_dwordx4 v154, v[136:139], s[100:101] sc0 sc1
	global_store_dwordx4 v154, v[140:143], s[100:101] offset:64 sc0 sc1
	v_pk_mul_f32 v[12:13], v[12:13], s[98:99] op_sel_hi:[1,0]
	v_pk_mul_f32 v[14:15], v[14:15], s[98:99] op_sel_hi:[1,0]
	v_pk_mul_f32 v[8:9], v[8:9], s[98:99] op_sel_hi:[1,0]
	v_pk_mul_f32 v[10:11], v[10:11], s[98:99] op_sel_hi:[1,0]
	v_pk_mul_f32 v[4:5], v[4:5], s[98:99] op_sel_hi:[1,0]
	v_pk_mul_f32 v[6:7], v[6:7], s[98:99] op_sel_hi:[1,0]
	v_pk_mul_f32 v[0:1], v[0:1], s[98:99] op_sel_hi:[1,0]
	v_pk_mul_f32 v[2:3], v[2:3], s[98:99] op_sel_hi:[1,0]
	v_cvt_pk_bf16_f32 v144, v12, v13
	v_cvt_pk_bf16_f32 v145, v14, v15
	v_cvt_pk_bf16_f32 v146, v8, v9
	v_cvt_pk_bf16_f32 v147, v10, v11
	v_cvt_pk_bf16_f32 v148, v4, v5
	v_cvt_pk_bf16_f32 v149, v6, v7
	v_cvt_pk_bf16_f32 v150, v0, v1
	v_cvt_pk_bf16_f32 v151, v2, v3
	s_nop 1
	v_permlane16_swap_b32_e32 v144, v146
	v_permlane16_swap_b32_e32 v145, v147
	v_permlane16_swap_b32_e32 v148, v150
	v_permlane16_swap_b32_e32 v149, v151
	global_store_dwordx4 v155, v[144:147], s[100:101] sc0 sc1
	global_store_dwordx4 v155, v[148:151], s[100:101] offset:64 sc0 sc1
	s_branch .Lfe_join_A
.Lfe_A_not_q:
	s_cmpk_ge_u32 s99, 0xa00
	s_cbranch_scc0 .Lfe_A_not_z
	s_cmpk_lt_u32 s99, 0xe00
	s_cbranch_scc0 .Lfe_A_not_z
	s_load_dwordx2 s[100:101], s[56:57], 0x130
	v_and_b32_e32 v152, 1, v84
	v_mul_u32_u24_e32 v152, 12, v152
	v_lshl_add_u32 v152, v84, 2, v152
	v_add_u32_e32 v152, v152, v66
	v_mul_u32_u24_e32 v153, 0xe00, v74
	v_add_u32_e32 v152, v152, v153
	v_lshlrev_b32_e32 v152, 1, v152
	v_add_u32_e32 v153, 0x1c000, v152
	v_add_u32_e32 v154, 0x38000, v152
	v_add_u32_e32 v155, 0x54000, v152
	s_nop 3
	v_mul_f32_e32 v156, 0xbfb8aa3b, v60
	v_mul_f32_e32 v157, 0xbfb8aa3b, v61
	v_mul_f32_e32 v158, 0xbfb8aa3b, v62
	v_mul_f32_e32 v159, 0xbfb8aa3b, v63
	v_mul_f32_e32 v160, 0xbfb8aa3b, v56
	v_mul_f32_e32 v161, 0xbfb8aa3b, v57
	v_mul_f32_e32 v162, 0xbfb8aa3b, v58
	v_mul_f32_e32 v163, 0xbfb8aa3b, v59
	v_exp_f32_e32 v156, v156
	v_exp_f32_e32 v157, v157
	v_exp_f32_e32 v158, v158
	v_exp_f32_e32 v159, v159
	v_exp_f32_e32 v160, v160
	v_exp_f32_e32 v161, v161
	v_exp_f32_e32 v162, v162
	v_exp_f32_e32 v163, v163
	v_add_f32_e32 v156, 1.0, v156
	v_add_f32_e32 v157, 1.0, v157
	v_add_f32_e32 v158, 1.0, v158
	v_add_f32_e32 v159, 1.0, v159
	v_add_f32_e32 v160, 1.0, v160
	v_add_f32_e32 v161, 1.0, v161
	v_add_f32_e32 v162, 1.0, v162
	v_add_f32_e32 v163, 1.0, v163
	v_rcp_f32_e32 v156, v156
	v_rcp_f32_e32 v157, v157
	v_rcp_f32_e32 v158, v158
	v_rcp_f32_e32 v159, v159
	v_rcp_f32_e32 v160, v160
	v_rcp_f32_e32 v161, v161
	v_rcp_f32_e32 v162, v162
	v_rcp_f32_e32 v163, v163
	v_mul_f32_e32 v60, v60, v156
	v_mul_f32_e32 v61, v61, v157
	v_mul_f32_e32 v62, v62, v158
	v_mul_f32_e32 v63, v63, v159
	v_mul_f32_e32 v56, v56, v160
	v_mul_f32_e32 v57, v57, v161
	v_mul_f32_e32 v58, v58, v162
	v_mul_f32_e32 v59, v59, v163
	v_mul_f32_e32 v156, 0xbfb8aa3b, v52
	v_mul_f32_e32 v157, 0xbfb8aa3b, v53
	v_mul_f32_e32 v158, 0xbfb8aa3b, v54
	v_mul_f32_e32 v159, 0xbfb8aa3b, v55
	v_mul_f32_e32 v160, 0xbfb8aa3b, v48
	v_mul_f32_e32 v161, 0xbfb8aa3b, v49
	v_mul_f32_e32 v162, 0xbfb8aa3b, v50
	v_mul_f32_e32 v163, 0xbfb8aa3b, v51
	v_exp_f32_e32 v156, v156
	v_exp_f32_e32 v157, v157
	v_exp_f32_e32 v158, v158
	v_exp_f32_e32 v159, v159
	v_exp_f32_e32 v160, v160
	v_exp_f32_e32 v161, v161
	v_exp_f32_e32 v162, v162
	v_exp_f32_e32 v163, v163
	v_add_f32_e32 v156, 1.0, v156
	v_add_f32_e32 v157, 1.0, v157
	v_add_f32_e32 v158, 1.0, v158
	v_add_f32_e32 v159, 1.0, v159
	v_add_f32_e32 v160, 1.0, v160
	v_add_f32_e32 v161, 1.0, v161
	v_add_f32_e32 v162, 1.0, v162
	v_add_f32_e32 v163, 1.0, v163
	v_rcp_f32_e32 v156, v156
	v_rcp_f32_e32 v157, v157
	v_rcp_f32_e32 v158, v158
	v_rcp_f32_e32 v159, v159
	v_rcp_f32_e32 v160, v160
	v_rcp_f32_e32 v161, v161
	v_rcp_f32_e32 v162, v162
	v_rcp_f32_e32 v163, v163
	v_mul_f32_e32 v52, v52, v156
	v_mul_f32_e32 v53, v53, v157
	v_mul_f32_e32 v54, v54, v158
	v_mul_f32_e32 v55, v55, v159
	v_mul_f32_e32 v48, v48, v160
	v_mul_f32_e32 v49, v49, v161
	v_mul_f32_e32 v50, v50, v162
	v_mul_f32_e32 v51, v51, v163
	v_cvt_pk_bf16_f32 v120, v60, v61
	v_cvt_pk_bf16_f32 v121, v62, v63
	v_cvt_pk_bf16_f32 v122, v56, v57
	v_cvt_pk_bf16_f32 v123, v58, v59
	v_cvt_pk_bf16_f32 v124, v52, v53
	v_cvt_pk_bf16_f32 v125, v54, v55
	v_cvt_pk_bf16_f32 v126, v48, v49
	v_cvt_pk_bf16_f32 v127, v50, v51
	s_nop 1
	v_permlane16_swap_b32_e32 v120, v122
	v_permlane16_swap_b32_e32 v121, v123
	v_permlane16_swap_b32_e32 v124, v126
	v_permlane16_swap_b32_e32 v125, v127
	s_waitcnt lgkmcnt(0)
; DI unsigned pack2(float a, float b) { v2f f = {a, b}; return __builtin_bit_cast(unsigned, __builtin_convertvector(f, v2bf)); }
; DI float silu_f(float v) { return v / (1.f + fexp(-v)); }
; template <class ARow, class Epi>
; DI void gemm_tile(const ARow& arow, long a_kstride, const u16* __restrict__ Bt, long ldb, int K, int m0, int n0,
;                   const Epi& epi, char* smem) {
;     ...
;       u16* rp = epi.rowp(m) + nh;
; #pragma unroll
;       for (int pp = 0; pp < 2; ++pp) {
;         u32x2 a = pk[2 * pp], b = pk[2 * pp + 1];
;         const u32x2 rx = __builtin_amdgcn_permlane16_swap(a.x, b.x, false, false);
;         const u32x2 ry = __builtin_amdgcn_permlane16_swap(a.y, b.y, false, false);
;         const int nst = (fq & 1) ? ((2 * pp + 1) * 16 + (fq - 1) * 4) : ((2 * pp) * 16 + fq * 4);
;         *(u32x4*)(rp + nst) = (u32x4){rx[0], ry[0], rx[1], ry[1]};
;       }
;   DI u32x2 pack(int m, int n, float a, float b, float c, float d, float& ss) const {
;     ...
;     else if (n >= z_start) { a = silu_f(a); b = silu_f(b); c = silu_f(c); d = silu_f(d); }
;     ss += a * a + b * b + c * c + d * d;
;     u32x2 v; v.x = pack2(a, b); v.y = pack2(c, d);
;     return v;
	global_store_dwordx4 v152, v[120:123], s[100:101] sc0 sc1
	global_store_dwordx4 v152, v[124:127], s[100:101] offset:64 sc0 sc1
	v_mul_f32_e32 v156, 0xbfb8aa3b, v44
	v_mul_f32_e32 v157, 0xbfb8aa3b, v45
	v_mul_f32_e32 v158, 0xbfb8aa3b, v46
	v_mul_f32_e32 v159, 0xbfb8aa3b, v47
	v_mul_f32_e32 v160, 0xbfb8aa3b, v40
	v_mul_f32_e32 v161, 0xbfb8aa3b, v41
	v_mul_f32_e32 v162, 0xbfb8aa3b, v42
	v_mul_f32_e32 v163, 0xbfb8aa3b, v43
	v_exp_f32_e32 v156, v156
	v_exp_f32_e32 v157, v157
	v_exp_f32_e32 v158, v158
	v_exp_f32_e32 v159, v159
	v_exp_f32_e32 v160, v160
	v_exp_f32_e32 v161, v161
	v_exp_f32_e32 v162, v162
	v_exp_f32_e32 v163, v163
	v_add_f32_e32 v156, 1.0, v156
	v_add_f32_e32 v157, 1.0, v157
	v_add_f32_e32 v158, 1.0, v158
	v_add_f32_e32 v159, 1.0, v159
	v_add_f32_e32 v160, 1.0, v160
	v_add_f32_e32 v161, 1.0, v161
	v_add_f32_e32 v162, 1.0, v162
	v_add_f32_e32 v163, 1.0, v163
	v_rcp_f32_e32 v156, v156
	v_rcp_f32_e32 v157, v157
	v_rcp_f32_e32 v158, v158
	v_rcp_f32_e32 v159, v159
	v_rcp_f32_e32 v160, v160
	v_rcp_f32_e32 v161, v161
	v_rcp_f32_e32 v162, v162
	v_rcp_f32_e32 v163, v163
	v_mul_f32_e32 v44, v44, v156
	v_mul_f32_e32 v45, v45, v157
	v_mul_f32_e32 v46, v46, v158
	v_mul_f32_e32 v47, v47, v159
	v_mul_f32_e32 v40, v40, v160
	v_mul_f32_e32 v41, v41, v161
	v_mul_f32_e32 v42, v42, v162
	v_mul_f32_e32 v43, v43, v163
	v_mul_f32_e32 v156, 0xbfb8aa3b, v36
	v_mul_f32_e32 v157, 0xbfb8aa3b, v37
	v_mul_f32_e32 v158, 0xbfb8aa3b, v38
	v_mul_f32_e32 v159, 0xbfb8aa3b, v39
	v_mul_f32_e32 v160, 0xbfb8aa3b, v32
	v_mul_f32_e32 v161, 0xbfb8aa3b, v33
	v_mul_f32_e32 v162, 0xbfb8aa3b, v34
	v_mul_f32_e32 v163, 0xbfb8aa3b, v35
	v_exp_f32_e32 v156, v156
	v_exp_f32_e32 v157, v157
	v_exp_f32_e32 v158, v158
	v_exp_f32_e32 v159, v159
	v_exp_f32_e32 v160, v160
	v_exp_f32_e32 v161, v161
	v_exp_f32_e32 v162, v162
	v_exp_f32_e32 v163, v163
	v_add_f32_e32 v156, 1.0, v156
	v_add_f32_e32 v157, 1.0, v157
	v_add_f32_e32 v158, 1.0, v158
	v_add_f32_e32 v159, 1.0, v159
	v_add_f32_e32 v160, 1.0, v160
	v_add_f32_e32 v161, 1.0, v161
	v_add_f32_e32 v162, 1.0, v162
	v_add_f32_e32 v163, 1.0, v163
	v_rcp_f32_e32 v156, v156
	v_rcp_f32_e32 v157, v157
	v_rcp_f32_e32 v158, v158
	v_rcp_f32_e32 v159, v159
	v_rcp_f32_e32 v160, v160
	v_rcp_f32_e32 v161, v161
	v_rcp_f32_e32 v162, v162
	v_rcp_f32_e32 v163, v163
	v_mul_f32_e32 v36, v36, v156
	v_mul_f32_e32 v37, v37, v157
	v_mul_f32_e32 v38, v38, v158
	v_mul_f32_e32 v39, v39, v159
	v_mul_f32_e32 v32, v32, v160
	v_mul_f32_e32 v33, v33, v161
	v_mul_f32_e32 v34, v34, v162
	v_mul_f32_e32 v35, v35, v163
	v_cvt_pk_bf16_f32 v128, v44, v45
	v_cvt_pk_bf16_f32 v129, v46, v47
	v_cvt_pk_bf16_f32 v130, v40, v41
	v_cvt_pk_bf16_f32 v131, v42, v43
	v_cvt_pk_bf16_f32 v132, v36, v37
	v_cvt_pk_bf16_f32 v133, v38, v39
	v_cvt_pk_bf16_f32 v134, v32, v33
	v_cvt_pk_bf16_f32 v135, v34, v35
	s_nop 1
	v_permlane16_swap_b32_e32 v128, v130
	v_permlane16_swap_b32_e32 v129, v131
	v_permlane16_swap_b32_e32 v132, v134
	v_permlane16_swap_b32_e32 v133, v135
	global_store_dwordx4 v153, v[128:131], s[100:101] sc0 sc1
	global_store_dwordx4 v153, v[132:135], s[100:101] offset:64 sc0 sc1
	v_mul_f32_e32 v156, 0xbfb8aa3b, v28
	v_mul_f32_e32 v157, 0xbfb8aa3b, v29
	v_mul_f32_e32 v158, 0xbfb8aa3b, v30
	v_mul_f32_e32 v159, 0xbfb8aa3b, v31
	v_mul_f32_e32 v160, 0xbfb8aa3b, v24
	v_mul_f32_e32 v161, 0xbfb8aa3b, v25
	v_mul_f32_e32 v162, 0xbfb8aa3b, v26
	v_mul_f32_e32 v163, 0xbfb8aa3b, v27
	v_exp_f32_e32 v156, v156
	v_exp_f32_e32 v157, v157
	v_exp_f32_e32 v158, v158
	v_exp_f32_e32 v159, v159
	v_exp_f32_e32 v160, v160
	v_exp_f32_e32 v161, v161
	v_exp_f32_e32 v162, v162
	v_exp_f32_e32 v163, v163
	v_add_f32_e32 v156, 1.0, v156
	v_add_f32_e32 v157, 1.0, v157
	v_add_f32_e32 v158, 1.0, v158
	v_add_f32_e32 v159, 1.0, v159
	v_add_f32_e32 v160, 1.0, v160
	v_add_f32_e32 v161, 1.0, v161
	v_add_f32_e32 v162, 1.0, v162
	v_add_f32_e32 v163, 1.0, v163
	v_rcp_f32_e32 v156, v156
	v_rcp_f32_e32 v157, v157
	v_rcp_f32_e32 v158, v158
	v_rcp_f32_e32 v159, v159
	v_rcp_f32_e32 v160, v160
	v_rcp_f32_e32 v161, v161
	v_rcp_f32_e32 v162, v162
	v_rcp_f32_e32 v163, v163
	v_mul_f32_e32 v28, v28, v156
	v_mul_f32_e32 v29, v29, v157
	v_mul_f32_e32 v30, v30, v158
	v_mul_f32_e32 v31, v31, v159
	v_mul_f32_e32 v24, v24, v160
	v_mul_f32_e32 v25, v25, v161
	v_mul_f32_e32 v26, v26, v162
	v_mul_f32_e32 v27, v27, v163
	v_mul_f32_e32 v156, 0xbfb8aa3b, v20
	v_mul_f32_e32 v157, 0xbfb8aa3b, v21
	v_mul_f32_e32 v158, 0xbfb8aa3b, v22
	v_mul_f32_e32 v159, 0xbfb8aa3b, v23
	v_mul_f32_e32 v160, 0xbfb8aa3b, v16
	v_mul_f32_e32 v161, 0xbfb8aa3b, v17
	v_mul_f32_e32 v162, 0xbfb8aa3b, v18
	v_mul_f32_e32 v163, 0xbfb8aa3b, v19
	v_exp_f32_e32 v156, v156
	v_exp_f32_e32 v157, v157
	v_exp_f32_e32 v158, v158
	v_exp_f32_e32 v159, v159
	v_exp_f32_e32 v160, v160
	v_exp_f32_e32 v161, v161
	v_exp_f32_e32 v162, v162
	v_exp_f32_e32 v163, v163
	v_add_f32_e32 v156, 1.0, v156
	v_add_f32_e32 v157, 1.0, v157
	v_add_f32_e32 v158, 1.0, v158
	v_add_f32_e32 v159, 1.0, v159
	v_add_f32_e32 v160, 1.0, v160
	v_add_f32_e32 v161, 1.0, v161
	v_add_f32_e32 v162, 1.0, v162
	v_add_f32_e32 v163, 1.0, v163
	v_rcp_f32_e32 v156, v156
	v_rcp_f32_e32 v157, v157
	v_rcp_f32_e32 v158, v158
	v_rcp_f32_e32 v159, v159
	v_rcp_f32_e32 v160, v160
	v_rcp_f32_e32 v161, v161
	v_rcp_f32_e32 v162, v162
	v_rcp_f32_e32 v163, v163
	v_mul_f32_e32 v20, v20, v156
	v_mul_f32_e32 v21, v21, v157
	v_mul_f32_e32 v22, v22, v158
	v_mul_f32_e32 v23, v23, v159
	v_mul_f32_e32 v16, v16, v160
	v_mul_f32_e32 v17, v17, v161
	v_mul_f32_e32 v18, v18, v162
	v_mul_f32_e32 v19, v19, v163
	v_cvt_pk_bf16_f32 v136, v28, v29
	v_cvt_pk_bf16_f32 v137, v30, v31
	v_cvt_pk_bf16_f32 v138, v24, v25
	v_cvt_pk_bf16_f32 v139, v26, v27
; DI unsigned pack2(float a, float b) { v2f f = {a, b}; return __builtin_bit_cast(unsigned, __builtin_convertvector(f, v2bf)); }
; DI float silu_f(float v) { return v / (1.f + fexp(-v)); }
;   DI u32x2 pack(int, int, float a, float b, float c, float d, float&) const { u32x2 v; v.x = pack2(a, b); v.y = pack2(c, d); return v; }
;   DI u32x2 pack(int m, int n, float a, float b, float c, float d, float& ss) const {
;     if (n < q_end) { a *= qscale; b *= qscale; c *= qscale; d *= qscale; }
;     else if (n >= z_start) { a = silu_f(a); b = silu_f(b); c = silu_f(c); d = silu_f(d); }
;     ss += a * a + b * b + c * c + d * d;
;     u32x2 v; v.x = pack2(a, b); v.y = pack2(c, d);
;     return v;
;   DI void finish16(int m, int nh, float ss) const {
;     if (nh >= kn_lo && nh < kn_hi) {
;       ss += __shfl_xor(ss, 16); ss += __shfl_xor(ss, 32);
; #pragma unroll
;       for (int o = 8; o > 0; o >>= 1) ss = fmaxf(ss, __shfl_xor(ss, o));
	v_cvt_pk_bf16_f32 v140, v20, v21
	v_cvt_pk_bf16_f32 v141, v22, v23
	v_cvt_pk_bf16_f32 v142, v16, v17
	v_cvt_pk_bf16_f32 v143, v18, v19
	s_nop 1
	v_permlane16_swap_b32_e32 v136, v138
	v_permlane16_swap_b32_e32 v137, v139
	v_permlane16_swap_b32_e32 v140, v142
	v_permlane16_swap_b32_e32 v141, v143
	global_store_dwordx4 v154, v[136:139], s[100:101] sc0 sc1
	global_store_dwordx4 v154, v[140:143], s[100:101] offset:64 sc0 sc1
	v_mul_f32_e32 v156, 0xbfb8aa3b, v12
	v_mul_f32_e32 v157, 0xbfb8aa3b, v13
	v_mul_f32_e32 v158, 0xbfb8aa3b, v14
	v_mul_f32_e32 v159, 0xbfb8aa3b, v15
	v_mul_f32_e32 v160, 0xbfb8aa3b, v8
	v_mul_f32_e32 v161, 0xbfb8aa3b, v9
	v_mul_f32_e32 v162, 0xbfb8aa3b, v10
	v_mul_f32_e32 v163, 0xbfb8aa3b, v11
	v_exp_f32_e32 v156, v156
	v_exp_f32_e32 v157, v157
	v_exp_f32_e32 v158, v158
	v_exp_f32_e32 v159, v159
	v_exp_f32_e32 v160, v160
	v_exp_f32_e32 v161, v161
	v_exp_f32_e32 v162, v162
	v_exp_f32_e32 v163, v163
	v_add_f32_e32 v156, 1.0, v156
	v_add_f32_e32 v157, 1.0, v157
	v_add_f32_e32 v158, 1.0, v158
	v_add_f32_e32 v159, 1.0, v159
	v_add_f32_e32 v160, 1.0, v160
	v_add_f32_e32 v161, 1.0, v161
	v_add_f32_e32 v162, 1.0, v162
	v_add_f32_e32 v163, 1.0, v163
	v_rcp_f32_e32 v156, v156
	v_rcp_f32_e32 v157, v157
	v_rcp_f32_e32 v158, v158
	v_rcp_f32_e32 v159, v159
	v_rcp_f32_e32 v160, v160
	v_rcp_f32_e32 v161, v161
	v_rcp_f32_e32 v162, v162
	v_rcp_f32_e32 v163, v163
	v_mul_f32_e32 v12, v12, v156
	v_mul_f32_e32 v13, v13, v157
	v_mul_f32_e32 v14, v14, v158
	v_mul_f32_e32 v15, v15, v159
	v_mul_f32_e32 v8, v8, v160
	v_mul_f32_e32 v9, v9, v161
	v_mul_f32_e32 v10, v10, v162
	v_mul_f32_e32 v11, v11, v163
	v_mul_f32_e32 v156, 0xbfb8aa3b, v4
	v_mul_f32_e32 v157, 0xbfb8aa3b, v5
	v_mul_f32_e32 v158, 0xbfb8aa3b, v6
	v_mul_f32_e32 v159, 0xbfb8aa3b, v7
	v_mul_f32_e32 v160, 0xbfb8aa3b, v0
	v_mul_f32_e32 v161, 0xbfb8aa3b, v1
	v_mul_f32_e32 v162, 0xbfb8aa3b, v2
	v_mul_f32_e32 v163, 0xbfb8aa3b, v3
	v_exp_f32_e32 v156, v156
	v_exp_f32_e32 v157, v157
	v_exp_f32_e32 v158, v158
	v_exp_f32_e32 v159, v159
	v_exp_f32_e32 v160, v160
	v_exp_f32_e32 v161, v161
	v_exp_f32_e32 v162, v162
	v_exp_f32_e32 v163, v163
	v_add_f32_e32 v156, 1.0, v156
	v_add_f32_e32 v157, 1.0, v157
	v_add_f32_e32 v158, 1.0, v158
	v_add_f32_e32 v159, 1.0, v159
	v_add_f32_e32 v160, 1.0, v160
	v_add_f32_e32 v161, 1.0, v161
	v_add_f32_e32 v162, 1.0, v162
	v_add_f32_e32 v163, 1.0, v163
	v_rcp_f32_e32 v156, v156
	v_rcp_f32_e32 v157, v157
	v_rcp_f32_e32 v158, v158
	v_rcp_f32_e32 v159, v159
	v_rcp_f32_e32 v160, v160
	v_rcp_f32_e32 v161, v161
	v_rcp_f32_e32 v162, v162
	v_rcp_f32_e32 v163, v163
	v_mul_f32_e32 v4, v4, v156
	v_mul_f32_e32 v5, v5, v157
	v_mul_f32_e32 v6, v6, v158
	v_mul_f32_e32 v7, v7, v159
	v_mul_f32_e32 v0, v0, v160
	v_mul_f32_e32 v1, v1, v161
	v_mul_f32_e32 v2, v2, v162
	v_mul_f32_e32 v3, v3, v163
	v_cvt_pk_bf16_f32 v144, v12, v13
	v_cvt_pk_bf16_f32 v145, v14, v15
	v_cvt_pk_bf16_f32 v146, v8, v9
	v_cvt_pk_bf16_f32 v147, v10, v11
	v_cvt_pk_bf16_f32 v148, v4, v5
	v_cvt_pk_bf16_f32 v149, v6, v7
	v_cvt_pk_bf16_f32 v150, v0, v1
	v_cvt_pk_bf16_f32 v151, v2, v3
	s_nop 1
	v_permlane16_swap_b32_e32 v144, v146
	v_permlane16_swap_b32_e32 v145, v147
	v_permlane16_swap_b32_e32 v148, v150
	v_permlane16_swap_b32_e32 v149, v151
	global_store_dwordx4 v155, v[144:147], s[100:101] sc0 sc1
	global_store_dwordx4 v155, v[148:151], s[100:101] offset:64 sc0 sc1
	s_branch .Lfe_join_A
.Lfe_A_not_z:
	s_cmpk_ge_u32 s99, 0x400
	s_cbranch_scc0 .Lfe_A_not_k
	s_cmpk_lt_u32 s99, 0xa00
	s_cbranch_scc0 .Lfe_A_not_k
	s_load_dwordx2 s[100:101], s[56:57], 0x130
	v_and_b32_e32 v152, 1, v84
	v_mul_u32_u24_e32 v152, 12, v152
	v_lshl_add_u32 v152, v84, 2, v152
	v_add_u32_e32 v152, v152, v66
	v_mul_u32_u24_e32 v153, 0xe00, v74
	v_add_u32_e32 v152, v152, v153
	v_lshlrev_b32_e32 v152, 1, v152
	v_add_u32_e32 v153, 0x1c000, v152
	v_add_u32_e32 v154, 0x38000, v152
	v_add_u32_e32 v155, 0x54000, v152
	s_load_dwordx2 s[98:99], s[56:57], 0x100
	v_lshrrev_b32_e32 v174, 6, v66
	v_lshrrev_b32_e32 v175, 13, v74
	v_lshl_add_u32 v174, v175, 6, v174
	v_lshlrev_b32_e32 v174, 2, v174
	s_nop 3
	v_pk_mul_f32 v[156:157], v[60:61], v[60:61]
	v_pk_mul_f32 v[158:159], v[62:63], v[62:63]
	v_pk_mul_f32 v[160:161], v[56:57], v[56:57]
	v_pk_mul_f32 v[162:163], v[58:59], v[58:59]
	v_pk_mul_f32 v[164:165], v[52:53], v[52:53]
	v_pk_mul_f32 v[166:167], v[54:55], v[54:55]
	v_pk_mul_f32 v[168:169], v[48:49], v[48:49]
	v_pk_mul_f32 v[170:171], v[50:51], v[50:51]
	v_add_f32_e32 v172, v157, v156
	v_add_f32_e32 v172, v158, v172
	v_add_f32_e32 v172, v159, v172
	v_add_f32_e32 v173, v161, v160
	v_add_f32_e32 v173, v162, v173
	v_add_f32_e32 v173, v163, v173
	v_add_f32_e32 v172, v172, v173
	v_add_f32_e32 v173, v165, v164
	v_add_f32_e32 v173, v166, v173
	v_add_f32_e32 v173, v167, v173
	v_add_f32_e32 v172, v172, v173
	v_add_f32_e32 v173, v169, v168
	v_add_f32_e32 v173, v170, v173
	v_add_f32_e32 v173, v171, v173
	v_add_f32_e32 v172, v172, v173
	v_mov_b32_e32 v173, v172
	s_nop 1
	v_permlane16_swap_b32_e32 v173, v172
	v_add_f32_e32 v172, v172, v173
	v_mov_b32_e32 v173, v172
	s_nop 1
	v_permlane32_swap_b32_e32 v173, v172
	v_add_f32_e32 v172, v172, v173
	s_nop 1
	v_max_f32_dpp v172, v172, v172 row_ror:8 row_mask:0xf bank_mask:0xf
	s_nop 1
	v_max_f32_dpp v173, v172, v172 row_shl:4 row_mask:0xf bank_mask:0x5
	v_max_f32_dpp v173, v172, v172 row_shr:4 row_mask:0xf bank_mask:0xa
	s_nop 1
	v_max_f32_dpp v172, v173, v173 quad_perm:[2,3,0,1] row_mask:0xf bank_mask:0xf
	s_nop 1
	v_max_f32_dpp v172, v172, v172 quad_perm:[1,0,3,2] row_mask:0xf bank_mask:0xf
	v_mov_b32_e32 v176, v172
	v_pk_mul_f32 v[156:157], v[44:45], v[44:45]
	v_pk_mul_f32 v[158:159], v[46:47], v[46:47]
; DI int ltid() { int x = threadIdx.x; asm volatile("" : "+v"(x)); return x; }
; template <class ARow, class Epi>
; DI void gemm_tile(const ARow& arow, long a_kstride, const u16* __restrict__ Bt, long ldb, int K, int m0, int n0,
;                   const Epi& epi, char* smem) {
;     ...
;       u16* rp = epi.rowp(m) + nh;
; #pragma unroll
;       for (int pp = 0; pp < 2; ++pp) {
;         u32x2 a = pk[2 * pp], b = pk[2 * pp + 1];
;         const u32x2 rx = __builtin_amdgcn_permlane16_swap(a.x, b.x, false, false);
;         const u32x2 ry = __builtin_amdgcn_permlane16_swap(a.y, b.y, false, false);
;         const int nst = (fq & 1) ? ((2 * pp + 1) * 16 + (fq - 1) * 4) : ((2 * pp) * 16 + fq * 4);
;         *(u32x4*)(rp + nst) = (u32x4){rx[0], ry[0], rx[1], ry[1]};
;       }
;   DI void finish16(int m, int nh, float ss) const {
;     if (nh >= kn_lo && nh < kn_hi) {
;       ss += __shfl_xor(ss, 16); ss += __shfl_xor(ss, 32);
; #pragma unroll
;       for (int o = 8; o > 0; o >>= 1) ss = fmaxf(ss, __shfl_xor(ss, o));
;       if ((ltid() & 63) == 0) atomicMax(kmax2 + (m >> 13) * 64 + (nh >> 6), __float_as_uint(ss));
;     }
	v_pk_mul_f32 v[160:161], v[40:41], v[40:41]
	v_pk_mul_f32 v[162:163], v[42:43], v[42:43]
	v_pk_mul_f32 v[164:165], v[36:37], v[36:37]
	v_pk_mul_f32 v[166:167], v[38:39], v[38:39]
	v_pk_mul_f32 v[168:169], v[32:33], v[32:33]
	v_pk_mul_f32 v[170:171], v[34:35], v[34:35]
	v_add_f32_e32 v172, v157, v156
	v_add_f32_e32 v172, v158, v172
	v_add_f32_e32 v172, v159, v172
	v_add_f32_e32 v173, v161, v160
	v_add_f32_e32 v173, v162, v173
	v_add_f32_e32 v173, v163, v173
	v_add_f32_e32 v172, v172, v173
	v_add_f32_e32 v173, v165, v164
	v_add_f32_e32 v173, v166, v173
	v_add_f32_e32 v173, v167, v173
	v_add_f32_e32 v172, v172, v173
	v_add_f32_e32 v173, v169, v168
	v_add_f32_e32 v173, v170, v173
	v_add_f32_e32 v173, v171, v173
	v_add_f32_e32 v172, v172, v173
	v_mov_b32_e32 v173, v172
	s_nop 1
	v_permlane16_swap_b32_e32 v173, v172
	v_add_f32_e32 v172, v172, v173
	v_mov_b32_e32 v173, v172
	s_nop 1
	v_permlane32_swap_b32_e32 v173, v172
	v_add_f32_e32 v172, v172, v173
	s_nop 1
	v_max_f32_dpp v172, v172, v172 row_ror:8 row_mask:0xf bank_mask:0xf
	s_nop 1
	v_max_f32_dpp v173, v172, v172 row_shl:4 row_mask:0xf bank_mask:0x5
	v_max_f32_dpp v173, v172, v172 row_shr:4 row_mask:0xf bank_mask:0xa
	s_nop 1
	v_max_f32_dpp v172, v173, v173 quad_perm:[2,3,0,1] row_mask:0xf bank_mask:0xf
	s_nop 1
	v_max_f32_dpp v172, v172, v172 quad_perm:[1,0,3,2] row_mask:0xf bank_mask:0xf
	v_max_f32_e32 v176, v176, v172
	v_pk_mul_f32 v[156:157], v[28:29], v[28:29]
	v_pk_mul_f32 v[158:159], v[30:31], v[30:31]
	v_pk_mul_f32 v[160:161], v[24:25], v[24:25]
	v_pk_mul_f32 v[162:163], v[26:27], v[26:27]
	v_pk_mul_f32 v[164:165], v[20:21], v[20:21]
	v_pk_mul_f32 v[166:167], v[22:23], v[22:23]
	v_pk_mul_f32 v[168:169], v[16:17], v[16:17]
	v_pk_mul_f32 v[170:171], v[18:19], v[18:19]
	v_add_f32_e32 v172, v157, v156
	v_add_f32_e32 v172, v158, v172
	v_add_f32_e32 v172, v159, v172
	v_add_f32_e32 v173, v161, v160
	v_add_f32_e32 v173, v162, v173
	v_add_f32_e32 v173, v163, v173
	v_add_f32_e32 v172, v172, v173
	v_add_f32_e32 v173, v165, v164
	v_add_f32_e32 v173, v166, v173
	v_add_f32_e32 v173, v167, v173
	v_add_f32_e32 v172, v172, v173
	v_add_f32_e32 v173, v169, v168
	v_add_f32_e32 v173, v170, v173
	v_add_f32_e32 v173, v171, v173
	v_add_f32_e32 v172, v172, v173
	v_mov_b32_e32 v173, v172
	s_nop 1
	v_permlane16_swap_b32_e32 v173, v172
	v_add_f32_e32 v172, v172, v173
	v_mov_b32_e32 v173, v172
	s_nop 1
	v_permlane32_swap_b32_e32 v173, v172
	v_add_f32_e32 v172, v172, v173
	s_nop 1
	v_max_f32_dpp v172, v172, v172 row_ror:8 row_mask:0xf bank_mask:0xf
	s_nop 1
	v_max_f32_dpp v173, v172, v172 row_shl:4 row_mask:0xf bank_mask:0x5
	v_max_f32_dpp v173, v172, v172 row_shr:4 row_mask:0xf bank_mask:0xa
	s_nop 1
	v_max_f32_dpp v172, v173, v173 quad_perm:[2,3,0,1] row_mask:0xf bank_mask:0xf
	s_nop 1
	v_max_f32_dpp v172, v172, v172 quad_perm:[1,0,3,2] row_mask:0xf bank_mask:0xf
	v_max_f32_e32 v176, v176, v172
	v_pk_mul_f32 v[156:157], v[12:13], v[12:13]
	v_pk_mul_f32 v[158:159], v[14:15], v[14:15]
	v_pk_mul_f32 v[160:161], v[8:9], v[8:9]
	v_pk_mul_f32 v[162:163], v[10:11], v[10:11]
	v_pk_mul_f32 v[164:165], v[4:5], v[4:5]
	v_pk_mul_f32 v[166:167], v[6:7], v[6:7]
	v_pk_mul_f32 v[168:169], v[0:1], v[0:1]
	v_pk_mul_f32 v[170:171], v[2:3], v[2:3]
	v_add_f32_e32 v172, v157, v156
	v_add_f32_e32 v172, v158, v172
	v_add_f32_e32 v172, v159, v172
	v_add_f32_e32 v173, v161, v160
	v_add_f32_e32 v173, v162, v173
	v_add_f32_e32 v173, v163, v173
	v_add_f32_e32 v172, v172, v173
	v_add_f32_e32 v173, v165, v164
	v_add_f32_e32 v173, v166, v173
	v_add_f32_e32 v173, v167, v173
	v_add_f32_e32 v172, v172, v173
	v_add_f32_e32 v173, v169, v168
	v_add_f32_e32 v173, v170, v173
	v_add_f32_e32 v173, v171, v173
	v_add_f32_e32 v172, v172, v173
	v_mov_b32_e32 v173, v172
	s_nop 1
	v_permlane16_swap_b32_e32 v173, v172
	v_add_f32_e32 v172, v172, v173
	v_mov_b32_e32 v173, v172
	s_nop 1
	v_permlane32_swap_b32_e32 v173, v172
	v_add_f32_e32 v172, v172, v173
	s_nop 1
	v_max_f32_dpp v172, v172, v172 row_ror:8 row_mask:0xf bank_mask:0xf
	s_nop 1
	v_max_f32_dpp v173, v172, v172 row_shl:4 row_mask:0xf bank_mask:0x5
	v_max_f32_dpp v173, v172, v172 row_shr:4 row_mask:0xf bank_mask:0xa
	s_nop 1
	v_max_f32_dpp v172, v173, v173 quad_perm:[2,3,0,1] row_mask:0xf bank_mask:0xf
	s_nop 1
	v_max_f32_dpp v172, v172, v172 quad_perm:[1,0,3,2] row_mask:0xf bank_mask:0xf
	v_max_f32_e32 v176, v176, v172
	v_and_b32_e32 v175, 63, v222
	v_cmp_eq_u32_e32 vcc, 0, v175
	s_waitcnt lgkmcnt(0)
	s_and_b64 exec, exec, vcc
	global_atomic_umax v174, v176, s[98:99]
	s_mov_b64 exec, -1
	s_nop 3
	v_cvt_pk_bf16_f32 v120, v60, v61
	v_cvt_pk_bf16_f32 v121, v62, v63
	v_cvt_pk_bf16_f32 v122, v56, v57
	v_cvt_pk_bf16_f32 v123, v58, v59
	v_cvt_pk_bf16_f32 v124, v52, v53
	v_cvt_pk_bf16_f32 v125, v54, v55
	v_cvt_pk_bf16_f32 v126, v48, v49
	v_cvt_pk_bf16_f32 v127, v50, v51
	s_nop 1
	v_permlane16_swap_b32_e32 v120, v122
	v_permlane16_swap_b32_e32 v121, v123
	v_permlane16_swap_b32_e32 v124, v126
	v_permlane16_swap_b32_e32 v125, v127
	s_waitcnt lgkmcnt(0)
	global_store_dwordx4 v152, v[120:123], s[100:101] sc0 sc1
	global_store_dwordx4 v152, v[124:127], s[100:101] offset:64 sc0 sc1
	v_cvt_pk_bf16_f32 v128, v44, v45
	v_cvt_pk_bf16_f32 v129, v46, v47
	v_cvt_pk_bf16_f32 v130, v40, v41
	v_cvt_pk_bf16_f32 v131, v42, v43
	v_cvt_pk_bf16_f32 v132, v36, v37
	v_cvt_pk_bf16_f32 v133, v38, v39
	v_cvt_pk_bf16_f32 v134, v32, v33
	v_cvt_pk_bf16_f32 v135, v34, v35
	s_nop 1
	v_permlane16_swap_b32_e32 v128, v130
	v_permlane16_swap_b32_e32 v129, v131
	v_permlane16_swap_b32_e32 v132, v134
	v_permlane16_swap_b32_e32 v133, v135
	global_store_dwordx4 v153, v[128:131], s[100:101] sc0 sc1
	global_store_dwordx4 v153, v[132:135], s[100:101] offset:64 sc0 sc1
	v_cvt_pk_bf16_f32 v136, v28, v29
	v_cvt_pk_bf16_f32 v137, v30, v31
	v_cvt_pk_bf16_f32 v138, v24, v25
	v_cvt_pk_bf16_f32 v139, v26, v27
	v_cvt_pk_bf16_f32 v140, v20, v21
	v_cvt_pk_bf16_f32 v141, v22, v23
	v_cvt_pk_bf16_f32 v142, v16, v17
	v_cvt_pk_bf16_f32 v143, v18, v19
	s_nop 1
	v_permlane16_swap_b32_e32 v136, v138
	v_permlane16_swap_b32_e32 v137, v139
	v_permlane16_swap_b32_e32 v140, v142
	v_permlane16_swap_b32_e32 v141, v143
	global_store_dwordx4 v154, v[136:139], s[100:101] sc0 sc1
	global_store_dwordx4 v154, v[140:143], s[100:101] offset:64 sc0 sc1
	v_cvt_pk_bf16_f32 v144, v12, v13
	v_cvt_pk_bf16_f32 v145, v14, v15
	v_cvt_pk_bf16_f32 v146, v8, v9
	v_cvt_pk_bf16_f32 v147, v10, v11
	v_cvt_pk_bf16_f32 v148, v4, v5
	v_cvt_pk_bf16_f32 v149, v6, v7
	v_cvt_pk_bf16_f32 v150, v0, v1
	v_cvt_pk_bf16_f32 v151, v2, v3
	s_nop 1
	v_permlane16_swap_b32_e32 v144, v146
	v_permlane16_swap_b32_e32 v145, v147
	v_permlane16_swap_b32_e32 v148, v150
	v_permlane16_swap_b32_e32 v149, v151
	global_store_dwordx4 v155, v[144:147], s[100:101] sc0 sc1
	global_store_dwordx4 v155, v[148:151], s[100:101] offset:64 sc0 sc1
	s_branch .Lfe_join_A
; DI float sigmoid_f(float v) { return 1.f / (1.f + fexp(-v)); }
;   DI void operator()(int m, int n, float a, float b, float c, float d, float& ss) const { u32x2 v; v.x = pack2(a, b); v.y = pack2(c, d); *(u32x2*)(y + (long)m * 1024 + n) = v; }
;   DI void operator()(int m, int n, float a, float b, float c, float d, float& ss) const {
;     if (n >= gl_start) {
;       const int j = n - gl_start;
;       if (j < 48) { float* g = gates + (long)m * 48 + j; g[0] = sigmoid_f(a); g[1] = sigmoid_f(b); g[2] = sigmoid_f(c); g[3] = sigmoid_f(d); }
;       return;
.Lfe_A_not_k:
	s_and_saveexec_b64 s[0:1], vcc
	s_xor_b64 s[12:13], exec, s[0:1]
	s_cbranch_execz .LBB0_364
	v_mad_i64_i32 v[68:69], s[0:1], v74, s38, 0
	v_cmp_lt_i32_e64 s[4:5], s33, v64
	v_add_u32_e32 v66, 0xfffff200, v64
	s_and_saveexec_b64 s[0:1], s[4:5]
	s_xor_b64 s[0:1], exec, s[0:1]
	s_cbranch_execz .LBB0_223
	v_cmp_gt_u32_e32 vcc, 48, v66
	s_and_saveexec_b64 s[6:7], vcc
	s_cbranch_execz .LBB0_222
	v_mul_f32_e32 v60, 0xbfb8aa3b, v60
	v_mul_f32_e32 v61, 0xbfb8aa3b, v61
	v_exp_f32_e32 v60, v60
	v_exp_f32_e32 v61, v61
	v_lshl_add_u64 v[70:71], s[2:3], 0, v[68:69]
	v_mov_b32_e32 v67, v65
	v_lshl_add_u64 v[70:71], v[66:67], 2, v[70:71]
	v_pk_add_f32 v[60:61], v[60:61], 1.0 op_sel_hi:[1,0]
	v_mul_f32_e32 v62, 0xbfb8aa3b, v62
	v_mul_f32_e32 v63, 0xbfb8aa3b, v63
	v_exp_f32_e32 v62, v62
	v_exp_f32_e32 v63, v63
	v_rcp_f32_e32 v67, v61
	s_nop 0
	v_mul_f32_e32 v61, 1.0, v67
	v_pk_add_f32 v[62:63], v[62:63], 1.0 op_sel_hi:[1,0]
	v_rcp_f32_e32 v67, v60
	s_nop 0
	v_mul_f32_e32 v60, 1.0, v67
	v_rcp_f32_e32 v67, v63
	s_nop 0
	v_mul_f32_e32 v63, 1.0, v67
	v_rcp_f32_e32 v67, v62
	s_nop 0
	v_mul_f32_e32 v62, 1.0, v67
	global_store_dwordx4 v[70:71], v[60:63], off sc0 sc1

; DI float sigmoid_f(float v) { return 1.f / (1.f + fexp(-v)); }
;   DI void operator()(int m, int n, float a, float b, float c, float d, float& ss) const { u32x2 v; v.x = pack2(a, b); v.y = pack2(c, d); *(u32x2*)(y + (long)m * 1024 + n) = v; }
;   DI void operator()(int m, int n, float a, float b, float c, float d, float& ss) const {
;     if (n >= gl_start) {
;       const int j = n - gl_start;
;       if (j < 48) { float* g = gates + (long)m * 48 + j; g[0] = sigmoid_f(a); g[1] = sigmoid_f(b); g[2] = sigmoid_f(c); g[3] = sigmoid_f(d); }
;       return;
.LBB0_229:
	s_or_b64 exec, exec, s[0:1]
	v_or_b32_e32 v72, 16, v64
	v_cmp_lt_i32_e64 s[6:7], s33, v72
	v_add_u32_e32 v60, 0xfffff210, v64
	s_and_saveexec_b64 s[0:1], s[6:7]
	s_xor_b64 s[0:1], exec, s[0:1]
	s_cbranch_execz .LBB0_233
	v_cmp_gt_u32_e32 vcc, 48, v60
	s_and_saveexec_b64 s[8:9], vcc
	s_cbranch_execz .LBB0_232
	v_mul_f32_e32 v56, 0xbfb8aa3b, v56
	v_mul_f32_e32 v57, 0xbfb8aa3b, v57
	v_exp_f32_e32 v56, v56
	v_exp_f32_e32 v57, v57
	v_lshl_add_u64 v[62:63], s[2:3], 0, v[68:69]
	v_mov_b32_e32 v61, v65
	v_lshl_add_u64 v[62:63], v[60:61], 2, v[62:63]
	v_pk_add_f32 v[56:57], v[56:57], 1.0 op_sel_hi:[1,0]
	v_mul_f32_e32 v58, 0xbfb8aa3b, v58
	v_mul_f32_e32 v59, 0xbfb8aa3b, v59
	v_exp_f32_e32 v58, v58
	v_exp_f32_e32 v59, v59
	v_rcp_f32_e32 v61, v57
	s_nop 0
	v_mul_f32_e32 v57, 1.0, v61
	v_pk_add_f32 v[58:59], v[58:59], 1.0 op_sel_hi:[1,0]
	v_rcp_f32_e32 v61, v56
	s_nop 0
	v_mul_f32_e32 v56, 1.0, v61
	v_rcp_f32_e32 v61, v59
	s_nop 0
	v_mul_f32_e32 v59, 1.0, v61
	v_rcp_f32_e32 v61, v58
	s_nop 0
	v_mul_f32_e32 v58, 1.0, v61
	global_store_dwordx4 v[62:63], v[56:59], off sc0 sc1

; DI float sigmoid_f(float v) { return 1.f / (1.f + fexp(-v)); }
;   DI void operator()(int m, int n, float a, float b, float c, float d, float& ss) const { u32x2 v; v.x = pack2(a, b); v.y = pack2(c, d); *(u32x2*)(y + (long)m * 1024 + n) = v; }
;   DI void operator()(int m, int n, float a, float b, float c, float d, float& ss) const {
;     if (n >= gl_start) {
;       const int j = n - gl_start;
;       if (j < 48) { float* g = gates + (long)m * 48 + j; g[0] = sigmoid_f(a); g[1] = sigmoid_f(b); g[2] = sigmoid_f(c); g[3] = sigmoid_f(d); }
;       return;
.LBB0_239:
	s_or_b64 exec, exec, s[0:1]
	v_or_b32_e32 v70, 32, v64
	v_cmp_lt_i32_e64 s[8:9], s33, v70
	v_add_u32_e32 v56, 0xfffff220, v64
	s_and_saveexec_b64 s[0:1], s[8:9]
	s_xor_b64 s[0:1], exec, s[0:1]
	s_cbranch_execz .LBB0_243
	v_cmp_gt_u32_e32 vcc, 48, v56
	s_and_saveexec_b64 s[10:11], vcc
	s_cbranch_execz .LBB0_242
	v_mul_f32_e32 v52, 0xbfb8aa3b, v52
	v_mul_f32_e32 v53, 0xbfb8aa3b, v53
	v_exp_f32_e32 v52, v52
	v_exp_f32_e32 v53, v53
	v_lshl_add_u64 v[58:59], s[2:3], 0, v[68:69]
	v_mov_b32_e32 v57, v65
	v_lshl_add_u64 v[58:59], v[56:57], 2, v[58:59]
	v_pk_add_f32 v[52:53], v[52:53], 1.0 op_sel_hi:[1,0]
	v_mul_f32_e32 v54, 0xbfb8aa3b, v54
	v_mul_f32_e32 v55, 0xbfb8aa3b, v55
	v_exp_f32_e32 v54, v54
	v_exp_f32_e32 v55, v55
	v_rcp_f32_e32 v57, v53
	s_nop 0
	v_mul_f32_e32 v53, 1.0, v57
	v_pk_add_f32 v[54:55], v[54:55], 1.0 op_sel_hi:[1,0]
	v_rcp_f32_e32 v57, v52
	s_nop 0
	v_mul_f32_e32 v52, 1.0, v57
	v_rcp_f32_e32 v57, v55
	s_nop 0
	v_mul_f32_e32 v55, 1.0, v57
	v_rcp_f32_e32 v57, v54
	s_nop 0
	v_mul_f32_e32 v54, 1.0, v57
	global_store_dwordx4 v[58:59], v[52:55], off sc0 sc1

; DI float sigmoid_f(float v) { return 1.f / (1.f + fexp(-v)); }
;   DI void operator()(int m, int n, float a, float b, float c, float d, float& ss) const { u32x2 v; v.x = pack2(a, b); v.y = pack2(c, d); *(u32x2*)(y + (long)m * 1024 + n) = v; }
;   DI void operator()(int m, int n, float a, float b, float c, float d, float& ss) const {
;     if (n >= gl_start) {
;       const int j = n - gl_start;
;       if (j < 48) { float* g = gates + (long)m * 48 + j; g[0] = sigmoid_f(a); g[1] = sigmoid_f(b); g[2] = sigmoid_f(c); g[3] = sigmoid_f(d); }
;       return;
.LBB0_262:
	v_cmp_gt_u32_e32 vcc, 48, v66
	s_and_saveexec_b64 s[34:35], vcc
	s_cbranch_execz .LBB0_264
	v_mul_f32_e32 v44, 0xbfb8aa3b, v44
	v_mul_f32_e32 v45, 0xbfb8aa3b, v45
	v_exp_f32_e32 v44, v44
	v_exp_f32_e32 v45, v45
	v_mul_f32_e32 v46, 0xbfb8aa3b, v46
	v_mul_f32_e32 v47, 0xbfb8aa3b, v47
	v_exp_f32_e32 v46, v46
	v_pk_add_f32 v[44:45], v[44:45], 1.0 op_sel_hi:[1,0]
	v_exp_f32_e32 v47, v47
	s_nop 0
	v_pk_add_f32 v[46:47], v[46:47], 1.0 op_sel_hi:[1,0]
	v_lshl_add_u64 v[50:51], s[2:3], 0, v[48:49]
	v_mov_b32_e32 v67, v65
	v_rcp_f32_e32 v52, v45
	s_nop 0
	v_mul_f32_e32 v45, 1.0, v52
	v_lshl_add_u64 v[50:51], v[66:67], 2, v[50:51]
	v_rcp_f32_e32 v52, v44
	s_nop 0
	v_mul_f32_e32 v44, 1.0, v52
	v_rcp_f32_e32 v52, v47
	s_nop 0
	v_mul_f32_e32 v47, 1.0, v52
	v_rcp_f32_e32 v52, v46
	s_nop 0
	v_mul_f32_e32 v46, 1.0, v52
	global_store_dwordx4 v[50:51], v[44:47], off sc0 sc1

; DI float sigmoid_f(float v) { return 1.f / (1.f + fexp(-v)); }
;   DI void operator()(int m, int n, float a, float b, float c, float d, float& ss) const { u32x2 v; v.x = pack2(a, b); v.y = pack2(c, d); *(u32x2*)(y + (long)m * 1024 + n) = v; }
;   DI void operator()(int m, int n, float a, float b, float c, float d, float& ss) const {
;     if (n >= gl_start) {
;       const int j = n - gl_start;
;       if (j < 48) { float* g = gates + (long)m * 48 + j; g[0] = sigmoid_f(a); g[1] = sigmoid_f(b); g[2] = sigmoid_f(c); g[3] = sigmoid_f(d); }
;       return;
.LBB0_270:
	v_cmp_gt_u32_e32 vcc, 48, v60
	s_and_saveexec_b64 s[34:35], vcc
	s_cbranch_execz .LBB0_272
	v_mul_f32_e32 v40, 0xbfb8aa3b, v40
	v_mul_f32_e32 v41, 0xbfb8aa3b, v41
	v_exp_f32_e32 v40, v40
	v_exp_f32_e32 v41, v41
	v_mul_f32_e32 v42, 0xbfb8aa3b, v42
	v_mul_f32_e32 v43, 0xbfb8aa3b, v43
	v_exp_f32_e32 v42, v42
	v_pk_add_f32 v[40:41], v[40:41], 1.0 op_sel_hi:[1,0]
	v_exp_f32_e32 v43, v43
	s_nop 0
	v_pk_add_f32 v[42:43], v[42:43], 1.0 op_sel_hi:[1,0]
	v_lshl_add_u64 v[44:45], s[2:3], 0, v[48:49]
	v_mov_b32_e32 v61, v65
	v_rcp_f32_e32 v46, v41
	s_nop 0
	v_mul_f32_e32 v41, 1.0, v46
	v_lshl_add_u64 v[44:45], v[60:61], 2, v[44:45]
	v_rcp_f32_e32 v46, v40
	s_nop 0
	v_mul_f32_e32 v40, 1.0, v46
	v_rcp_f32_e32 v46, v43
	s_nop 0
	v_mul_f32_e32 v43, 1.0, v46
	v_rcp_f32_e32 v46, v42
	s_nop 0
	v_mul_f32_e32 v42, 1.0, v46
	global_store_dwordx4 v[44:45], v[40:43], off sc0 sc1

; DI float sigmoid_f(float v) { return 1.f / (1.f + fexp(-v)); }
;   DI void operator()(int m, int n, float a, float b, float c, float d, float& ss) const { u32x2 v; v.x = pack2(a, b); v.y = pack2(c, d); *(u32x2*)(y + (long)m * 1024 + n) = v; }
;   DI void operator()(int m, int n, float a, float b, float c, float d, float& ss) const {
;     if (n >= gl_start) {
;       const int j = n - gl_start;
;       if (j < 48) { float* g = gates + (long)m * 48 + j; g[0] = sigmoid_f(a); g[1] = sigmoid_f(b); g[2] = sigmoid_f(c); g[3] = sigmoid_f(d); }
;       return;
.LBB0_278:
	v_cmp_gt_u32_e32 vcc, 48, v56
	s_and_saveexec_b64 s[34:35], vcc
	s_cbranch_execz .LBB0_280
	v_mul_f32_e32 v36, 0xbfb8aa3b, v36
	v_mul_f32_e32 v37, 0xbfb8aa3b, v37
	v_exp_f32_e32 v36, v36
	v_exp_f32_e32 v37, v37
	v_mul_f32_e32 v38, 0xbfb8aa3b, v38
	v_mul_f32_e32 v39, 0xbfb8aa3b, v39
	v_exp_f32_e32 v38, v38
	v_pk_add_f32 v[36:37], v[36:37], 1.0 op_sel_hi:[1,0]
	v_exp_f32_e32 v39, v39
	s_nop 0
	v_pk_add_f32 v[38:39], v[38:39], 1.0 op_sel_hi:[1,0]
	v_lshl_add_u64 v[40:41], s[2:3], 0, v[48:49]
	v_mov_b32_e32 v57, v65
	v_rcp_f32_e32 v42, v37
	s_nop 0
	v_mul_f32_e32 v37, 1.0, v42
	v_lshl_add_u64 v[40:41], v[56:57], 2, v[40:41]
	v_rcp_f32_e32 v42, v36
	s_nop 0
	v_mul_f32_e32 v36, 1.0, v42
	v_rcp_f32_e32 v42, v39
	s_nop 0
	v_mul_f32_e32 v39, 1.0, v42
	v_rcp_f32_e32 v42, v38
	s_nop 0
	v_mul_f32_e32 v38, 1.0, v42
	global_store_dwordx4 v[40:41], v[36:39], off sc0 sc1

; DI float sigmoid_f(float v) { return 1.f / (1.f + fexp(-v)); }
;   DI void operator()(int m, int n, float a, float b, float c, float d, float& ss) const { u32x2 v; v.x = pack2(a, b); v.y = pack2(c, d); *(u32x2*)(y + (long)m * 1024 + n) = v; }
;   DI void operator()(int m, int n, float a, float b, float c, float d, float& ss) const {
;     if (n >= gl_start) {
;       const int j = n - gl_start;
;       if (j < 48) { float* g = gates + (long)m * 48 + j; g[0] = sigmoid_f(a); g[1] = sigmoid_f(b); g[2] = sigmoid_f(c); g[3] = sigmoid_f(d); }
;       return;
.LBB0_298:
	v_cmp_gt_u32_e32 vcc, 48, v66
	s_and_saveexec_b64 s[34:35], vcc
	s_cbranch_execz .LBB0_300
	v_mul_f32_e32 v28, 0xbfb8aa3b, v28
	v_mul_f32_e32 v29, 0xbfb8aa3b, v29
	v_exp_f32_e32 v28, v28
	v_exp_f32_e32 v29, v29
	v_mul_f32_e32 v30, 0xbfb8aa3b, v30
	v_mul_f32_e32 v31, 0xbfb8aa3b, v31
	v_exp_f32_e32 v30, v30
	v_pk_add_f32 v[28:29], v[28:29], 1.0 op_sel_hi:[1,0]
	v_exp_f32_e32 v31, v31
	s_nop 0
	v_pk_add_f32 v[30:31], v[30:31], 1.0 op_sel_hi:[1,0]
	v_lshl_add_u64 v[34:35], s[2:3], 0, v[32:33]
	v_mov_b32_e32 v67, v65
	v_rcp_f32_e32 v36, v29
	s_nop 0
	v_mul_f32_e32 v29, 1.0, v36
	v_lshl_add_u64 v[34:35], v[66:67], 2, v[34:35]
	v_rcp_f32_e32 v36, v28
	s_nop 0
	v_mul_f32_e32 v28, 1.0, v36
	v_rcp_f32_e32 v36, v31
	s_nop 0
	v_mul_f32_e32 v31, 1.0, v36
	v_rcp_f32_e32 v36, v30
	s_nop 0
	v_mul_f32_e32 v30, 1.0, v36
	global_store_dwordx4 v[34:35], v[28:31], off sc0 sc1

; DI float sigmoid_f(float v) { return 1.f / (1.f + fexp(-v)); }
;   DI void operator()(int m, int n, float a, float b, float c, float d, float& ss) const { u32x2 v; v.x = pack2(a, b); v.y = pack2(c, d); *(u32x2*)(y + (long)m * 1024 + n) = v; }
;   DI void operator()(int m, int n, float a, float b, float c, float d, float& ss) const {
;     if (n >= gl_start) {
;       const int j = n - gl_start;
;       if (j < 48) { float* g = gates + (long)m * 48 + j; g[0] = sigmoid_f(a); g[1] = sigmoid_f(b); g[2] = sigmoid_f(c); g[3] = sigmoid_f(d); }
;       return;
.LBB0_306:
	v_cmp_gt_u32_e32 vcc, 48, v60
	s_and_saveexec_b64 s[34:35], vcc
	s_cbranch_execz .LBB0_308
	v_mul_f32_e32 v24, 0xbfb8aa3b, v24
	v_mul_f32_e32 v25, 0xbfb8aa3b, v25
	v_exp_f32_e32 v24, v24
	v_exp_f32_e32 v25, v25
	v_mul_f32_e32 v26, 0xbfb8aa3b, v26
	v_mul_f32_e32 v27, 0xbfb8aa3b, v27
	v_exp_f32_e32 v26, v26
	v_pk_add_f32 v[24:25], v[24:25], 1.0 op_sel_hi:[1,0]
	v_exp_f32_e32 v27, v27
	s_nop 0
	v_pk_add_f32 v[26:27], v[26:27], 1.0 op_sel_hi:[1,0]
	v_lshl_add_u64 v[28:29], s[2:3], 0, v[32:33]
	v_mov_b32_e32 v61, v65
	v_rcp_f32_e32 v30, v25
	s_nop 0
	v_mul_f32_e32 v25, 1.0, v30
	v_lshl_add_u64 v[28:29], v[60:61], 2, v[28:29]
	v_rcp_f32_e32 v30, v24
	s_nop 0
	v_mul_f32_e32 v24, 1.0, v30
	v_rcp_f32_e32 v30, v27
	s_nop 0
	v_mul_f32_e32 v27, 1.0, v30
	v_rcp_f32_e32 v30, v26
	s_nop 0
	v_mul_f32_e32 v26, 1.0, v30
	global_store_dwordx4 v[28:29], v[24:27], off sc0 sc1

; DI float sigmoid_f(float v) { return 1.f / (1.f + fexp(-v)); }
;   DI void operator()(int m, int n, float a, float b, float c, float d, float& ss) const { u32x2 v; v.x = pack2(a, b); v.y = pack2(c, d); *(u32x2*)(y + (long)m * 1024 + n) = v; }
;   DI void operator()(int m, int n, float a, float b, float c, float d, float& ss) const {
;     if (n >= gl_start) {
;       const int j = n - gl_start;
;       if (j < 48) { float* g = gates + (long)m * 48 + j; g[0] = sigmoid_f(a); g[1] = sigmoid_f(b); g[2] = sigmoid_f(c); g[3] = sigmoid_f(d); }
;       return;
.LBB0_314:
	v_cmp_gt_u32_e32 vcc, 48, v56
	s_and_saveexec_b64 s[34:35], vcc
	s_cbranch_execz .LBB0_316
	v_mul_f32_e32 v20, 0xbfb8aa3b, v20
	v_mul_f32_e32 v21, 0xbfb8aa3b, v21
	v_exp_f32_e32 v20, v20
	v_exp_f32_e32 v21, v21
	v_mul_f32_e32 v22, 0xbfb8aa3b, v22
	v_mul_f32_e32 v23, 0xbfb8aa3b, v23
	v_exp_f32_e32 v22, v22
	v_pk_add_f32 v[20:21], v[20:21], 1.0 op_sel_hi:[1,0]
	v_exp_f32_e32 v23, v23
	s_nop 0
	v_pk_add_f32 v[22:23], v[22:23], 1.0 op_sel_hi:[1,0]
	v_lshl_add_u64 v[24:25], s[2:3], 0, v[32:33]
	v_mov_b32_e32 v57, v65
	v_rcp_f32_e32 v26, v21
	s_nop 0
	v_mul_f32_e32 v21, 1.0, v26
	v_lshl_add_u64 v[24:25], v[56:57], 2, v[24:25]
	v_rcp_f32_e32 v26, v20
	s_nop 0
	v_mul_f32_e32 v20, 1.0, v26
	v_rcp_f32_e32 v26, v23
	s_nop 0
	v_mul_f32_e32 v23, 1.0, v26
	v_rcp_f32_e32 v26, v22
	s_nop 0
	v_mul_f32_e32 v22, 1.0, v26
	global_store_dwordx4 v[24:25], v[20:23], off sc0 sc1

; DI float sigmoid_f(float v) { return 1.f / (1.f + fexp(-v)); }
;   DI void operator()(int m, int n, float a, float b, float c, float d, float& ss) const { u32x2 v; v.x = pack2(a, b); v.y = pack2(c, d); *(u32x2*)(y + (long)m * 1024 + n) = v; }
;   DI void operator()(int m, int n, float a, float b, float c, float d, float& ss) const {
;     if (n >= gl_start) {
;       const int j = n - gl_start;
;       if (j < 48) { float* g = gates + (long)m * 48 + j; g[0] = sigmoid_f(a); g[1] = sigmoid_f(b); g[2] = sigmoid_f(c); g[3] = sigmoid_f(d); }
;       return;
.LBB0_334:
	v_cmp_gt_u32_e32 vcc, 48, v66
	s_and_saveexec_b64 s[4:5], vcc
	s_cbranch_execz .LBB0_336
	v_mul_f32_e32 v12, 0xbfb8aa3b, v12
	v_mul_f32_e32 v13, 0xbfb8aa3b, v13
	v_exp_f32_e32 v12, v12
	v_exp_f32_e32 v13, v13
	v_mul_f32_e32 v14, 0xbfb8aa3b, v14
	v_mul_f32_e32 v15, 0xbfb8aa3b, v15
	v_exp_f32_e32 v14, v14
	v_pk_add_f32 v[12:13], v[12:13], 1.0 op_sel_hi:[1,0]
	v_exp_f32_e32 v15, v15
	s_nop 0
	v_pk_add_f32 v[14:15], v[14:15], 1.0 op_sel_hi:[1,0]
	v_lshl_add_u64 v[18:19], s[2:3], 0, v[16:17]
	v_mov_b32_e32 v67, v65
	v_rcp_f32_e32 v20, v13
	s_nop 0
	v_mul_f32_e32 v13, 1.0, v20
	v_lshl_add_u64 v[18:19], v[66:67], 2, v[18:19]
	v_rcp_f32_e32 v20, v12
	s_nop 0
	v_mul_f32_e32 v12, 1.0, v20
	v_rcp_f32_e32 v20, v15
	s_nop 0
	v_mul_f32_e32 v15, 1.0, v20
	v_rcp_f32_e32 v20, v14
	s_nop 0
	v_mul_f32_e32 v14, 1.0, v20
	global_store_dwordx4 v[18:19], v[12:15], off sc0 sc1

; DI float sigmoid_f(float v) { return 1.f / (1.f + fexp(-v)); }
;   DI void operator()(int m, int n, float a, float b, float c, float d, float& ss) const { u32x2 v; v.x = pack2(a, b); v.y = pack2(c, d); *(u32x2*)(y + (long)m * 1024 + n) = v; }
;   DI void operator()(int m, int n, float a, float b, float c, float d, float& ss) const {
;     if (n >= gl_start) {
;       const int j = n - gl_start;
;       if (j < 48) { float* g = gates + (long)m * 48 + j; g[0] = sigmoid_f(a); g[1] = sigmoid_f(b); g[2] = sigmoid_f(c); g[3] = sigmoid_f(d); }
;       return;
.LBB0_342:
	v_cmp_gt_u32_e32 vcc, 48, v60
	s_and_saveexec_b64 s[4:5], vcc
	s_cbranch_execz .LBB0_344
	v_mul_f32_e32 v8, 0xbfb8aa3b, v8
	v_mul_f32_e32 v9, 0xbfb8aa3b, v9
	v_exp_f32_e32 v8, v8
	v_exp_f32_e32 v9, v9
	v_mul_f32_e32 v10, 0xbfb8aa3b, v10
	v_mul_f32_e32 v11, 0xbfb8aa3b, v11
	v_exp_f32_e32 v10, v10
	v_pk_add_f32 v[8:9], v[8:9], 1.0 op_sel_hi:[1,0]
	v_exp_f32_e32 v11, v11
	s_nop 0
	v_pk_add_f32 v[10:11], v[10:11], 1.0 op_sel_hi:[1,0]
	v_lshl_add_u64 v[12:13], s[2:3], 0, v[16:17]
	v_mov_b32_e32 v61, v65
	v_rcp_f32_e32 v14, v9
	s_nop 0
	v_mul_f32_e32 v9, 1.0, v14
	v_lshl_add_u64 v[12:13], v[60:61], 2, v[12:13]
	v_rcp_f32_e32 v14, v8
	s_nop 0
	v_mul_f32_e32 v8, 1.0, v14
	v_rcp_f32_e32 v14, v11
	s_nop 0
	v_mul_f32_e32 v11, 1.0, v14
	v_rcp_f32_e32 v14, v10
	s_nop 0
	v_mul_f32_e32 v10, 1.0, v14
	global_store_dwordx4 v[12:13], v[8:11], off sc0 sc1

; DI float sigmoid_f(float v) { return 1.f / (1.f + fexp(-v)); }
;   DI void operator()(int m, int n, float a, float b, float c, float d, float& ss) const { u32x2 v; v.x = pack2(a, b); v.y = pack2(c, d); *(u32x2*)(y + (long)m * 1024 + n) = v; }
;   DI void operator()(int m, int n, float a, float b, float c, float d, float& ss) const {
;     if (n >= gl_start) {
;       const int j = n - gl_start;
;       if (j < 48) { float* g = gates + (long)m * 48 + j; g[0] = sigmoid_f(a); g[1] = sigmoid_f(b); g[2] = sigmoid_f(c); g[3] = sigmoid_f(d); }
;       return;
.LBB0_350:
	v_cmp_gt_u32_e32 vcc, 48, v56
	s_and_saveexec_b64 s[4:5], vcc
	s_cbranch_execz .LBB0_352
	v_mul_f32_e32 v4, 0xbfb8aa3b, v4
	v_mul_f32_e32 v5, 0xbfb8aa3b, v5
	v_exp_f32_e32 v4, v4
	v_exp_f32_e32 v5, v5
	v_mul_f32_e32 v6, 0xbfb8aa3b, v6
	v_mul_f32_e32 v7, 0xbfb8aa3b, v7
	v_exp_f32_e32 v6, v6
	v_pk_add_f32 v[4:5], v[4:5], 1.0 op_sel_hi:[1,0]
	v_exp_f32_e32 v7, v7
	s_nop 0
	v_pk_add_f32 v[6:7], v[6:7], 1.0 op_sel_hi:[1,0]
	v_lshl_add_u64 v[8:9], s[2:3], 0, v[16:17]
	v_mov_b32_e32 v57, v65
	v_rcp_f32_e32 v10, v5
	s_nop 0
	v_mul_f32_e32 v5, 1.0, v10
	v_lshl_add_u64 v[8:9], v[56:57], 2, v[8:9]
	v_rcp_f32_e32 v10, v4
	s_nop 0
	v_mul_f32_e32 v4, 1.0, v10
	v_rcp_f32_e32 v10, v7
	s_nop 0
	v_mul_f32_e32 v7, 1.0, v10
	v_rcp_f32_e32 v10, v6
	s_nop 0
	v_mul_f32_e32 v6, 1.0, v10
	global_store_dwordx4 v[8:9], v[4:7], off sc0 sc1

;   DI u32x2 pack(int, int, float a, float b, float c, float d, float&) const { u32x2 v; v.x = pack2(a, b); v.y = pack2(c, d); return v; }
; template <class ARow, class Epi>
; DI void gemm_tile(const ARow& arow, long a_kstride, const u16* __restrict__ Bt, long ldb, int K, int m0, int n0,
;                   const Epi& epi, char* smem) {
;     ...
;       for (int ni = 0; ni < 4; ++ni) pk[ni] = epi.pack(m, nh + ni * 16 + fq * 4, acc[ni][mi][0], acc[ni][mi][1], acc[ni][mi][2], acc[ni][mi][3], ss);
;       epi.finish16(m, nh, ss);
;       u16* rp = epi.rowp(m) + nh;
; #pragma unroll
;       for (int pp = 0; pp < 2; ++pp) {
;         u32x2 a = pk[2 * pp], b = pk[2 * pp + 1];
;         const u32x2 rx = __builtin_amdgcn_permlane16_swap(a.x, b.x, false, false);
;         const u32x2 ry = __builtin_amdgcn_permlane16_swap(a.y, b.y, false, false);
;         const int nst = (fq & 1) ? ((2 * pp + 1) * 16 + (fq - 1) * 4) : ((2 * pp) * 16 + fq * 4);
;         *(u32x4*)(rp + nst) = (u32x4){rx[0], ry[0], rx[1], ry[1]};
;       }
.LBB0_389:
	v_cvt_pk_bf16_f32 v77, v54, v55
	v_and_b32_e32 v54, 16, v83
	v_cvt_pk_bf16_f32 v76, v52, v53
	v_mov_b64_e32 v[52:53], s[18:19]
	v_add_u32_e32 v55, 12, v70
	v_cmp_eq_u32_e32 vcc, 0, v54
	s_waitcnt lgkmcnt(0)
	v_ashrrev_i32_e32 v67, 31, v66
	v_mad_i64_i32 v[52:53], s[0:1], v74, s40, v[52:53]
	v_cndmask_b32_e32 v54, v55, v70, vcc
	v_cvt_pk_bf16_f32 v78, v48, v49
	v_cvt_pk_bf16_f32 v79, v50, v51
	v_cvt_pk_bf16_f32 v50, v56, v57
	v_cvt_pk_bf16_f32 v51, v58, v59
	v_cvt_pk_bf16_f32 v48, v60, v61
	v_cvt_pk_bf16_f32 v49, v62, v63
	v_lshl_add_u64 v[52:53], v[66:67], 1, v[52:53]
	v_lshlrev_b32_e32 v64, 1, v54
	v_permlane16_swap_b32_e32 v48, v50
	v_permlane16_swap_b32_e32 v49, v51
	v_lshl_add_u64 v[54:55], v[52:53], 0, v[64:65]
	global_store_dwordx4 v[54:55], v[48:51], off sc0 sc1
	v_permlane16_swap_b32_e32 v76, v78
	s_nop 0
	v_add_u32_e32 v48, 44, v70
	v_or_b32_e32 v49, 32, v70
	v_cndmask_b32_e32 v48, v48, v49, vcc
	v_lshlrev_b32_e32 v48, 1, v48
	v_mov_b32_e32 v49, v65
	v_permlane16_swap_b32_e32 v77, v79
	v_lshl_add_u64 v[50:51], v[52:53], 0, v[48:49]
	global_store_dwordx4 v[50:51], v[76:79], off sc0 sc1
	s_and_saveexec_b64 s[0:1], s[4:5]
	s_xor_b64 s[0:1], exec, s[0:1]
	s_cbranch_execz .LBB0_392
	s_cmpk_lt_u32 s42, 0xa00
	s_cbranch_scc1 .LBB0_392
	v_mul_f32_e32 v49, 0xbfb8aa3b, v44
	v_exp_f32_e32 v50, v49
	v_mul_f32_e32 v49, 0xbfb8aa3b, v45
	v_exp_f32_e32 v51, v49
	s_nop 0
	v_pk_add_f32 v[50:51], v[50:51], 1.0 op_sel_hi:[1,0]
	s_nop 0
	v_rcp_f32_e32 v49, v50
	v_mul_f32_e32 v52, 0xbfb8aa3b, v46
	v_mul_f32_e32 v53, 0xbfb8aa3b, v47
	v_exp_f32_e32 v52, v52
	v_exp_f32_e32 v53, v53
	v_mul_f32_e32 v44, v44, v49
	v_pk_add_f32 v[52:53], v[52:53], 1.0 op_sel_hi:[1,0]
	v_rcp_f32_e32 v49, v51
	s_nop 0
	v_mul_f32_e32 v45, v45, v49
	v_rcp_f32_e32 v49, v52
	s_nop 0
	v_mul_f32_e32 v46, v46, v49
	v_rcp_f32_e32 v49, v53
	s_nop 0
	v_mul_f32_e32 v47, v47, v49

;   DI u32x2 pack(int, int, float a, float b, float c, float d, float&) const { u32x2 v; v.x = pack2(a, b); v.y = pack2(c, d); return v; }
; template <class ARow, class Epi>
; DI void gemm_tile(const ARow& arow, long a_kstride, const u16* __restrict__ Bt, long ldb, int K, int m0, int n0,
;                   const Epi& epi, char* smem) {
;     ...
;       for (int ni = 0; ni < 4; ++ni) pk[ni] = epi.pack(m, nh + ni * 16 + fq * 4, acc[ni][mi][0], acc[ni][mi][1], acc[ni][mi][2], acc[ni][mi][3], ss);
;       epi.finish16(m, nh, ss);
;       u16* rp = epi.rowp(m) + nh;
; #pragma unroll
;       for (int pp = 0; pp < 2; ++pp) {
;         u32x2 a = pk[2 * pp], b = pk[2 * pp + 1];
;         const u32x2 rx = __builtin_amdgcn_permlane16_swap(a.x, b.x, false, false);
;         const u32x2 ry = __builtin_amdgcn_permlane16_swap(a.y, b.y, false, false);
;         const int nst = (fq & 1) ? ((2 * pp + 1) * 16 + (fq - 1) * 4) : ((2 * pp) * 16 + fq * 4);
;         *(u32x4*)(rp + nst) = (u32x4){rx[0], ry[0], rx[1], ry[1]};
;       }
.LBB0_413:
	v_or_b32_e32 v49, 16, v74
	s_waitcnt lgkmcnt(0)
	v_cvt_pk_bf16_f32 v50, v36, v37
	v_mov_b64_e32 v[36:37], s[18:19]
	v_mad_i64_i32 v[36:37], s[0:1], v49, s40, v[36:37]
	v_cvt_pk_bf16_f32 v52, v32, v33
	v_cvt_pk_bf16_f32 v53, v34, v35
	v_cvt_pk_bf16_f32 v34, v40, v41
	v_cvt_pk_bf16_f32 v35, v42, v43
	v_cvt_pk_bf16_f32 v32, v44, v45
	v_cvt_pk_bf16_f32 v33, v46, v47
	v_lshl_add_u64 v[36:37], v[66:67], 1, v[36:37]
	v_cvt_pk_bf16_f32 v51, v38, v39
	v_permlane16_swap_b32_e32 v32, v34
	v_permlane16_swap_b32_e32 v33, v35
	v_lshl_add_u64 v[38:39], v[36:37], 0, v[64:65]
	v_mov_b32_e32 v49, v65
	global_store_dwordx4 v[38:39], v[32:35], off sc0 sc1
	v_permlane16_swap_b32_e32 v50, v52
	v_permlane16_swap_b32_e32 v51, v53
	v_lshl_add_u64 v[32:33], v[36:37], 0, v[48:49]
	global_store_dwordx4 v[32:33], v[50:53], off sc0 sc1
	s_and_saveexec_b64 s[0:1], s[4:5]
	s_xor_b64 s[0:1], exec, s[0:1]
	s_cbranch_execz .LBB0_416
	s_cmpk_lt_u32 s42, 0xa00
	s_cbranch_scc1 .LBB0_416
	v_mul_f32_e32 v32, 0xbfb8aa3b, v28
	v_mul_f32_e32 v33, 0xbfb8aa3b, v29
	v_exp_f32_e32 v32, v32
	v_exp_f32_e32 v33, v33
	s_nop 0
	v_pk_add_f32 v[32:33], v[32:33], 1.0 op_sel_hi:[1,0]
	s_nop 0
	v_rcp_f32_e32 v34, v32
	s_nop 0
	v_mul_f32_e32 v28, v28, v34
	v_mul_f32_e32 v34, 0xbfb8aa3b, v30
	v_mul_f32_e32 v35, 0xbfb8aa3b, v31
	v_exp_f32_e32 v34, v34
	v_exp_f32_e32 v35, v35
	s_nop 0
	v_pk_add_f32 v[34:35], v[34:35], 1.0 op_sel_hi:[1,0]
	v_rcp_f32_e32 v32, v33
	s_nop 0
	v_mul_f32_e32 v29, v29, v32
	v_rcp_f32_e32 v32, v34
	s_nop 0
	v_mul_f32_e32 v30, v30, v32
	v_rcp_f32_e32 v32, v35
	s_nop 0
	v_mul_f32_e32 v31, v31, v32

;   DI u32x2 pack(int, int, float a, float b, float c, float d, float&) const { u32x2 v; v.x = pack2(a, b); v.y = pack2(c, d); return v; }
; template <class ARow, class Epi>
; DI void gemm_tile(const ARow& arow, long a_kstride, const u16* __restrict__ Bt, long ldb, int K, int m0, int n0,
;                   const Epi& epi, char* smem) {
;     ...
;       for (int ni = 0; ni < 4; ++ni) pk[ni] = epi.pack(m, nh + ni * 16 + fq * 4, acc[ni][mi][0], acc[ni][mi][1], acc[ni][mi][2], acc[ni][mi][3], ss);
;       epi.finish16(m, nh, ss);
;       u16* rp = epi.rowp(m) + nh;
; #pragma unroll
;       for (int pp = 0; pp < 2; ++pp) {
;         u32x2 a = pk[2 * pp], b = pk[2 * pp + 1];
;         const u32x2 rx = __builtin_amdgcn_permlane16_swap(a.x, b.x, false, false);
;         const u32x2 ry = __builtin_amdgcn_permlane16_swap(a.y, b.y, false, false);
;         const int nst = (fq & 1) ? ((2 * pp + 1) * 16 + (fq - 1) * 4) : ((2 * pp) * 16 + fq * 4);
;         *(u32x4*)(rp + nst) = (u32x4){rx[0], ry[0], rx[1], ry[1]};
;       }
.LBB0_437:
	v_or_b32_e32 v36, 32, v74
	v_cvt_pk_bf16_f32 v32, v20, v21
	v_mov_b64_e32 v[20:21], s[18:19]
	v_mad_i64_i32 v[20:21], s[0:1], v36, s40, v[20:21]
	v_cvt_pk_bf16_f32 v34, v16, v17
	v_cvt_pk_bf16_f32 v35, v18, v19
	v_cvt_pk_bf16_f32 v18, v24, v25
	v_cvt_pk_bf16_f32 v19, v26, v27
	v_cvt_pk_bf16_f32 v16, v28, v29
	v_cvt_pk_bf16_f32 v17, v30, v31
	v_lshl_add_u64 v[20:21], v[66:67], 1, v[20:21]
	s_waitcnt lgkmcnt(0)
	v_cvt_pk_bf16_f32 v33, v22, v23
	v_permlane16_swap_b32_e32 v16, v18
	v_permlane16_swap_b32_e32 v17, v19
	v_lshl_add_u64 v[22:23], v[20:21], 0, v[64:65]
	v_mov_b32_e32 v49, v65
	global_store_dwordx4 v[22:23], v[16:19], off sc0 sc1
	v_permlane16_swap_b32_e32 v32, v34
	v_permlane16_swap_b32_e32 v33, v35
	v_lshl_add_u64 v[16:17], v[20:21], 0, v[48:49]
	global_store_dwordx4 v[16:17], v[32:35], off sc0 sc1
	s_and_saveexec_b64 s[0:1], s[4:5]
	s_xor_b64 s[0:1], exec, s[0:1]
	s_cbranch_execz .LBB0_440
	s_cmpk_lt_u32 s42, 0xa00
	s_cbranch_scc1 .LBB0_440
	v_mul_f32_e32 v16, 0xbfb8aa3b, v12
	v_mul_f32_e32 v17, 0xbfb8aa3b, v13
	v_exp_f32_e32 v16, v16
	v_exp_f32_e32 v17, v17
	s_nop 0
	v_pk_add_f32 v[16:17], v[16:17], 1.0 op_sel_hi:[1,0]
	s_nop 0
	v_rcp_f32_e32 v18, v16
	s_nop 0
	v_mul_f32_e32 v12, v12, v18
	v_mul_f32_e32 v18, 0xbfb8aa3b, v14
	v_mul_f32_e32 v19, 0xbfb8aa3b, v15
	v_exp_f32_e32 v18, v18
	v_exp_f32_e32 v19, v19
	s_nop 0
	v_pk_add_f32 v[18:19], v[18:19], 1.0 op_sel_hi:[1,0]
	v_rcp_f32_e32 v16, v17
	s_nop 0
	v_mul_f32_e32 v13, v13, v16
	v_rcp_f32_e32 v16, v18
	s_nop 0
	v_mul_f32_e32 v14, v14, v16
	v_rcp_f32_e32 v16, v19
	s_nop 0
	v_mul_f32_e32 v15, v15, v16

; DI unsigned pack2(float a, float b) { v2f f = {a, b}; return __builtin_bit_cast(unsigned, __builtin_convertvector(f, v2bf)); }
; DI void wprep_tile(const float* __restrict__ src, int Nsrc, u16* __restrict__ dst, int K, int kt, int nt, int remap, char* smem) {
;     ...
;   const int n2 = tid >> 2, k0 = (tid & 3) * 16;
;   unsigned w[8];
; #pragma unroll
;   for (int j = 0; j < 8; ++j) w[j] = pack2(tile[n2 * 65 + k0 + 2 * j], tile[n2 * 65 + k0 + 2 * j + 1]);
;   u16* d = dst + (long)(nt * 64 + n2) * K + kt * 64 + k0;
;   *(u32x4*)d = (u32x4){w[0], w[1], w[2], w[3]};
;   *(u32x4*)(d + 8) = (u32x4){w[4], w[5], w[6], w[7]};
.LBB0_519:
	v_ashrrev_i32_e32 v0, 2, v4
	v_lshlrev_b32_e32 v2, 4, v4
	v_and_b32_e32 v16, 48, v2
	v_mul_lo_u32 v2, v0, s13
	v_lshl_add_u32 v14, v16, 2, v2
	s_waitcnt lgkmcnt(0)
	s_barrier
	ds_read2_b32 v[2:3], v14 offset1:1
	ds_read2_b32 v[4:5], v14 offset0:2 offset1:3
	ds_read2_b32 v[6:7], v14 offset0:4 offset1:5
	ds_read2_b32 v[8:9], v14 offset0:6 offset1:7
	s_add_i32 s11, s11, s22
	s_waitcnt lgkmcnt(3)
	v_cvt_pk_bf16_f32 v2, v2, v3
	s_waitcnt lgkmcnt(2)
	v_cvt_pk_bf16_f32 v3, v4, v5
	s_waitcnt lgkmcnt(1)
	v_cvt_pk_bf16_f32 v4, v6, v7
	ds_read2_b32 v[6:7], v14 offset0:8 offset1:9
	ds_read2_b32 v[10:11], v14 offset0:10 offset1:11
	ds_read2_b32 v[12:13], v14 offset0:12 offset1:13
	ds_read2_b32 v[14:15], v14 offset0:14 offset1:15
	s_waitcnt lgkmcnt(4)
	v_cvt_pk_bf16_f32 v5, v8, v9
	s_waitcnt lgkmcnt(3)
	v_cvt_pk_bf16_f32 v6, v6, v7
	s_waitcnt lgkmcnt(2)
	v_cvt_pk_bf16_f32 v7, v10, v11
	v_add_u32_e32 v10, s1, v0
	v_ashrrev_i32_e32 v11, 31, v10
	v_lshlrev_b64 v[10:11], 11, v[10:11]
	v_lshl_add_u64 v[10:11], s[6:7], 0, v[10:11]
	s_ashr_i32 s1, s0, 31
	v_lshl_add_u64 v[10:11], s[0:1], 1, v[10:11]
	v_lshlrev_b32_e32 v0, 1, v16
	s_waitcnt lgkmcnt(1)
	v_cvt_pk_bf16_f32 v8, v12, v13
	s_waitcnt lgkmcnt(0)
	v_cvt_pk_bf16_f32 v9, v14, v15
	v_lshl_add_u64 v[10:11], v[10:11], 0, v[0:1]
	s_cmpk_gt_i32 s11, 0x3ff
	global_store_dwordx4 v[10:11], v[2:5], off sc0 sc1
	global_store_dwordx4 v[10:11], v[6:9], off offset:16 sc0 sc1
	s_cbranch_scc1 .LBB0_530

; DI unsigned pack2(float a, float b) { v2f f = {a, b}; return __builtin_bit_cast(unsigned, __builtin_convertvector(f, v2bf)); }
; DI void wprep_tile(const float* __restrict__ src, int Nsrc, u16* __restrict__ dst, int K, int kt, int nt, int remap, char* smem) {
;     ...
;   const int n2 = tid >> 2, k0 = (tid & 3) * 16;
;   unsigned w[8];
; #pragma unroll
;   for (int j = 0; j < 8; ++j) w[j] = pack2(tile[n2 * 65 + k0 + 2 * j], tile[n2 * 65 + k0 + 2 * j + 1]);
;   u16* d = dst + (long)(nt * 64 + n2) * K + kt * 64 + k0;
;   *(u32x4*)d = (u32x4){w[0], w[1], w[2], w[3]};
;   *(u32x4*)(d + 8) = (u32x4){w[4], w[5], w[6], w[7]};
.LBB0_532:
	v_ashrrev_i32_e32 v0, 2, v4
	v_lshlrev_b32_e32 v2, 4, v4
	v_and_b32_e32 v16, 48, v2
	v_mul_lo_u32 v2, v0, s15
	v_lshl_add_u32 v14, v16, 2, v2
	s_waitcnt lgkmcnt(0)
	s_barrier
	ds_read2_b32 v[2:3], v14 offset1:1
	ds_read2_b32 v[4:5], v14 offset0:2 offset1:3
	ds_read2_b32 v[6:7], v14 offset0:4 offset1:5
	ds_read2_b32 v[8:9], v14 offset0:6 offset1:7
	s_add_i32 s13, s13, s22
	s_waitcnt lgkmcnt(3)
	v_cvt_pk_bf16_f32 v2, v2, v3
	s_waitcnt lgkmcnt(2)
	v_cvt_pk_bf16_f32 v3, v4, v5
	s_waitcnt lgkmcnt(1)
	v_cvt_pk_bf16_f32 v4, v6, v7
	ds_read2_b32 v[6:7], v14 offset0:8 offset1:9
	ds_read2_b32 v[10:11], v14 offset0:10 offset1:11
	ds_read2_b32 v[12:13], v14 offset0:12 offset1:13
	ds_read2_b32 v[14:15], v14 offset0:14 offset1:15
	s_waitcnt lgkmcnt(4)
	v_cvt_pk_bf16_f32 v5, v8, v9
	s_waitcnt lgkmcnt(3)
	v_cvt_pk_bf16_f32 v6, v6, v7
	s_waitcnt lgkmcnt(2)
	v_cvt_pk_bf16_f32 v7, v10, v11
	v_add_u32_e32 v10, s1, v0
	v_ashrrev_i32_e32 v11, 31, v10
	v_lshlrev_b64 v[10:11], 11, v[10:11]
	v_lshl_add_u64 v[10:11], s[6:7], 0, v[10:11]
	s_ashr_i32 s1, s0, 31
	v_lshl_add_u64 v[10:11], s[0:1], 1, v[10:11]
	v_lshlrev_b32_e32 v0, 1, v16
	s_waitcnt lgkmcnt(1)
	v_cvt_pk_bf16_f32 v8, v12, v13
	s_waitcnt lgkmcnt(0)
	v_cvt_pk_bf16_f32 v9, v14, v15
	v_lshl_add_u64 v[10:11], v[10:11], 0, v[0:1]
	s_cmpk_gt_i32 s13, 0xff
	global_store_dwordx4 v[10:11], v[2:5], off sc0 sc1
	global_store_dwordx4 v[10:11], v[6:9], off offset:16 sc0 sc1
	s_cbranch_scc1 .LBB0_543

; DI unsigned pack2(float a, float b) { v2f f = {a, b}; return __builtin_bit_cast(unsigned, __builtin_convertvector(f, v2bf)); }
; DI void wprep_tile(const float* __restrict__ src, int Nsrc, u16* __restrict__ dst, int K, int kt, int nt, int remap, char* smem) {
;     ...
;   const int n2 = tid >> 2, k0 = (tid & 3) * 16;
;   unsigned w[8];
; #pragma unroll
;   for (int j = 0; j < 8; ++j) w[j] = pack2(tile[n2 * 65 + k0 + 2 * j], tile[n2 * 65 + k0 + 2 * j + 1]);
;   u16* d = dst + (long)(nt * 64 + n2) * K + kt * 64 + k0;
;   *(u32x4*)d = (u32x4){w[0], w[1], w[2], w[3]};
;   *(u32x4*)(d + 8) = (u32x4){w[4], w[5], w[6], w[7]};
.LBB0_545:
	v_ashrrev_i32_e32 v0, 2, v4
	v_lshlrev_b32_e32 v2, 4, v4
	v_and_b32_e32 v16, 48, v2
	v_mul_lo_u32 v2, v0, s15
	v_lshl_add_u32 v14, v16, 2, v2
	s_waitcnt lgkmcnt(0)
	s_barrier
	ds_read2_b32 v[2:3], v14 offset1:1
	ds_read2_b32 v[4:5], v14 offset0:2 offset1:3
	ds_read2_b32 v[6:7], v14 offset0:4 offset1:5
	ds_read2_b32 v[8:9], v14 offset0:6 offset1:7
	s_add_i32 s13, s13, s22
	s_waitcnt lgkmcnt(3)
	v_cvt_pk_bf16_f32 v2, v2, v3
	s_waitcnt lgkmcnt(2)
	v_cvt_pk_bf16_f32 v3, v4, v5
	s_waitcnt lgkmcnt(1)
	v_cvt_pk_bf16_f32 v4, v6, v7
	ds_read2_b32 v[6:7], v14 offset0:8 offset1:9
	ds_read2_b32 v[10:11], v14 offset0:10 offset1:11
	ds_read2_b32 v[12:13], v14 offset0:12 offset1:13
	ds_read2_b32 v[14:15], v14 offset0:14 offset1:15
	s_waitcnt lgkmcnt(4)
	v_cvt_pk_bf16_f32 v5, v8, v9
	s_waitcnt lgkmcnt(3)
	v_cvt_pk_bf16_f32 v6, v6, v7
	s_waitcnt lgkmcnt(2)
	v_cvt_pk_bf16_f32 v7, v10, v11
	v_add_u32_e32 v10, s7, v0
	v_ashrrev_i32_e32 v11, 31, v10
	v_lshlrev_b64 v[10:11], 11, v[10:11]
	v_lshl_add_u64 v[10:11], s[4:5], 0, v[10:11]
	s_ashr_i32 s7, s6, 31
	v_lshl_add_u64 v[10:11], s[6:7], 1, v[10:11]
	v_lshlrev_b32_e32 v0, 1, v16
	s_waitcnt lgkmcnt(1)
	v_cvt_pk_bf16_f32 v8, v12, v13
	s_waitcnt lgkmcnt(0)
	v_cvt_pk_bf16_f32 v9, v14, v15
	v_lshl_add_u64 v[10:11], v[10:11], 0, v[0:1]
	s_cmpk_gt_i32 s13, 0x37f
	global_store_dwordx4 v[10:11], v[2:5], off sc0 sc1
	global_store_dwordx4 v[10:11], v[6:9], off offset:16 sc0 sc1
	s_cbranch_scc1 .LBB0_556

; DI unsigned pack2(float a, float b) { v2f f = {a, b}; return __builtin_bit_cast(unsigned, __builtin_convertvector(f, v2bf)); }
; DI void wprep_tile(const float* __restrict__ src, int Nsrc, u16* __restrict__ dst, int K, int kt, int nt, int remap, char* smem) {
;     ...
;   const int n2 = tid >> 2, k0 = (tid & 3) * 16;
;   unsigned w[8];
; #pragma unroll
;   for (int j = 0; j < 8; ++j) w[j] = pack2(tile[n2 * 65 + k0 + 2 * j], tile[n2 * 65 + k0 + 2 * j + 1]);
;   u16* d = dst + (long)(nt * 64 + n2) * K + kt * 64 + k0;
;   *(u32x4*)d = (u32x4){w[0], w[1], w[2], w[3]};
;   *(u32x4*)(d + 8) = (u32x4){w[4], w[5], w[6], w[7]};
.LBB0_571:
	v_ashrrev_i32_e32 v0, 2, v4
	v_lshlrev_b32_e32 v2, 4, v4
	v_and_b32_e32 v16, 48, v2
	v_mul_lo_u32 v2, v0, s15
	v_lshl_add_u32 v14, v16, 2, v2
	s_waitcnt lgkmcnt(0)
	s_barrier
	ds_read2_b32 v[2:3], v14 offset1:1
	ds_read2_b32 v[4:5], v14 offset0:2 offset1:3
	ds_read2_b32 v[6:7], v14 offset0:4 offset1:5
	ds_read2_b32 v[8:9], v14 offset0:6 offset1:7
	s_add_i32 s13, s13, s22
	s_waitcnt lgkmcnt(3)
	v_cvt_pk_bf16_f32 v2, v2, v3
	s_waitcnt lgkmcnt(2)
	v_cvt_pk_bf16_f32 v3, v4, v5
	s_waitcnt lgkmcnt(1)
	v_cvt_pk_bf16_f32 v4, v6, v7
	ds_read2_b32 v[6:7], v14 offset0:8 offset1:9
	ds_read2_b32 v[10:11], v14 offset0:10 offset1:11
	ds_read2_b32 v[12:13], v14 offset0:12 offset1:13
	ds_read2_b32 v[14:15], v14 offset0:14 offset1:15
	s_waitcnt lgkmcnt(4)
	v_cvt_pk_bf16_f32 v5, v8, v9
	s_waitcnt lgkmcnt(3)
	v_cvt_pk_bf16_f32 v6, v6, v7
	s_waitcnt lgkmcnt(2)
	v_cvt_pk_bf16_f32 v7, v10, v11
	v_add_u32_e32 v10, s1, v0
	v_ashrrev_i32_e32 v11, 31, v10
	v_lshlrev_b64 v[10:11], 11, v[10:11]
	v_lshl_add_u64 v[10:11], s[6:7], 0, v[10:11]
	s_ashr_i32 s1, s0, 31
	v_lshl_add_u64 v[10:11], s[0:1], 1, v[10:11]
	v_lshlrev_b32_e32 v0, 1, v16
	s_waitcnt lgkmcnt(1)
	v_cvt_pk_bf16_f32 v8, v12, v13
	s_waitcnt lgkmcnt(0)
	v_cvt_pk_bf16_f32 v9, v14, v15
	v_lshl_add_u64 v[10:11], v[10:11], 0, v[0:1]
	s_cmpk_gt_i32 s13, 0x3ff
	global_store_dwordx4 v[10:11], v[2:5], off sc0 sc1
	global_store_dwordx4 v[10:11], v[6:9], off offset:16 sc0 sc1
	s_cbranch_scc1 .LBB0_582

; DI unsigned pack2(float a, float b) { v2f f = {a, b}; return __builtin_bit_cast(unsigned, __builtin_convertvector(f, v2bf)); }
; DI void wprep_tile(const float* __restrict__ src, int Nsrc, u16* __restrict__ dst, int K, int kt, int nt, int remap, char* smem) {
;     ...
;   const int n2 = tid >> 2, k0 = (tid & 3) * 16;
;   unsigned w[8];
; #pragma unroll
;   for (int j = 0; j < 8; ++j) w[j] = pack2(tile[n2 * 65 + k0 + 2 * j], tile[n2 * 65 + k0 + 2 * j + 1]);
;   u16* d = dst + (long)(nt * 64 + n2) * K + kt * 64 + k0;
;   *(u32x4*)d = (u32x4){w[0], w[1], w[2], w[3]};
;   *(u32x4*)(d + 8) = (u32x4){w[4], w[5], w[6], w[7]};
.LBB0_584:
	v_ashrrev_i32_e32 v0, 2, v4
	v_lshlrev_b32_e32 v2, 4, v4
	v_and_b32_e32 v16, 48, v2
	v_mul_lo_u32 v2, v0, s12
	v_lshl_add_u32 v14, v16, 2, v2
	s_waitcnt lgkmcnt(0)
	s_barrier
	ds_read2_b32 v[2:3], v14 offset1:1
	ds_read2_b32 v[4:5], v14 offset0:2 offset1:3
	ds_read2_b32 v[6:7], v14 offset0:4 offset1:5
	ds_read2_b32 v[8:9], v14 offset0:6 offset1:7
	s_add_i32 s10, s10, s22
	s_waitcnt lgkmcnt(3)
	v_cvt_pk_bf16_f32 v2, v2, v3
	s_waitcnt lgkmcnt(2)
	v_cvt_pk_bf16_f32 v3, v4, v5
	s_waitcnt lgkmcnt(1)
	v_cvt_pk_bf16_f32 v4, v6, v7
	ds_read2_b32 v[6:7], v14 offset0:8 offset1:9
	ds_read2_b32 v[10:11], v14 offset0:10 offset1:11
	ds_read2_b32 v[12:13], v14 offset0:12 offset1:13
	ds_read2_b32 v[14:15], v14 offset0:14 offset1:15
	s_waitcnt lgkmcnt(4)
	v_cvt_pk_bf16_f32 v5, v8, v9
	s_waitcnt lgkmcnt(3)
	v_cvt_pk_bf16_f32 v6, v6, v7
	s_waitcnt lgkmcnt(2)
	v_cvt_pk_bf16_f32 v7, v10, v11
	v_add_u32_e32 v10, s1, v0
	v_ashrrev_i32_e32 v11, 31, v10
	v_lshlrev_b64 v[10:11], 11, v[10:11]
	v_lshl_add_u64 v[10:11], s[6:7], 0, v[10:11]
	s_ashr_i32 s1, s0, 31
	v_lshl_add_u64 v[10:11], s[0:1], 1, v[10:11]
	v_lshlrev_b32_e32 v0, 1, v16
	s_waitcnt lgkmcnt(1)
	v_cvt_pk_bf16_f32 v8, v12, v13
	s_waitcnt lgkmcnt(0)
	v_cvt_pk_bf16_f32 v9, v14, v15
	v_lshl_add_u64 v[10:11], v[10:11], 0, v[0:1]
	s_cmpk_lt_i32 s10, 0x100
	global_store_dwordx4 v[10:11], v[2:5], off sc0 sc1
	global_store_dwordx4 v[10:11], v[6:9], off offset:16 sc0 sc1
	s_cbranch_scc0 .LBB0_595

; DI unsigned pack2(float a, float b) { v2f f = {a, b}; return __builtin_bit_cast(unsigned, __builtin_convertvector(f, v2bf)); }
; DI void wprep_tile(const float* __restrict__ src, int Nsrc, u16* __restrict__ dst, int K, int kt, int nt, int remap, char* smem) {
;     ...
;   const int n2 = tid >> 2, k0 = (tid & 3) * 16;
;   unsigned w[8];
; #pragma unroll
;   for (int j = 0; j < 8; ++j) w[j] = pack2(tile[n2 * 65 + k0 + 2 * j], tile[n2 * 65 + k0 + 2 * j + 1]);
;   u16* d = dst + (long)(nt * 64 + n2) * K + kt * 64 + k0;
;   *(u32x4*)d = (u32x4){w[0], w[1], w[2], w[3]};
;   *(u32x4*)(d + 8) = (u32x4){w[4], w[5], w[6], w[7]};
.LBB0_599:
	v_ashrrev_i32_e32 v0, 2, v4
	v_lshlrev_b32_e32 v2, 4, v4
	v_and_b32_e32 v16, 48, v2
	v_mul_lo_u32 v2, v0, s14
	v_lshl_add_u32 v14, v16, 2, v2
	s_waitcnt lgkmcnt(0)
	s_barrier
	ds_read2_b32 v[2:3], v14 offset1:1
	ds_read2_b32 v[4:5], v14 offset0:2 offset1:3
	ds_read2_b32 v[6:7], v14 offset0:4 offset1:5
	ds_read2_b32 v[8:9], v14 offset0:6 offset1:7
	s_add_i32 s12, s12, s10
	s_waitcnt lgkmcnt(3)
	v_cvt_pk_bf16_f32 v2, v2, v3
	s_waitcnt lgkmcnt(2)
	v_cvt_pk_bf16_f32 v3, v4, v5
	s_waitcnt lgkmcnt(1)
	v_cvt_pk_bf16_f32 v4, v6, v7
	ds_read2_b32 v[6:7], v14 offset0:8 offset1:9
	ds_read2_b32 v[10:11], v14 offset0:10 offset1:11
	ds_read2_b32 v[12:13], v14 offset0:12 offset1:13
	ds_read2_b32 v[14:15], v14 offset0:14 offset1:15
	s_waitcnt lgkmcnt(4)
	v_cvt_pk_bf16_f32 v5, v8, v9
	s_waitcnt lgkmcnt(3)
	v_cvt_pk_bf16_f32 v6, v6, v7
	s_waitcnt lgkmcnt(2)
	v_cvt_pk_bf16_f32 v7, v10, v11
	v_add_u32_e32 v10, s1, v0
	v_ashrrev_i32_e32 v11, 31, v10
	v_lshlrev_b64 v[10:11], 11, v[10:11]
	v_lshl_add_u64 v[10:11], s[6:7], 0, v[10:11]
	s_ashr_i32 s1, s0, 31
	v_lshl_add_u64 v[10:11], s[0:1], 1, v[10:11]
	v_lshlrev_b32_e32 v0, 1, v16
	s_waitcnt lgkmcnt(1)
	v_cvt_pk_bf16_f32 v8, v12, v13
	s_waitcnt lgkmcnt(0)
	v_cvt_pk_bf16_f32 v9, v14, v15
	v_lshl_add_u64 v[10:11], v[10:11], 0, v[0:1]
	s_cmpk_gt_i32 s12, 0x3ff
	global_store_dwordx4 v[10:11], v[2:5], off sc0 sc1
	global_store_dwordx4 v[10:11], v[6:9], off offset:16 sc0 sc1
	s_cbranch_scc1 .LBB0_610

; DI unsigned pack2(float a, float b) { v2f f = {a, b}; return __builtin_bit_cast(unsigned, __builtin_convertvector(f, v2bf)); }
; DI void wprep_tile(const float* __restrict__ src, int Nsrc, u16* __restrict__ dst, int K, int kt, int nt, int remap, char* smem) {
;     ...
;   const int n2 = tid >> 2, k0 = (tid & 3) * 16;
;   unsigned w[8];
; #pragma unroll
;   for (int j = 0; j < 8; ++j) w[j] = pack2(tile[n2 * 65 + k0 + 2 * j], tile[n2 * 65 + k0 + 2 * j + 1]);
;   u16* d = dst + (long)(nt * 64 + n2) * K + kt * 64 + k0;
;   *(u32x4*)d = (u32x4){w[0], w[1], w[2], w[3]};
;   *(u32x4*)(d + 8) = (u32x4){w[4], w[5], w[6], w[7]};
.LBB0_612:
	v_ashrrev_i32_e32 v0, 2, v4
	v_lshlrev_b32_e32 v2, 4, v4
	v_and_b32_e32 v16, 48, v2
	v_mul_lo_u32 v2, v0, s15
	v_lshl_add_u32 v14, v16, 2, v2
	s_waitcnt lgkmcnt(0)
	s_barrier
	ds_read2_b32 v[2:3], v14 offset1:1
	ds_read2_b32 v[4:5], v14 offset0:2 offset1:3
	ds_read2_b32 v[6:7], v14 offset0:4 offset1:5
	ds_read2_b32 v[8:9], v14 offset0:6 offset1:7
	s_add_i32 s13, s13, s10
	s_waitcnt lgkmcnt(3)
	v_cvt_pk_bf16_f32 v2, v2, v3
	s_waitcnt lgkmcnt(2)
	v_cvt_pk_bf16_f32 v3, v4, v5
	s_waitcnt lgkmcnt(1)
	v_cvt_pk_bf16_f32 v4, v6, v7
	ds_read2_b32 v[6:7], v14 offset0:8 offset1:9
	ds_read2_b32 v[10:11], v14 offset0:10 offset1:11
	ds_read2_b32 v[12:13], v14 offset0:12 offset1:13
	ds_read2_b32 v[14:15], v14 offset0:14 offset1:15
	s_waitcnt lgkmcnt(4)
	v_cvt_pk_bf16_f32 v5, v8, v9
	s_waitcnt lgkmcnt(3)
	v_cvt_pk_bf16_f32 v6, v6, v7
	s_waitcnt lgkmcnt(2)
	v_cvt_pk_bf16_f32 v7, v10, v11
	v_add_u32_e32 v10, s1, v0
	v_ashrrev_i32_e32 v11, 31, v10
	v_lshlrev_b64 v[10:11], 11, v[10:11]
	v_lshl_add_u64 v[10:11], s[6:7], 0, v[10:11]
	s_ashr_i32 s1, s0, 31
	v_lshl_add_u64 v[10:11], s[0:1], 1, v[10:11]
	v_lshlrev_b32_e32 v0, 1, v16
	s_waitcnt lgkmcnt(1)
	v_cvt_pk_bf16_f32 v8, v12, v13
	s_waitcnt lgkmcnt(0)
	v_cvt_pk_bf16_f32 v9, v14, v15
	v_lshl_add_u64 v[10:11], v[10:11], 0, v[0:1]
	s_cmpk_gt_i32 s13, 0xff
	global_store_dwordx4 v[10:11], v[2:5], off sc0 sc1
	global_store_dwordx4 v[10:11], v[6:9], off offset:16 sc0 sc1
	s_cbranch_scc1 .LBB0_623

; DI unsigned pack2(float a, float b) { v2f f = {a, b}; return __builtin_bit_cast(unsigned, __builtin_convertvector(f, v2bf)); }
; DI void wprep_tile(const float* __restrict__ src, int Nsrc, u16* __restrict__ dst, int K, int kt, int nt, int remap, char* smem) {
;     ...
;   __syncthreads();
;   const int n2 = tid >> 2, k0 = (tid & 3) * 16;
;   unsigned w[8];
; #pragma unroll
;   for (int j = 0; j < 8; ++j) w[j] = pack2(tile[n2 * 65 + k0 + 2 * j], tile[n2 * 65 + k0 + 2 * j + 1]);
;   u16* d = dst + (long)(nt * 64 + n2) * K + kt * 64 + k0;
;   *(u32x4*)d = (u32x4){w[0], w[1], w[2], w[3]};
;   *(u32x4*)(d + 8) = (u32x4){w[4], w[5], w[6], w[7]};
.LBB0_625:
	v_ashrrev_i32_e32 v0, 2, v4
	v_lshlrev_b32_e32 v2, 4, v4
	v_and_b32_e32 v16, 48, v2
	v_mul_lo_u32 v2, v0, s15
	v_lshl_add_u32 v14, v16, 2, v2
	s_waitcnt lgkmcnt(0)
	s_barrier
	ds_read2_b32 v[2:3], v14 offset1:1
	ds_read2_b32 v[4:5], v14 offset0:2 offset1:3
	ds_read2_b32 v[6:7], v14 offset0:4 offset1:5
	ds_read2_b32 v[8:9], v14 offset0:6 offset1:7
	s_add_i32 s13, s13, s10
	s_waitcnt lgkmcnt(3)
	v_cvt_pk_bf16_f32 v2, v2, v3
	s_waitcnt lgkmcnt(2)
	v_cvt_pk_bf16_f32 v3, v4, v5
	s_waitcnt lgkmcnt(1)
	v_cvt_pk_bf16_f32 v4, v6, v7
	ds_read2_b32 v[6:7], v14 offset0:8 offset1:9
	ds_read2_b32 v[10:11], v14 offset0:10 offset1:11
	ds_read2_b32 v[12:13], v14 offset0:12 offset1:13
	ds_read2_b32 v[14:15], v14 offset0:14 offset1:15
	s_waitcnt lgkmcnt(4)
	v_cvt_pk_bf16_f32 v5, v8, v9
	s_waitcnt lgkmcnt(3)
	v_cvt_pk_bf16_f32 v6, v6, v7
	s_waitcnt lgkmcnt(2)
	v_cvt_pk_bf16_f32 v7, v10, v11
	v_add_u32_e32 v10, s7, v0
	v_ashrrev_i32_e32 v11, 31, v10
	v_lshlrev_b64 v[10:11], 11, v[10:11]
	v_lshl_add_u64 v[10:11], s[4:5], 0, v[10:11]
	s_ashr_i32 s7, s6, 31
	v_lshl_add_u64 v[10:11], s[6:7], 1, v[10:11]
	v_lshlrev_b32_e32 v0, 1, v16
	s_waitcnt lgkmcnt(1)
	v_cvt_pk_bf16_f32 v8, v12, v13
	s_waitcnt lgkmcnt(0)
	v_cvt_pk_bf16_f32 v9, v14, v15
	v_lshl_add_u64 v[10:11], v[10:11], 0, v[0:1]
	s_cmpk_gt_i32 s13, 0x37f
	global_store_dwordx4 v[10:11], v[2:5], off sc0 sc1
	global_store_dwordx4 v[10:11], v[6:9], off offset:16 sc0 sc1
	s_cbranch_scc1 .LBB0_636

; DI unsigned pack2(float a, float b) { v2f f = {a, b}; return __builtin_bit_cast(unsigned, __builtin_convertvector(f, v2bf)); }
; DI void wprep_tile(const float* __restrict__ src, int Nsrc, u16* __restrict__ dst, int K, int kt, int nt, int remap, char* smem) {
;     ...
;   __syncthreads();
;   const int n2 = tid >> 2, k0 = (tid & 3) * 16;
;   unsigned w[8];
; #pragma unroll
;   for (int j = 0; j < 8; ++j) w[j] = pack2(tile[n2 * 65 + k0 + 2 * j], tile[n2 * 65 + k0 + 2 * j + 1]);
;   u16* d = dst + (long)(nt * 64 + n2) * K + kt * 64 + k0;
;   *(u32x4*)d = (u32x4){w[0], w[1], w[2], w[3]};
;   *(u32x4*)(d + 8) = (u32x4){w[4], w[5], w[6], w[7]};
.LBB0_651:
	v_ashrrev_i32_e32 v0, 2, v4
	v_lshlrev_b32_e32 v2, 4, v4
	v_and_b32_e32 v16, 48, v2
	v_mul_lo_u32 v2, v0, s15
	v_lshl_add_u32 v14, v16, 2, v2
	s_waitcnt lgkmcnt(0)
	s_barrier
	ds_read2_b32 v[2:3], v14 offset1:1
	ds_read2_b32 v[4:5], v14 offset0:2 offset1:3
	ds_read2_b32 v[6:7], v14 offset0:4 offset1:5
	ds_read2_b32 v[8:9], v14 offset0:6 offset1:7
	s_add_i32 s13, s13, s10
	s_waitcnt lgkmcnt(3)
	v_cvt_pk_bf16_f32 v2, v2, v3
	s_waitcnt lgkmcnt(2)
	v_cvt_pk_bf16_f32 v3, v4, v5
	s_waitcnt lgkmcnt(1)
	v_cvt_pk_bf16_f32 v4, v6, v7
	ds_read2_b32 v[6:7], v14 offset0:8 offset1:9
	ds_read2_b32 v[10:11], v14 offset0:10 offset1:11
	ds_read2_b32 v[12:13], v14 offset0:12 offset1:13
	ds_read2_b32 v[14:15], v14 offset0:14 offset1:15
	s_waitcnt lgkmcnt(4)
	v_cvt_pk_bf16_f32 v5, v8, v9
	s_waitcnt lgkmcnt(3)
	v_cvt_pk_bf16_f32 v6, v6, v7
	s_waitcnt lgkmcnt(2)
	v_cvt_pk_bf16_f32 v7, v10, v11
	v_add_u32_e32 v10, s1, v0
	v_ashrrev_i32_e32 v11, 31, v10
	v_lshlrev_b64 v[10:11], 11, v[10:11]
	v_lshl_add_u64 v[10:11], s[6:7], 0, v[10:11]
	s_ashr_i32 s1, s0, 31
	v_lshl_add_u64 v[10:11], s[0:1], 1, v[10:11]
	v_lshlrev_b32_e32 v0, 1, v16
	s_waitcnt lgkmcnt(1)
	v_cvt_pk_bf16_f32 v8, v12, v13
	s_waitcnt lgkmcnt(0)
	v_cvt_pk_bf16_f32 v9, v14, v15
	v_lshl_add_u64 v[10:11], v[10:11], 0, v[0:1]
	s_cmpk_gt_i32 s13, 0x3ff
	global_store_dwordx4 v[10:11], v[2:5], off sc0 sc1
	global_store_dwordx4 v[10:11], v[6:9], off offset:16 sc0 sc1
	s_cbranch_scc1 .LBB0_662

; DI unsigned pack2(float a, float b) { v2f f = {a, b}; return __builtin_bit_cast(unsigned, __builtin_convertvector(f, v2bf)); }
; DI void wprep_tile(const float* __restrict__ src, int Nsrc, u16* __restrict__ dst, int K, int kt, int nt, int remap, char* smem) {
;     ...
;   __syncthreads();
;   const int n2 = tid >> 2, k0 = (tid & 3) * 16;
;   unsigned w[8];
; #pragma unroll
;   for (int j = 0; j < 8; ++j) w[j] = pack2(tile[n2 * 65 + k0 + 2 * j], tile[n2 * 65 + k0 + 2 * j + 1]);
;   u16* d = dst + (long)(nt * 64 + n2) * K + kt * 64 + k0;
;   *(u32x4*)d = (u32x4){w[0], w[1], w[2], w[3]};
;   *(u32x4*)(d + 8) = (u32x4){w[4], w[5], w[6], w[7]};
.LBB0_664:
	v_ashrrev_i32_e32 v0, 2, v4
	v_lshlrev_b32_e32 v2, 4, v4
	v_and_b32_e32 v16, 48, v2
	v_mul_lo_u32 v2, v0, s13
	v_lshl_add_u32 v14, v16, 2, v2
	s_waitcnt lgkmcnt(0)
	s_barrier
	ds_read2_b32 v[2:3], v14 offset1:1
	ds_read2_b32 v[4:5], v14 offset0:2 offset1:3
	ds_read2_b32 v[6:7], v14 offset0:4 offset1:5
	ds_read2_b32 v[8:9], v14 offset0:6 offset1:7
	s_add_i32 s11, s11, s10
	s_waitcnt lgkmcnt(3)
	v_cvt_pk_bf16_f32 v2, v2, v3
	s_waitcnt lgkmcnt(2)
	v_cvt_pk_bf16_f32 v3, v4, v5
	s_waitcnt lgkmcnt(1)
	v_cvt_pk_bf16_f32 v4, v6, v7
	ds_read2_b32 v[6:7], v14 offset0:8 offset1:9
	ds_read2_b32 v[10:11], v14 offset0:10 offset1:11
	ds_read2_b32 v[12:13], v14 offset0:12 offset1:13
	ds_read2_b32 v[14:15], v14 offset0:14 offset1:15
	s_waitcnt lgkmcnt(4)
	v_cvt_pk_bf16_f32 v5, v8, v9
	s_waitcnt lgkmcnt(3)
	v_cvt_pk_bf16_f32 v6, v6, v7
	s_waitcnt lgkmcnt(2)
	v_cvt_pk_bf16_f32 v7, v10, v11
	v_add_u32_e32 v10, s1, v0
	v_ashrrev_i32_e32 v11, 31, v10
	v_lshlrev_b64 v[10:11], 11, v[10:11]
	v_lshl_add_u64 v[10:11], s[6:7], 0, v[10:11]
	s_ashr_i32 s1, s0, 31
	v_lshl_add_u64 v[10:11], s[0:1], 1, v[10:11]
	v_lshlrev_b32_e32 v0, 1, v16
	s_waitcnt lgkmcnt(1)
	v_cvt_pk_bf16_f32 v8, v12, v13
	s_waitcnt lgkmcnt(0)
	v_cvt_pk_bf16_f32 v9, v14, v15
	v_lshl_add_u64 v[10:11], v[10:11], 0, v[0:1]
	s_cmpk_gt_i32 s11, 0xff
	global_store_dwordx4 v[10:11], v[2:5], off sc0 sc1
	global_store_dwordx4 v[10:11], v[6:9], off offset:16 sc0 sc1
	s_cbranch_scc1 .LBB0_675

; template <class ARow, class Epi>
; DI void gemm_tile(const ARow& arow, long a_kstride, const u16* __restrict__ Bt, long ldb, int K, int m0, int n0,
;                   const Epi& epi, char* smem) {
;     ...
;   const int fr = lane & 15, fq = lane >> 4;
;   int foff[2];
; #pragma unroll
;   for (int ks = 0; ks < 2; ++ks) foff[ks] = fr * 128 + ((((4 * ks + fq) ^ ((fr >> 1) & 7))) << 4);
;   f32x4 acc[4][4];
; #pragma unroll
;   for (int a = 0; a < 4; ++a)
; #pragma unroll
;     for (int b = 0; b < 4; ++b) acc[a][b] = (f32x4){0.f, 0.f, 0.f, 0.f};
;   const int KT = K >> 6;
;   GEMM_STAGE(0, 0);
;   asm volatile("s_waitcnt vmcnt(0)" ::: "memory");
;   __syncthreads();
;   for (int kt = 0; kt < KT; ++kt) {
;     const int cur = kt & 1;
;     if (kt + 1 < KT) GEMM_STAGE(cur ^ 1, kt + 1);
;     const char* sa = smem + cur * 32768 + wm * 64 * 128;
;     const char* sb = smem + cur * 32768 + 16384 + wn * 64 * 128;
; #pragma unroll
;     for (int ks = 0; ks < 2; ++ks) {
;       bf16x8 wf[4], af[4];
; #pragma unroll
;       for (int j = 0; j < 4; ++j) {
;         wf[j] = *(const bf16x8*)(sb + j * 2048 + foff[ks]);
;         af[j] = *(const bf16x8*)(sa + j * 2048 + foff[ks]);
;       }
; #pragma unroll
;       for (int ni = 0; ni < 4; ++ni)
; #pragma unroll
;         for (int mi = 0; mi < 4; ++mi) acc[ni][mi] = __builtin_amdgcn_mfma_f32_16x16x32_bf16(wf[ni], af[mi], acc[ni][mi], 0, 0, 0);
;     }
;     asm volatile("s_waitcnt vmcnt(0)" ::: "memory");
;     __syncthreads();
;   }
.LBB0_678:
	s_and_b32 s1, s0, 0x8000
	s_xor_b32 s36, s1, 0x8000
	v_add_u32_e32 v54, s36, v33
	v_add_u32_e32 v39, s1, v38
	v_or_b32_e32 v114, s1, v37
	v_readfirstlane_b32 s1, v54
	v_add_u32_e32 v55, 0x4000, v54
	v_lshl_add_u64 v[34:35], v[30:31], 0, s[18:19]
	v_add_u32_e32 v72, 0x400, v54
	v_readfirstlane_b32 s36, v55
	s_mov_b32 m0, s1
	v_lshl_add_u64 v[40:41], v[16:17], 0, s[20:21]
	v_add_u32_e32 v73, 0x4400, v54
	v_readfirstlane_b32 s37, v72
	global_load_lds_dwordx4 v[34:35], off
	s_mov_b32 m0, s36
	v_lshl_add_u64 v[42:43], v[28:29], 0, s[18:19]
	v_add_u32_e32 v74, 0x800, v54
	v_readfirstlane_b32 s38, v73
	global_load_lds_dwordx4 v[40:41], off
	s_mov_b32 m0, s37
	v_lshl_add_u64 v[44:45], v[18:19], 0, s[20:21]
	v_add_u32_e32 v75, 0x4800, v54
	v_readfirstlane_b32 s39, v74
	global_load_lds_dwordx4 v[42:43], off
	s_mov_b32 m0, s38
	v_lshl_add_u64 v[46:47], v[26:27], 0, s[18:19]
	v_add_u32_e32 v76, 0xc00, v54
	v_readfirstlane_b32 s40, v75
	global_load_lds_dwordx4 v[44:45], off
	s_mov_b32 m0, s39
	v_lshl_add_u64 v[48:49], v[20:21], 0, s[20:21]
	v_add_u32_e32 v54, 0x4c00, v54
	v_readfirstlane_b32 s41, v76
	global_load_lds_dwordx4 v[46:47], off
	s_mov_b32 m0, s40
	v_lshl_add_u64 v[50:51], v[24:25], 0, s[18:19]
	v_readfirstlane_b32 s42, v54
	global_load_lds_dwordx4 v[48:49], off
	s_mov_b32 m0, s41
	v_lshl_add_u64 v[52:53], v[22:23], 0, s[20:21]
	global_load_lds_dwordx4 v[50:51], off
	s_mov_b32 m0, s42
	v_add_u32_e32 v100, v114, v36
	global_load_lds_dwordx4 v[52:53], off
	v_add_u32_e32 v96, v39, v36
	ds_read_b128 v[40:43], v100 offset:16384
	ds_read_b128 v[44:47], v96
	ds_read_b128 v[48:51], v100 offset:18432
	ds_read_b128 v[52:55], v96 offset:2048
	s_waitcnt lgkmcnt(0)
	v_mfma_f32_16x16x32_bf16 v[76:79], v[40:43], v[52:55], v[92:95]
	s_nop 2
	ds_read_b128 v[92:95], v96 offset:4096
	ds_read_b128 v[96:99], v96 offset:6144
	v_add_u32_e32 v34, v114, v32
	v_add_u32_e32 v35, v39, v32
	v_mfma_f32_16x16x32_bf16 v[72:75], v[40:43], v[44:47], v[144:147]
	s_add_i32 s0, s0, 0x8000
	s_add_u32 s20, s20, 0x80
	s_addc_u32 s21, s21, 0
	s_waitcnt lgkmcnt(0)
	v_mfma_f32_16x16x32_bf16 v[68:71], v[40:43], v[92:95], v[68:71]
	v_lshl_add_u64 v[24:25], v[24:25], 0, s[14:15]
	v_lshl_add_u64 v[26:27], v[26:27], 0, s[14:15]
	v_lshl_add_u64 v[28:29], v[28:29], 0, s[14:15]
	v_mfma_f32_16x16x32_bf16 v[12:15], v[40:43], v[96:99], v[12:15]
	v_lshl_add_u64 v[30:31], v[30:31], 0, s[14:15]
	s_cmpk_lg_i32 s20, 0xf80
	v_mfma_f32_16x16x32_bf16 v[40:43], v[48:51], v[44:47], v[140:143]
	v_mfma_f32_16x16x32_bf16 v[84:87], v[48:51], v[52:55], v[84:87]
	v_mfma_f32_16x16x32_bf16 v[60:63], v[48:51], v[92:95], v[60:63]
	v_mfma_f32_16x16x32_bf16 v[4:7], v[48:51], v[96:99], v[4:7]
	ds_read_b128 v[48:51], v100 offset:20480
	ds_read_b128 v[100:103], v100 offset:22528
	s_waitcnt lgkmcnt(0)
	v_mfma_f32_16x16x32_bf16 v[108:111], v[48:51], v[44:47], v[128:131]
	v_mfma_f32_16x16x32_bf16 v[80:83], v[48:51], v[52:55], v[80:83]
	v_mfma_f32_16x16x32_bf16 v[56:59], v[48:51], v[92:95], v[56:59]
	v_mfma_f32_16x16x32_bf16 v[0:3], v[48:51], v[96:99], v[0:3]
	v_mfma_f32_16x16x32_bf16 v[48:51], v[100:103], v[52:55], v[88:91]
	v_mfma_f32_16x16x32_bf16 v[52:55], v[100:103], v[92:95], v[64:67]
	s_nop 2
	ds_read_b128 v[64:67], v34 offset:16384
	v_mfma_f32_16x16x32_bf16 v[44:47], v[100:103], v[44:47], v[104:107]
	v_mfma_f32_16x16x32_bf16 v[8:11], v[100:103], v[96:99], v[8:11]
	ds_read_b128 v[88:91], v35
	ds_read_b128 v[96:99], v34 offset:18432
	ds_read_b128 v[100:103], v35 offset:2048
	s_waitcnt lgkmcnt(0)
	v_mfma_f32_16x16x32_bf16 v[144:147], v[64:67], v[88:91], v[72:75]
	v_mfma_f32_16x16x32_bf16 v[92:95], v[64:67], v[100:103], v[76:79]
	s_nop 1
	ds_read_b128 v[72:75], v35 offset:4096
	ds_read_b128 v[76:79], v35 offset:6144
	v_mfma_f32_16x16x32_bf16 v[140:143], v[96:99], v[88:91], v[40:43]
	v_mfma_f32_16x16x32_bf16 v[84:87], v[96:99], v[100:103], v[84:87]
	s_waitcnt lgkmcnt(0)
	v_mfma_f32_16x16x32_bf16 v[60:63], v[96:99], v[72:75], v[60:63]
	v_mfma_f32_16x16x32_bf16 v[4:7], v[96:99], v[76:79], v[4:7]
	ds_read_b128 v[40:43], v34 offset:20480
	ds_read_b128 v[96:99], v34 offset:22528
	s_waitcnt vmcnt(0)
	s_waitcnt vmcnt(0) lgkmcnt(0)
	v_mfma_f32_16x16x32_bf16 v[68:71], v[64:67], v[72:75], v[68:71]
	s_barrier
	v_mfma_f32_16x16x32_bf16 v[12:15], v[64:67], v[76:79], v[12:15]
	v_mfma_f32_16x16x32_bf16 v[128:131], v[40:43], v[88:91], v[108:111]
	v_mfma_f32_16x16x32_bf16 v[80:83], v[40:43], v[100:103], v[80:83]
	v_mfma_f32_16x16x32_bf16 v[56:59], v[40:43], v[72:75], v[56:59]
	v_mfma_f32_16x16x32_bf16 v[0:3], v[40:43], v[76:79], v[0:3]
	v_mfma_f32_16x16x32_bf16 v[104:107], v[96:99], v[88:91], v[44:47]
	v_mfma_f32_16x16x32_bf16 v[88:91], v[96:99], v[100:103], v[48:51]
	v_mfma_f32_16x16x32_bf16 v[64:67], v[96:99], v[72:75], v[52:55]
	v_mfma_f32_16x16x32_bf16 v[8:11], v[96:99], v[76:79], v[8:11]
	s_cbranch_scc1 .LBB0_678
	s_lshl_b64 s[0:1], s[16:17], 21
	s_lshl_b32 s16, s16, 12
	s_ashr_i32 s17, s16, 31
	s_add_u32 s0, s8, s0
	s_addc_u32 s1, s9, s1
	s_lshl_b64 s[16:17], s[16:17], 2
	v_lshl_or_b32 v112, v112, 6, s35
	v_lshlrev_b32_e32 v226, 2, v113
	s_add_u32 s16, s6, s16
	v_or_b32_e32 v113, v112, v226
	v_lshlrev_b32_e32 v212, 1, v112
	s_addc_u32 s17, s7, s17
	v_lshl_add_u64 v[214:215], s[0:1], 0, v[212:213]
	v_lshlrev_b32_e32 v212, 2, v113
	v_lshl_add_u64 v[156:157], s[16:17], 0, v[212:213]
	v_add_u32_e32 v28, v38, v32
	v_add_u32_e32 v32, v37, v32
	v_add_u32_e32 v48, v38, v36
	v_add_u32_e32 v52, v37, v36
	v_add_co_u32_e32 v216, vcc, s31, v156
	ds_read_b128 v[16:19], v28 offset:38912
	ds_read_b128 v[72:75], v28 offset:36864
	ds_read_b128 v[20:23], v32 offset:55296
	ds_read_b128 v[24:27], v32 offset:53248
	ds_read_b128 v[96:99], v28 offset:34816
	ds_read_b128 v[108:111], v28 offset:32768
	ds_read_b128 v[28:31], v32 offset:51200
	ds_read_b128 v[32:35], v32 offset:49152
	ds_read_b128 v[36:39], v48 offset:38912
	ds_read_b128 v[76:79], v48 offset:36864
	ds_read_b128 v[40:43], v52 offset:55296
	ds_read_b128 v[44:47], v52 offset:53248
	ds_read_b128 v[100:103], v48 offset:34816
	ds_read_b128 v[148:151], v48 offset:32768
	ds_read_b128 v[48:51], v52 offset:51200
	ds_read_b128 v[52:55], v52 offset:49152
	v_addc_co_u32_e32 v217, vcc, 0, v157, vcc
	s_waitcnt vmcnt(0)
	s_waitcnt lgkmcnt(0)
	s_barrier
; DI unsigned pack2(float a, float b) { v2f f = {a, b}; return __builtin_bit_cast(unsigned, __builtin_convertvector(f, v2bf)); }
; DI float fexp(float x) { return __builtin_amdgcn_exp2f(x * LOG2E); }
;   DI u32x2 pack(int, int, float a, float b, float c, float d, float&) const { u32x2 v; v.x = pack2(a, b); v.y = pack2(c, d); return v; }
; DI float gelu_tanh(float x) {
;   float u = 0.7978845608028654f * (x + 0.044715f * x * x * x);
;   float t = 1.f - 2.f / (fexp(2.f * u) + 1.f);
;   return 0.5f * x * (1.f + t);
; }
;   DI u32x2 pack(int m, int n, float a, float b, float c, float d, float& ss) const {
;     f32x4 bs = {0.f, 0.f, 0.f, 0.f};
; #pragma unroll
;     for (int kc = 0; kc < 16; ++kc) bs += *(const f32x4*)(bias_part + kc * 256 + n);
;     u32x2 v; v.x = pack2(gelu_tanh(a + bs[0]), gelu_tanh(b + bs[1])); v.y = pack2(gelu_tanh(c + bs[2]), gelu_tanh(d + bs[3]));
;     return v;
;   }
	global_load_dwordx4 v[112:115], v212, s[16:17]
	global_load_dwordx4 v[116:119], v212, s[16:17] offset:1024
	global_load_dwordx4 v[120:123], v212, s[16:17] offset:2048
	global_load_dwordx4 v[124:127], v212, s[16:17] offset:3072
	v_add_co_u32_e32 v220, vcc, s30, v156
	global_load_dwordx4 v[132:135], v[216:217], off offset:-4096
	s_nop 0
	v_addc_co_u32_e32 v221, vcc, 0, v157, vcc
	global_load_dwordx4 v[136:139], v[220:221], off offset:1024
	v_mfma_f32_16x16x32_bf16 v[172:175], v[52:55], v[148:151], v[144:147]
	s_nop 2
	global_load_dwordx4 v[144:147], v[220:221], off offset:2048
	global_load_dwordx4 v[152:155], v[220:221], off offset:3072
	global_load_dwordx4 v[164:167], v[216:217], off
	global_load_dwordx4 v[168:171], v[216:217], off offset:1024
	v_add_co_u32_e32 v218, vcc, s33, v156
	v_mfma_f32_16x16x32_bf16 v[184:187], v[44:47], v[148:151], v[128:131]
	global_load_dwordx4 v[176:179], v[216:217], off offset:2048
	s_nop 1
	global_load_dwordx4 v[128:131], v[216:217], off offset:3072
	v_addc_co_u32_e32 v219, vcc, 0, v157, vcc
	v_mfma_f32_16x16x32_bf16 v[188:191], v[48:51], v[148:151], v[140:143]
	v_and_b32_e32 v223, 16, v223
	s_add_i32 s23, s23, s22
	s_add_i32 s24, s24, s25
	global_load_dwordx4 v[140:143], v[218:219], off
	global_load_dwordx4 v[156:159], v[218:219], off offset:1024
	global_load_dwordx4 v[160:163], v[218:219], off offset:2048
	v_mfma_f32_16x16x32_bf16 v[180:183], v[40:43], v[148:151], v[104:107]
	s_add_i32 s26, s26, s27
	s_cmpk_lt_i32 s23, 0x80
	s_waitcnt vmcnt(14)
	v_pk_add_f32 v[112:113], v[112:113], 0 op_sel_hi:[1,0]
	v_mfma_f32_16x16x32_bf16 v[148:151], v[32:35], v[108:111], v[172:175]
	s_waitcnt vmcnt(13)
	v_pk_add_f32 v[112:113], v[112:113], v[116:117]
	v_pk_add_f32 v[114:115], v[114:115], 0 op_sel_hi:[1,0]
	s_waitcnt vmcnt(12)
	v_pk_add_f32 v[112:113], v[112:113], v[120:121]
	global_load_dwordx4 v[172:175], v[218:219], off offset:3072
	s_waitcnt vmcnt(12)
	v_pk_add_f32 v[112:113], v[112:113], v[124:125]
	v_pk_add_f32 v[114:115], v[114:115], v[118:119]
	s_waitcnt vmcnt(11)
	v_pk_add_f32 v[112:113], v[112:113], v[132:133]
	v_pk_add_f32 v[114:115], v[114:115], v[122:123]
	s_waitcnt vmcnt(10)
	v_pk_add_f32 v[112:113], v[112:113], v[136:137]
	v_pk_add_f32 v[114:115], v[114:115], v[126:127]
	s_waitcnt vmcnt(9)
	v_pk_add_f32 v[112:113], v[112:113], v[144:145]
	v_pk_add_f32 v[114:115], v[114:115], v[134:135]
	s_waitcnt vmcnt(8)
	v_pk_add_f32 v[112:113], v[112:113], v[152:153]
	v_pk_add_f32 v[114:115], v[114:115], v[138:139]
	s_waitcnt vmcnt(7)
	v_pk_add_f32 v[112:113], v[112:113], v[164:165]
	v_pk_add_f32 v[114:115], v[114:115], v[146:147]
	s_waitcnt vmcnt(6)
	v_pk_add_f32 v[112:113], v[112:113], v[168:169]
	v_pk_add_f32 v[114:115], v[114:115], v[154:155]
	s_waitcnt vmcnt(5)
	v_pk_add_f32 v[112:113], v[112:113], v[176:177]
	v_pk_add_f32 v[114:115], v[114:115], v[166:167]
	s_waitcnt vmcnt(4)
	v_pk_add_f32 v[112:113], v[112:113], v[128:129]
	v_pk_add_f32 v[114:115], v[114:115], v[170:171]
	s_waitcnt vmcnt(3)
	v_pk_add_f32 v[112:113], v[112:113], v[140:141]
	v_pk_add_f32 v[178:179], v[114:115], v[178:179]
	s_waitcnt vmcnt(2)
	v_pk_add_f32 v[112:113], v[112:113], v[156:157]
	v_pk_add_f32 v[130:131], v[178:179], v[130:131]
	s_waitcnt vmcnt(1)
	v_pk_add_f32 v[128:129], v[112:113], v[160:161]
	v_pk_add_f32 v[130:131], v[130:131], v[142:143]
	v_mfma_f32_16x16x32_bf16 v[104:107], v[28:31], v[108:111], v[188:191]
	v_add_f32_e64 v130, v130, v158
	v_add_f32_e64 v131, v131, v159
	s_nop 0
	global_load_dwordx4 v[188:191], v212, s[16:17] offset:192
	global_load_dwordx4 v[192:195], v212, s[16:17] offset:1216
	global_load_dwordx4 v[196:199], v212, s[16:17] offset:2240
	s_waitcnt vmcnt(3)
	v_pk_add_f32 v[128:129], v[128:129], v[172:173]
	s_nop 0
	v_pk_add_f32 v[228:229], v[148:149], v[128:129]
	v_mfma_f32_16x16x32_bf16 v[208:211], v[24:27], v[108:111], v[184:187]
	v_mul_f32_e32 v128, 0x3d372713, v228
	v_mul_f32_e32 v129, 0x3d372713, v229
	v_mul_f32_e32 v128, v228, v128
	v_mul_f32_e32 v129, v229, v129
	v_fma_f32 v128, v228, v128, v228
	v_fma_f32 v129, v229, v129, v229
	v_mul_f32_e32 v128, 0x3f4c422a, v128
	v_mul_f32_e32 v129, 0x3f4c422a, v129
	v_add_f32_e32 v128, v128, v128
	v_add_f32_e32 v129, v129, v129
	v_mul_f32_e32 v128, 0x3fb8aa3b, v128
	v_mul_f32_e32 v129, 0x3fb8aa3b, v129
	v_exp_f32_e32 v128, v128
	v_exp_f32_e32 v129, v129
	global_load_dwordx4 v[184:187], v212, s[16:17] offset:3264
	global_load_dwordx4 v[200:203], v[220:221], off offset:192
	global_load_dwordx4 v[204:207], v[218:219], off offset:3264
	global_load_dwordx4 v[112:115], v[218:219], off offset:2240
	v_mfma_f32_16x16x32_bf16 v[108:111], v[20:23], v[108:111], v[180:183]
	v_add_f32_e64 v230, v128, 1.0
	v_add_f32_e64 v231, v129, 1.0
	v_pk_add_f32 v[128:129], v[130:131], v[162:163]
	v_div_scale_f32 v160, s[0:1], v231, v231, 2.0
	v_rcp_f32_e32 v176, v160
	v_pk_add_f32 v[128:129], v[128:129], v[174:175]
	v_div_scale_f32 v161, vcc, 2.0, v231, 2.0
	v_fma_f32 v140, -v160, v176, 1.0
	v_pk_add_f32 v[244:245], v[150:151], v[128:129]
	global_load_dwordx4 v[128:131], v212, s[16:17] offset:64
	v_fmac_f32_e32 v176, v140, v176
	global_load_dwordx4 v[140:143], v212, s[16:17] offset:1088
	v_mul_f32_e32 v177, v161, v176
	v_div_scale_f32 v224, s[0:1], v230, v230, 2.0
	global_load_dwordx4 v[148:151], v212, s[16:17] offset:2112
	v_fma_f32 v156, -v160, v177, v161
	v_rcp_f32_e32 v225, v224
	v_fmac_f32_e32 v177, v156, v176
	global_load_dwordx4 v[156:159], v212, s[16:17] offset:3136
	v_fma_f32 v178, -v160, v177, v161
	global_load_dwordx4 v[160:163], v[220:221], off offset:64
	global_load_dwordx4 v[172:175], v[220:221], off offset:1088
	v_div_fmas_f32 v180, v178, v176, v177
; DI unsigned pack2(float a, float b) { v2f f = {a, b}; return __builtin_bit_cast(unsigned, __builtin_convertvector(f, v2bf)); }
; DI float fexp(float x) { return __builtin_amdgcn_exp2f(x * LOG2E); }
;   DI u32x2 pack(int, int, float a, float b, float c, float d, float&) const { u32x2 v; v.x = pack2(a, b); v.y = pack2(c, d); return v; }
; DI float gelu_tanh(float x) {
;   float u = 0.7978845608028654f * (x + 0.044715f * x * x * x);
;   float t = 1.f - 2.f / (fexp(2.f * u) + 1.f);
;   return 0.5f * x * (1.f + t);
; }
;   DI u32x2 pack(int m, int n, float a, float b, float c, float d, float& ss) const {
;     f32x4 bs = {0.f, 0.f, 0.f, 0.f};
; #pragma unroll
;     for (int kc = 0; kc < 16; ++kc) bs += *(const f32x4*)(bias_part + kc * 256 + n);
;     u32x2 v; v.x = pack2(gelu_tanh(a + bs[0]), gelu_tanh(b + bs[1])); v.y = pack2(gelu_tanh(c + bs[2]), gelu_tanh(d + bs[3]));
;     return v;
;   }
	global_load_dwordx4 v[176:179], v[220:221], off offset:2112
	v_div_fixup_f32 v231, v180, v231, 2.0
	v_fma_f32 v180, -v224, v225, 1.0
	global_load_dwordx4 v[132:135], v[220:221], off offset:2240
	v_fmac_f32_e32 v225, v180, v225
	global_load_dwordx4 v[180:183], v[220:221], off offset:3136
	v_div_scale_f32 v232, vcc, 2.0, v230, 2.0
	v_mul_f32_e32 v234, v232, v225
	v_fma_f32 v233, -v224, v234, v232
	v_fmac_f32_e32 v234, v233, v225
	v_fma_f32 v224, -v224, v234, v232
	v_mul_f32_e32 v232, 0x3d372713, v244
	v_mul_f32_e32 v233, 0x3d372713, v245
	v_mul_f32_e32 v232, v244, v232
	v_mul_f32_e32 v233, v245, v233
	v_fma_f32 v232, v244, v232, v244
	v_fma_f32 v233, v245, v233, v245
	v_mul_f32_e32 v232, 0x3f4c422a, v232
	v_mul_f32_e32 v233, 0x3f4c422a, v233
	v_add_f32_e32 v232, v232, v232
	v_add_f32_e32 v233, v233, v233
	v_mul_f32_e32 v232, 0x3fb8aa3b, v232
	v_mul_f32_e32 v233, 0x3fb8aa3b, v233
	v_exp_f32_e32 v232, v232
	v_exp_f32_e32 v233, v233
	v_div_fmas_f32 v224, v224, v225, v234
	v_div_fixup_f32 v230, v224, v230, 2.0
	v_pk_add_f32 v[230:231], v[230:231], 1.0 op_sel_hi:[1,0] neg_lo:[1,0] neg_hi:[1,0]
	v_pk_add_f32 v[232:233], v[232:233], 1.0 op_sel_hi:[1,0]
	v_pk_mul_f32 v[228:229], v[228:229], 0.5 op_sel_hi:[1,0]
	v_div_scale_f32 v224, s[0:1], v233, v233, 2.0
	v_rcp_f32_e32 v225, v224
	v_pk_add_f32 v[230:231], v[230:231], 1.0 op_sel_hi:[1,0]
	global_load_dwordx4 v[144:147], v[216:217], off offset:64
	global_load_dwordx4 v[152:155], v[216:217], off offset:1088
	v_pk_mul_f32 v[248:249], v[228:229], v[230:231]
	v_fma_f32 v228, -v224, v225, 1.0
	v_fmac_f32_e32 v225, v228, v225
	v_div_scale_f32 v228, vcc, 2.0, v233, 2.0
	v_mul_f32_e32 v229, v228, v225
	v_fma_f32 v230, -v224, v229, v228
	v_fmac_f32_e32 v229, v230, v225
	v_fma_f32 v224, -v224, v229, v228
	v_div_scale_f32 v228, s[0:1], v232, v232, 2.0
	v_rcp_f32_e32 v230, v228
	v_div_fmas_f32 v224, v224, v225, v229
	v_div_fixup_f32 v247, v224, v233, 2.0
	global_load_dwordx4 v[164:167], v[216:217], off offset:2112
	global_load_dwordx4 v[168:171], v[216:217], off offset:3136
	v_fma_f32 v224, -v228, v230, 1.0
	v_fmac_f32_e32 v230, v224, v230
	v_div_scale_f32 v224, vcc, 2.0, v232, 2.0
	v_mul_f32_e32 v225, v224, v230
	v_fma_f32 v229, -v228, v225, v224
	v_fmac_f32_e32 v225, v229, v230
	v_fma_f32 v224, -v228, v225, v224
	v_div_fmas_f32 v224, v224, v230, v225
	v_div_fixup_f32 v246, v224, v232, 2.0
	global_load_dwordx4 v[228:231], v212, s[16:17] offset:128
	global_load_dwordx4 v[124:127], v[220:221], off offset:1216
	s_waitcnt vmcnt(14)
	v_pk_add_f32 v[232:233], v[130:131], 0 op_sel_hi:[1,0]
	v_pk_add_f32 v[234:235], v[128:129], 0 op_sel_hi:[1,0]
	global_load_dwordx4 v[128:131], v212, s[16:17] offset:1152
	s_waitcnt vmcnt(14)
	v_pk_add_f32 v[232:233], v[232:233], v[142:143]
	v_pk_add_f32 v[234:235], v[234:235], v[140:141]
	global_load_dwordx4 v[140:143], v212, s[16:17] offset:2176
	s_waitcnt vmcnt(14)
	v_pk_add_f32 v[232:233], v[232:233], v[150:151]
	v_pk_add_f32 v[234:235], v[234:235], v[148:149]
	global_load_dwordx4 v[148:151], v212, s[16:17] offset:3200
	global_load_dwordx4 v[136:139], v[220:221], off offset:3264
	s_waitcnt vmcnt(15)
	v_pk_add_f32 v[232:233], v[232:233], v[158:159]
	v_pk_add_f32 v[234:235], v[234:235], v[156:157]
	s_waitcnt vmcnt(14)
	v_pk_add_f32 v[232:233], v[232:233], v[162:163]
	global_load_dwordx4 v[156:159], v[220:221], off offset:128
	v_pk_add_f32 v[234:235], v[234:235], v[160:161]
	s_waitcnt vmcnt(14)
	v_pk_add_f32 v[232:233], v[232:233], v[174:175]
	v_pk_add_f32 v[234:235], v[234:235], v[172:173]
	global_load_dwordx4 v[172:175], v[220:221], off offset:2176
	s_waitcnt vmcnt(14)
	v_pk_add_f32 v[240:241], v[232:233], v[178:179]
	global_load_dwordx4 v[116:119], v[218:219], off offset:192
	global_load_dwordx4 v[120:123], v[218:219], off offset:1216
	global_load_dwordx4 v[160:163], v[220:221], off offset:1152
	v_pk_add_f32 v[250:251], v[234:235], v[176:177]
	global_load_dwordx4 v[176:179], v[218:219], off offset:64
	global_load_dwordx4 v[232:235], v[218:219], off offset:1088
	global_load_dwordx4 v[236:239], v[220:221], off offset:3200
	s_waitcnt vmcnt(18)
	v_pk_add_f32 v[252:253], v[240:241], v[182:183]
	global_load_dwordx4 v[240:243], v[218:219], off offset:2112
	v_pk_add_f32 v[250:251], v[250:251], v[180:181]
	global_load_dwordx4 v[180:183], v[218:219], off offset:3136
	v_pk_add_f32 v[246:247], v[246:247], 1.0 op_sel_hi:[1,0] neg_lo:[1,0] neg_hi:[1,0]
	v_pk_mul_f32 v[244:245], v[244:245], 0.5 op_sel_hi:[1,0]
	v_pk_add_f32 v[246:247], v[246:247], 1.0 op_sel_hi:[1,0]
	v_mfma_f32_16x16x32_bf16 v[92:95], v[52:55], v[100:103], v[92:95]
	v_mul_f32_e64 v224, v244, v246
	v_mul_f32_e64 v225, v245, v247
	global_load_dwordx4 v[244:247], v[218:219], off offset:3200
	s_waitcnt vmcnt(20)
	v_pk_add_f32 v[144:145], v[250:251], v[144:145]
	s_waitcnt vmcnt(19)
	v_pk_add_f32 v[144:145], v[144:145], v[152:153]
	v_pk_add_f32 v[146:147], v[252:253], v[146:147]
	v_mfma_f32_16x16x32_bf16 v[84:87], v[48:51], v[100:103], v[84:87]
	v_add_f32_e64 v146, v146, v154
	v_add_f32_e64 v147, v147, v155
	s_waitcnt vmcnt(18)
	v_pk_add_f32 v[144:145], v[144:145], v[164:165]
	s_waitcnt vmcnt(17)
	v_pk_add_f32 v[152:153], v[144:145], v[168:169]
	v_pk_add_f32 v[146:147], v[146:147], v[166:167]
	global_load_dwordx4 v[166:169], v[218:219], off offset:2176
	v_pk_add_f32 v[170:171], v[146:147], v[170:171]
	global_load_dwordx4 v[144:147], v[218:219], off offset:128
	v_mfma_f32_16x16x32_bf16 v[80:83], v[44:47], v[100:103], v[80:83]
	s_waitcnt vmcnt(7)
	v_pk_add_f32 v[164:165], v[152:153], v[176:177]
	s_waitcnt vmcnt(6)
	v_pk_add_f32 v[164:165], v[164:165], v[232:233]
	v_pk_add_f32 v[170:171], v[170:171], v[178:179]
	global_load_dwordx4 v[152:155], v[218:219], off offset:1152
	s_waitcnt vmcnt(5)
; DI unsigned pack2(float a, float b) { v2f f = {a, b}; return __builtin_bit_cast(unsigned, __builtin_convertvector(f, v2bf)); }
; DI float fexp(float x) { return __builtin_amdgcn_exp2f(x * LOG2E); }
;   DI u32x2 pack(int, int, float a, float b, float c, float d, float&) const { u32x2 v; v.x = pack2(a, b); v.y = pack2(c, d); return v; }
; DI float gelu_tanh(float x) {
;   float u = 0.7978845608028654f * (x + 0.044715f * x * x * x);
;   float t = 1.f - 2.f / (fexp(2.f * u) + 1.f);
;   return 0.5f * x * (1.f + t);
; }
;   DI u32x2 pack(int m, int n, float a, float b, float c, float d, float& ss) const {
;     f32x4 bs = {0.f, 0.f, 0.f, 0.f};
; #pragma unroll
;     for (int kc = 0; kc < 16; ++kc) bs += *(const f32x4*)(bias_part + kc * 256 + n);
;     u32x2 v; v.x = pack2(gelu_tanh(a + bs[0]), gelu_tanh(b + bs[1])); v.y = pack2(gelu_tanh(c + bs[2]), gelu_tanh(d + bs[3]));
;     return v;
;   }
	v_pk_add_f32 v[164:165], v[164:165], v[240:241]
	v_pk_add_f32 v[170:171], v[170:171], v[234:235]
	s_waitcnt vmcnt(4)
	v_pk_add_f32 v[164:165], v[164:165], v[180:181]
	v_pk_add_f32 v[170:171], v[170:171], v[242:243]
	v_pk_add_f32 v[250:251], v[104:105], v[164:165]
	v_pk_add_f32 v[170:171], v[170:171], v[182:183]
	v_mul_f32_e32 v104, 0x3d372713, v250
	v_mul_f32_e32 v105, 0x3d372713, v251
	v_mul_f32_e32 v104, v250, v104
	v_mul_f32_e32 v105, v251, v105
	v_fma_f32 v104, v250, v104, v250
	v_fma_f32 v105, v251, v105, v251
	v_mul_f32_e32 v104, 0x3f4c422a, v104
	v_mul_f32_e32 v105, 0x3f4c422a, v105
	v_add_f32_e32 v104, v104, v104
	v_add_f32_e32 v105, v105, v105
	v_mul_f32_e32 v104, 0x3fb8aa3b, v104
	v_mul_f32_e32 v105, 0x3fb8aa3b, v105
	v_exp_f32_e32 v104, v104
	v_exp_f32_e32 v105, v105
	v_pk_add_f32 v[170:171], v[106:107], v[170:171]
	v_or_b32_e32 v164, s34, v227
	global_load_dwordx4 v[180:183], v[216:217], off offset:1152
	v_pk_add_f32 v[104:105], v[104:105], 1.0 op_sel_hi:[1,0]
	global_load_dwordx4 v[232:235], v[216:217], off offset:2176
	v_div_scale_f32 v165, s[0:1], v105, v105, 2.0
	v_rcp_f32_e32 v176, v165
	global_load_dwordx4 v[240:243], v[216:217], off offset:3200
	v_lshl_add_u32 v164, v254, 6, v164
	v_mfma_f32_16x16x32_bf16 v[92:95], v[32:35], v[96:99], v[92:95]
	v_fma_f32 v106, -v165, v176, 1.0
	v_fmac_f32_e32 v176, v106, v176
	v_div_scale_f32 v106, vcc, 2.0, v105, 2.0
	v_mul_f32_e32 v107, v106, v176
	v_fma_f32 v177, -v165, v107, v106
	v_fmac_f32_e32 v107, v177, v176
	v_fma_f32 v106, -v165, v107, v106
	v_div_scale_f32 v165, s[0:1], v104, v104, 2.0
	v_rcp_f32_e32 v227, v165
	v_div_fmas_f32 v106, v106, v176, v107
	v_div_fixup_f32 v107, v106, v105, 2.0
	v_mfma_f32_16x16x32_bf16 v[68:71], v[52:55], v[76:79], v[68:71]
	v_fma_f32 v105, -v165, v227, 1.0
	v_fmac_f32_e32 v227, v105, v227
	v_div_scale_f32 v105, vcc, 2.0, v104, 2.0
	v_mul_f32_e32 v106, v105, v227
	v_fma_f32 v176, -v165, v106, v105
	v_fmac_f32_e32 v106, v176, v227
	global_load_dwordx4 v[176:179], v[216:217], off offset:128
	v_fma_f32 v105, -v165, v106, v105
	v_div_fmas_f32 v105, v105, v227, v106
	v_div_fixup_f32 v106, v105, v104, 2.0
	v_mul_f32_e32 v104, 0x3d372713, v170
	v_mul_f32_e32 v104, v170, v104
	v_fma_f32 v104, v170, v104, v170
	v_mul_f32_e32 v104, 0x3f4c422a, v104
	v_add_f32_e32 v104, v104, v104
	v_mul_f32_e32 v104, 0x3fb8aa3b, v104
	v_exp_f32_e32 v252, v104
	v_mul_f32_e32 v104, 0x3d372713, v171
	v_mul_f32_e32 v104, v171, v104
	v_fma_f32 v104, v171, v104, v171
	v_mul_f32_e32 v104, 0x3f4c422a, v104
	v_add_f32_e32 v104, v104, v104
	v_mul_f32_e32 v104, 0x3fb8aa3b, v104
	v_exp_f32_e32 v253, v104
	v_cvt_pk_bf16_f32 v104, v248, v249
	v_pk_add_f32 v[106:107], v[106:107], 1.0 op_sel_hi:[1,0] neg_lo:[1,0] neg_hi:[1,0]
	v_cvt_pk_bf16_f32 v105, v224, v225
	v_pk_add_f32 v[248:249], v[252:253], 1.0 op_sel_hi:[1,0]
	v_pk_mul_f32 v[224:225], v[250:251], 0.5 op_sel_hi:[1,0]
	v_div_scale_f32 v165, s[0:1], v249, v249, 2.0
	v_rcp_f32_e32 v227, v165
	v_pk_add_f32 v[106:107], v[106:107], 1.0 op_sel_hi:[1,0]
	v_div_scale_f32 v250, s[0:1], v248, v248, 2.0
	v_pk_mul_f32 v[106:107], v[224:225], v[106:107]
	v_rcp_f32_e32 v251, v250
	v_cvt_pk_bf16_f32 v106, v106, v107
	v_fma_f32 v107, -v165, v227, 1.0
	v_fmac_f32_e32 v227, v107, v227
	v_div_scale_f32 v107, vcc, 2.0, v249, 2.0
	v_mul_f32_e32 v224, v107, v227
	v_fma_f32 v225, -v165, v224, v107
	v_fmac_f32_e32 v224, v225, v227
	v_fma_f32 v107, -v165, v224, v107
	v_fma_f32 v165, -v250, v251, 1.0
	v_div_fmas_f32 v107, v107, v227, v224
	v_fmac_f32_e32 v251, v165, v251
	v_div_scale_f32 v165, vcc, 2.0, v248, 2.0
	v_mul_f32_e32 v224, v165, v251
	v_fma_f32 v225, -v250, v224, v165
	v_fmac_f32_e32 v224, v225, v251
	v_div_fixup_f32 v225, v107, v249, 2.0
	v_fma_f32 v107, -v250, v224, v165
	v_div_fmas_f32 v107, v107, v251, v224
	v_div_fixup_f32 v224, v107, v248, 2.0
	v_pk_add_f32 v[224:225], v[224:225], 1.0 op_sel_hi:[1,0] neg_lo:[1,0] neg_hi:[1,0]
	v_pk_mul_f32 v[170:171], v[170:171], 0.5 op_sel_hi:[1,0]
	v_pk_add_f32 v[224:225], v[224:225], 1.0 op_sel_hi:[1,0]
	v_ashrrev_i32_e32 v165, 31, v164
	v_pk_mul_f32 v[170:171], v[170:171], v[224:225]
	v_pk_add_f32 v[224:225], v[228:229], 0 op_sel_hi:[1,0]
	v_cvt_pk_bf16_f32 v107, v170, v171
	v_pk_add_f32 v[170:171], v[230:231], 0 op_sel_hi:[1,0]
	v_pk_add_f32 v[128:129], v[224:225], v[128:129]
	v_pk_add_f32 v[130:131], v[170:171], v[130:131]
	v_pk_add_f32 v[128:129], v[128:129], v[140:141]
	v_pk_add_f32 v[130:131], v[130:131], v[142:143]
	v_pk_add_f32 v[128:129], v[128:129], v[148:149]
	v_pk_add_f32 v[130:131], v[130:131], v[150:151]
	v_pk_add_f32 v[128:129], v[128:129], v[156:157]
	v_pk_add_f32 v[130:131], v[130:131], v[158:159]
	v_pk_add_f32 v[128:129], v[128:129], v[160:161]
	v_pk_add_f32 v[130:131], v[130:131], v[162:163]
	v_pk_add_f32 v[128:129], v[128:129], v[172:173]
	v_pk_add_f32 v[130:131], v[130:131], v[174:175]
	v_pk_add_f32 v[142:143], v[128:129], v[236:237]
	v_pk_add_f32 v[140:141], v[130:131], v[238:239]
	global_load_dwordx4 v[128:131], v[216:217], off offset:192
	v_permlane16_swap_b32_e32 v104, v106
	v_permlane16_swap_b32_e32 v105, v107
	v_mfma_f32_16x16x32_bf16 v[170:173], v[40:43], v[100:103], v[88:91]
	s_waitcnt vmcnt(1)
; DI unsigned pack2(float a, float b) { v2f f = {a, b}; return __builtin_bit_cast(unsigned, __builtin_convertvector(f, v2bf)); }
; DI float fexp(float x) { return __builtin_amdgcn_exp2f(x * LOG2E); }
;   DI u32x2 pack(int, int, float a, float b, float c, float d, float&) const { u32x2 v; v.x = pack2(a, b); v.y = pack2(c, d); return v; }
; DI float gelu_tanh(float x) {
;   float u = 0.7978845608028654f * (x + 0.044715f * x * x * x);
;   float t = 1.f - 2.f / (fexp(2.f * u) + 1.f);
;   return 0.5f * x * (1.f + t);
; }
;   DI u32x2 pack(int m, int n, float a, float b, float c, float d, float& ss) const {
;     f32x4 bs = {0.f, 0.f, 0.f, 0.f};
; #pragma unroll
;     for (int kc = 0; kc < 16; ++kc) bs += *(const f32x4*)(bias_part + kc * 256 + n);
;     u32x2 v; v.x = pack2(gelu_tanh(a + bs[0]), gelu_tanh(b + bs[1])); v.y = pack2(gelu_tanh(c + bs[2]), gelu_tanh(d + bs[3]));
;     return v;
;   }
	v_pk_add_f32 v[150:151], v[142:143], v[176:177]
	v_pk_add_f32 v[148:149], v[140:141], v[178:179]
	global_load_dwordx4 v[140:143], v[216:217], off offset:1216
	v_pk_add_f32 v[158:159], v[150:151], v[180:181]
	v_pk_add_f32 v[156:157], v[148:149], v[182:183]
	global_load_dwordx4 v[148:151], v[216:217], off offset:2240
	v_pk_add_f32 v[162:163], v[158:159], v[232:233]
	v_pk_add_f32 v[160:161], v[156:157], v[234:235]
	global_load_dwordx4 v[156:159], v[216:217], off offset:3264
	v_pk_add_f32 v[162:163], v[162:163], v[240:241]
	v_pk_add_f32 v[160:161], v[160:161], v[242:243]
	v_pk_add_f32 v[144:145], v[162:163], v[144:145]
	v_pk_add_f32 v[146:147], v[160:161], v[146:147]
	v_pk_add_f32 v[144:145], v[144:145], v[152:153]
	v_pk_add_f32 v[146:147], v[146:147], v[154:155]
	v_pk_add_f32 v[144:145], v[144:145], v[166:167]
	v_pk_add_f32 v[146:147], v[146:147], v[168:169]
	v_pk_add_f32 v[144:145], v[144:145], v[244:245]
	v_pk_add_f32 v[146:147], v[146:147], v[246:247]
	v_pk_add_f32 v[144:145], v[208:209], v[144:145]
	v_pk_add_f32 v[146:147], v[210:211], v[146:147]
	v_mul_f32_e32 v152, 0x3d372713, v144
	v_mul_f32_e32 v153, 0x3d372713, v145
	v_mul_f32_e32 v152, v144, v152
	v_mul_f32_e32 v153, v145, v153
	v_fma_f32 v152, v144, v152, v144
	v_fma_f32 v153, v145, v153, v145
	v_mul_f32_e32 v152, 0x3f4c422a, v152
	v_mul_f32_e32 v153, 0x3f4c422a, v153
	v_add_f32_e32 v152, v152, v152
	v_add_f32_e32 v153, v153, v153
	v_mul_f32_e32 v152, 0x3fb8aa3b, v152
	v_mul_f32_e32 v153, 0x3fb8aa3b, v153
	v_exp_f32_e32 v152, v152
	v_exp_f32_e32 v153, v153
	v_pk_mul_f32 v[144:145], v[144:145], 0.5 op_sel_hi:[1,0]
	v_mov_b32_e32 v167, v213
	v_mov_b32_e32 v169, v213
	v_pk_add_f32 v[152:153], v[152:153], 1.0 op_sel_hi:[1,0]
	v_mfma_f32_16x16x32_bf16 v[88:91], v[28:31], v[96:99], v[84:87]
	v_div_scale_f32 v154, s[0:1], v153, v153, 2.0
	v_rcp_f32_e32 v155, v154
	v_mfma_f32_16x16x32_bf16 v[84:87], v[24:27], v[96:99], v[80:83]
	v_fma_f32 v160, -v154, v155, 1.0
	v_fmac_f32_e32 v155, v160, v155
	v_div_scale_f32 v160, vcc, 2.0, v153, 2.0
	v_mul_f32_e32 v161, v160, v155
	v_fma_f32 v162, -v154, v161, v160
	v_fmac_f32_e32 v161, v162, v155
	v_fma_f32 v154, -v154, v161, v160
	v_div_scale_f32 v160, s[0:1], v152, v152, 2.0
	v_rcp_f32_e32 v162, v160
	v_div_fmas_f32 v154, v154, v155, v161
	v_div_fixup_f32 v153, v154, v153, 2.0
	v_mfma_f32_16x16x32_bf16 v[80:83], v[20:23], v[96:99], v[170:173]
	v_fma_f32 v154, -v160, v162, 1.0
	v_fmac_f32_e32 v162, v154, v162
	v_div_scale_f32 v154, vcc, 2.0, v152, 2.0
	v_mul_f32_e32 v155, v154, v162
	v_fma_f32 v161, -v160, v155, v154
	v_fmac_f32_e32 v155, v161, v162
	v_fma_f32 v154, -v160, v155, v154
	v_div_fmas_f32 v160, v154, v162, v155
	v_mul_f32_e32 v154, 0x3d372713, v146
	v_mul_f32_e32 v155, 0x3d372713, v147
	v_mul_f32_e32 v154, v146, v154
	v_mul_f32_e32 v155, v147, v155
	v_fma_f32 v154, v146, v154, v146
	v_fma_f32 v155, v147, v155, v147
	v_mul_f32_e32 v154, 0x3f4c422a, v154
	v_mul_f32_e32 v155, 0x3f4c422a, v155
	v_add_f32_e32 v154, v154, v154
	v_add_f32_e32 v155, v155, v155
	v_mul_f32_e32 v154, 0x3fb8aa3b, v154
	v_mul_f32_e32 v155, 0x3fb8aa3b, v155
	v_exp_f32_e32 v154, v154
	v_exp_f32_e32 v155, v155
	v_div_fixup_f32 v152, v160, v152, 2.0
	v_pk_add_f32 v[152:153], v[152:153], 1.0 op_sel_hi:[1,0] neg_lo:[1,0] neg_hi:[1,0]
	v_pk_mul_f32 v[146:147], v[146:147], 0.5 op_sel_hi:[1,0]
	v_pk_add_f32 v[154:155], v[154:155], 1.0 op_sel_hi:[1,0]
	v_pk_add_f32 v[152:153], v[152:153], 1.0 op_sel_hi:[1,0]
	v_div_scale_f32 v160, s[0:1], v155, v155, 2.0
	v_rcp_f32_e32 v161, v160
	v_pk_mul_f32 v[144:145], v[144:145], v[152:153]
	v_mfma_f32_16x16x32_bf16 v[60:63], v[48:51], v[76:79], v[60:63]
	v_cvt_pk_bf16_f32 v144, v144, v145
	v_fma_f32 v145, -v160, v161, 1.0
	v_fmac_f32_e32 v161, v145, v161
	v_div_scale_f32 v145, vcc, 2.0, v155, 2.0
	v_mul_f32_e32 v152, v145, v161
	v_fma_f32 v153, -v160, v152, v145
	v_fmac_f32_e32 v152, v153, v161
	v_fma_f32 v145, -v160, v152, v145
	v_div_scale_f32 v160, s[0:1], v154, v154, 2.0
	v_rcp_f32_e32 v162, v160
	v_div_fmas_f32 v145, v145, v161, v152
	v_div_fixup_f32 v153, v145, v155, 2.0
	v_mfma_f32_16x16x32_bf16 v[56:59], v[44:47], v[76:79], v[56:59]
	v_fma_f32 v145, -v160, v162, 1.0
	v_fmac_f32_e32 v162, v145, v162
	v_div_scale_f32 v145, vcc, 2.0, v154, 2.0
	v_mul_f32_e32 v152, v145, v162
	v_fma_f32 v155, -v160, v152, v145
	v_fmac_f32_e32 v152, v155, v162
	v_fma_f32 v145, -v160, v152, v145
	v_div_fmas_f32 v145, v145, v162, v152
	v_div_fixup_f32 v152, v145, v154, 2.0
	v_pk_add_f32 v[152:153], v[152:153], 1.0 op_sel_hi:[1,0] neg_lo:[1,0] neg_hi:[1,0]
	v_mfma_f32_16x16x32_bf16 v[68:71], v[32:35], v[72:75], v[68:71]
	v_add_f32_e64 v152, v152, 1.0
	v_add_f32_e64 v153, v153, 1.0
	v_pk_mul_f32 v[146:147], v[146:147], v[152:153]
	v_pk_add_f32 v[152:153], v[188:189], 0 op_sel_hi:[1,0]
	v_cvt_pk_bf16_f32 v145, v146, v147
	v_pk_add_f32 v[152:153], v[152:153], v[192:193]
	v_pk_add_f32 v[146:147], v[190:191], 0 op_sel_hi:[1,0]
	v_pk_add_f32 v[152:153], v[152:153], v[196:197]
	v_pk_add_f32 v[146:147], v[146:147], v[194:195]
	v_pk_add_f32 v[152:153], v[152:153], v[184:185]
	v_pk_add_f32 v[146:147], v[146:147], v[198:199]
	v_pk_add_f32 v[152:153], v[152:153], v[200:201]
	v_pk_add_f32 v[146:147], v[146:147], v[186:187]
	v_pk_add_f32 v[124:125], v[152:153], v[124:125]
	v_pk_add_f32 v[146:147], v[146:147], v[202:203]
	v_pk_add_f32 v[124:125], v[124:125], v[132:133]
	v_pk_add_f32 v[126:127], v[146:147], v[126:127]
	v_pk_add_f32 v[124:125], v[124:125], v[136:137]
	v_pk_add_f32 v[126:127], v[126:127], v[134:135]
	s_waitcnt vmcnt(3)
	v_pk_add_f32 v[124:125], v[124:125], v[128:129]
	v_pk_add_f32 v[126:127], v[126:127], v[138:139]
	s_waitcnt vmcnt(2)
; DI unsigned pack2(float a, float b) { v2f f = {a, b}; return __builtin_bit_cast(unsigned, __builtin_convertvector(f, v2bf)); }
;   DI u32x2 pack(int, int, float a, float b, float c, float d, float&) const { u32x2 v; v.x = pack2(a, b); v.y = pack2(c, d); return v; }
; template <class ARow, class Epi>
; DI void gemm_tile(const ARow& arow, long a_kstride, const u16* __restrict__ Bt, long ldb, int K, int m0, int n0,
;                   const Epi& epi, char* smem) {
;     ...
;       for (int ni = 0; ni < 4; ++ni) pk[ni] = epi.pack(m, nh + ni * 16 + fq * 4, acc[ni][mi][0], acc[ni][mi][1], acc[ni][mi][2], acc[ni][mi][3], ss);
;       epi.finish16(m, nh, ss);
;       u16* rp = epi.rowp(m) + nh;
; #pragma unroll
;       for (int pp = 0; pp < 2; ++pp) {
;         u32x2 a = pk[2 * pp], b = pk[2 * pp + 1];
;         const u32x2 rx = __builtin_amdgcn_permlane16_swap(a.x, b.x, false, false);
;         const u32x2 ry = __builtin_amdgcn_permlane16_swap(a.y, b.y, false, false);
;         const int nst = (fq & 1) ? ((2 * pp + 1) * 16 + (fq - 1) * 4) : ((2 * pp) * 16 + fq * 4);
;         *(u32x4*)(rp + nst) = (u32x4){rx[0], ry[0], rx[1], ry[1]};
;   DI u32x2 pack(int m, int n, float a, float b, float c, float d, float& ss) const {
;     f32x4 bs = {0.f, 0.f, 0.f, 0.f};
; #pragma unroll
;     for (int kc = 0; kc < 16; ++kc) bs += *(const f32x4*)(bias_part + kc * 256 + n);
;     u32x2 v; v.x = pack2(gelu_tanh(a + bs[0]), gelu_tanh(b + bs[1])); v.y = pack2(gelu_tanh(c + bs[2]), gelu_tanh(d + bs[3]));
;     return v;
;   }
	v_pk_add_f32 v[124:125], v[124:125], v[140:141]
	v_pk_add_f32 v[126:127], v[126:127], v[130:131]
	s_waitcnt vmcnt(1)
	v_pk_add_f32 v[124:125], v[124:125], v[148:149]
	v_pk_add_f32 v[126:127], v[126:127], v[142:143]
	s_waitcnt vmcnt(0)
	v_pk_add_f32 v[124:125], v[124:125], v[156:157]
	v_pk_add_f32 v[126:127], v[126:127], v[150:151]
	v_pk_add_f32 v[116:117], v[124:125], v[116:117]
	v_mfma_f32_16x16x32_bf16 v[12:15], v[52:55], v[36:39], v[12:15]
	v_add_f32_e64 v116, v116, v120
	v_add_f32_e64 v117, v117, v121
	v_pk_add_f32 v[112:113], v[116:117], v[112:113]
	v_pk_add_f32 v[116:117], v[126:127], v[158:159]
	v_pk_add_f32 v[112:113], v[112:113], v[204:205]
	v_pk_add_f32 v[116:117], v[116:117], v[118:119]
	v_pk_add_f32 v[108:109], v[108:109], v[112:113]
	v_pk_add_f32 v[116:117], v[116:117], v[122:123]
	v_mul_f32_e32 v112, 0x3d372713, v108
	v_mul_f32_e32 v113, 0x3d372713, v109
	v_mul_f32_e32 v112, v108, v112
	v_mul_f32_e32 v113, v109, v113
	v_fma_f32 v112, v108, v112, v108
	v_fma_f32 v113, v109, v113, v109
	v_mul_f32_e32 v112, 0x3f4c422a, v112
	v_mul_f32_e32 v113, 0x3f4c422a, v113
	v_add_f32_e32 v112, v112, v112
	v_add_f32_e32 v113, v113, v113
	v_mul_f32_e32 v112, 0x3fb8aa3b, v112
	v_mul_f32_e32 v113, 0x3fb8aa3b, v113
	v_exp_f32_e32 v112, v112
	v_exp_f32_e32 v113, v113
	v_pk_add_f32 v[114:115], v[116:117], v[114:115]
	v_pk_mul_f32 v[108:109], v[108:109], 0.5 op_sel_hi:[1,0]
	v_pk_add_f32 v[114:115], v[114:115], v[206:207]
	v_pk_add_f32 v[112:113], v[112:113], 1.0 op_sel_hi:[1,0]
	v_pk_add_f32 v[110:111], v[110:111], v[114:115]
	v_div_scale_f32 v118, s[0:1], v113, v113, 2.0
	v_rcp_f32_e32 v119, v118
	v_mfma_f32_16x16x32_bf16 v[4:7], v[48:51], v[36:39], v[4:7]
	v_fma_f32 v114, -v118, v119, 1.0
	v_fmac_f32_e32 v119, v114, v119
	v_div_scale_f32 v114, vcc, 2.0, v113, 2.0
	v_mul_f32_e32 v115, v114, v119
	v_fma_f32 v116, -v118, v115, v114
	v_fmac_f32_e32 v115, v116, v119
	v_div_scale_f32 v116, s[0:1], v112, v112, 2.0
	v_rcp_f32_e32 v117, v116
	v_fma_f32 v114, -v118, v115, v114
	v_div_fmas_f32 v114, v114, v119, v115
	v_div_fixup_f32 v113, v114, v113, 2.0
	v_fma_f32 v114, -v116, v117, 1.0
	v_fmac_f32_e32 v117, v114, v117
	v_div_scale_f32 v114, vcc, 2.0, v112, 2.0
	v_mul_f32_e32 v115, v114, v117
	v_fma_f32 v118, -v116, v115, v114
	v_fmac_f32_e32 v115, v118, v117
	v_fma_f32 v114, -v116, v115, v114
	v_div_fmas_f32 v116, v114, v117, v115
	v_mul_f32_e32 v114, 0x3d372713, v110
	v_mul_f32_e32 v115, 0x3d372713, v111
	v_mul_f32_e32 v114, v110, v114
	v_mul_f32_e32 v115, v111, v115
	v_fma_f32 v114, v110, v114, v110
	v_fma_f32 v115, v111, v115, v111
	v_mul_f32_e32 v114, 0x3f4c422a, v114
	v_mul_f32_e32 v115, 0x3f4c422a, v115
	v_add_f32_e32 v114, v114, v114
	v_add_f32_e32 v115, v115, v115
	v_mul_f32_e32 v114, 0x3fb8aa3b, v114
	v_mul_f32_e32 v115, 0x3fb8aa3b, v115
	v_exp_f32_e32 v114, v114
	v_exp_f32_e32 v115, v115
	v_div_fixup_f32 v112, v116, v112, 2.0
	v_pk_add_f32 v[112:113], v[112:113], 1.0 op_sel_hi:[1,0] neg_lo:[1,0] neg_hi:[1,0]
	v_pk_mul_f32 v[110:111], v[110:111], 0.5 op_sel_hi:[1,0]
	v_pk_add_f32 v[114:115], v[114:115], 1.0 op_sel_hi:[1,0]
	v_pk_add_f32 v[112:113], v[112:113], 1.0 op_sel_hi:[1,0]
	v_div_scale_f32 v116, s[0:1], v115, v115, 2.0
	v_rcp_f32_e32 v117, v116
	v_pk_mul_f32 v[108:109], v[108:109], v[112:113]
	v_mfma_f32_16x16x32_bf16 v[0:3], v[44:47], v[36:39], v[0:3]
	v_cvt_pk_bf16_f32 v146, v108, v109
	v_fma_f32 v108, -v116, v117, 1.0
	v_fmac_f32_e32 v117, v108, v117
	v_div_scale_f32 v108, vcc, 2.0, v115, 2.0
	v_mul_f32_e32 v109, v108, v117
	v_fma_f32 v112, -v116, v109, v108
	v_fmac_f32_e32 v109, v112, v117
	v_div_scale_f32 v112, s[0:1], v114, v114, 2.0
	v_rcp_f32_e32 v113, v112
	v_fma_f32 v108, -v116, v109, v108
	v_div_fmas_f32 v108, v108, v117, v109
	v_div_fixup_f32 v109, v108, v115, 2.0
	v_fma_f32 v108, -v112, v113, 1.0
	v_fmac_f32_e32 v113, v108, v113
	v_div_scale_f32 v108, vcc, 2.0, v114, 2.0
	v_mul_f32_e32 v115, v108, v113
	v_fma_f32 v116, -v112, v115, v108
	v_fmac_f32_e32 v115, v116, v113
	v_fma_f32 v108, -v112, v115, v108
	v_div_fmas_f32 v108, v108, v113, v115
	v_div_fixup_f32 v108, v108, v114, 2.0
	v_pk_add_f32 v[108:109], v[108:109], 1.0 op_sel_hi:[1,0] neg_lo:[1,0] neg_hi:[1,0]
	v_cmp_eq_u32_e32 vcc, 0, v223
	v_pk_add_f32 v[108:109], v[108:109], 1.0 op_sel_hi:[1,0]
	v_permlane16_swap_b32_e32 v144, v146
	v_pk_mul_f32 v[108:109], v[110:111], v[108:109]
	v_add_u32_e32 v110, 12, v226
	v_cvt_pk_bf16_f32 v147, v108, v109
	v_lshlrev_b64 v[108:109], 9, v[164:165]
	v_cndmask_b32_e32 v110, v110, v226, vcc
	v_lshl_add_u64 v[108:109], v[214:215], 0, v[108:109]
	v_lshlrev_b32_e32 v166, 1, v110
	v_lshl_add_u64 v[110:111], v[108:109], 0, v[166:167]
	global_store_dwordx4 v[110:111], v[104:107], off sc0 sc1
	v_permlane16_swap_b32_e32 v145, v147
	s_nop 0
	v_add_u32_e32 v104, 44, v226
	v_or_b32_e32 v105, 32, v226
	v_cndmask_b32_e32 v104, v104, v105, vcc
	v_lshlrev_b32_e32 v168, 1, v104
	v_lshl_add_u64 v[104:105], v[108:109], 0, v[168:169]
	global_store_dwordx4 v[104:105], v[144:147], off sc0 sc1
	global_load_dwordx4 v[144:147], v212, s[16:17]
	s_nop 0
	global_load_dwordx4 v[148:151], v212, s[16:17] offset:1024
	global_load_dwordx4 v[152:155], v212, s[16:17] offset:2048
	global_load_dwordx4 v[156:159], v212, s[16:17] offset:3072
	global_load_dwordx4 v[160:163], v[216:217], off offset:-4096
	global_load_dwordx4 v[136:139], v[220:221], off offset:1024
	global_load_dwordx4 v[128:131], v[220:221], off offset:2048
	global_load_dwordx4 v[124:127], v[220:221], off offset:3072
	global_load_dwordx4 v[116:119], v[218:219], off offset:-4096
	global_load_dwordx4 v[132:135], v[216:217], off offset:1024
	global_load_dwordx4 v[140:143], v[216:217], off offset:2048
	global_load_dwordx4 v[100:103], v[216:217], off offset:3072
	global_load_dwordx4 v[104:107], v[218:219], off
	global_load_dwordx4 v[108:111], v[218:219], off offset:1024
	global_load_dwordx4 v[112:115], v[218:219], off offset:2048
	global_load_dwordx4 v[120:123], v[218:219], off offset:3072
	global_load_dwordx4 v[182:185], v[218:219], off offset:3136
	global_load_dwordx4 v[96:99], v212, s[16:17] offset:64
	global_load_dwordx4 v[174:177], v[218:219], off offset:1088
	global_load_dwordx4 v[178:181], v[218:219], off offset:2112
	v_mfma_f32_16x16x32_bf16 v[12:15], v[32:35], v[16:19], v[12:15]
	s_waitcnt vmcnt(19)
; DI unsigned pack2(float a, float b) { v2f f = {a, b}; return __builtin_bit_cast(unsigned, __builtin_convertvector(f, v2bf)); }
; DI float fexp(float x) { return __builtin_amdgcn_exp2f(x * LOG2E); }
;   DI u32x2 pack(int, int, float a, float b, float c, float d, float&) const { u32x2 v; v.x = pack2(a, b); v.y = pack2(c, d); return v; }
; DI float gelu_tanh(float x) {
;   float u = 0.7978845608028654f * (x + 0.044715f * x * x * x);
;   float t = 1.f - 2.f / (fexp(2.f * u) + 1.f);
;   return 0.5f * x * (1.f + t);
; }
;   DI u32x2 pack(int m, int n, float a, float b, float c, float d, float& ss) const {
;     f32x4 bs = {0.f, 0.f, 0.f, 0.f};
; #pragma unroll
;     for (int kc = 0; kc < 16; ++kc) bs += *(const f32x4*)(bias_part + kc * 256 + n);
;     u32x2 v; v.x = pack2(gelu_tanh(a + bs[0]), gelu_tanh(b + bs[1])); v.y = pack2(gelu_tanh(c + bs[2]), gelu_tanh(d + bs[3]));
;     return v;
;   }
	v_pk_add_f32 v[170:171], v[146:147], 0 op_sel_hi:[1,0]
	v_pk_add_f32 v[172:173], v[144:145], 0 op_sel_hi:[1,0]
	s_waitcnt vmcnt(18)
	v_pk_add_f32 v[170:171], v[170:171], v[150:151]
	v_pk_add_f32 v[172:173], v[172:173], v[148:149]
	s_waitcnt vmcnt(17)
	v_pk_add_f32 v[170:171], v[170:171], v[154:155]
	v_pk_add_f32 v[172:173], v[172:173], v[152:153]
	s_waitcnt vmcnt(16)
	v_pk_add_f32 v[170:171], v[170:171], v[158:159]
	v_pk_add_f32 v[172:173], v[172:173], v[156:157]
	s_waitcnt vmcnt(15)
	v_pk_add_f32 v[170:171], v[170:171], v[162:163]
	v_pk_add_f32 v[172:173], v[172:173], v[160:161]
	s_waitcnt vmcnt(14)
	v_pk_add_f32 v[170:171], v[170:171], v[138:139]
	v_pk_add_f32 v[172:173], v[172:173], v[136:137]
	s_waitcnt vmcnt(13)
	v_pk_add_f32 v[170:171], v[170:171], v[130:131]
	v_pk_add_f32 v[172:173], v[172:173], v[128:129]
	s_waitcnt vmcnt(12)
	v_pk_add_f32 v[170:171], v[170:171], v[126:127]
	v_pk_add_f32 v[172:173], v[172:173], v[124:125]
	s_waitcnt vmcnt(11)
	v_pk_add_f32 v[170:171], v[170:171], v[118:119]
	v_pk_add_f32 v[172:173], v[172:173], v[116:117]
	s_waitcnt vmcnt(10)
	v_pk_add_f32 v[170:171], v[170:171], v[134:135]
	v_pk_add_f32 v[172:173], v[172:173], v[132:133]
	s_waitcnt vmcnt(9)
	v_pk_add_f32 v[186:187], v[170:171], v[142:143]
	v_pk_add_f32 v[170:171], v[172:173], v[140:141]
	s_waitcnt vmcnt(8)
	v_pk_add_f32 v[102:103], v[186:187], v[102:103]
	v_pk_add_f32 v[100:101], v[170:171], v[100:101]
	s_waitcnt vmcnt(7)
	v_pk_add_f32 v[102:103], v[102:103], v[106:107]
	v_pk_add_f32 v[100:101], v[100:101], v[104:105]
	s_waitcnt vmcnt(6)
	v_pk_add_f32 v[102:103], v[102:103], v[110:111]
	v_pk_add_f32 v[100:101], v[100:101], v[108:109]
	global_load_dwordx4 v[144:147], v212, s[16:17] offset:1088
	s_waitcnt vmcnt(6)
	v_pk_add_f32 v[100:101], v[100:101], v[112:113]
	global_load_dwordx4 v[148:151], v212, s[16:17] offset:2112
	global_load_dwordx4 v[152:155], v212, s[16:17] offset:3136
	s_waitcnt vmcnt(7)
	v_pk_add_f32 v[100:101], v[100:101], v[120:121]
	global_load_dwordx4 v[136:139], v[220:221], off offset:1216
	v_pk_add_f32 v[92:93], v[92:93], v[100:101]
	global_load_dwordx4 v[156:159], v[216:217], off offset:64
	global_load_dwordx4 v[116:119], v[216:217], off offset:1088
	v_mul_f32_e32 v100, 0x3d372713, v92
	v_mul_f32_e32 v101, 0x3d372713, v93
	v_mul_f32_e32 v100, v92, v100
	v_mul_f32_e32 v101, v93, v101
	v_fma_f32 v100, v92, v100, v92
	v_fma_f32 v101, v93, v101, v93
	v_mul_f32_e32 v100, 0x3f4c422a, v100
	v_mul_f32_e32 v101, 0x3f4c422a, v101
	v_add_f32_e32 v100, v100, v100
	v_add_f32_e32 v101, v101, v101
	v_mul_f32_e32 v100, 0x3fb8aa3b, v100
	v_mul_f32_e32 v101, 0x3fb8aa3b, v101
	v_exp_f32_e32 v100, v100
	v_exp_f32_e32 v101, v101
	global_load_dwordx4 v[132:135], v[216:217], off offset:2112
	global_load_dwordx4 v[140:143], v[216:217], off offset:3136
	global_load_dwordx4 v[170:173], v[218:219], off offset:64
	v_pk_add_f32 v[120:121], v[100:101], 1.0 op_sel_hi:[1,0]
	v_pk_add_f32 v[100:101], v[102:103], v[114:115]
	v_div_scale_f32 v104, s[0:1], v121, v121, 2.0
	v_rcp_f32_e32 v105, v104
	v_pk_add_f32 v[100:101], v[100:101], v[122:123]
	v_div_scale_f32 v122, s[0:1], v120, v120, 2.0
	v_pk_add_f32 v[94:95], v[94:95], v[100:101]
	v_fma_f32 v100, -v104, v105, 1.0
	v_fmac_f32_e32 v105, v100, v105
	v_div_scale_f32 v100, vcc, 2.0, v121, 2.0
	v_mul_f32_e32 v106, v100, v105
	v_fma_f32 v101, -v104, v106, v100
	v_rcp_f32_e32 v123, v122
	v_fmac_f32_e32 v106, v101, v105
	v_fma_f32 v104, -v104, v106, v100
	global_load_dwordx4 v[100:103], v[220:221], off offset:64
	v_div_fmas_f32 v108, v104, v105, v106
	global_load_dwordx4 v[104:107], v[220:221], off offset:1088
	v_div_fixup_f32 v121, v108, v121, 2.0
	v_fma_f32 v112, -v122, v123, 1.0
	global_load_dwordx4 v[108:111], v[220:221], off offset:2112
	v_fmac_f32_e32 v123, v112, v123
	global_load_dwordx4 v[112:115], v[220:221], off offset:3136
	v_div_scale_f32 v165, vcc, 2.0, v120, 2.0
	v_mul_f32_e32 v186, v165, v123
	v_fma_f32 v187, -v122, v186, v165
	v_fmac_f32_e32 v186, v187, v123
	v_fma_f32 v122, -v122, v186, v165
	v_div_fmas_f32 v165, v122, v123, v186
	v_mul_f32_e32 v122, 0x3d372713, v94
	v_mul_f32_e32 v123, 0x3d372713, v95
	v_mul_f32_e32 v122, v94, v122
	v_mul_f32_e32 v123, v95, v123
	v_fma_f32 v122, v94, v122, v94
	v_fma_f32 v123, v95, v123, v95
	v_mul_f32_e32 v122, 0x3f4c422a, v122
	v_mul_f32_e32 v123, 0x3f4c422a, v123
	v_add_f32_e32 v122, v122, v122
	v_add_f32_e32 v123, v123, v123
	v_mul_f32_e32 v122, 0x3fb8aa3b, v122
	v_mul_f32_e32 v123, 0x3fb8aa3b, v123
	v_exp_f32_e32 v122, v122
	v_exp_f32_e32 v123, v123
	v_div_fixup_f32 v120, v165, v120, 2.0
	v_pk_add_f32 v[120:121], v[120:121], 1.0 op_sel_hi:[1,0] neg_lo:[1,0] neg_hi:[1,0]
	v_pk_mul_f32 v[92:93], v[92:93], 0.5 op_sel_hi:[1,0]
	v_pk_add_f32 v[122:123], v[122:123], 1.0 op_sel_hi:[1,0]
	v_pk_add_f32 v[120:121], v[120:121], 1.0 op_sel_hi:[1,0]
	v_div_scale_f32 v165, s[0:1], v123, v123, 2.0
	v_rcp_f32_e32 v186, v165
	v_pk_mul_f32 v[92:93], v[92:93], v[120:121]
	v_pk_mul_f32 v[94:95], v[94:95], 0.5 op_sel_hi:[1,0]
	v_cvt_pk_bf16_f32 v92, v92, v93
	v_fma_f32 v93, -v165, v186, 1.0
	v_fmac_f32_e32 v186, v93, v186
	v_div_scale_f32 v93, vcc, 2.0, v123, 2.0
	v_mul_f32_e32 v120, v93, v186
	v_fma_f32 v121, -v165, v120, v93
	v_fmac_f32_e32 v120, v121, v186
	v_fma_f32 v93, -v165, v120, v93
	v_div_scale_f32 v165, s[0:1], v122, v122, 2.0
	v_rcp_f32_e32 v187, v165
	v_div_fmas_f32 v93, v93, v186, v120
	v_div_fixup_f32 v121, v93, v123, 2.0
	s_waitcnt vmcnt(15)
; DI unsigned pack2(float a, float b) { v2f f = {a, b}; return __builtin_bit_cast(unsigned, __builtin_convertvector(f, v2bf)); }
; DI float fexp(float x) { return __builtin_amdgcn_exp2f(x * LOG2E); }
;   DI u32x2 pack(int, int, float a, float b, float c, float d, float&) const { u32x2 v; v.x = pack2(a, b); v.y = pack2(c, d); return v; }
; DI float gelu_tanh(float x) {
;   float u = 0.7978845608028654f * (x + 0.044715f * x * x * x);
;   float t = 1.f - 2.f / (fexp(2.f * u) + 1.f);
;   return 0.5f * x * (1.f + t);
; }
;   DI u32x2 pack(int m, int n, float a, float b, float c, float d, float& ss) const {
;     f32x4 bs = {0.f, 0.f, 0.f, 0.f};
; #pragma unroll
;     for (int kc = 0; kc < 16; ++kc) bs += *(const f32x4*)(bias_part + kc * 256 + n);
;     u32x2 v; v.x = pack2(gelu_tanh(a + bs[0]), gelu_tanh(b + bs[1])); v.y = pack2(gelu_tanh(c + bs[2]), gelu_tanh(d + bs[3]));
;     return v;
;   }
	v_pk_add_f32 v[96:97], v[96:97], 0 op_sel_hi:[1,0]
	v_fma_f32 v93, -v165, v187, 1.0
	v_fmac_f32_e32 v187, v93, v187
	v_div_scale_f32 v93, vcc, 2.0, v122, 2.0
	v_mul_f32_e32 v120, v93, v187
	v_fma_f32 v123, -v165, v120, v93
	v_fmac_f32_e32 v120, v123, v187
	v_fma_f32 v93, -v165, v120, v93
	v_div_fmas_f32 v93, v93, v187, v120
	v_div_fixup_f32 v120, v93, v122, 2.0
	v_pk_add_f32 v[120:121], v[120:121], 1.0 op_sel_hi:[1,0] neg_lo:[1,0] neg_hi:[1,0]
	s_waitcnt vmcnt(12)
	v_pk_add_f32 v[96:97], v[96:97], v[144:145]
	v_pk_add_f32 v[120:121], v[120:121], 1.0 op_sel_hi:[1,0]
	s_waitcnt vmcnt(11)
	v_pk_add_f32 v[96:97], v[96:97], v[148:149]
	v_pk_mul_f32 v[94:95], v[94:95], v[120:121]
	s_waitcnt vmcnt(10)
	v_pk_add_f32 v[120:121], v[96:97], v[152:153]
	v_cvt_pk_bf16_f32 v93, v94, v95
	v_pk_add_f32 v[94:95], v[98:99], 0 op_sel_hi:[1,0]
	global_load_dwordx4 v[96:99], v[220:221], off offset:128
	v_pk_add_f32 v[94:95], v[94:95], v[146:147]
	global_load_dwordx4 v[128:131], v[220:221], off offset:2240
	v_pk_add_f32 v[94:95], v[94:95], v[150:151]
	global_load_dwordx4 v[160:163], v[220:221], off offset:192
	v_pk_add_f32 v[94:95], v[94:95], v[154:155]
	global_load_dwordx4 v[124:127], v[220:221], off offset:3264
	s_waitcnt vmcnt(7)
	v_pk_add_f32 v[120:121], v[120:121], v[100:101]
	v_pk_add_f32 v[94:95], v[94:95], v[102:103]
	global_load_dwordx4 v[100:103], v[220:221], off offset:1152
	s_waitcnt vmcnt(7)
	v_pk_add_f32 v[120:121], v[120:121], v[104:105]
	v_pk_add_f32 v[94:95], v[94:95], v[106:107]
	s_waitcnt vmcnt(6)
	v_pk_add_f32 v[120:121], v[120:121], v[108:109]
	v_pk_add_f32 v[94:95], v[94:95], v[110:111]
	global_load_dwordx4 v[108:111], v[220:221], off offset:3200
	s_waitcnt vmcnt(6)
	v_pk_add_f32 v[112:113], v[120:121], v[112:113]
	v_pk_add_f32 v[94:95], v[94:95], v[114:115]
	v_pk_add_f32 v[112:113], v[112:113], v[156:157]
	v_pk_add_f32 v[94:95], v[94:95], v[158:159]
	v_pk_add_f32 v[112:113], v[112:113], v[116:117]
	v_pk_add_f32 v[94:95], v[94:95], v[118:119]
	v_pk_add_f32 v[112:113], v[112:113], v[132:133]
	v_pk_add_f32 v[94:95], v[94:95], v[134:135]
	v_pk_add_f32 v[112:113], v[112:113], v[140:141]
	v_pk_add_f32 v[94:95], v[94:95], v[142:143]
	v_pk_add_f32 v[112:113], v[112:113], v[170:171]
	v_pk_add_f32 v[94:95], v[94:95], v[172:173]
	v_pk_add_f32 v[112:113], v[112:113], v[174:175]
	global_load_dwordx4 v[170:173], v[218:219], off offset:2176
	v_pk_add_f32 v[112:113], v[112:113], v[178:179]
	v_pk_add_f32 v[94:95], v[94:95], v[176:177]
	v_pk_add_f32 v[112:113], v[112:113], v[182:183]
	global_load_dwordx4 v[116:119], v212, s[16:17] offset:2176
	v_pk_add_f32 v[178:179], v[88:89], v[112:113]
	global_load_dwordx4 v[120:123], v212, s[16:17] offset:3200
	v_mul_f32_e32 v88, 0x3d372713, v178
	v_mul_f32_e32 v89, 0x3d372713, v179
	v_mul_f32_e32 v88, v178, v88
	v_mul_f32_e32 v89, v179, v89
	v_fma_f32 v88, v178, v88, v178
	v_fma_f32 v89, v179, v89, v179
	v_mul_f32_e32 v88, 0x3f4c422a, v88
	v_mul_f32_e32 v89, 0x3f4c422a, v89
	v_add_f32_e32 v88, v88, v88
	v_add_f32_e32 v89, v89, v89
	v_mul_f32_e32 v88, 0x3fb8aa3b, v88
	v_mul_f32_e32 v89, 0x3fb8aa3b, v89
	v_exp_f32_e32 v88, v88
	v_exp_f32_e32 v89, v89
	global_load_dwordx4 v[104:107], v[220:221], off offset:2176
	global_load_dwordx4 v[174:177], v[218:219], off offset:3200
	v_pk_mul_f32 v[178:179], v[178:179], 0.5 op_sel_hi:[1,0]
	v_pk_add_f32 v[182:183], v[88:89], 1.0 op_sel_hi:[1,0]
	v_pk_add_f32 v[88:89], v[94:95], v[180:181]
	v_div_scale_f32 v112, s[0:1], v183, v183, 2.0
	v_rcp_f32_e32 v113, v112
	v_pk_add_f32 v[88:89], v[88:89], v[184:185]
	v_div_scale_f32 v132, s[0:1], v182, v182, 2.0
	v_pk_add_f32 v[180:181], v[90:91], v[88:89]
	v_fma_f32 v88, -v112, v113, 1.0
	v_fmac_f32_e32 v113, v88, v113
	v_div_scale_f32 v88, vcc, 2.0, v183, 2.0
	v_mul_f32_e32 v94, v88, v113
	v_fma_f32 v89, -v112, v94, v88
	v_rcp_f32_e32 v133, v132
	v_fmac_f32_e32 v94, v89, v113
	v_fma_f32 v95, -v112, v94, v88
	v_div_fmas_f32 v94, v95, v113, v94
	v_div_fixup_f32 v95, v94, v183, 2.0
	v_fma_f32 v94, -v132, v133, 1.0
	global_load_dwordx4 v[88:91], v212, s[16:17] offset:128
	v_fmac_f32_e32 v133, v94, v133
	v_div_scale_f32 v94, vcc, 2.0, v182, 2.0
	global_load_dwordx4 v[112:115], v212, s[16:17] offset:1152
	v_mul_f32_e32 v134, v94, v133
	v_fma_f32 v135, -v132, v134, v94
	v_fmac_f32_e32 v134, v135, v133
	v_fma_f32 v94, -v132, v134, v94
	v_mul_f32_e32 v132, 0x3d372713, v180
	v_mul_f32_e32 v132, v180, v132
	v_fma_f32 v140, v180, v132, v180
	v_mul_f32_e32 v140, 0x3f4c422a, v140
	v_div_fmas_f32 v94, v94, v133, v134
	global_load_dwordx4 v[132:135], v[216:217], off offset:128
	v_add_f32_e32 v144, v140, v140
	global_load_dwordx4 v[140:143], v[216:217], off offset:1152
	v_mul_f32_e32 v144, 0x3fb8aa3b, v144
	v_exp_f32_e32 v184, v144
	global_load_dwordx4 v[144:147], v[216:217], off offset:2176
	v_mul_f32_e32 v148, 0x3d372713, v181
	v_mul_f32_e32 v152, v181, v148
	global_load_dwordx4 v[148:151], v[216:217], off offset:3200
	v_fma_f32 v156, v181, v152, v181
	global_load_dwordx4 v[152:155], v[218:219], off offset:128
	v_mul_f32_e32 v165, 0x3f4c422a, v156
	global_load_dwordx4 v[156:159], v[218:219], off offset:1152
	v_add_f32_e32 v165, v165, v165
	v_mul_f32_e32 v165, 0x3fb8aa3b, v165
	v_exp_f32_e32 v185, v165
	v_div_fixup_f32 v94, v94, v182, 2.0
	v_pk_add_f32 v[94:95], v[94:95], 1.0 op_sel_hi:[1,0] neg_lo:[1,0] neg_hi:[1,0]
	v_pk_mul_f32 v[180:181], v[180:181], 0.5 op_sel_hi:[1,0]
	v_pk_add_f32 v[182:183], v[184:185], 1.0 op_sel_hi:[1,0]
	v_pk_add_f32 v[94:95], v[94:95], 1.0 op_sel_hi:[1,0]
	v_div_scale_f32 v165, s[0:1], v183, v183, 2.0
	v_rcp_f32_e32 v184, v165
	v_pk_mul_f32 v[94:95], v[178:179], v[94:95]
	s_nop 0
	v_cvt_pk_bf16_f32 v94, v94, v95
	v_fma_f32 v95, -v165, v184, 1.0
	v_fmac_f32_e32 v184, v95, v184
	v_div_scale_f32 v95, vcc, 2.0, v183, 2.0
	v_mul_f32_e32 v178, v95, v184
	v_fma_f32 v179, -v165, v178, v95
	v_fmac_f32_e32 v178, v179, v184
	v_fma_f32 v95, -v165, v178, v95
	v_div_scale_f32 v165, s[0:1], v182, v182, 2.0
	v_rcp_f32_e32 v185, v165
	v_div_fmas_f32 v95, v95, v184, v178
	v_div_fixup_f32 v179, v95, v183, 2.0
	v_permlane16_swap_b32_e32 v92, v94
	v_fma_f32 v95, -v165, v185, 1.0
	v_fmac_f32_e32 v185, v95, v185
	v_div_scale_f32 v95, vcc, 2.0, v182, 2.0
	v_mul_f32_e32 v178, v95, v185
	v_fma_f32 v183, -v165, v178, v95
	v_fmac_f32_e32 v178, v183, v185
	v_fma_f32 v95, -v165, v178, v95
	v_div_fmas_f32 v95, v95, v185, v178
	v_div_fixup_f32 v178, v95, v182, 2.0
	v_pk_add_f32 v[178:179], v[178:179], 1.0 op_sel_hi:[1,0] neg_lo:[1,0] neg_hi:[1,0]
	s_nop 0
	v_pk_add_f32 v[178:179], v[178:179], 1.0 op_sel_hi:[1,0]
	s_nop 0
	v_pk_mul_f32 v[178:179], v[180:181], v[178:179]
	s_nop 0
	v_cvt_pk_bf16_f32 v95, v178, v179
	global_load_dwordx4 v[178:181], v212, s[16:17] offset:192
	s_nop 0
	v_permlane16_swap_b32_e32 v93, v95
	s_waitcnt vmcnt(8)
; DI unsigned pack2(float a, float b) { v2f f = {a, b}; return __builtin_bit_cast(unsigned, __builtin_convertvector(f, v2bf)); }
; DI float fexp(float x) { return __builtin_amdgcn_exp2f(x * LOG2E); }
;   DI u32x2 pack(int, int, float a, float b, float c, float d, float&) const { u32x2 v; v.x = pack2(a, b); v.y = pack2(c, d); return v; }
; DI float gelu_tanh(float x) {
;   float u = 0.7978845608028654f * (x + 0.044715f * x * x * x);
;   float t = 1.f - 2.f / (fexp(2.f * u) + 1.f);
;   return 0.5f * x * (1.f + t);
; }
;   DI u32x2 pack(int m, int n, float a, float b, float c, float d, float& ss) const {
;     f32x4 bs = {0.f, 0.f, 0.f, 0.f};
; #pragma unroll
;     for (int kc = 0; kc < 16; ++kc) bs += *(const f32x4*)(bias_part + kc * 256 + n);
;     u32x2 v; v.x = pack2(gelu_tanh(a + bs[0]), gelu_tanh(b + bs[1])); v.y = pack2(gelu_tanh(c + bs[2]), gelu_tanh(d + bs[3]));
;     return v;
;   }
	v_pk_add_f32 v[184:185], v[88:89], 0 op_sel_hi:[1,0]
	v_pk_add_f32 v[182:183], v[90:91], 0 op_sel_hi:[1,0]
	global_load_dwordx4 v[88:91], v212, s[16:17] offset:1216
	s_waitcnt vmcnt(8)
	v_pk_add_f32 v[184:185], v[184:185], v[112:113]
	v_pk_add_f32 v[182:183], v[182:183], v[114:115]
	global_load_dwordx4 v[112:115], v212, s[16:17] offset:2240
	v_pk_add_f32 v[184:185], v[184:185], v[116:117]
	v_pk_add_f32 v[182:183], v[182:183], v[118:119]
	global_load_dwordx4 v[116:119], v212, s[16:17] offset:3264
	v_pk_add_f32 v[120:121], v[184:185], v[120:121]
	v_pk_add_f32 v[122:123], v[182:183], v[122:123]
	v_pk_add_f32 v[96:97], v[120:121], v[96:97]
	v_pk_add_f32 v[98:99], v[122:123], v[98:99]
	v_pk_add_f32 v[96:97], v[96:97], v[100:101]
	v_pk_add_f32 v[98:99], v[98:99], v[102:103]
	v_pk_add_f32 v[96:97], v[96:97], v[104:105]
	v_pk_add_f32 v[98:99], v[98:99], v[106:107]
	v_pk_add_f32 v[102:103], v[96:97], v[108:109]
	v_pk_add_f32 v[100:101], v[98:99], v[110:111]
	global_load_dwordx4 v[96:99], v[216:217], off offset:192
	s_waitcnt vmcnt(10)
	v_pk_add_f32 v[106:107], v[102:103], v[132:133]
	v_pk_add_f32 v[104:105], v[100:101], v[134:135]
	global_load_dwordx4 v[100:103], v[216:217], off offset:1216
	s_waitcnt vmcnt(10)
	v_pk_add_f32 v[110:111], v[106:107], v[140:141]
	v_pk_add_f32 v[108:109], v[104:105], v[142:143]
	global_load_dwordx4 v[104:107], v[216:217], off offset:2240
	s_waitcnt vmcnt(10)
	v_pk_add_f32 v[120:121], v[110:111], v[144:145]
	v_pk_add_f32 v[182:183], v[108:109], v[146:147]
	global_load_dwordx4 v[108:111], v[216:217], off offset:3264
	s_waitcnt vmcnt(10)
	v_pk_add_f32 v[132:133], v[120:121], v[148:149]
	global_load_dwordx4 v[120:123], v[218:219], off offset:192
	s_waitcnt vmcnt(10)
	v_pk_add_f32 v[140:141], v[132:133], v[152:153]
	global_load_dwordx4 v[132:135], v[218:219], off offset:1216
	s_waitcnt vmcnt(10)
	v_pk_add_f32 v[144:145], v[140:141], v[156:157]
	global_load_dwordx4 v[140:143], v[218:219], off offset:2240
	v_pk_add_f32 v[148:149], v[144:145], v[170:171]
	global_load_dwordx4 v[144:147], v[218:219], off offset:3264
	v_pk_add_f32 v[148:149], v[148:149], v[174:175]
	v_pk_add_f32 v[150:151], v[182:183], v[150:151]
	v_pk_add_f32 v[84:85], v[84:85], v[148:149]
	v_pk_add_f32 v[150:151], v[150:151], v[154:155]
	v_mul_f32_e32 v148, 0x3d372713, v84
	v_mul_f32_e32 v149, 0x3d372713, v85
	v_mul_f32_e32 v148, v84, v148
	v_mul_f32_e32 v149, v85, v149
	v_fma_f32 v148, v84, v148, v84
	v_fma_f32 v149, v85, v149, v85
	v_mul_f32_e32 v148, 0x3f4c422a, v148
	v_mul_f32_e32 v149, 0x3f4c422a, v149
	v_add_f32_e32 v148, v148, v148
	v_add_f32_e32 v149, v149, v149
	v_mul_f32_e32 v148, 0x3fb8aa3b, v148
	v_mul_f32_e32 v149, 0x3fb8aa3b, v149
	v_exp_f32_e32 v148, v148
	v_exp_f32_e32 v149, v149
	v_pk_add_f32 v[150:151], v[150:151], v[158:159]
	v_pk_mul_f32 v[84:85], v[84:85], 0.5 op_sel_hi:[1,0]
	v_pk_add_f32 v[150:151], v[150:151], v[172:173]
	v_pk_add_f32 v[148:149], v[148:149], 1.0 op_sel_hi:[1,0]
	v_pk_add_f32 v[150:151], v[150:151], v[176:177]
	v_div_scale_f32 v152, s[0:1], v149, v149, 2.0
	v_rcp_f32_e32 v153, v152
	v_pk_add_f32 v[86:87], v[86:87], v[150:151]
	v_fma_f32 v150, -v152, v153, 1.0
	v_fmac_f32_e32 v153, v150, v153
	v_div_scale_f32 v150, vcc, 2.0, v149, 2.0
	v_mul_f32_e32 v151, v150, v153
	v_fma_f32 v154, -v152, v151, v150
	v_fmac_f32_e32 v151, v154, v153
	v_fma_f32 v150, -v152, v151, v150
	v_div_scale_f32 v152, s[0:1], v148, v148, 2.0
	v_rcp_f32_e32 v154, v152
	v_div_fmas_f32 v150, v150, v153, v151
	v_div_fixup_f32 v149, v150, v149, 2.0
	v_fma_f32 v150, -v152, v154, 1.0
	v_fmac_f32_e32 v154, v150, v154
	v_div_scale_f32 v150, vcc, 2.0, v148, 2.0
	v_mul_f32_e32 v151, v150, v154
	v_fma_f32 v153, -v152, v151, v150
	v_fmac_f32_e32 v151, v153, v154
	v_fma_f32 v150, -v152, v151, v150
	v_div_fmas_f32 v152, v150, v154, v151
	v_mul_f32_e32 v150, 0x3d372713, v86
	v_mul_f32_e32 v151, 0x3d372713, v87
	v_mul_f32_e32 v150, v86, v150
	v_mul_f32_e32 v151, v87, v151
	v_fma_f32 v150, v86, v150, v86
	v_fma_f32 v151, v87, v151, v87
	v_mul_f32_e32 v150, 0x3f4c422a, v150
	v_mul_f32_e32 v151, 0x3f4c422a, v151
	v_add_f32_e32 v150, v150, v150
	v_add_f32_e32 v151, v151, v151
	v_mul_f32_e32 v150, 0x3fb8aa3b, v150
	v_mul_f32_e32 v151, 0x3fb8aa3b, v151
	v_exp_f32_e32 v150, v150
	v_exp_f32_e32 v151, v151
	v_div_fixup_f32 v148, v152, v148, 2.0
	v_pk_add_f32 v[148:149], v[148:149], 1.0 op_sel_hi:[1,0] neg_lo:[1,0] neg_hi:[1,0]
	v_pk_mul_f32 v[86:87], v[86:87], 0.5 op_sel_hi:[1,0]
	v_pk_add_f32 v[150:151], v[150:151], 1.0 op_sel_hi:[1,0]
	v_pk_add_f32 v[148:149], v[148:149], 1.0 op_sel_hi:[1,0]
	v_div_scale_f32 v152, s[0:1], v151, v151, 2.0
	v_rcp_f32_e32 v153, v152
	v_pk_mul_f32 v[84:85], v[84:85], v[148:149]
	s_nop 0
	v_cvt_pk_bf16_f32 v84, v84, v85
	v_fma_f32 v85, -v152, v153, 1.0
	v_fmac_f32_e32 v153, v85, v153
	v_div_scale_f32 v85, vcc, 2.0, v151, 2.0
	v_mul_f32_e32 v148, v85, v153
	v_fma_f32 v149, -v152, v148, v85
	v_fmac_f32_e32 v148, v149, v153
	v_fma_f32 v85, -v152, v148, v85
	v_div_scale_f32 v152, s[0:1], v150, v150, 2.0
	v_rcp_f32_e32 v154, v152
	v_div_fmas_f32 v85, v85, v153, v148
	v_div_fixup_f32 v149, v85, v151, 2.0
	v_fma_f32 v85, -v152, v154, 1.0
	v_fmac_f32_e32 v154, v85, v154
	v_div_scale_f32 v85, vcc, 2.0, v150, 2.0
	v_mul_f32_e32 v148, v85, v154
	v_fma_f32 v151, -v152, v148, v85
	v_fmac_f32_e32 v148, v151, v154
	v_fma_f32 v85, -v152, v148, v85
	v_div_fmas_f32 v85, v85, v154, v148
	v_div_fixup_f32 v148, v85, v150, 2.0
	v_pk_add_f32 v[148:149], v[148:149], 1.0 op_sel_hi:[1,0] neg_lo:[1,0] neg_hi:[1,0]
	s_nop 0
	v_pk_add_f32 v[148:149], v[148:149], 1.0 op_sel_hi:[1,0]
	s_nop 0
	v_pk_mul_f32 v[86:87], v[86:87], v[148:149]
	s_waitcnt vmcnt(11)
; DI unsigned pack2(float a, float b) { v2f f = {a, b}; return __builtin_bit_cast(unsigned, __builtin_convertvector(f, v2bf)); }
;   DI u32x2 pack(int, int, float a, float b, float c, float d, float&) const { u32x2 v; v.x = pack2(a, b); v.y = pack2(c, d); return v; }
; template <class ARow, class Epi>
; DI void gemm_tile(const ARow& arow, long a_kstride, const u16* __restrict__ Bt, long ldb, int K, int m0, int n0,
;                   const Epi& epi, char* smem) {
;     ...
;       for (int ni = 0; ni < 4; ++ni) pk[ni] = epi.pack(m, nh + ni * 16 + fq * 4, acc[ni][mi][0], acc[ni][mi][1], acc[ni][mi][2], acc[ni][mi][3], ss);
;       epi.finish16(m, nh, ss);
;       u16* rp = epi.rowp(m) + nh;
; #pragma unroll
;       for (int pp = 0; pp < 2; ++pp) {
;         u32x2 a = pk[2 * pp], b = pk[2 * pp + 1];
;         const u32x2 rx = __builtin_amdgcn_permlane16_swap(a.x, b.x, false, false);
;         const u32x2 ry = __builtin_amdgcn_permlane16_swap(a.y, b.y, false, false);
;         const int nst = (fq & 1) ? ((2 * pp + 1) * 16 + (fq - 1) * 4) : ((2 * pp) * 16 + fq * 4);
;         *(u32x4*)(rp + nst) = (u32x4){rx[0], ry[0], rx[1], ry[1]};
;   DI u32x2 pack(int m, int n, float a, float b, float c, float d, float& ss) const {
;     f32x4 bs = {0.f, 0.f, 0.f, 0.f};
; #pragma unroll
;     for (int kc = 0; kc < 16; ++kc) bs += *(const f32x4*)(bias_part + kc * 256 + n);
;     u32x2 v; v.x = pack2(gelu_tanh(a + bs[0]), gelu_tanh(b + bs[1])); v.y = pack2(gelu_tanh(c + bs[2]), gelu_tanh(d + bs[3]));
;     return v;
;   }
	v_pk_add_f32 v[148:149], v[178:179], 0 op_sel_hi:[1,0]
	v_cvt_pk_bf16_f32 v85, v86, v87
	s_waitcnt vmcnt(10)
	v_pk_add_f32 v[88:89], v[148:149], v[88:89]
	v_pk_add_f32 v[86:87], v[180:181], 0 op_sel_hi:[1,0]
	s_waitcnt vmcnt(9)
	v_pk_add_f32 v[88:89], v[88:89], v[112:113]
	v_pk_add_f32 v[86:87], v[86:87], v[90:91]
	s_waitcnt vmcnt(8)
	v_pk_add_f32 v[88:89], v[88:89], v[116:117]
	v_pk_add_f32 v[86:87], v[86:87], v[114:115]
	v_pk_add_f32 v[88:89], v[88:89], v[160:161]
	v_pk_add_f32 v[86:87], v[86:87], v[118:119]
	v_pk_add_f32 v[88:89], v[88:89], v[136:137]
	v_pk_add_f32 v[86:87], v[86:87], v[162:163]
	v_pk_add_f32 v[88:89], v[88:89], v[128:129]
	v_pk_add_f32 v[86:87], v[86:87], v[138:139]
	v_pk_add_f32 v[88:89], v[88:89], v[124:125]
	v_pk_add_f32 v[86:87], v[86:87], v[130:131]
	s_waitcnt vmcnt(7)
	v_pk_add_f32 v[88:89], v[88:89], v[96:97]
	v_pk_add_f32 v[86:87], v[86:87], v[126:127]
	s_waitcnt vmcnt(6)
	v_pk_add_f32 v[88:89], v[88:89], v[100:101]
	v_pk_add_f32 v[86:87], v[86:87], v[98:99]
	s_waitcnt vmcnt(5)
	v_pk_add_f32 v[88:89], v[88:89], v[104:105]
	v_pk_add_f32 v[86:87], v[86:87], v[102:103]
	s_waitcnt vmcnt(4)
	v_pk_add_f32 v[88:89], v[88:89], v[108:109]
	v_pk_add_f32 v[86:87], v[86:87], v[106:107]
	s_waitcnt vmcnt(3)
	v_pk_add_f32 v[88:89], v[88:89], v[120:121]
	v_pk_add_f32 v[86:87], v[86:87], v[110:111]
	s_waitcnt vmcnt(2)
	v_pk_add_f32 v[88:89], v[88:89], v[132:133]
	v_pk_add_f32 v[86:87], v[86:87], v[122:123]
	s_waitcnt vmcnt(1)
	v_pk_add_f32 v[88:89], v[88:89], v[140:141]
	v_pk_add_f32 v[86:87], v[86:87], v[134:135]
	s_waitcnt vmcnt(0)
	v_pk_add_f32 v[88:89], v[88:89], v[144:145]
	v_pk_add_f32 v[86:87], v[86:87], v[142:143]
	v_pk_add_f32 v[80:81], v[80:81], v[88:89]
	v_pk_add_f32 v[86:87], v[86:87], v[146:147]
	v_mul_f32_e32 v88, 0x3d372713, v80
	v_mul_f32_e32 v89, 0x3d372713, v81
	v_mul_f32_e32 v88, v80, v88
	v_mul_f32_e32 v89, v81, v89
	v_fma_f32 v88, v80, v88, v80
	v_fma_f32 v89, v81, v89, v81
	v_mul_f32_e32 v88, 0x3f4c422a, v88
	v_mul_f32_e32 v89, 0x3f4c422a, v89
	v_add_f32_e32 v88, v88, v88
	v_add_f32_e32 v89, v89, v89
	v_mul_f32_e32 v88, 0x3fb8aa3b, v88
	v_mul_f32_e32 v89, 0x3fb8aa3b, v89
	v_exp_f32_e32 v88, v88
	v_exp_f32_e32 v89, v89
	v_pk_add_f32 v[82:83], v[82:83], v[86:87]
	v_pk_mul_f32 v[80:81], v[80:81], 0.5 op_sel_hi:[1,0]
	v_mfma_f32_16x16x32_bf16 v[140:143], v[40:43], v[76:79], v[64:67]
	v_add_f32_e64 v88, v88, 1.0
	v_add_f32_e64 v89, v89, 1.0
	v_div_scale_f32 v90, s[0:1], v89, v89, 2.0
	v_rcp_f32_e32 v91, v90
	v_mfma_f32_16x16x32_bf16 v[64:67], v[28:31], v[72:75], v[60:63]
	v_fma_f32 v86, -v90, v91, 1.0
	v_fmac_f32_e32 v91, v86, v91
	v_div_scale_f32 v86, vcc, 2.0, v89, 2.0
	v_mul_f32_e32 v87, v86, v91
	v_fma_f32 v96, -v90, v87, v86
	v_fmac_f32_e32 v87, v96, v91
	v_fma_f32 v86, -v90, v87, v86
	v_div_scale_f32 v90, s[0:1], v88, v88, 2.0
	v_rcp_f32_e32 v96, v90
	v_div_fmas_f32 v86, v86, v91, v87
	v_div_fixup_f32 v87, v86, v89, 2.0
	v_mfma_f32_16x16x32_bf16 v[60:63], v[24:27], v[72:75], v[56:59]
	v_fma_f32 v86, -v90, v96, 1.0
	v_fmac_f32_e32 v96, v86, v96
	v_div_scale_f32 v86, vcc, 2.0, v88, 2.0
	v_mul_f32_e32 v89, v86, v96
	v_fma_f32 v91, -v90, v89, v86
	v_fmac_f32_e32 v89, v91, v96
	v_fma_f32 v86, -v90, v89, v86
	v_div_fmas_f32 v86, v86, v96, v89
	v_mul_f32_e32 v89, 0x3d372713, v82
	v_mul_f32_e32 v89, v82, v89
	v_fma_f32 v89, v82, v89, v82
	v_mul_f32_e32 v89, 0x3f4c422a, v89
	v_add_f32_e32 v89, v89, v89
	v_mul_f32_e32 v89, 0x3fb8aa3b, v89
	v_exp_f32_e32 v90, v89
	v_mul_f32_e32 v89, 0x3d372713, v83
	v_mul_f32_e32 v89, v83, v89
	v_fma_f32 v89, v83, v89, v83
	v_mul_f32_e32 v89, 0x3f4c422a, v89
	v_add_f32_e32 v89, v89, v89
	v_mul_f32_e32 v89, 0x3fb8aa3b, v89
	v_exp_f32_e32 v91, v89
	v_div_fixup_f32 v86, v86, v88, 2.0
	v_pk_add_f32 v[86:87], v[86:87], 1.0 op_sel_hi:[1,0] neg_lo:[1,0] neg_hi:[1,0]
	v_pk_mul_f32 v[82:83], v[82:83], 0.5 op_sel_hi:[1,0]
	v_pk_add_f32 v[88:89], v[90:91], 1.0 op_sel_hi:[1,0]
	v_pk_add_f32 v[86:87], v[86:87], 1.0 op_sel_hi:[1,0]
	v_div_scale_f32 v90, s[0:1], v89, v89, 2.0
	v_rcp_f32_e32 v91, v90
	v_pk_mul_f32 v[80:81], v[80:81], v[86:87]
	v_mfma_f32_16x16x32_bf16 v[56:59], v[20:23], v[72:75], v[140:143]
	v_cvt_pk_bf16_f32 v86, v80, v81
	v_fma_f32 v80, -v90, v91, 1.0
	v_fmac_f32_e32 v91, v80, v91
	v_div_scale_f32 v80, vcc, 2.0, v89, 2.0
	v_mul_f32_e32 v81, v80, v91
	v_fma_f32 v87, -v90, v81, v80
	v_fmac_f32_e32 v81, v87, v91
	v_div_scale_f32 v87, s[0:1], v88, v88, 2.0
	v_fma_f32 v80, -v90, v81, v80
	v_rcp_f32_e32 v90, v87
	v_div_fmas_f32 v80, v80, v91, v81
	v_div_fixup_f32 v81, v80, v89, 2.0
	v_permlane16_swap_b32_e32 v84, v86
	v_fma_f32 v80, -v87, v90, 1.0
	v_fmac_f32_e32 v90, v80, v90
	v_div_scale_f32 v80, vcc, 2.0, v88, 2.0
	v_mul_f32_e32 v89, v80, v90
	v_fma_f32 v91, -v87, v89, v80
	v_fmac_f32_e32 v89, v91, v90
	v_fma_f32 v80, -v87, v89, v80
	v_div_fmas_f32 v80, v80, v90, v89
	v_div_fixup_f32 v80, v80, v88, 2.0
	v_pk_add_f32 v[80:81], v[80:81], 1.0 op_sel_hi:[1,0] neg_lo:[1,0] neg_hi:[1,0]
	s_nop 0
	v_pk_add_f32 v[80:81], v[80:81], 1.0 op_sel_hi:[1,0]
	s_nop 0
	v_pk_mul_f32 v[80:81], v[82:83], v[80:81]
	s_nop 0
	v_cvt_pk_bf16_f32 v87, v80, v81
	v_or_b32_e32 v80, 16, v164
	v_ashrrev_i32_e32 v81, 31, v80
	v_lshlrev_b64 v[80:81], 9, v[80:81]
	v_lshl_add_u64 v[80:81], v[214:215], 0, v[80:81]
	v_lshl_add_u64 v[82:83], v[80:81], 0, v[166:167]
	v_permlane16_swap_b32_e32 v85, v87
	v_lshl_add_u64 v[80:81], v[80:81], 0, v[168:169]
	global_store_dwordx4 v[82:83], v[92:95], off sc0 sc1
	global_store_dwordx4 v[80:81], v[84:87], off sc0 sc1
	global_load_dwordx4 v[120:123], v212, s[16:17]
	global_load_dwordx4 v[124:127], v212, s[16:17] offset:1024
	global_load_dwordx4 v[128:131], v212, s[16:17] offset:2048
	global_load_dwordx4 v[132:135], v212, s[16:17] offset:3072
	global_load_dwordx4 v[136:139], v[216:217], off offset:-4096
	global_load_dwordx4 v[112:115], v[220:221], off offset:1024
	global_load_dwordx4 v[104:107], v[220:221], off offset:2048
	global_load_dwordx4 v[100:103], v[220:221], off offset:3072
	global_load_dwordx4 v[92:95], v[218:219], off offset:-4096
	global_load_dwordx4 v[108:111], v[216:217], off offset:1024
	global_load_dwordx4 v[116:119], v[216:217], off offset:2048
	global_load_dwordx4 v[76:79], v[216:217], off offset:3072
	global_load_dwordx4 v[80:83], v[218:219], off
	global_load_dwordx4 v[84:87], v[218:219], off offset:1024
	global_load_dwordx4 v[88:91], v[218:219], off offset:2048
	global_load_dwordx4 v[96:99], v[218:219], off offset:3072
	global_load_dwordx4 v[148:151], v[218:219], off offset:2112
	global_load_dwordx4 v[72:75], v212, s[16:17] offset:64
	global_load_dwordx4 v[152:155], v[218:219], off offset:3136
	global_load_dwordx4 v[144:147], v[218:219], off offset:1088
	s_waitcnt vmcnt(19)
; DI unsigned pack2(float a, float b) { v2f f = {a, b}; return __builtin_bit_cast(unsigned, __builtin_convertvector(f, v2bf)); }
; DI float fexp(float x) { return __builtin_amdgcn_exp2f(x * LOG2E); }
;   DI u32x2 pack(int, int, float a, float b, float c, float d, float&) const { u32x2 v; v.x = pack2(a, b); v.y = pack2(c, d); return v; }
; DI float gelu_tanh(float x) {
;   float u = 0.7978845608028654f * (x + 0.044715f * x * x * x);
;   float t = 1.f - 2.f / (fexp(2.f * u) + 1.f);
;   return 0.5f * x * (1.f + t);
; }
;   DI u32x2 pack(int m, int n, float a, float b, float c, float d, float& ss) const {
;     f32x4 bs = {0.f, 0.f, 0.f, 0.f};
; #pragma unroll
;     for (int kc = 0; kc < 16; ++kc) bs += *(const f32x4*)(bias_part + kc * 256 + n);
;     u32x2 v; v.x = pack2(gelu_tanh(a + bs[0]), gelu_tanh(b + bs[1])); v.y = pack2(gelu_tanh(c + bs[2]), gelu_tanh(d + bs[3]));
;     return v;
;   }
	v_pk_add_f32 v[140:141], v[122:123], 0 op_sel_hi:[1,0]
	v_pk_add_f32 v[142:143], v[120:121], 0 op_sel_hi:[1,0]
	s_waitcnt vmcnt(18)
	v_pk_add_f32 v[140:141], v[140:141], v[126:127]
	v_pk_add_f32 v[142:143], v[142:143], v[124:125]
	s_waitcnt vmcnt(17)
	v_pk_add_f32 v[140:141], v[140:141], v[130:131]
	v_pk_add_f32 v[142:143], v[142:143], v[128:129]
	s_waitcnt vmcnt(16)
	v_pk_add_f32 v[140:141], v[140:141], v[134:135]
	v_pk_add_f32 v[142:143], v[142:143], v[132:133]
	s_waitcnt vmcnt(15)
	v_pk_add_f32 v[140:141], v[140:141], v[138:139]
	v_pk_add_f32 v[142:143], v[142:143], v[136:137]
	s_waitcnt vmcnt(14)
	v_pk_add_f32 v[140:141], v[140:141], v[114:115]
	v_pk_add_f32 v[142:143], v[142:143], v[112:113]
	s_waitcnt vmcnt(13)
	v_pk_add_f32 v[140:141], v[140:141], v[106:107]
	v_pk_add_f32 v[142:143], v[142:143], v[104:105]
	s_waitcnt vmcnt(12)
	v_pk_add_f32 v[140:141], v[140:141], v[102:103]
	v_pk_add_f32 v[142:143], v[142:143], v[100:101]
	s_waitcnt vmcnt(11)
	v_pk_add_f32 v[140:141], v[140:141], v[94:95]
	v_pk_add_f32 v[142:143], v[142:143], v[92:93]
	s_waitcnt vmcnt(10)
	v_pk_add_f32 v[140:141], v[140:141], v[110:111]
	v_pk_add_f32 v[142:143], v[142:143], v[108:109]
	s_waitcnt vmcnt(9)
	v_pk_add_f32 v[156:157], v[140:141], v[118:119]
	v_pk_add_f32 v[140:141], v[142:143], v[116:117]
	s_waitcnt vmcnt(8)
	v_pk_add_f32 v[78:79], v[156:157], v[78:79]
	v_pk_add_f32 v[76:77], v[140:141], v[76:77]
	s_waitcnt vmcnt(7)
	v_pk_add_f32 v[78:79], v[78:79], v[82:83]
	v_pk_add_f32 v[76:77], v[76:77], v[80:81]
	s_waitcnt vmcnt(6)
	v_pk_add_f32 v[78:79], v[78:79], v[86:87]
	v_pk_add_f32 v[76:77], v[76:77], v[84:85]
	global_load_dwordx4 v[120:123], v212, s[16:17] offset:1088
	s_waitcnt vmcnt(6)
	v_pk_add_f32 v[76:77], v[76:77], v[88:89]
	global_load_dwordx4 v[124:127], v212, s[16:17] offset:2112
	global_load_dwordx4 v[128:131], v212, s[16:17] offset:3136
	s_waitcnt vmcnt(7)
	v_pk_add_f32 v[76:77], v[76:77], v[96:97]
	global_load_dwordx4 v[112:115], v[220:221], off offset:1216
	v_pk_add_f32 v[68:69], v[68:69], v[76:77]
	global_load_dwordx4 v[132:135], v[216:217], off offset:64
	global_load_dwordx4 v[92:95], v[216:217], off offset:1088
	v_mul_f32_e32 v76, 0x3d372713, v68
	v_mul_f32_e32 v77, 0x3d372713, v69
	v_mul_f32_e32 v76, v68, v76
	v_mul_f32_e32 v77, v69, v77
	v_fma_f32 v76, v68, v76, v68
	v_fma_f32 v77, v69, v77, v69
	v_mul_f32_e32 v76, 0x3f4c422a, v76
	v_mul_f32_e32 v77, 0x3f4c422a, v77
	v_add_f32_e32 v76, v76, v76
	v_add_f32_e32 v77, v77, v77
	v_mul_f32_e32 v76, 0x3fb8aa3b, v76
	v_mul_f32_e32 v77, 0x3fb8aa3b, v77
	v_exp_f32_e32 v76, v76
	v_exp_f32_e32 v77, v77
	global_load_dwordx4 v[108:111], v[216:217], off offset:2112
	global_load_dwordx4 v[116:119], v[216:217], off offset:3136
	global_load_dwordx4 v[140:143], v[218:219], off offset:64
	v_pk_add_f32 v[96:97], v[76:77], 1.0 op_sel_hi:[1,0]
	v_pk_add_f32 v[76:77], v[78:79], v[90:91]
	v_div_scale_f32 v80, s[0:1], v97, v97, 2.0
	v_rcp_f32_e32 v81, v80
	v_pk_add_f32 v[76:77], v[76:77], v[98:99]
	v_div_scale_f32 v98, s[0:1], v96, v96, 2.0
	v_pk_add_f32 v[70:71], v[70:71], v[76:77]
	v_fma_f32 v76, -v80, v81, 1.0
	v_fmac_f32_e32 v81, v76, v81
	v_div_scale_f32 v76, vcc, 2.0, v97, 2.0
	v_mul_f32_e32 v82, v76, v81
	v_fma_f32 v77, -v80, v82, v76
	v_rcp_f32_e32 v99, v98
	v_fmac_f32_e32 v82, v77, v81
	v_fma_f32 v80, -v80, v82, v76
	global_load_dwordx4 v[76:79], v[220:221], off offset:64
	v_div_fmas_f32 v84, v80, v81, v82
	global_load_dwordx4 v[80:83], v[220:221], off offset:1088
	v_div_fixup_f32 v97, v84, v97, 2.0
	v_fma_f32 v88, -v98, v99, 1.0
	global_load_dwordx4 v[84:87], v[220:221], off offset:2112
	v_fmac_f32_e32 v99, v88, v99
	global_load_dwordx4 v[88:91], v[220:221], off offset:3136
	v_div_scale_f32 v156, vcc, 2.0, v96, 2.0
	v_mul_f32_e32 v157, v156, v99
	v_fma_f32 v158, -v98, v157, v156
	v_fmac_f32_e32 v157, v158, v99
	v_fma_f32 v98, -v98, v157, v156
	v_div_fmas_f32 v156, v98, v99, v157
	v_mul_f32_e32 v98, 0x3d372713, v70
	v_mul_f32_e32 v99, 0x3d372713, v71
	v_mul_f32_e32 v98, v70, v98
	v_mul_f32_e32 v99, v71, v99
	v_fma_f32 v98, v70, v98, v70
	v_fma_f32 v99, v71, v99, v71
	v_mul_f32_e32 v98, 0x3f4c422a, v98
	v_mul_f32_e32 v99, 0x3f4c422a, v99
	v_add_f32_e32 v98, v98, v98
	v_add_f32_e32 v99, v99, v99
	v_mul_f32_e32 v98, 0x3fb8aa3b, v98
	v_mul_f32_e32 v99, 0x3fb8aa3b, v99
	v_exp_f32_e32 v98, v98
	v_exp_f32_e32 v99, v99
	v_div_fixup_f32 v96, v156, v96, 2.0
	v_pk_add_f32 v[96:97], v[96:97], 1.0 op_sel_hi:[1,0] neg_lo:[1,0] neg_hi:[1,0]
	v_pk_mul_f32 v[68:69], v[68:69], 0.5 op_sel_hi:[1,0]
	v_pk_add_f32 v[98:99], v[98:99], 1.0 op_sel_hi:[1,0]
	v_pk_add_f32 v[96:97], v[96:97], 1.0 op_sel_hi:[1,0]
	v_div_scale_f32 v156, s[0:1], v99, v99, 2.0
	v_rcp_f32_e32 v157, v156
	v_pk_mul_f32 v[68:69], v[68:69], v[96:97]
	v_pk_mul_f32 v[70:71], v[70:71], 0.5 op_sel_hi:[1,0]
	v_cvt_pk_bf16_f32 v68, v68, v69
	v_fma_f32 v69, -v156, v157, 1.0
	v_fmac_f32_e32 v157, v69, v157
	v_div_scale_f32 v69, vcc, 2.0, v99, 2.0
	v_mul_f32_e32 v96, v69, v157
	v_fma_f32 v97, -v156, v96, v69
	v_fmac_f32_e32 v96, v97, v157
	v_fma_f32 v69, -v156, v96, v69
	v_div_scale_f32 v156, s[0:1], v98, v98, 2.0
	v_rcp_f32_e32 v158, v156
	v_div_fmas_f32 v69, v69, v157, v96
	v_div_fixup_f32 v97, v69, v99, 2.0
	s_waitcnt vmcnt(15)
	v_pk_add_f32 v[72:73], v[72:73], 0 op_sel_hi:[1,0]
	v_fma_f32 v69, -v156, v158, 1.0
	v_fmac_f32_e32 v158, v69, v158
	v_div_scale_f32 v69, vcc, 2.0, v98, 2.0
	v_mul_f32_e32 v96, v69, v158
	v_fma_f32 v99, -v156, v96, v69
	v_fmac_f32_e32 v96, v99, v158
	v_fma_f32 v69, -v156, v96, v69
	v_div_fmas_f32 v69, v69, v158, v96
	v_div_fixup_f32 v96, v69, v98, 2.0
	v_pk_add_f32 v[96:97], v[96:97], 1.0 op_sel_hi:[1,0] neg_lo:[1,0] neg_hi:[1,0]
	s_waitcnt vmcnt(12)
; DI unsigned pack2(float a, float b) { v2f f = {a, b}; return __builtin_bit_cast(unsigned, __builtin_convertvector(f, v2bf)); }
; DI float fexp(float x) { return __builtin_amdgcn_exp2f(x * LOG2E); }
;   DI u32x2 pack(int, int, float a, float b, float c, float d, float&) const { u32x2 v; v.x = pack2(a, b); v.y = pack2(c, d); return v; }
; DI float gelu_tanh(float x) {
;   float u = 0.7978845608028654f * (x + 0.044715f * x * x * x);
;   float t = 1.f - 2.f / (fexp(2.f * u) + 1.f);
;   return 0.5f * x * (1.f + t);
; }
;   DI u32x2 pack(int m, int n, float a, float b, float c, float d, float& ss) const {
;     f32x4 bs = {0.f, 0.f, 0.f, 0.f};
; #pragma unroll
;     for (int kc = 0; kc < 16; ++kc) bs += *(const f32x4*)(bias_part + kc * 256 + n);
;     u32x2 v; v.x = pack2(gelu_tanh(a + bs[0]), gelu_tanh(b + bs[1])); v.y = pack2(gelu_tanh(c + bs[2]), gelu_tanh(d + bs[3]));
;     return v;
;   }
	v_pk_add_f32 v[72:73], v[72:73], v[120:121]
	v_pk_add_f32 v[96:97], v[96:97], 1.0 op_sel_hi:[1,0]
	s_waitcnt vmcnt(11)
	v_pk_add_f32 v[72:73], v[72:73], v[124:125]
	v_pk_mul_f32 v[70:71], v[70:71], v[96:97]
	s_waitcnt vmcnt(10)
	v_pk_add_f32 v[96:97], v[72:73], v[128:129]
	v_cvt_pk_bf16_f32 v69, v70, v71
	v_pk_add_f32 v[70:71], v[74:75], 0 op_sel_hi:[1,0]
	global_load_dwordx4 v[136:139], v[220:221], off offset:192
	global_load_dwordx4 v[72:75], v[220:221], off offset:128
	v_pk_add_f32 v[70:71], v[70:71], v[122:123]
	global_load_dwordx4 v[104:107], v[220:221], off offset:2240
	v_pk_add_f32 v[70:71], v[70:71], v[126:127]
	global_load_dwordx4 v[100:103], v[220:221], off offset:3264
	v_pk_add_f32 v[70:71], v[70:71], v[130:131]
	s_waitcnt vmcnt(7)
	v_pk_add_f32 v[96:97], v[96:97], v[76:77]
	v_pk_add_f32 v[70:71], v[70:71], v[78:79]
	global_load_dwordx4 v[76:79], v[220:221], off offset:1152
	s_waitcnt vmcnt(7)
	v_pk_add_f32 v[96:97], v[96:97], v[80:81]
	v_pk_add_f32 v[70:71], v[70:71], v[82:83]
	s_waitcnt vmcnt(6)
	v_pk_add_f32 v[96:97], v[96:97], v[84:85]
	v_pk_add_f32 v[70:71], v[70:71], v[86:87]
	global_load_dwordx4 v[84:87], v[220:221], off offset:3200
	s_waitcnt vmcnt(6)
	v_pk_add_f32 v[88:89], v[96:97], v[88:89]
	v_pk_add_f32 v[70:71], v[70:71], v[90:91]
	v_pk_add_f32 v[88:89], v[88:89], v[132:133]
	v_pk_add_f32 v[70:71], v[70:71], v[134:135]
	v_pk_add_f32 v[88:89], v[88:89], v[92:93]
	v_pk_add_f32 v[70:71], v[70:71], v[94:95]
	v_pk_add_f32 v[88:89], v[88:89], v[108:109]
	v_pk_add_f32 v[70:71], v[70:71], v[110:111]
	v_pk_add_f32 v[88:89], v[88:89], v[116:117]
	v_pk_add_f32 v[70:71], v[70:71], v[118:119]
	v_pk_add_f32 v[88:89], v[88:89], v[140:141]
	v_pk_add_f32 v[70:71], v[70:71], v[142:143]
	v_pk_add_f32 v[88:89], v[88:89], v[144:145]
	v_pk_add_f32 v[70:71], v[70:71], v[146:147]
	v_pk_add_f32 v[88:89], v[88:89], v[148:149]
	global_load_dwordx4 v[92:95], v212, s[16:17] offset:2176
	v_pk_add_f32 v[88:89], v[88:89], v[152:153]
	global_load_dwordx4 v[96:99], v212, s[16:17] offset:3200
	v_pk_add_f32 v[148:149], v[64:65], v[88:89]
	global_load_dwordx4 v[80:83], v[220:221], off offset:2176
	v_mul_f32_e32 v64, 0x3d372713, v148
	v_mul_f32_e32 v65, 0x3d372713, v149
	v_mul_f32_e32 v64, v148, v64
	v_mul_f32_e32 v65, v149, v65
	v_fma_f32 v64, v148, v64, v148
	v_fma_f32 v65, v149, v65, v149
	v_mul_f32_e32 v64, 0x3f4c422a, v64
	v_mul_f32_e32 v65, 0x3f4c422a, v65
	v_add_f32_e32 v64, v64, v64
	v_add_f32_e32 v65, v65, v65
	v_mul_f32_e32 v64, 0x3fb8aa3b, v64
	v_mul_f32_e32 v65, 0x3fb8aa3b, v65
	v_exp_f32_e32 v64, v64
	v_exp_f32_e32 v65, v65
	v_pk_mul_f32 v[148:149], v[148:149], 0.5 op_sel_hi:[1,0]
	v_pk_add_f32 v[152:153], v[64:65], 1.0 op_sel_hi:[1,0]
	s_nop 0
	v_div_scale_f32 v88, s[0:1], v153, v153, 2.0
	v_rcp_f32_e32 v89, v88
	v_pk_add_f32 v[64:65], v[70:71], v[150:151]
	v_div_scale_f32 v108, s[0:1], v152, v152, 2.0
	v_pk_add_f32 v[64:65], v[64:65], v[154:155]
	v_rcp_f32_e32 v109, v108
	v_pk_add_f32 v[150:151], v[66:67], v[64:65]
	v_fma_f32 v64, -v88, v89, 1.0
	v_fmac_f32_e32 v89, v64, v89
	v_div_scale_f32 v64, vcc, 2.0, v153, 2.0
	v_mul_f32_e32 v70, v64, v89
	v_fma_f32 v65, -v88, v70, v64
	v_fmac_f32_e32 v70, v65, v89
	v_fma_f32 v71, -v88, v70, v64
	v_div_fmas_f32 v70, v71, v89, v70
	v_div_fixup_f32 v71, v70, v153, 2.0
	v_fma_f32 v70, -v108, v109, 1.0
	global_load_dwordx4 v[64:67], v212, s[16:17] offset:128
	v_fmac_f32_e32 v109, v70, v109
	v_div_scale_f32 v70, vcc, 2.0, v152, 2.0
	global_load_dwordx4 v[88:91], v212, s[16:17] offset:1152
	v_mul_f32_e32 v110, v70, v109
	v_fma_f32 v111, -v108, v110, v70
	v_fmac_f32_e32 v110, v111, v109
	v_fma_f32 v70, -v108, v110, v70
	v_mul_f32_e32 v108, 0x3d372713, v150
	v_mul_f32_e32 v108, v150, v108
	v_fma_f32 v116, v150, v108, v150
	v_mul_f32_e32 v116, 0x3f4c422a, v116
	v_div_fmas_f32 v70, v70, v109, v110
	global_load_dwordx4 v[108:111], v[216:217], off offset:128
	v_add_f32_e32 v120, v116, v116
	global_load_dwordx4 v[116:119], v[216:217], off offset:1152
	v_mul_f32_e32 v120, 0x3fb8aa3b, v120
	v_exp_f32_e32 v154, v120
	global_load_dwordx4 v[120:123], v[216:217], off offset:2176
	v_mul_f32_e32 v124, 0x3d372713, v151
	v_mul_f32_e32 v128, v151, v124
	global_load_dwordx4 v[124:127], v[216:217], off offset:3200
	v_fma_f32 v132, v151, v128, v151
	global_load_dwordx4 v[128:131], v[218:219], off offset:128
	v_mul_f32_e32 v140, 0x3f4c422a, v132
	global_load_dwordx4 v[132:135], v[218:219], off offset:1152
	v_add_f32_e32 v144, v140, v140
	global_load_dwordx4 v[140:143], v[218:219], off offset:2176
	v_mul_f32_e32 v153, 0x3fb8aa3b, v144
	global_load_dwordx4 v[144:147], v[218:219], off offset:3200
	v_exp_f32_e32 v155, v153
	v_div_fixup_f32 v70, v70, v152, 2.0
	v_pk_add_f32 v[70:71], v[70:71], 1.0 op_sel_hi:[1,0] neg_lo:[1,0] neg_hi:[1,0]
	v_pk_mul_f32 v[150:151], v[150:151], 0.5 op_sel_hi:[1,0]
	v_pk_add_f32 v[152:153], v[154:155], 1.0 op_sel_hi:[1,0]
	v_pk_add_f32 v[70:71], v[70:71], 1.0 op_sel_hi:[1,0]
	v_div_scale_f32 v154, s[0:1], v153, v153, 2.0
	v_rcp_f32_e32 v155, v154
	v_pk_mul_f32 v[70:71], v[148:149], v[70:71]
	s_nop 0
	v_cvt_pk_bf16_f32 v70, v70, v71
	v_fma_f32 v71, -v154, v155, 1.0
	v_fmac_f32_e32 v155, v71, v155
	v_div_scale_f32 v71, vcc, 2.0, v153, 2.0
	v_mul_f32_e32 v148, v71, v155
	v_fma_f32 v149, -v154, v148, v71
	v_fmac_f32_e32 v148, v149, v155
	v_fma_f32 v71, -v154, v148, v71
	v_div_scale_f32 v154, s[0:1], v152, v152, 2.0
	v_rcp_f32_e32 v156, v154
	v_div_fmas_f32 v71, v71, v155, v148
	v_div_fixup_f32 v149, v71, v153, 2.0
	v_permlane16_swap_b32_e32 v68, v70
	v_fma_f32 v71, -v154, v156, 1.0
	v_fmac_f32_e32 v156, v71, v156
	v_div_scale_f32 v71, vcc, 2.0, v152, 2.0
	v_mul_f32_e32 v148, v71, v156
	v_fma_f32 v153, -v154, v148, v71
	v_fmac_f32_e32 v148, v153, v156
	v_fma_f32 v71, -v154, v148, v71
	v_div_fmas_f32 v71, v71, v156, v148
	v_div_fixup_f32 v148, v71, v152, 2.0
	v_pk_add_f32 v[148:149], v[148:149], 1.0 op_sel_hi:[1,0] neg_lo:[1,0] neg_hi:[1,0]
	s_nop 0
	v_pk_add_f32 v[148:149], v[148:149], 1.0 op_sel_hi:[1,0]
	s_nop 0
	v_pk_mul_f32 v[148:149], v[150:151], v[148:149]
	s_nop 0
	v_cvt_pk_bf16_f32 v71, v148, v149
	global_load_dwordx4 v[148:151], v212, s[16:17] offset:192
	s_nop 0
	v_permlane16_swap_b32_e32 v69, v71
	s_waitcnt vmcnt(10)
; DI unsigned pack2(float a, float b) { v2f f = {a, b}; return __builtin_bit_cast(unsigned, __builtin_convertvector(f, v2bf)); }
; DI float fexp(float x) { return __builtin_amdgcn_exp2f(x * LOG2E); }
;   DI u32x2 pack(int, int, float a, float b, float c, float d, float&) const { u32x2 v; v.x = pack2(a, b); v.y = pack2(c, d); return v; }
; DI float gelu_tanh(float x) {
;   float u = 0.7978845608028654f * (x + 0.044715f * x * x * x);
;   float t = 1.f - 2.f / (fexp(2.f * u) + 1.f);
;   return 0.5f * x * (1.f + t);
; }
;   DI u32x2 pack(int m, int n, float a, float b, float c, float d, float& ss) const {
;     f32x4 bs = {0.f, 0.f, 0.f, 0.f};
; #pragma unroll
;     for (int kc = 0; kc < 16; ++kc) bs += *(const f32x4*)(bias_part + kc * 256 + n);
;     u32x2 v; v.x = pack2(gelu_tanh(a + bs[0]), gelu_tanh(b + bs[1])); v.y = pack2(gelu_tanh(c + bs[2]), gelu_tanh(d + bs[3]));
;     return v;
;   }
	v_pk_add_f32 v[154:155], v[64:65], 0 op_sel_hi:[1,0]
	v_pk_add_f32 v[152:153], v[66:67], 0 op_sel_hi:[1,0]
	global_load_dwordx4 v[64:67], v212, s[16:17] offset:1216
	s_waitcnt vmcnt(10)
	v_pk_add_f32 v[154:155], v[154:155], v[88:89]
	v_pk_add_f32 v[152:153], v[152:153], v[90:91]
	global_load_dwordx4 v[88:91], v212, s[16:17] offset:2240
	v_pk_add_f32 v[154:155], v[154:155], v[92:93]
	v_pk_add_f32 v[152:153], v[152:153], v[94:95]
	global_load_dwordx4 v[92:95], v212, s[16:17] offset:3264
	v_pk_add_f32 v[96:97], v[154:155], v[96:97]
	v_pk_add_f32 v[98:99], v[152:153], v[98:99]
	v_pk_add_f32 v[72:73], v[96:97], v[72:73]
	v_pk_add_f32 v[74:75], v[98:99], v[74:75]
	v_pk_add_f32 v[72:73], v[72:73], v[76:77]
	v_pk_add_f32 v[74:75], v[74:75], v[78:79]
	v_pk_add_f32 v[72:73], v[72:73], v[80:81]
	v_pk_add_f32 v[74:75], v[74:75], v[82:83]
	v_pk_add_f32 v[78:79], v[72:73], v[84:85]
	v_pk_add_f32 v[76:77], v[74:75], v[86:87]
	global_load_dwordx4 v[72:75], v[216:217], off offset:192
	s_waitcnt vmcnt(12)
	v_pk_add_f32 v[82:83], v[78:79], v[108:109]
	v_pk_add_f32 v[80:81], v[76:77], v[110:111]
	global_load_dwordx4 v[76:79], v[216:217], off offset:1216
	s_waitcnt vmcnt(12)
	v_pk_add_f32 v[86:87], v[82:83], v[116:117]
	v_pk_add_f32 v[84:85], v[80:81], v[118:119]
	global_load_dwordx4 v[80:83], v[216:217], off offset:2240
	s_waitcnt vmcnt(12)
	v_pk_add_f32 v[96:97], v[86:87], v[120:121]
	v_pk_add_f32 v[152:153], v[84:85], v[122:123]
	global_load_dwordx4 v[84:87], v[216:217], off offset:3264
	s_waitcnt vmcnt(12)
	v_pk_add_f32 v[108:109], v[96:97], v[124:125]
	global_load_dwordx4 v[96:99], v[218:219], off offset:192
	s_waitcnt vmcnt(12)
	v_pk_add_f32 v[116:117], v[108:109], v[128:129]
	global_load_dwordx4 v[108:111], v[218:219], off offset:1216
	s_waitcnt vmcnt(12)
	v_pk_add_f32 v[120:121], v[116:117], v[132:133]
	global_load_dwordx4 v[116:119], v[218:219], off offset:2240
	s_waitcnt vmcnt(12)
	v_pk_add_f32 v[124:125], v[120:121], v[140:141]
	global_load_dwordx4 v[120:123], v[218:219], off offset:3264
	s_waitcnt vmcnt(12)
	v_pk_add_f32 v[124:125], v[124:125], v[144:145]
	v_pk_add_f32 v[126:127], v[152:153], v[126:127]
	v_pk_add_f32 v[60:61], v[60:61], v[124:125]
	v_pk_add_f32 v[126:127], v[126:127], v[130:131]
	v_mul_f32_e32 v124, 0x3d372713, v60
	v_mul_f32_e32 v125, 0x3d372713, v61
	v_mul_f32_e32 v124, v60, v124
	v_mul_f32_e32 v125, v61, v125
	v_fma_f32 v124, v60, v124, v60
	v_fma_f32 v125, v61, v125, v61
	v_mul_f32_e32 v124, 0x3f4c422a, v124
	v_mul_f32_e32 v125, 0x3f4c422a, v125
	v_add_f32_e32 v124, v124, v124
	v_add_f32_e32 v125, v125, v125
	v_mul_f32_e32 v124, 0x3fb8aa3b, v124
	v_mul_f32_e32 v125, 0x3fb8aa3b, v125
	v_exp_f32_e32 v124, v124
	v_exp_f32_e32 v125, v125
	v_pk_add_f32 v[126:127], v[126:127], v[134:135]
	v_pk_mul_f32 v[60:61], v[60:61], 0.5 op_sel_hi:[1,0]
	v_pk_add_f32 v[126:127], v[126:127], v[142:143]
	v_pk_add_f32 v[124:125], v[124:125], 1.0 op_sel_hi:[1,0]
	v_pk_add_f32 v[126:127], v[126:127], v[146:147]
	v_div_scale_f32 v128, s[0:1], v125, v125, 2.0
	v_rcp_f32_e32 v129, v128
	v_pk_add_f32 v[62:63], v[62:63], v[126:127]
	v_fma_f32 v126, -v128, v129, 1.0
	v_fmac_f32_e32 v129, v126, v129
	v_div_scale_f32 v126, vcc, 2.0, v125, 2.0
	v_mul_f32_e32 v127, v126, v129
	v_fma_f32 v130, -v128, v127, v126
	v_fmac_f32_e32 v127, v130, v129
	v_fma_f32 v126, -v128, v127, v126
	v_div_scale_f32 v128, s[0:1], v124, v124, 2.0
	v_rcp_f32_e32 v130, v128
	v_div_fmas_f32 v126, v126, v129, v127
	v_div_fixup_f32 v125, v126, v125, 2.0
	v_fma_f32 v126, -v128, v130, 1.0
	v_fmac_f32_e32 v130, v126, v130
	v_div_scale_f32 v126, vcc, 2.0, v124, 2.0
	v_mul_f32_e32 v127, v126, v130
	v_fma_f32 v129, -v128, v127, v126
	v_fmac_f32_e32 v127, v129, v130
	v_fma_f32 v126, -v128, v127, v126
	v_div_fmas_f32 v128, v126, v130, v127
	v_mul_f32_e32 v126, 0x3d372713, v62
	v_mul_f32_e32 v127, 0x3d372713, v63
	v_mul_f32_e32 v126, v62, v126
	v_mul_f32_e32 v127, v63, v127
	v_fma_f32 v126, v62, v126, v62
	v_fma_f32 v127, v63, v127, v63
	v_mul_f32_e32 v126, 0x3f4c422a, v126
	v_mul_f32_e32 v127, 0x3f4c422a, v127
	v_add_f32_e32 v126, v126, v126
	v_add_f32_e32 v127, v127, v127
	v_mul_f32_e32 v126, 0x3fb8aa3b, v126
	v_mul_f32_e32 v127, 0x3fb8aa3b, v127
	v_exp_f32_e32 v126, v126
	v_exp_f32_e32 v127, v127
	v_div_fixup_f32 v124, v128, v124, 2.0
	v_pk_add_f32 v[124:125], v[124:125], 1.0 op_sel_hi:[1,0] neg_lo:[1,0] neg_hi:[1,0]
	v_pk_mul_f32 v[62:63], v[62:63], 0.5 op_sel_hi:[1,0]
	v_pk_add_f32 v[126:127], v[126:127], 1.0 op_sel_hi:[1,0]
	v_pk_add_f32 v[124:125], v[124:125], 1.0 op_sel_hi:[1,0]
	v_div_scale_f32 v128, s[0:1], v127, v127, 2.0
	v_rcp_f32_e32 v129, v128
	v_pk_mul_f32 v[60:61], v[60:61], v[124:125]
	s_nop 0
	v_cvt_pk_bf16_f32 v60, v60, v61
	v_fma_f32 v61, -v128, v129, 1.0
	v_fmac_f32_e32 v129, v61, v129
	v_div_scale_f32 v61, vcc, 2.0, v127, 2.0
	v_mul_f32_e32 v124, v61, v129
	v_fma_f32 v125, -v128, v124, v61
	v_fmac_f32_e32 v124, v125, v129
	v_fma_f32 v61, -v128, v124, v61
	v_div_scale_f32 v128, s[0:1], v126, v126, 2.0
	v_rcp_f32_e32 v130, v128
	v_div_fmas_f32 v61, v61, v129, v124
	v_div_fixup_f32 v125, v61, v127, 2.0
	v_fma_f32 v61, -v128, v130, 1.0
	v_fmac_f32_e32 v130, v61, v130
	v_div_scale_f32 v61, vcc, 2.0, v126, 2.0
	v_mul_f32_e32 v124, v61, v130
	v_fma_f32 v127, -v128, v124, v61
	v_fmac_f32_e32 v124, v127, v130
	v_fma_f32 v61, -v128, v124, v61
	v_div_fmas_f32 v61, v61, v130, v124
	v_div_fixup_f32 v124, v61, v126, 2.0
	v_pk_add_f32 v[124:125], v[124:125], 1.0 op_sel_hi:[1,0] neg_lo:[1,0] neg_hi:[1,0]
	s_nop 0
	v_pk_add_f32 v[124:125], v[124:125], 1.0 op_sel_hi:[1,0]
	s_nop 0
	v_pk_mul_f32 v[62:63], v[62:63], v[124:125]
	s_waitcnt vmcnt(11)
; DI unsigned pack2(float a, float b) { v2f f = {a, b}; return __builtin_bit_cast(unsigned, __builtin_convertvector(f, v2bf)); }
;   DI u32x2 pack(int, int, float a, float b, float c, float d, float&) const { u32x2 v; v.x = pack2(a, b); v.y = pack2(c, d); return v; }
; template <class ARow, class Epi>
; DI void gemm_tile(const ARow& arow, long a_kstride, const u16* __restrict__ Bt, long ldb, int K, int m0, int n0,
;                   const Epi& epi, char* smem) {
;     ...
;       for (int ni = 0; ni < 4; ++ni) pk[ni] = epi.pack(m, nh + ni * 16 + fq * 4, acc[ni][mi][0], acc[ni][mi][1], acc[ni][mi][2], acc[ni][mi][3], ss);
;       epi.finish16(m, nh, ss);
;       u16* rp = epi.rowp(m) + nh;
; #pragma unroll
;       for (int pp = 0; pp < 2; ++pp) {
;         u32x2 a = pk[2 * pp], b = pk[2 * pp + 1];
;         const u32x2 rx = __builtin_amdgcn_permlane16_swap(a.x, b.x, false, false);
;         const u32x2 ry = __builtin_amdgcn_permlane16_swap(a.y, b.y, false, false);
;         const int nst = (fq & 1) ? ((2 * pp + 1) * 16 + (fq - 1) * 4) : ((2 * pp) * 16 + fq * 4);
;         *(u32x4*)(rp + nst) = (u32x4){rx[0], ry[0], rx[1], ry[1]};
;   DI u32x2 pack(int m, int n, float a, float b, float c, float d, float& ss) const {
;     f32x4 bs = {0.f, 0.f, 0.f, 0.f};
; #pragma unroll
;     for (int kc = 0; kc < 16; ++kc) bs += *(const f32x4*)(bias_part + kc * 256 + n);
;     u32x2 v; v.x = pack2(gelu_tanh(a + bs[0]), gelu_tanh(b + bs[1])); v.y = pack2(gelu_tanh(c + bs[2]), gelu_tanh(d + bs[3]));
;     return v;
;   }
	v_pk_add_f32 v[124:125], v[148:149], 0 op_sel_hi:[1,0]
	v_cvt_pk_bf16_f32 v61, v62, v63
	s_waitcnt vmcnt(10)
	v_pk_add_f32 v[64:65], v[124:125], v[64:65]
	v_pk_add_f32 v[62:63], v[150:151], 0 op_sel_hi:[1,0]
	s_waitcnt vmcnt(9)
	v_pk_add_f32 v[64:65], v[64:65], v[88:89]
	v_pk_add_f32 v[62:63], v[62:63], v[66:67]
	s_waitcnt vmcnt(8)
	v_pk_add_f32 v[64:65], v[64:65], v[92:93]
	v_pk_add_f32 v[62:63], v[62:63], v[90:91]
	v_pk_add_f32 v[64:65], v[64:65], v[136:137]
	v_pk_add_f32 v[62:63], v[62:63], v[94:95]
	v_pk_add_f32 v[64:65], v[64:65], v[112:113]
	v_pk_add_f32 v[62:63], v[62:63], v[138:139]
	v_pk_add_f32 v[64:65], v[64:65], v[104:105]
	v_pk_add_f32 v[62:63], v[62:63], v[114:115]
	v_pk_add_f32 v[64:65], v[64:65], v[100:101]
	v_pk_add_f32 v[62:63], v[62:63], v[106:107]
	s_waitcnt vmcnt(7)
	v_pk_add_f32 v[64:65], v[64:65], v[72:73]
	v_pk_add_f32 v[62:63], v[62:63], v[102:103]
	s_waitcnt vmcnt(6)
	v_pk_add_f32 v[64:65], v[64:65], v[76:77]
	v_pk_add_f32 v[62:63], v[62:63], v[74:75]
	s_waitcnt vmcnt(5)
	v_pk_add_f32 v[64:65], v[64:65], v[80:81]
	v_pk_add_f32 v[62:63], v[62:63], v[78:79]
	s_waitcnt vmcnt(4)
	v_pk_add_f32 v[64:65], v[64:65], v[84:85]
	v_pk_add_f32 v[62:63], v[62:63], v[82:83]
	s_waitcnt vmcnt(3)
	v_pk_add_f32 v[64:65], v[64:65], v[96:97]
	v_pk_add_f32 v[62:63], v[62:63], v[86:87]
	s_waitcnt vmcnt(2)
	v_pk_add_f32 v[64:65], v[64:65], v[108:109]
	v_pk_add_f32 v[62:63], v[62:63], v[98:99]
	s_waitcnt vmcnt(1)
	v_pk_add_f32 v[64:65], v[64:65], v[116:117]
	v_pk_add_f32 v[62:63], v[62:63], v[110:111]
	s_waitcnt vmcnt(0)
	v_pk_add_f32 v[64:65], v[64:65], v[120:121]
	v_pk_add_f32 v[62:63], v[62:63], v[118:119]
	v_pk_add_f32 v[56:57], v[56:57], v[64:65]
	v_pk_add_f32 v[62:63], v[62:63], v[122:123]
	v_mul_f32_e32 v64, 0x3d372713, v56
	v_mul_f32_e32 v65, 0x3d372713, v57
	v_mul_f32_e32 v64, v56, v64
	v_mul_f32_e32 v65, v57, v65
	v_fma_f32 v64, v56, v64, v56
	v_fma_f32 v65, v57, v65, v57
	v_mul_f32_e32 v64, 0x3f4c422a, v64
	v_mul_f32_e32 v65, 0x3f4c422a, v65
	v_add_f32_e32 v64, v64, v64
	v_add_f32_e32 v65, v65, v65
	v_mul_f32_e32 v64, 0x3fb8aa3b, v64
	v_mul_f32_e32 v65, 0x3fb8aa3b, v65
	v_exp_f32_e32 v64, v64
	v_exp_f32_e32 v65, v65
	v_pk_add_f32 v[58:59], v[58:59], v[62:63]
	v_pk_mul_f32 v[56:57], v[56:57], 0.5 op_sel_hi:[1,0]
	v_mfma_f32_16x16x32_bf16 v[90:93], v[40:43], v[36:39], v[8:11]
	v_add_f32_e64 v64, v64, 1.0
	v_add_f32_e64 v65, v65, 1.0
	v_div_scale_f32 v66, s[0:1], v65, v65, 2.0
	v_rcp_f32_e32 v67, v66
	v_mfma_f32_16x16x32_bf16 v[8:11], v[28:31], v[16:19], v[4:7]
	v_fma_f32 v62, -v66, v67, 1.0
	v_fmac_f32_e32 v67, v62, v67
	v_div_scale_f32 v62, vcc, 2.0, v65, 2.0
	v_mul_f32_e32 v63, v62, v67
	v_fma_f32 v72, -v66, v63, v62
	v_fmac_f32_e32 v63, v72, v67
	v_fma_f32 v62, -v66, v63, v62
	v_div_scale_f32 v66, s[0:1], v64, v64, 2.0
	v_rcp_f32_e32 v72, v66
	v_div_fmas_f32 v62, v62, v67, v63
	v_div_fixup_f32 v63, v62, v65, 2.0
	v_mfma_f32_16x16x32_bf16 v[4:7], v[24:27], v[16:19], v[0:3]
	v_fma_f32 v62, -v66, v72, 1.0
	v_fmac_f32_e32 v72, v62, v72
	v_div_scale_f32 v62, vcc, 2.0, v64, 2.0
	v_mul_f32_e32 v65, v62, v72
	v_fma_f32 v67, -v66, v65, v62
	v_fmac_f32_e32 v65, v67, v72
	v_fma_f32 v62, -v66, v65, v62
	v_div_fmas_f32 v62, v62, v72, v65
	v_mul_f32_e32 v65, 0x3d372713, v58
	v_mul_f32_e32 v65, v58, v65
	v_fma_f32 v65, v58, v65, v58
	v_mul_f32_e32 v65, 0x3f4c422a, v65
	v_add_f32_e32 v65, v65, v65
	v_mul_f32_e32 v65, 0x3fb8aa3b, v65
	v_exp_f32_e32 v66, v65
	v_mul_f32_e32 v65, 0x3d372713, v59
	v_mul_f32_e32 v65, v59, v65
	v_fma_f32 v65, v59, v65, v59
	v_mul_f32_e32 v65, 0x3f4c422a, v65
	v_add_f32_e32 v65, v65, v65
	v_mul_f32_e32 v65, 0x3fb8aa3b, v65
	v_exp_f32_e32 v67, v65
	v_div_fixup_f32 v62, v62, v64, 2.0
	v_pk_add_f32 v[62:63], v[62:63], 1.0 op_sel_hi:[1,0] neg_lo:[1,0] neg_hi:[1,0]
	v_pk_mul_f32 v[58:59], v[58:59], 0.5 op_sel_hi:[1,0]
	v_pk_add_f32 v[64:65], v[66:67], 1.0 op_sel_hi:[1,0]
	v_pk_add_f32 v[62:63], v[62:63], 1.0 op_sel_hi:[1,0]
	v_div_scale_f32 v66, s[0:1], v65, v65, 2.0
	v_rcp_f32_e32 v67, v66
	v_pk_mul_f32 v[56:57], v[56:57], v[62:63]
	v_mfma_f32_16x16x32_bf16 v[0:3], v[20:23], v[16:19], v[90:93]
	v_cvt_pk_bf16_f32 v62, v56, v57
	v_fma_f32 v56, -v66, v67, 1.0
	v_fmac_f32_e32 v67, v56, v67
	v_div_scale_f32 v56, vcc, 2.0, v65, 2.0
	v_mul_f32_e32 v57, v56, v67
	v_fma_f32 v63, -v66, v57, v56
	v_fmac_f32_e32 v57, v63, v67
	v_div_scale_f32 v63, s[0:1], v64, v64, 2.0
	v_fma_f32 v56, -v66, v57, v56
	v_rcp_f32_e32 v66, v63
	v_div_fmas_f32 v56, v56, v67, v57
	v_div_fixup_f32 v57, v56, v65, 2.0
	v_permlane16_swap_b32_e32 v60, v62
	v_fma_f32 v56, -v63, v66, 1.0
	v_fmac_f32_e32 v66, v56, v66
	v_div_scale_f32 v56, vcc, 2.0, v64, 2.0
	v_mul_f32_e32 v65, v56, v66
	v_fma_f32 v67, -v63, v65, v56
	v_fmac_f32_e32 v65, v67, v66
	v_fma_f32 v56, -v63, v65, v56
	v_div_fmas_f32 v56, v56, v66, v65
	v_div_fixup_f32 v56, v56, v64, 2.0
	v_pk_add_f32 v[56:57], v[56:57], 1.0 op_sel_hi:[1,0] neg_lo:[1,0] neg_hi:[1,0]
	s_nop 0
	v_pk_add_f32 v[56:57], v[56:57], 1.0 op_sel_hi:[1,0]
	s_nop 0
	v_pk_mul_f32 v[56:57], v[58:59], v[56:57]
	s_nop 0
	v_cvt_pk_bf16_f32 v63, v56, v57
	v_or_b32_e32 v56, 32, v164
	v_ashrrev_i32_e32 v57, 31, v56
	v_lshlrev_b64 v[56:57], 9, v[56:57]
	v_lshl_add_u64 v[56:57], v[214:215], 0, v[56:57]
	v_lshl_add_u64 v[58:59], v[56:57], 0, v[166:167]
	v_permlane16_swap_b32_e32 v61, v63
	v_lshl_add_u64 v[56:57], v[56:57], 0, v[168:169]
	global_store_dwordx4 v[58:59], v[68:71], off sc0 sc1
	global_store_dwordx4 v[56:57], v[60:63], off sc0 sc1
	global_load_dwordx4 v[68:71], v212, s[16:17]
	s_nop 0
	global_load_dwordx4 v[72:75], v212, s[16:17] offset:1024
	global_load_dwordx4 v[76:79], v212, s[16:17] offset:2048
	global_load_dwordx4 v[80:83], v212, s[16:17] offset:3072
	global_load_dwordx4 v[86:89], v[216:217], off offset:-4096
	global_load_dwordx4 v[60:63], v[220:221], off offset:1024
	global_load_dwordx4 v[52:55], v[220:221], off offset:2048
	global_load_dwordx4 v[48:51], v[220:221], off offset:3072
	global_load_dwordx4 v[44:47], v[218:219], off offset:-4096
	global_load_dwordx4 v[56:59], v[216:217], off offset:1024
	global_load_dwordx4 v[64:67], v[216:217], off offset:2048
	global_load_dwordx4 v[32:35], v[216:217], off offset:3072
	global_load_dwordx4 v[36:39], v[218:219], off
	global_load_dwordx4 v[28:31], v[218:219], off offset:1024
	global_load_dwordx4 v[40:43], v[218:219], off offset:2048
	global_load_dwordx4 v[24:27], v[218:219], off offset:3072
	global_load_dwordx4 v[92:95], v[218:219], off offset:2112
	global_load_dwordx4 v[16:19], v212, s[16:17] offset:64
	global_load_dwordx4 v[20:23], v212, s[16:17] offset:1088
	global_load_dwordx4 v[96:99], v[218:219], off offset:3136
	s_waitcnt vmcnt(19)
; DI unsigned pack2(float a, float b) { v2f f = {a, b}; return __builtin_bit_cast(unsigned, __builtin_convertvector(f, v2bf)); }
; DI float fexp(float x) { return __builtin_amdgcn_exp2f(x * LOG2E); }
;   DI u32x2 pack(int, int, float a, float b, float c, float d, float&) const { u32x2 v; v.x = pack2(a, b); v.y = pack2(c, d); return v; }
; DI float gelu_tanh(float x) {
;   float u = 0.7978845608028654f * (x + 0.044715f * x * x * x);
;   float t = 1.f - 2.f / (fexp(2.f * u) + 1.f);
;   return 0.5f * x * (1.f + t);
; }
;   DI u32x2 pack(int m, int n, float a, float b, float c, float d, float& ss) const {
;     f32x4 bs = {0.f, 0.f, 0.f, 0.f};
; #pragma unroll
;     for (int kc = 0; kc < 16; ++kc) bs += *(const f32x4*)(bias_part + kc * 256 + n);
;     u32x2 v; v.x = pack2(gelu_tanh(a + bs[0]), gelu_tanh(b + bs[1])); v.y = pack2(gelu_tanh(c + bs[2]), gelu_tanh(d + bs[3]));
;     return v;
;   }
	v_pk_add_f32 v[70:71], v[70:71], 0 op_sel_hi:[1,0]
	v_pk_add_f32 v[68:69], v[68:69], 0 op_sel_hi:[1,0]
	s_waitcnt vmcnt(18)
	v_pk_add_f32 v[74:75], v[70:71], v[74:75]
	v_pk_add_f32 v[72:73], v[68:69], v[72:73]
	s_waitcnt vmcnt(17)
	v_pk_add_f32 v[78:79], v[74:75], v[78:79]
	v_pk_add_f32 v[76:77], v[72:73], v[76:77]
	s_waitcnt vmcnt(16)
	v_pk_add_f32 v[82:83], v[78:79], v[82:83]
	v_pk_add_f32 v[80:81], v[76:77], v[80:81]
	s_waitcnt vmcnt(15)
	v_pk_add_f32 v[84:85], v[82:83], v[88:89]
	v_pk_add_f32 v[86:87], v[80:81], v[86:87]
	s_waitcnt vmcnt(14)
	v_pk_add_f32 v[84:85], v[84:85], v[62:63]
	v_pk_add_f32 v[86:87], v[86:87], v[60:61]
	s_waitcnt vmcnt(13)
	v_pk_add_f32 v[84:85], v[84:85], v[54:55]
	v_pk_add_f32 v[86:87], v[86:87], v[52:53]
	s_waitcnt vmcnt(12)
	v_pk_add_f32 v[84:85], v[84:85], v[50:51]
	v_pk_add_f32 v[86:87], v[86:87], v[48:49]
	s_waitcnt vmcnt(11)
	v_pk_add_f32 v[84:85], v[84:85], v[46:47]
	v_pk_add_f32 v[86:87], v[86:87], v[44:45]
	s_waitcnt vmcnt(10)
	v_pk_add_f32 v[84:85], v[84:85], v[58:59]
	v_pk_add_f32 v[86:87], v[86:87], v[56:57]
	s_waitcnt vmcnt(9)
	v_pk_add_f32 v[100:101], v[84:85], v[66:67]
	v_pk_add_f32 v[84:85], v[86:87], v[64:65]
	global_load_dwordx4 v[68:71], v212, s[16:17] offset:2112
	global_load_dwordx4 v[72:75], v212, s[16:17] offset:3136
	s_waitcnt vmcnt(10)
	v_pk_add_f32 v[32:33], v[84:85], v[32:33]
	global_load_dwordx4 v[60:63], v[220:221], off offset:1216
	s_waitcnt vmcnt(10)
	v_pk_add_f32 v[32:33], v[32:33], v[36:37]
	global_load_dwordx4 v[76:79], v[216:217], off offset:64
	global_load_dwordx4 v[44:47], v[216:217], off offset:1088
	s_waitcnt vmcnt(11)
	v_pk_add_f32 v[28:29], v[32:33], v[28:29]
	global_load_dwordx4 v[56:59], v[216:217], off offset:2112
	global_load_dwordx4 v[64:67], v[216:217], off offset:3136
	s_waitcnt vmcnt(12)
	v_pk_add_f32 v[28:29], v[28:29], v[40:41]
	global_load_dwordx4 v[84:87], v[218:219], off offset:64
	global_load_dwordx4 v[88:91], v[218:219], off offset:1088
	s_waitcnt vmcnt(13)
	v_pk_add_f32 v[24:25], v[28:29], v[24:25]
	v_pk_add_f32 v[28:29], v[100:101], v[34:35]
	v_pk_add_f32 v[12:13], v[12:13], v[24:25]
	v_pk_add_f32 v[28:29], v[28:29], v[38:39]
	v_mul_f32_e32 v24, 0x3d372713, v12
	v_mul_f32_e32 v25, 0x3d372713, v13
	v_mul_f32_e32 v24, v12, v24
	v_mul_f32_e32 v25, v13, v25
	v_fma_f32 v24, v12, v24, v12
	v_fma_f32 v25, v13, v25, v13
	v_mul_f32_e32 v24, 0x3f4c422a, v24
	v_mul_f32_e32 v25, 0x3f4c422a, v25
	v_add_f32_e32 v24, v24, v24
	v_add_f32_e32 v25, v25, v25
	v_mul_f32_e32 v24, 0x3fb8aa3b, v24
	v_mul_f32_e32 v25, 0x3fb8aa3b, v25
	v_exp_f32_e32 v24, v24
	v_exp_f32_e32 v25, v25
	v_pk_add_f32 v[28:29], v[28:29], v[30:31]
	v_pk_mul_f32 v[12:13], v[12:13], 0.5 op_sel_hi:[1,0]
	s_waitcnt vmcnt(11)
	v_pk_add_f32 v[16:17], v[16:17], 0 op_sel_hi:[1,0]
	v_pk_add_f32 v[40:41], v[24:25], 1.0 op_sel_hi:[1,0]
	v_pk_add_f32 v[24:25], v[28:29], v[42:43]
	v_div_scale_f32 v30, s[0:1], v41, v41, 2.0
	v_rcp_f32_e32 v31, v30
	v_pk_add_f32 v[24:25], v[24:25], v[26:27]
	v_div_scale_f32 v42, s[0:1], v40, v40, 2.0
	v_pk_add_f32 v[14:15], v[14:15], v[24:25]
	v_fma_f32 v24, -v30, v31, 1.0
	v_fmac_f32_e32 v31, v24, v31
	v_div_scale_f32 v24, vcc, 2.0, v41, 2.0
	v_mul_f32_e32 v28, v24, v31
	v_fma_f32 v25, -v30, v28, v24
	v_rcp_f32_e32 v43, v42
	v_fmac_f32_e32 v28, v25, v31
	v_fma_f32 v29, -v30, v28, v24
	global_load_dwordx4 v[24:27], v[220:221], off offset:64
	v_div_fmas_f32 v32, v29, v31, v28
	global_load_dwordx4 v[28:31], v[220:221], off offset:1088
	v_div_fixup_f32 v41, v32, v41, 2.0
	v_fma_f32 v36, -v42, v43, 1.0
	global_load_dwordx4 v[32:35], v[220:221], off offset:2112
	v_fmac_f32_e32 v43, v36, v43
	global_load_dwordx4 v[36:39], v[220:221], off offset:3136
	v_div_scale_f32 v100, vcc, 2.0, v40, 2.0
	v_mul_f32_e32 v101, v100, v43
	v_fma_f32 v102, -v42, v101, v100
	v_fmac_f32_e32 v101, v102, v43
	v_fma_f32 v42, -v42, v101, v100
	v_div_fmas_f32 v100, v42, v43, v101
	v_mul_f32_e32 v42, 0x3d372713, v14
	v_mul_f32_e32 v43, 0x3d372713, v15
	v_mul_f32_e32 v42, v14, v42
	v_mul_f32_e32 v43, v15, v43
	v_fma_f32 v42, v14, v42, v14
	v_fma_f32 v43, v15, v43, v15
	v_mul_f32_e32 v42, 0x3f4c422a, v42
	v_mul_f32_e32 v43, 0x3f4c422a, v43
	v_add_f32_e32 v42, v42, v42
	v_add_f32_e32 v43, v43, v43
	v_mul_f32_e32 v42, 0x3fb8aa3b, v42
	v_mul_f32_e32 v43, 0x3fb8aa3b, v43
	v_exp_f32_e32 v42, v42
	v_exp_f32_e32 v43, v43
	v_div_fixup_f32 v40, v100, v40, 2.0
	v_pk_add_f32 v[40:41], v[40:41], 1.0 op_sel_hi:[1,0] neg_lo:[1,0] neg_hi:[1,0]
	v_pk_mul_f32 v[14:15], v[14:15], 0.5 op_sel_hi:[1,0]
	v_pk_add_f32 v[42:43], v[42:43], 1.0 op_sel_hi:[1,0]
	v_pk_add_f32 v[40:41], v[40:41], 1.0 op_sel_hi:[1,0]
	v_div_scale_f32 v100, s[0:1], v43, v43, 2.0
	v_rcp_f32_e32 v101, v100
	v_pk_mul_f32 v[12:13], v[12:13], v[40:41]
	s_waitcnt vmcnt(14)
	v_pk_add_f32 v[16:17], v[16:17], v[20:21]
	v_cvt_pk_bf16_f32 v12, v12, v13
	v_fma_f32 v13, -v100, v101, 1.0
	v_fmac_f32_e32 v101, v13, v101
	v_div_scale_f32 v13, vcc, 2.0, v43, 2.0
	v_mul_f32_e32 v40, v13, v101
	v_fma_f32 v41, -v100, v40, v13
	v_fmac_f32_e32 v40, v41, v101
	v_fma_f32 v13, -v100, v40, v13
	v_div_scale_f32 v100, s[0:1], v42, v42, 2.0
	v_rcp_f32_e32 v102, v100
	v_div_fmas_f32 v13, v13, v101, v40
	v_div_fixup_f32 v41, v13, v43, 2.0
	s_waitcnt vmcnt(12)
	v_pk_add_f32 v[16:17], v[16:17], v[68:69]
	v_fma_f32 v13, -v100, v102, 1.0
	v_fmac_f32_e32 v102, v13, v102
	v_div_scale_f32 v13, vcc, 2.0, v42, 2.0
	v_mul_f32_e32 v40, v13, v102
	v_fma_f32 v43, -v100, v40, v13
	v_fmac_f32_e32 v40, v43, v102
	v_fma_f32 v13, -v100, v40, v13
	v_div_fmas_f32 v13, v13, v102, v40
	v_div_fixup_f32 v40, v13, v42, 2.0
	v_pk_add_f32 v[40:41], v[40:41], 1.0 op_sel_hi:[1,0] neg_lo:[1,0] neg_hi:[1,0]
	s_waitcnt vmcnt(11)
; DI unsigned pack2(float a, float b) { v2f f = {a, b}; return __builtin_bit_cast(unsigned, __builtin_convertvector(f, v2bf)); }
; DI float fexp(float x) { return __builtin_amdgcn_exp2f(x * LOG2E); }
;   DI u32x2 pack(int, int, float a, float b, float c, float d, float&) const { u32x2 v; v.x = pack2(a, b); v.y = pack2(c, d); return v; }
; DI float gelu_tanh(float x) {
;   float u = 0.7978845608028654f * (x + 0.044715f * x * x * x);
;   float t = 1.f - 2.f / (fexp(2.f * u) + 1.f);
;   return 0.5f * x * (1.f + t);
; }
;   DI u32x2 pack(int m, int n, float a, float b, float c, float d, float& ss) const {
;     f32x4 bs = {0.f, 0.f, 0.f, 0.f};
; #pragma unroll
;     for (int kc = 0; kc < 16; ++kc) bs += *(const f32x4*)(bias_part + kc * 256 + n);
;     u32x2 v; v.x = pack2(gelu_tanh(a + bs[0]), gelu_tanh(b + bs[1])); v.y = pack2(gelu_tanh(c + bs[2]), gelu_tanh(d + bs[3]));
;     return v;
;   }
	v_pk_add_f32 v[20:21], v[16:17], v[72:73]
	v_pk_add_f32 v[40:41], v[40:41], 1.0 op_sel_hi:[1,0]
	global_load_dwordx4 v[80:83], v[220:221], off offset:192
	v_pk_mul_f32 v[14:15], v[14:15], v[40:41]
	global_load_dwordx4 v[40:43], v212, s[16:17] offset:3200
	v_cvt_pk_bf16_f32 v13, v14, v15
	v_pk_add_f32 v[14:15], v[18:19], 0 op_sel_hi:[1,0]
	global_load_dwordx4 v[16:19], v[220:221], off offset:128
	v_pk_add_f32 v[14:15], v[14:15], v[22:23]
	global_load_dwordx4 v[52:55], v[220:221], off offset:2240
	v_pk_add_f32 v[14:15], v[14:15], v[70:71]
	global_load_dwordx4 v[48:51], v[220:221], off offset:3264
	v_pk_add_f32 v[14:15], v[14:15], v[74:75]
	s_waitcnt vmcnt(8)
	v_pk_add_f32 v[24:25], v[20:21], v[24:25]
	global_load_dwordx4 v[20:23], v[220:221], off offset:1152
	s_waitcnt vmcnt(8)
	v_pk_add_f32 v[28:29], v[24:25], v[28:29]
	v_pk_add_f32 v[14:15], v[14:15], v[26:27]
	global_load_dwordx4 v[24:27], v[220:221], off offset:2176
	s_waitcnt vmcnt(8)
	v_pk_add_f32 v[32:33], v[28:29], v[32:33]
	v_pk_add_f32 v[14:15], v[14:15], v[30:31]
	global_load_dwordx4 v[28:31], v[220:221], off offset:3200
	s_waitcnt vmcnt(8)
	v_pk_add_f32 v[32:33], v[32:33], v[36:37]
	v_pk_add_f32 v[14:15], v[14:15], v[34:35]
	v_pk_add_f32 v[32:33], v[32:33], v[76:77]
	v_pk_add_f32 v[14:15], v[14:15], v[38:39]
	v_pk_add_f32 v[32:33], v[32:33], v[44:45]
	v_pk_add_f32 v[14:15], v[14:15], v[78:79]
	v_pk_add_f32 v[32:33], v[32:33], v[56:57]
	v_pk_add_f32 v[14:15], v[14:15], v[46:47]
	v_pk_add_f32 v[32:33], v[32:33], v[64:65]
	v_pk_add_f32 v[14:15], v[14:15], v[58:59]
	v_pk_add_f32 v[32:33], v[32:33], v[84:85]
	v_pk_add_f32 v[14:15], v[14:15], v[66:67]
	v_pk_add_f32 v[32:33], v[32:33], v[88:89]
	v_pk_add_f32 v[14:15], v[14:15], v[86:87]
	v_pk_add_f32 v[32:33], v[32:33], v[92:93]
	v_pk_add_f32 v[14:15], v[14:15], v[90:91]
	v_pk_add_f32 v[32:33], v[32:33], v[96:97]
	global_load_dwordx4 v[36:39], v212, s[16:17] offset:2176
	v_pk_add_f32 v[92:93], v[8:9], v[32:33]
	s_nop 0
	v_mul_f32_e32 v8, 0x3d372713, v92
	v_mul_f32_e32 v9, 0x3d372713, v93
	v_mul_f32_e32 v8, v92, v8
	v_mul_f32_e32 v9, v93, v9
	v_fma_f32 v8, v92, v8, v92
	v_fma_f32 v9, v93, v9, v93
	v_mul_f32_e32 v8, 0x3f4c422a, v8
	v_mul_f32_e32 v9, 0x3f4c422a, v9
	v_add_f32_e32 v8, v8, v8
	v_add_f32_e32 v9, v9, v9
	v_mul_f32_e32 v8, 0x3fb8aa3b, v8
	v_mul_f32_e32 v9, 0x3fb8aa3b, v9
	v_exp_f32_e32 v8, v8
	v_exp_f32_e32 v9, v9
	v_pk_mul_f32 v[92:93], v[92:93], 0.5 op_sel_hi:[1,0]
	v_pk_add_f32 v[96:97], v[8:9], 1.0 op_sel_hi:[1,0]
	s_nop 0
	v_div_scale_f32 v32, s[0:1], v97, v97, 2.0
	v_rcp_f32_e32 v33, v32
	v_pk_add_f32 v[8:9], v[14:15], v[94:95]
	v_div_scale_f32 v44, s[0:1], v96, v96, 2.0
	v_pk_add_f32 v[8:9], v[8:9], v[98:99]
	v_rcp_f32_e32 v45, v44
	v_pk_add_f32 v[94:95], v[10:11], v[8:9]
	v_fma_f32 v8, -v32, v33, 1.0
	v_fmac_f32_e32 v33, v8, v33
	v_div_scale_f32 v8, vcc, 2.0, v97, 2.0
	v_mul_f32_e32 v14, v8, v33
	v_fma_f32 v9, -v32, v14, v8
	v_fmac_f32_e32 v14, v9, v33
	v_fma_f32 v15, -v32, v14, v8
	v_div_fmas_f32 v14, v15, v33, v14
	v_div_fixup_f32 v15, v14, v97, 2.0
	v_fma_f32 v14, -v44, v45, 1.0
	global_load_dwordx4 v[8:11], v212, s[16:17] offset:128
	v_fmac_f32_e32 v45, v14, v45
	v_div_scale_f32 v14, vcc, 2.0, v96, 2.0
	global_load_dwordx4 v[32:35], v212, s[16:17] offset:1152
	v_mul_f32_e32 v46, v14, v45
	v_fma_f32 v47, -v44, v46, v14
	v_fmac_f32_e32 v46, v47, v45
	v_fma_f32 v14, -v44, v46, v14
	v_mul_f32_e32 v44, 0x3d372713, v94
	v_mul_f32_e32 v44, v94, v44
	v_fma_f32 v56, v94, v44, v94
	v_mul_f32_e32 v56, 0x3f4c422a, v56
	v_div_fmas_f32 v14, v14, v45, v46
	global_load_dwordx4 v[44:47], v[216:217], off offset:128
	v_add_f32_e32 v64, v56, v56
	global_load_dwordx4 v[56:59], v[216:217], off offset:1152
	v_mul_f32_e32 v64, 0x3fb8aa3b, v64
	v_exp_f32_e32 v98, v64
	global_load_dwordx4 v[64:67], v[216:217], off offset:2176
	v_mul_f32_e32 v68, 0x3d372713, v95
	v_mul_f32_e32 v72, v95, v68
	global_load_dwordx4 v[68:71], v[216:217], off offset:3200
	v_fma_f32 v76, v95, v72, v95
	global_load_dwordx4 v[72:75], v[218:219], off offset:128
	v_mul_f32_e32 v84, 0x3f4c422a, v76
	global_load_dwordx4 v[76:79], v[218:219], off offset:1152
	v_add_f32_e32 v88, v84, v84
	global_load_dwordx4 v[84:87], v[218:219], off offset:2176
	v_mul_f32_e32 v97, 0x3fb8aa3b, v88
	global_load_dwordx4 v[88:91], v[218:219], off offset:3200
	v_exp_f32_e32 v99, v97
	v_div_fixup_f32 v14, v14, v96, 2.0
	v_pk_add_f32 v[14:15], v[14:15], 1.0 op_sel_hi:[1,0] neg_lo:[1,0] neg_hi:[1,0]
	v_pk_mul_f32 v[94:95], v[94:95], 0.5 op_sel_hi:[1,0]
	v_pk_add_f32 v[96:97], v[98:99], 1.0 op_sel_hi:[1,0]
	v_pk_add_f32 v[14:15], v[14:15], 1.0 op_sel_hi:[1,0]
	v_div_scale_f32 v98, s[0:1], v97, v97, 2.0
	v_rcp_f32_e32 v99, v98
	v_pk_mul_f32 v[14:15], v[92:93], v[14:15]
	s_nop 0
	v_cvt_pk_bf16_f32 v14, v14, v15
	v_fma_f32 v15, -v98, v99, 1.0
	v_fmac_f32_e32 v99, v15, v99
	v_div_scale_f32 v15, vcc, 2.0, v97, 2.0
	v_mul_f32_e32 v92, v15, v99
	v_fma_f32 v93, -v98, v92, v15
	v_fmac_f32_e32 v92, v93, v99
	v_fma_f32 v15, -v98, v92, v15
	v_div_scale_f32 v98, s[0:1], v96, v96, 2.0
	v_rcp_f32_e32 v100, v98
	v_div_fmas_f32 v15, v15, v99, v92
	v_div_fixup_f32 v93, v15, v97, 2.0
	v_permlane16_swap_b32_e32 v12, v14
	v_fma_f32 v15, -v98, v100, 1.0
	v_fmac_f32_e32 v100, v15, v100
	v_div_scale_f32 v15, vcc, 2.0, v96, 2.0
	v_mul_f32_e32 v92, v15, v100
	v_fma_f32 v97, -v98, v92, v15
	v_fmac_f32_e32 v92, v97, v100
	v_fma_f32 v15, -v98, v92, v15
	v_div_fmas_f32 v15, v15, v100, v92
	v_div_fixup_f32 v92, v15, v96, 2.0
	v_pk_add_f32 v[92:93], v[92:93], 1.0 op_sel_hi:[1,0] neg_lo:[1,0] neg_hi:[1,0]
	s_nop 0
	v_pk_add_f32 v[92:93], v[92:93], 1.0 op_sel_hi:[1,0]
	s_nop 0
	v_pk_mul_f32 v[92:93], v[94:95], v[92:93]
	s_nop 0
	v_cvt_pk_bf16_f32 v15, v92, v93
	global_load_dwordx4 v[92:95], v212, s[16:17] offset:192
	s_nop 0
	v_permlane16_swap_b32_e32 v13, v15
	s_waitcnt vmcnt(10)
; DI unsigned pack2(float a, float b) { v2f f = {a, b}; return __builtin_bit_cast(unsigned, __builtin_convertvector(f, v2bf)); }
; DI float fexp(float x) { return __builtin_amdgcn_exp2f(x * LOG2E); }
;   DI u32x2 pack(int, int, float a, float b, float c, float d, float&) const { u32x2 v; v.x = pack2(a, b); v.y = pack2(c, d); return v; }
; DI float gelu_tanh(float x) {
;   float u = 0.7978845608028654f * (x + 0.044715f * x * x * x);
;   float t = 1.f - 2.f / (fexp(2.f * u) + 1.f);
;   return 0.5f * x * (1.f + t);
; }
;   DI u32x2 pack(int m, int n, float a, float b, float c, float d, float& ss) const {
;     f32x4 bs = {0.f, 0.f, 0.f, 0.f};
; #pragma unroll
;     for (int kc = 0; kc < 16; ++kc) bs += *(const f32x4*)(bias_part + kc * 256 + n);
;     u32x2 v; v.x = pack2(gelu_tanh(a + bs[0]), gelu_tanh(b + bs[1])); v.y = pack2(gelu_tanh(c + bs[2]), gelu_tanh(d + bs[3]));
;     return v;
;   }
	v_pk_add_f32 v[98:99], v[8:9], 0 op_sel_hi:[1,0]
	v_pk_add_f32 v[96:97], v[10:11], 0 op_sel_hi:[1,0]
	global_load_dwordx4 v[8:11], v212, s[16:17] offset:1216
	s_waitcnt vmcnt(10)
	v_pk_add_f32 v[98:99], v[98:99], v[32:33]
	v_pk_add_f32 v[96:97], v[96:97], v[34:35]
	global_load_dwordx4 v[32:35], v212, s[16:17] offset:2240
	v_pk_add_f32 v[98:99], v[98:99], v[36:37]
	v_pk_add_f32 v[96:97], v[96:97], v[38:39]
	global_load_dwordx4 v[36:39], v212, s[16:17] offset:3264
	v_pk_add_f32 v[40:41], v[98:99], v[40:41]
	v_pk_add_f32 v[42:43], v[96:97], v[42:43]
	v_pk_add_f32 v[16:17], v[40:41], v[16:17]
	v_pk_add_f32 v[18:19], v[42:43], v[18:19]
	v_pk_add_f32 v[16:17], v[16:17], v[20:21]
	v_pk_add_f32 v[18:19], v[18:19], v[22:23]
	v_pk_add_f32 v[16:17], v[16:17], v[24:25]
	v_pk_add_f32 v[18:19], v[18:19], v[26:27]
	v_pk_add_f32 v[22:23], v[16:17], v[28:29]
	v_pk_add_f32 v[20:21], v[18:19], v[30:31]
	global_load_dwordx4 v[16:19], v[216:217], off offset:192
	s_waitcnt vmcnt(12)
	v_pk_add_f32 v[26:27], v[22:23], v[44:45]
	v_pk_add_f32 v[24:25], v[20:21], v[46:47]
	global_load_dwordx4 v[20:23], v[216:217], off offset:1216
	s_waitcnt vmcnt(12)
	v_pk_add_f32 v[30:31], v[26:27], v[56:57]
	v_pk_add_f32 v[28:29], v[24:25], v[58:59]
	global_load_dwordx4 v[24:27], v[216:217], off offset:2240
	s_waitcnt vmcnt(12)
	v_pk_add_f32 v[40:41], v[30:31], v[64:65]
	v_pk_add_f32 v[96:97], v[28:29], v[66:67]
	global_load_dwordx4 v[28:31], v[216:217], off offset:3264
	s_waitcnt vmcnt(12)
	v_pk_add_f32 v[44:45], v[40:41], v[68:69]
	global_load_dwordx4 v[40:43], v[218:219], off offset:192
	s_waitcnt vmcnt(12)
	v_pk_add_f32 v[56:57], v[44:45], v[72:73]
	global_load_dwordx4 v[44:47], v[218:219], off offset:1216
	s_waitcnt vmcnt(12)
	v_pk_add_f32 v[64:65], v[56:57], v[76:77]
	global_load_dwordx4 v[56:59], v[218:219], off offset:2240
	s_waitcnt vmcnt(12)
	v_pk_add_f32 v[68:69], v[64:65], v[84:85]
	global_load_dwordx4 v[64:67], v[218:219], off offset:3264
	s_waitcnt vmcnt(12)
	v_pk_add_f32 v[68:69], v[68:69], v[88:89]
	v_pk_add_f32 v[70:71], v[96:97], v[70:71]
	v_pk_add_f32 v[4:5], v[4:5], v[68:69]
	v_pk_add_f32 v[70:71], v[70:71], v[74:75]
	v_mul_f32_e32 v68, 0x3d372713, v4
	v_mul_f32_e32 v69, 0x3d372713, v5
	v_mul_f32_e32 v68, v4, v68
	v_mul_f32_e32 v69, v5, v69
	v_fma_f32 v68, v4, v68, v4
	v_fma_f32 v69, v5, v69, v5
	v_mul_f32_e32 v68, 0x3f4c422a, v68
	v_mul_f32_e32 v69, 0x3f4c422a, v69
	v_add_f32_e32 v68, v68, v68
	v_add_f32_e32 v69, v69, v69
	v_mul_f32_e32 v68, 0x3fb8aa3b, v68
	v_mul_f32_e32 v69, 0x3fb8aa3b, v69
	v_exp_f32_e32 v68, v68
	v_exp_f32_e32 v69, v69
	v_pk_add_f32 v[70:71], v[70:71], v[78:79]
	v_pk_mul_f32 v[4:5], v[4:5], 0.5 op_sel_hi:[1,0]
	v_pk_add_f32 v[70:71], v[70:71], v[86:87]
	v_pk_add_f32 v[68:69], v[68:69], 1.0 op_sel_hi:[1,0]
	v_pk_add_f32 v[70:71], v[70:71], v[90:91]
	v_div_scale_f32 v72, s[0:1], v69, v69, 2.0
	v_rcp_f32_e32 v73, v72
	v_pk_add_f32 v[6:7], v[6:7], v[70:71]
	v_fma_f32 v70, -v72, v73, 1.0
	v_fmac_f32_e32 v73, v70, v73
	v_div_scale_f32 v70, vcc, 2.0, v69, 2.0
	v_mul_f32_e32 v71, v70, v73
	v_fma_f32 v74, -v72, v71, v70
	v_fmac_f32_e32 v71, v74, v73
	v_fma_f32 v70, -v72, v71, v70
	v_div_scale_f32 v72, s[0:1], v68, v68, 2.0
	v_rcp_f32_e32 v74, v72
	v_div_fmas_f32 v70, v70, v73, v71
	v_div_fixup_f32 v69, v70, v69, 2.0
	v_fma_f32 v70, -v72, v74, 1.0
	v_fmac_f32_e32 v74, v70, v74
	v_div_scale_f32 v70, vcc, 2.0, v68, 2.0
	v_mul_f32_e32 v71, v70, v74
	v_fma_f32 v73, -v72, v71, v70
	v_fmac_f32_e32 v71, v73, v74
	v_fma_f32 v70, -v72, v71, v70
	v_div_fmas_f32 v72, v70, v74, v71
	v_mul_f32_e32 v70, 0x3d372713, v6
	v_mul_f32_e32 v71, 0x3d372713, v7
	v_mul_f32_e32 v70, v6, v70
	v_mul_f32_e32 v71, v7, v71
	v_fma_f32 v70, v6, v70, v6
	v_fma_f32 v71, v7, v71, v7
	v_mul_f32_e32 v70, 0x3f4c422a, v70
	v_mul_f32_e32 v71, 0x3f4c422a, v71
	v_add_f32_e32 v70, v70, v70
	v_add_f32_e32 v71, v71, v71
	v_mul_f32_e32 v70, 0x3fb8aa3b, v70
	v_mul_f32_e32 v71, 0x3fb8aa3b, v71
	v_exp_f32_e32 v70, v70
	v_exp_f32_e32 v71, v71
	v_div_fixup_f32 v68, v72, v68, 2.0
	v_pk_add_f32 v[68:69], v[68:69], 1.0 op_sel_hi:[1,0] neg_lo:[1,0] neg_hi:[1,0]
	v_pk_mul_f32 v[6:7], v[6:7], 0.5 op_sel_hi:[1,0]
	v_pk_add_f32 v[70:71], v[70:71], 1.0 op_sel_hi:[1,0]
	v_pk_add_f32 v[68:69], v[68:69], 1.0 op_sel_hi:[1,0]
	v_div_scale_f32 v72, s[0:1], v71, v71, 2.0
	v_rcp_f32_e32 v73, v72
	v_pk_mul_f32 v[4:5], v[4:5], v[68:69]
	s_nop 0
	v_cvt_pk_bf16_f32 v4, v4, v5
	v_fma_f32 v5, -v72, v73, 1.0
	v_fmac_f32_e32 v73, v5, v73
	v_div_scale_f32 v5, vcc, 2.0, v71, 2.0
	v_mul_f32_e32 v68, v5, v73
	v_fma_f32 v69, -v72, v68, v5
	v_fmac_f32_e32 v68, v69, v73
	v_fma_f32 v5, -v72, v68, v5
	v_div_scale_f32 v72, s[0:1], v70, v70, 2.0
	v_rcp_f32_e32 v74, v72
	v_div_fmas_f32 v5, v5, v73, v68
	v_div_fixup_f32 v69, v5, v71, 2.0
	v_fma_f32 v5, -v72, v74, 1.0
	v_fmac_f32_e32 v74, v5, v74
	v_div_scale_f32 v5, vcc, 2.0, v70, 2.0
	v_mul_f32_e32 v68, v5, v74
	v_fma_f32 v71, -v72, v68, v5
	v_fmac_f32_e32 v68, v71, v74
	v_fma_f32 v5, -v72, v68, v5
	v_div_fmas_f32 v5, v5, v74, v68
	v_div_fixup_f32 v68, v5, v70, 2.0
	v_pk_add_f32 v[68:69], v[68:69], 1.0 op_sel_hi:[1,0] neg_lo:[1,0] neg_hi:[1,0]
	s_nop 0
	v_pk_add_f32 v[68:69], v[68:69], 1.0 op_sel_hi:[1,0]
	s_nop 0
	v_pk_mul_f32 v[6:7], v[6:7], v[68:69]
	s_waitcnt vmcnt(11)
; DI unsigned pack2(float a, float b) { v2f f = {a, b}; return __builtin_bit_cast(unsigned, __builtin_convertvector(f, v2bf)); }
;   DI u32x2 pack(int, int, float a, float b, float c, float d, float&) const { u32x2 v; v.x = pack2(a, b); v.y = pack2(c, d); return v; }
; template <class ARow, class Epi>
; DI void gemm_tile(const ARow& arow, long a_kstride, const u16* __restrict__ Bt, long ldb, int K, int m0, int n0,
;                   const Epi& epi, char* smem) {
;     ...
;       for (int ni = 0; ni < 4; ++ni) pk[ni] = epi.pack(m, nh + ni * 16 + fq * 4, acc[ni][mi][0], acc[ni][mi][1], acc[ni][mi][2], acc[ni][mi][3], ss);
;       epi.finish16(m, nh, ss);
;       u16* rp = epi.rowp(m) + nh;
; #pragma unroll
;       for (int pp = 0; pp < 2; ++pp) {
;         u32x2 a = pk[2 * pp], b = pk[2 * pp + 1];
;         const u32x2 rx = __builtin_amdgcn_permlane16_swap(a.x, b.x, false, false);
;         const u32x2 ry = __builtin_amdgcn_permlane16_swap(a.y, b.y, false, false);
;         const int nst = (fq & 1) ? ((2 * pp + 1) * 16 + (fq - 1) * 4) : ((2 * pp) * 16 + fq * 4);
;         *(u32x4*)(rp + nst) = (u32x4){rx[0], ry[0], rx[1], ry[1]};
;   DI u32x2 pack(int m, int n, float a, float b, float c, float d, float& ss) const {
;     f32x4 bs = {0.f, 0.f, 0.f, 0.f};
; #pragma unroll
;     for (int kc = 0; kc < 16; ++kc) bs += *(const f32x4*)(bias_part + kc * 256 + n);
;     u32x2 v; v.x = pack2(gelu_tanh(a + bs[0]), gelu_tanh(b + bs[1])); v.y = pack2(gelu_tanh(c + bs[2]), gelu_tanh(d + bs[3]));
;     return v;
;   }
	v_pk_add_f32 v[68:69], v[92:93], 0 op_sel_hi:[1,0]
	v_cvt_pk_bf16_f32 v5, v6, v7
	s_waitcnt vmcnt(10)
	v_pk_add_f32 v[8:9], v[68:69], v[8:9]
	v_pk_add_f32 v[6:7], v[94:95], 0 op_sel_hi:[1,0]
	s_waitcnt vmcnt(9)
	v_pk_add_f32 v[8:9], v[8:9], v[32:33]
	v_pk_add_f32 v[6:7], v[6:7], v[10:11]
	s_waitcnt vmcnt(8)
	v_pk_add_f32 v[8:9], v[8:9], v[36:37]
	v_pk_add_f32 v[6:7], v[6:7], v[34:35]
	v_pk_add_f32 v[8:9], v[8:9], v[80:81]
	v_pk_add_f32 v[6:7], v[6:7], v[38:39]
	v_pk_add_f32 v[8:9], v[8:9], v[60:61]
	v_pk_add_f32 v[6:7], v[6:7], v[82:83]
	v_pk_add_f32 v[8:9], v[8:9], v[52:53]
	v_pk_add_f32 v[6:7], v[6:7], v[62:63]
	v_pk_add_f32 v[8:9], v[8:9], v[48:49]
	v_pk_add_f32 v[6:7], v[6:7], v[54:55]
	s_waitcnt vmcnt(7)
	v_pk_add_f32 v[8:9], v[8:9], v[16:17]
	v_pk_add_f32 v[6:7], v[6:7], v[50:51]
	s_waitcnt vmcnt(6)
	v_pk_add_f32 v[8:9], v[8:9], v[20:21]
	v_pk_add_f32 v[6:7], v[6:7], v[18:19]
	s_waitcnt vmcnt(5)
	v_pk_add_f32 v[8:9], v[8:9], v[24:25]
	v_pk_add_f32 v[6:7], v[6:7], v[22:23]
	s_waitcnt vmcnt(4)
	v_pk_add_f32 v[8:9], v[8:9], v[28:29]
	v_pk_add_f32 v[6:7], v[6:7], v[26:27]
	s_waitcnt vmcnt(3)
	v_pk_add_f32 v[8:9], v[8:9], v[40:41]
	v_pk_add_f32 v[6:7], v[6:7], v[30:31]
	s_waitcnt vmcnt(2)
	v_pk_add_f32 v[8:9], v[8:9], v[44:45]
	v_pk_add_f32 v[6:7], v[6:7], v[42:43]
	s_waitcnt vmcnt(1)
	v_pk_add_f32 v[8:9], v[8:9], v[56:57]
	v_pk_add_f32 v[6:7], v[6:7], v[46:47]
	s_waitcnt vmcnt(0)
	v_pk_add_f32 v[8:9], v[8:9], v[64:65]
	v_pk_add_f32 v[6:7], v[6:7], v[58:59]
	v_pk_add_f32 v[0:1], v[0:1], v[8:9]
	v_pk_add_f32 v[6:7], v[6:7], v[66:67]
	v_mul_f32_e32 v8, 0x3d372713, v0
	v_mul_f32_e32 v9, 0x3d372713, v1
	v_mul_f32_e32 v8, v0, v8
	v_mul_f32_e32 v9, v1, v9
	v_fma_f32 v8, v0, v8, v0
	v_fma_f32 v9, v1, v9, v1
	v_mul_f32_e32 v8, 0x3f4c422a, v8
	v_mul_f32_e32 v9, 0x3f4c422a, v9
	v_add_f32_e32 v8, v8, v8
	v_add_f32_e32 v9, v9, v9
	v_mul_f32_e32 v8, 0x3fb8aa3b, v8
	v_mul_f32_e32 v9, 0x3fb8aa3b, v9
	v_exp_f32_e32 v8, v8
	v_exp_f32_e32 v9, v9
	v_pk_add_f32 v[2:3], v[2:3], v[6:7]
	v_pk_mul_f32 v[0:1], v[0:1], 0.5 op_sel_hi:[1,0]
	v_pk_add_f32 v[8:9], v[8:9], 1.0 op_sel_hi:[1,0]
	s_nop 0
	v_div_scale_f32 v10, s[0:1], v9, v9, 2.0
	v_rcp_f32_e32 v11, v10
	s_nop 0
	v_fma_f32 v6, -v10, v11, 1.0
	v_fmac_f32_e32 v11, v6, v11
	v_div_scale_f32 v6, vcc, 2.0, v9, 2.0
	v_mul_f32_e32 v7, v6, v11
	v_fma_f32 v16, -v10, v7, v6
	v_fmac_f32_e32 v7, v16, v11
	v_fma_f32 v6, -v10, v7, v6
	v_div_scale_f32 v10, s[0:1], v8, v8, 2.0
	v_rcp_f32_e32 v16, v10
	v_div_fmas_f32 v6, v6, v11, v7
	v_div_fixup_f32 v7, v6, v9, 2.0
	v_fma_f32 v6, -v10, v16, 1.0
	v_fmac_f32_e32 v16, v6, v16
	v_div_scale_f32 v6, vcc, 2.0, v8, 2.0
	v_mul_f32_e32 v9, v6, v16
	v_fma_f32 v11, -v10, v9, v6
	v_fmac_f32_e32 v9, v11, v16
	v_fma_f32 v6, -v10, v9, v6
	v_div_fmas_f32 v6, v6, v16, v9
	v_mul_f32_e32 v9, 0x3d372713, v2
	v_mul_f32_e32 v9, v2, v9
	v_fma_f32 v9, v2, v9, v2
	v_mul_f32_e32 v9, 0x3f4c422a, v9
	v_add_f32_e32 v9, v9, v9
	v_mul_f32_e32 v9, 0x3fb8aa3b, v9
	v_exp_f32_e32 v10, v9
	v_mul_f32_e32 v9, 0x3d372713, v3
	v_mul_f32_e32 v9, v3, v9
	v_fma_f32 v9, v3, v9, v3
	v_mul_f32_e32 v9, 0x3f4c422a, v9
	v_add_f32_e32 v9, v9, v9
	v_mul_f32_e32 v9, 0x3fb8aa3b, v9
	v_exp_f32_e32 v11, v9
	v_div_fixup_f32 v6, v6, v8, 2.0
	v_pk_add_f32 v[6:7], v[6:7], 1.0 op_sel_hi:[1,0] neg_lo:[1,0] neg_hi:[1,0]
	v_pk_mul_f32 v[2:3], v[2:3], 0.5 op_sel_hi:[1,0]
	v_pk_add_f32 v[8:9], v[10:11], 1.0 op_sel_hi:[1,0]
	v_pk_add_f32 v[6:7], v[6:7], 1.0 op_sel_hi:[1,0]
	v_div_scale_f32 v10, s[0:1], v9, v9, 2.0
	v_rcp_f32_e32 v11, v10
	v_pk_mul_f32 v[0:1], v[0:1], v[6:7]
	s_nop 0
	v_cvt_pk_bf16_f32 v6, v0, v1
	v_fma_f32 v0, -v10, v11, 1.0
	v_fmac_f32_e32 v11, v0, v11
	v_div_scale_f32 v0, vcc, 2.0, v9, 2.0
	v_mul_f32_e32 v1, v0, v11
	v_fma_f32 v7, -v10, v1, v0
	v_fmac_f32_e32 v1, v7, v11
	v_div_scale_f32 v7, s[0:1], v8, v8, 2.0
	v_fma_f32 v0, -v10, v1, v0
	v_rcp_f32_e32 v10, v7
	v_div_fmas_f32 v0, v0, v11, v1
	v_div_fixup_f32 v1, v0, v9, 2.0
	v_permlane16_swap_b32_e32 v4, v6
	v_fma_f32 v0, -v7, v10, 1.0
	v_fmac_f32_e32 v10, v0, v10
	v_div_scale_f32 v0, vcc, 2.0, v8, 2.0
	v_mul_f32_e32 v9, v0, v10
	v_fma_f32 v11, -v7, v9, v0
	v_fmac_f32_e32 v9, v11, v10
	v_fma_f32 v0, -v7, v9, v0
	v_div_fmas_f32 v0, v0, v10, v9
	v_div_fixup_f32 v0, v0, v8, 2.0
	v_pk_add_f32 v[0:1], v[0:1], 1.0 op_sel_hi:[1,0] neg_lo:[1,0] neg_hi:[1,0]
	s_nop 0
	v_pk_add_f32 v[0:1], v[0:1], 1.0 op_sel_hi:[1,0]
	s_nop 0
	v_pk_mul_f32 v[0:1], v[2:3], v[0:1]
	s_nop 0
	v_cvt_pk_bf16_f32 v7, v0, v1
	v_or_b32_e32 v0, 48, v164
	v_ashrrev_i32_e32 v1, 31, v0
	v_lshlrev_b64 v[0:1], 9, v[0:1]
	v_lshl_add_u64 v[0:1], v[214:215], 0, v[0:1]
	v_lshl_add_u64 v[2:3], v[0:1], 0, v[166:167]
	v_permlane16_swap_b32_e32 v5, v7
	v_lshl_add_u64 v[0:1], v[0:1], 0, v[168:169]
	global_store_dwordx4 v[2:3], v[12:15], off sc0 sc1
	global_store_dwordx4 v[0:1], v[4:7], off sc0 sc1
	s_cbranch_scc1 .LBB0_677

; template <class ARow, class Epi>
; DI void gemm_tile(const ARow& arow, long a_kstride, const u16* __restrict__ Bt, long ldb, int K, int m0, int n0,
;                   const Epi& epi, char* smem) {
;     ...
;   const int fr = lane & 15, fq = lane >> 4;
;   int foff[2];
; #pragma unroll
;   for (int ks = 0; ks < 2; ++ks) foff[ks] = fr * 128 + ((((4 * ks + fq) ^ ((fr >> 1) & 7))) << 4);
;   f32x4 acc[4][4];
; #pragma unroll
;   for (int a = 0; a < 4; ++a)
; #pragma unroll
;     for (int b = 0; b < 4; ++b) acc[a][b] = (f32x4){0.f, 0.f, 0.f, 0.f};
;   const int KT = K >> 6;
;   GEMM_STAGE(0, 0);
;   asm volatile("s_waitcnt vmcnt(0)" ::: "memory");
;   __syncthreads();
;   for (int kt = 0; kt < KT; ++kt) {
;     const int cur = kt & 1;
;     if (kt + 1 < KT) GEMM_STAGE(cur ^ 1, kt + 1);
;     const char* sa = smem + cur * 32768 + wm * 64 * 128;
;     const char* sb = smem + cur * 32768 + 16384 + wn * 64 * 128;
; #pragma unroll
;     for (int ks = 0; ks < 2; ++ks) {
;       bf16x8 wf[4], af[4];
; #pragma unroll
;       for (int j = 0; j < 4; ++j) {
;         wf[j] = *(const bf16x8*)(sb + j * 2048 + foff[ks]);
;         af[j] = *(const bf16x8*)(sa + j * 2048 + foff[ks]);
;       }
; #pragma unroll
;       for (int ni = 0; ni < 4; ++ni)
; #pragma unroll
;         for (int mi = 0; mi < 4; ++mi) acc[ni][mi] = __builtin_amdgcn_mfma_f32_16x16x32_bf16(wf[ni], af[mi], acc[ni][mi], 0, 0, 0);
;     }
;     asm volatile("s_waitcnt vmcnt(0)" ::: "memory");
;     __syncthreads();
;   }
.LBB0_1045:
	s_and_b32 s20, s19, 0x8000
	s_xor_b32 s21, s20, 0x8000
	v_add_u32_e32 v108, s21, v88
	v_add_u32_e32 v91, s20, v89
	v_or_b32_e32 v116, s20, v90
	v_readfirstlane_b32 s20, v108
	v_add_u32_e32 v109, 0x4000, v108
	v_lshl_add_u64 v[92:93], v[66:67], 0, s[16:17]
	v_add_u32_e32 v110, 0x400, v108
	v_readfirstlane_b32 s21, v109
	s_mov_b32 m0, s20
	v_lshl_add_u64 v[94:95], v[68:69], 0, s[16:17]
	v_add_u32_e32 v111, 0x4400, v108
	v_readfirstlane_b32 s22, v110
	global_load_lds_dwordx4 v[92:93], off
	s_mov_b32 m0, s21
	v_lshl_add_u64 v[96:97], v[70:71], 0, s[16:17]
	v_add_u32_e32 v113, 0x800, v108
	v_readfirstlane_b32 s23, v111
	global_load_lds_dwordx4 v[94:95], off
	s_mov_b32 m0, s22
	v_lshl_add_u64 v[98:99], v[72:73], 0, s[16:17]
	v_add_u32_e32 v114, 0x4800, v108
	v_readfirstlane_b32 s24, v113
	global_load_lds_dwordx4 v[96:97], off
	s_mov_b32 m0, s23
	v_lshl_add_u64 v[100:101], v[74:75], 0, s[16:17]
	v_add_u32_e32 v115, 0xc00, v108
	v_readfirstlane_b32 s25, v114
	global_load_lds_dwordx4 v[98:99], off
	s_mov_b32 m0, s24
	v_lshl_add_u64 v[102:103], v[76:77], 0, s[16:17]
	v_add_u32_e32 v108, 0x4c00, v108
	v_readfirstlane_b32 s26, v115
	global_load_lds_dwordx4 v[100:101], off
	s_mov_b32 m0, s25
	v_lshl_add_u64 v[104:105], v[78:79], 0, s[16:17]
	v_readfirstlane_b32 s27, v108
	global_load_lds_dwordx4 v[102:103], off
	s_mov_b32 m0, s26
	v_lshl_add_u64 v[106:107], v[80:81], 0, s[16:17]
	global_load_lds_dwordx4 v[104:105], off
	s_mov_b32 m0, s27
	v_add_u32_e32 v117, v116, v87
	global_load_lds_dwordx4 v[106:107], off
	v_add_u32_e32 v112, v91, v87
	ds_read_b128 v[92:95], v117 offset:16384
	ds_read_b128 v[96:99], v112
	ds_read_b128 v[100:103], v117 offset:18432
	ds_read_b128 v[104:107], v112 offset:2048
	ds_read_b128 v[108:111], v112 offset:4096
	ds_read_b128 v[112:115], v112 offset:6144
	s_waitcnt lgkmcnt(0)
	v_mfma_f32_16x16x32_bf16 v[60:63], v[92:95], v[96:99], v[60:63]
	v_add_u32_e32 v116, v116, v86
	v_add_u32_e32 v91, v91, v86
	s_add_i32 s19, s19, 0x8000
	v_mfma_f32_16x16x32_bf16 v[56:59], v[92:95], v[104:107], v[56:59]
	s_add_u32 s16, s16, 0x80
	s_addc_u32 s17, s17, 0
	s_cmpk_lg_i32 s16, 0x780
	v_mfma_f32_16x16x32_bf16 v[52:55], v[92:95], v[108:111], v[52:55]
	v_mfma_f32_16x16x32_bf16 v[48:51], v[92:95], v[112:115], v[48:51]
	v_mfma_f32_16x16x32_bf16 v[44:47], v[100:103], v[96:99], v[44:47]
	v_mfma_f32_16x16x32_bf16 v[40:43], v[100:103], v[104:107], v[40:43]
	v_mfma_f32_16x16x32_bf16 v[36:39], v[100:103], v[108:111], v[36:39]
	v_mfma_f32_16x16x32_bf16 v[16:19], v[100:103], v[112:115], v[16:19]
	ds_read_b128 v[92:95], v117 offset:20480
	ds_read_b128 v[100:103], v117 offset:22528
	s_waitcnt lgkmcnt(0)
	v_mfma_f32_16x16x32_bf16 v[32:35], v[92:95], v[96:99], v[32:35]
	v_mfma_f32_16x16x32_bf16 v[12:15], v[92:95], v[104:107], v[12:15]
	v_mfma_f32_16x16x32_bf16 v[8:11], v[92:95], v[108:111], v[8:11]
	v_mfma_f32_16x16x32_bf16 v[4:7], v[92:95], v[112:115], v[4:7]
	ds_read_b128 v[92:95], v116 offset:16384
	v_mfma_f32_16x16x32_bf16 v[24:27], v[100:103], v[96:99], v[24:27]
	v_mfma_f32_16x16x32_bf16 v[0:3], v[100:103], v[104:107], v[0:3]
	v_mfma_f32_16x16x32_bf16 v[28:31], v[100:103], v[108:111], v[28:31]
	v_mfma_f32_16x16x32_bf16 v[20:23], v[100:103], v[112:115], v[20:23]
	ds_read_b128 v[96:99], v91
	ds_read_b128 v[100:103], v116 offset:18432
	ds_read_b128 v[104:107], v91 offset:2048
	ds_read_b128 v[108:111], v91 offset:4096
	ds_read_b128 v[112:115], v91 offset:6144
	s_waitcnt lgkmcnt(0)
	v_mfma_f32_16x16x32_bf16 v[60:63], v[92:95], v[96:99], v[60:63]
	v_mfma_f32_16x16x32_bf16 v[56:59], v[92:95], v[104:107], v[56:59]
	v_mfma_f32_16x16x32_bf16 v[52:55], v[92:95], v[108:111], v[52:55]
	v_mfma_f32_16x16x32_bf16 v[48:51], v[92:95], v[112:115], v[48:51]
	v_mfma_f32_16x16x32_bf16 v[44:47], v[100:103], v[96:99], v[44:47]
	v_mfma_f32_16x16x32_bf16 v[40:43], v[100:103], v[104:107], v[40:43]
	v_mfma_f32_16x16x32_bf16 v[36:39], v[100:103], v[108:111], v[36:39]
	v_mfma_f32_16x16x32_bf16 v[16:19], v[100:103], v[112:115], v[16:19]
	ds_read_b128 v[92:95], v116 offset:20480
	ds_read_b128 v[100:103], v116 offset:22528
	s_waitcnt vmcnt(0)
	s_waitcnt vmcnt(0) lgkmcnt(0)
	v_mfma_f32_16x16x32_bf16 v[32:35], v[92:95], v[96:99], v[32:35]
	s_barrier
	v_mfma_f32_16x16x32_bf16 v[12:15], v[92:95], v[104:107], v[12:15]
	v_mfma_f32_16x16x32_bf16 v[8:11], v[92:95], v[108:111], v[8:11]
	v_mfma_f32_16x16x32_bf16 v[4:7], v[92:95], v[112:115], v[4:7]
	v_mfma_f32_16x16x32_bf16 v[24:27], v[100:103], v[96:99], v[24:27]
	v_mfma_f32_16x16x32_bf16 v[0:3], v[100:103], v[104:107], v[0:3]
	v_mfma_f32_16x16x32_bf16 v[28:31], v[100:103], v[108:111], v[28:31]
	v_mfma_f32_16x16x32_bf16 v[20:23], v[100:103], v[112:115], v[20:23]
	s_cbranch_scc1 .LBB0_1045
	v_add_u32_e32 v91, v90, v87
	ds_read_b128 v[66:69], v91 offset:49152
	v_add_u32_e32 v87, v89, v87
	ds_read_b128 v[70:73], v87 offset:32768
	ds_read_b128 v[74:77], v87 offset:34816
	ds_read_b128 v[78:81], v87 offset:36864
	ds_read_b128 v[92:95], v87 offset:38912
	v_add_u32_e32 v120, v89, v86
	v_add_u32_e32 v90, v90, v86
	v_or_b32_e32 v64, s1, v64
	s_waitcnt lgkmcnt(3)
	v_mfma_f32_16x16x32_bf16 v[60:63], v[66:69], v[70:73], v[60:63]
	s_waitcnt lgkmcnt(2)
	v_mfma_f32_16x16x32_bf16 v[56:59], v[66:69], v[74:77], v[56:59]
	s_waitcnt lgkmcnt(1)
	v_mfma_f32_16x16x32_bf16 v[52:55], v[66:69], v[78:81], v[52:55]
	s_waitcnt lgkmcnt(0)
	v_mfma_f32_16x16x32_bf16 v[48:51], v[66:69], v[92:95], v[48:51]
	ds_read_b128 v[66:69], v91 offset:51200
	ds_read_b128 v[86:89], v120 offset:38912
	ds_read_b128 v[96:99], v120 offset:36864
	ds_read_b128 v[100:103], v91 offset:55296
	ds_read_b128 v[104:107], v91 offset:53248
	ds_read_b128 v[108:111], v90 offset:55296
	ds_read_b128 v[112:115], v90 offset:53248
	ds_read_b128 v[116:119], v120 offset:34816
	ds_read_b128 v[120:123], v120 offset:32768
	ds_read_b128 v[124:127], v90 offset:51200
	ds_read_b128 v[128:131], v90 offset:49152
	s_waitcnt lgkmcnt(6)
	v_mfma_f32_16x16x32_bf16 v[32:35], v[104:107], v[70:73], v[32:35]
	s_waitcnt vmcnt(0)
	s_waitcnt lgkmcnt(0)
	s_barrier
; DI unsigned pack2(float a, float b) { v2f f = {a, b}; return __builtin_bit_cast(unsigned, __builtin_convertvector(f, v2bf)); }
; template <class ARow, class Epi>
; DI void gemm_tile(const ARow& arow, long a_kstride, const u16* __restrict__ Bt, long ldb, int K, int m0, int n0,
;                   const Epi& epi, char* smem) {
;     ...
;   const int nh = n0 + wn * 64;
;   if (epi.packed(nh)) {
; #pragma unroll
;     for (int mi = 0; mi < 4; ++mi) {
;       const int m = m0 + wm * 64 + mi * 16 + fr;
;       float ss = 0.f;
;       u32x2 pk[4];
; #pragma unroll
;       for (int ni = 0; ni < 4; ++ni) pk[ni] = epi.pack(m, nh + ni * 16 + fq * 4, acc[ni][mi][0], acc[ni][mi][1], acc[ni][mi][2], acc[ni][mi][3], ss);
;       epi.finish16(m, nh, ss);
;       u16* rp = epi.rowp(m) + nh;
; #pragma unroll
;       for (int pp = 0; pp < 2; ++pp) {
;         u32x2 a = pk[2 * pp], b = pk[2 * pp + 1];
;         const u32x2 rx = __builtin_amdgcn_permlane16_swap(a.x, b.x, false, false);
;         const u32x2 ry = __builtin_amdgcn_permlane16_swap(a.y, b.y, false, false);
;         const int nst = (fq & 1) ? ((2 * pp + 1) * 16 + (fq - 1) * 4) : ((2 * pp) * 16 + fq * 4);
;         *(u32x4*)(rp + nst) = (u32x4){rx[0], ry[0], rx[1], ry[1]};
;       }
;     }
;   DI u32x2 pack(int, int, float a, float b, float c, float d, float&) const { u32x2 v; v.x = pack2(a, b); v.y = pack2(c, d); return v; }
	v_mfma_f32_16x16x32_bf16 v[24:27], v[100:103], v[70:73], v[24:27]
	v_mfma_f32_16x16x32_bf16 v[44:47], v[66:69], v[70:73], v[44:47]
	v_lshl_add_u32 v72, v85, 6, v64
	v_lshl_or_b32 v70, v84, 6, s18
	v_ashrrev_i32_e32 v73, 31, v72
	v_mfma_f32_16x16x32_bf16 v[32:35], v[112:115], v[120:123], v[32:35]
	v_ashrrev_i32_e32 v71, 31, v70
	v_and_b32_e32 v64, 16, v82
	v_lshlrev_b32_e32 v82, 2, v83
	v_mfma_f32_16x16x32_bf16 v[24:27], v[108:111], v[120:123], v[24:27]
	v_cmp_eq_u32_e32 vcc, 0, v64
	s_nop 2
	v_cvt_pk_bf16_f32 v32, v32, v33
	v_cvt_pk_bf16_f32 v33, v34, v35
	v_mfma_f32_16x16x32_bf16 v[60:63], v[128:131], v[120:123], v[60:63]
	v_mfma_f32_16x16x32_bf16 v[44:47], v[124:127], v[120:123], v[44:47]
	v_cvt_pk_bf16_f32 v34, v24, v25
	v_lshlrev_b64 v[24:25], 11, v[72:73]
	s_nop 4
	v_cvt_pk_bf16_f32 v60, v60, v61
	v_cvt_pk_bf16_f32 v61, v62, v63
	v_lshl_add_u64 v[24:25], s[6:7], 0, v[24:25]
	v_cvt_pk_bf16_f32 v62, v44, v45
	v_lshlrev_b64 v[44:45], 1, v[70:71]
	v_cvt_pk_bf16_f32 v63, v46, v47
	v_lshl_add_u64 v[46:47], v[24:25], 0, v[44:45]
	v_add_u32_e32 v24, 12, v82
	v_cndmask_b32_e32 v24, v24, v82, vcc
	v_lshlrev_b32_e32 v64, 1, v24
	v_permlane16_swap_b32_e32 v60, v62
	v_permlane16_swap_b32_e32 v61, v63
	v_lshl_add_u64 v[24:25], v[46:47], 0, v[64:65]
	v_mfma_f32_16x16x32_bf16 v[40:43], v[66:69], v[74:77], v[40:43]
	v_cvt_pk_bf16_f32 v35, v26, v27
	global_store_dwordx4 v[24:25], v[60:63], off sc0 sc1
	v_permlane16_swap_b32_e32 v32, v34
	v_mfma_f32_16x16x32_bf16 v[24:27], v[100:103], v[78:81], v[28:31]
	v_mov_b32_e32 v61, v65
	v_permlane16_swap_b32_e32 v33, v35
	s_nop 0
	v_add_u32_e32 v28, 44, v82
	v_or_b32_e32 v29, 32, v82
	v_cndmask_b32_e32 v28, v28, v29, vcc
	v_lshlrev_b32_e32 v60, 1, v28
	v_lshl_add_u64 v[46:47], v[46:47], 0, v[60:61]
	v_mfma_f32_16x16x32_bf16 v[28:31], v[128:131], v[116:119], v[56:59]
	global_store_dwordx4 v[46:47], v[32:35], off sc0 sc1
	s_nop 1
	v_mfma_f32_16x16x32_bf16 v[32:35], v[124:127], v[116:119], v[40:43]
	v_mfma_f32_16x16x32_bf16 v[12:15], v[104:107], v[74:77], v[12:15]
	s_nop 2
	v_cvt_pk_bf16_f32 v28, v28, v29
	v_cvt_pk_bf16_f32 v29, v30, v31
	s_nop 1
	v_cvt_pk_bf16_f32 v30, v32, v33
	v_mfma_f32_16x16x32_bf16 v[0:3], v[100:103], v[74:77], v[0:3]
	v_or_b32_e32 v32, 16, v72
	v_ashrrev_i32_e32 v33, 31, v32
	v_lshlrev_b64 v[32:33], 11, v[32:33]
	v_mfma_f32_16x16x32_bf16 v[12:15], v[112:115], v[116:119], v[12:15]
	v_lshl_add_u64 v[40:41], s[6:7], 0, v[32:33]
	v_cvt_pk_bf16_f32 v31, v34, v35
	v_lshl_add_u64 v[40:41], v[40:41], 0, v[44:45]
	v_mfma_f32_16x16x32_bf16 v[0:3], v[108:111], v[116:119], v[0:3]
	v_permlane16_swap_b32_e32 v28, v30
	s_nop 2
	v_cvt_pk_bf16_f32 v12, v12, v13
	v_mfma_f32_16x16x32_bf16 v[8:11], v[104:107], v[78:81], v[8:11]
	v_cvt_pk_bf16_f32 v13, v14, v15
	s_nop 0
	v_cvt_pk_bf16_f32 v14, v0, v1
	v_cvt_pk_bf16_f32 v15, v2, v3
	v_permlane16_swap_b32_e32 v29, v31
	v_lshl_add_u64 v[42:43], v[40:41], 0, v[64:65]
	global_store_dwordx4 v[42:43], v[28:31], off sc0 sc1
	v_permlane16_swap_b32_e32 v12, v14
	v_permlane16_swap_b32_e32 v13, v15
	v_lshl_add_u64 v[28:29], v[40:41], 0, v[60:61]
	v_mfma_f32_16x16x32_bf16 v[36:39], v[66:69], v[78:81], v[36:39]
	global_store_dwordx4 v[28:29], v[12:15], off sc0 sc1
	v_mfma_f32_16x16x32_bf16 v[8:11], v[112:115], v[96:99], v[8:11]
	s_nop 0
	v_mfma_f32_16x16x32_bf16 v[12:15], v[108:111], v[96:99], v[24:27]
	v_mfma_f32_16x16x32_bf16 v[0:3], v[128:131], v[96:99], v[52:55]
	s_nop 4
	v_cvt_pk_bf16_f32 v8, v8, v9
	v_cvt_pk_bf16_f32 v9, v10, v11
	v_cvt_pk_bf16_f32 v10, v12, v13
	v_mfma_f32_16x16x32_bf16 v[36:39], v[124:127], v[96:99], v[36:39]
	v_or_b32_e32 v12, 32, v72
	v_ashrrev_i32_e32 v13, 31, v12
	v_lshlrev_b64 v[12:13], 11, v[12:13]
	v_mfma_f32_16x16x32_bf16 v[16:19], v[66:69], v[92:95], v[16:19]
	v_lshl_add_u64 v[12:13], s[6:7], 0, v[12:13]
	v_cvt_pk_bf16_f32 v0, v0, v1
	v_cvt_pk_bf16_f32 v1, v2, v3
	v_mfma_f32_16x16x32_bf16 v[4:7], v[104:107], v[92:95], v[4:7]
	v_cvt_pk_bf16_f32 v2, v36, v37
	v_cvt_pk_bf16_f32 v3, v38, v39
	v_lshl_add_u64 v[12:13], v[12:13], 0, v[44:45]
	v_mfma_f32_16x16x32_bf16 v[20:23], v[100:103], v[92:95], v[20:23]
	v_cvt_pk_bf16_f32 v11, v14, v15
	v_permlane16_swap_b32_e32 v0, v2
	v_permlane16_swap_b32_e32 v1, v3
	v_lshl_add_u64 v[14:15], v[12:13], 0, v[64:65]
	global_store_dwordx4 v[14:15], v[0:3], off sc0 sc1
	v_permlane16_swap_b32_e32 v8, v10
	v_permlane16_swap_b32_e32 v9, v11
	v_lshl_add_u64 v[0:1], v[12:13], 0, v[60:61]
	v_mfma_f32_16x16x32_bf16 v[32:35], v[128:131], v[86:89], v[48:51]
	global_store_dwordx4 v[0:1], v[8:11], off sc0 sc1
	v_mfma_f32_16x16x32_bf16 v[16:19], v[124:127], v[86:89], v[16:19]
	s_nop 0
	v_or_b32_e32 v8, 48, v72
	v_ashrrev_i32_e32 v9, 31, v8
	v_lshlrev_b64 v[8:9], 11, v[8:9]
	v_mfma_f32_16x16x32_bf16 v[4:7], v[112:115], v[86:89], v[4:7]
	v_lshl_add_u64 v[8:9], s[6:7], 0, v[8:9]
	v_cvt_pk_bf16_f32 v0, v32, v33
	v_cvt_pk_bf16_f32 v1, v34, v35
	v_mfma_f32_16x16x32_bf16 v[20:23], v[108:111], v[86:89], v[20:23]
	v_cvt_pk_bf16_f32 v2, v16, v17
	v_cvt_pk_bf16_f32 v3, v18, v19
	v_lshl_add_u64 v[8:9], v[8:9], 0, v[44:45]
	s_nop 0
	v_cvt_pk_bf16_f32 v4, v4, v5
	v_cvt_pk_bf16_f32 v5, v6, v7
	s_nop 1
	v_cvt_pk_bf16_f32 v6, v20, v21
	v_cvt_pk_bf16_f32 v7, v22, v23
	v_permlane16_swap_b32_e32 v0, v2
	v_permlane16_swap_b32_e32 v1, v3
	v_lshl_add_u64 v[10:11], v[8:9], 0, v[64:65]
	global_store_dwordx4 v[10:11], v[0:3], off sc0 sc1
	v_permlane16_swap_b32_e32 v4, v6
	v_permlane16_swap_b32_e32 v5, v7
	v_lshl_add_u64 v[0:1], v[8:9], 0, v[60:61]
	global_store_dwordx4 v[0:1], v[4:7], off sc0 sc1
	s_load_dword s1, s[10:11], 0x0
	s_waitcnt lgkmcnt(0)
	s_add_i32 s0, s1, s0
	s_cmpk_lt_i32 s0, 0x400
	s_cbranch_scc1 .LBB0_1044

; template <class ARow, class Epi>
; DI void gemm_tile(const ARow& arow, long a_kstride, const u16* __restrict__ Bt, long ldb, int K, int m0, int n0,
;                   const Epi& epi, char* smem) {
;     ...
;       u16* rp = epi.rowp(m) + nh;
; #pragma unroll
;       for (int pp = 0; pp < 2; ++pp) {
;         u32x2 a = pk[2 * pp], b = pk[2 * pp + 1];
;         const u32x2 rx = __builtin_amdgcn_permlane16_swap(a.x, b.x, false, false);
;         const u32x2 ry = __builtin_amdgcn_permlane16_swap(a.y, b.y, false, false);
;         const int nst = (fq & 1) ? ((2 * pp + 1) * 16 + (fq - 1) * 4) : ((2 * pp) * 16 + fq * 4);
;         *(u32x4*)(rp + nst) = (u32x4){rx[0], ry[0], rx[1], ry[1]};
.LBB0_1170:
	v_or_b32_e32 v20, 48, v66
	v_ashrrev_i32_e32 v21, 31, v20
	v_cvt_pk_bf16_f32 v16, v4, v5
	v_lshlrev_b64 v[4:5], 13, v[20:21]
	v_lshl_add_u64 v[4:5], s[18:19], 0, v[4:5]
	v_cvt_pk_bf16_f32 v18, v0, v1
	v_cvt_pk_bf16_f32 v19, v2, v3
	v_cvt_pk_bf16_f32 v2, v8, v9
	v_cvt_pk_bf16_f32 v3, v10, v11
	v_cvt_pk_bf16_f32 v0, v12, v13
	v_cvt_pk_bf16_f32 v1, v14, v15
	v_lshl_add_u64 v[4:5], v[68:69], 1, v[4:5]
	s_waitcnt lgkmcnt(0)
	v_cvt_pk_bf16_f32 v17, v6, v7
	v_permlane16_swap_b32_e32 v0, v2
	v_permlane16_swap_b32_e32 v1, v3
	v_lshl_add_u64 v[6:7], v[4:5], 0, v[64:65]
	v_mov_b32_e32 v49, v65
	global_store_dwordx4 v[6:7], v[0:3], off sc0 sc1
	v_permlane16_swap_b32_e32 v16, v18
	v_permlane16_swap_b32_e32 v17, v19
	v_lshl_add_u64 v[0:1], v[4:5], 0, v[48:49]
	global_store_dwordx4 v[0:1], v[16:19], off sc0 sc1

; template <class ARow, class Epi>
; DI void gemm_tile(const ARow& arow, long a_kstride, const u16* __restrict__ Bt, long ldb, int K, int m0, int n0,
;                   const Epi& epi, char* smem) {
;     ...
;   const int fr = lane & 15, fq = lane >> 4;
;   int foff[2];
; #pragma unroll
;   for (int ks = 0; ks < 2; ++ks) foff[ks] = fr * 128 + ((((4 * ks + fq) ^ ((fr >> 1) & 7))) << 4);
;   f32x4 acc[4][4];
; #pragma unroll
;   for (int a = 0; a < 4; ++a)
; #pragma unroll
;     for (int b = 0; b < 4; ++b) acc[a][b] = (f32x4){0.f, 0.f, 0.f, 0.f};
;   const int KT = K >> 6;
;   GEMM_STAGE(0, 0);
;   asm volatile("s_waitcnt vmcnt(0)" ::: "memory");
;   __syncthreads();
;   for (int kt = 0; kt < KT; ++kt) {
;     const int cur = kt & 1;
;     if (kt + 1 < KT) GEMM_STAGE(cur ^ 1, kt + 1);
;     const char* sa = smem + cur * 32768 + wm * 64 * 128;
;     const char* sb = smem + cur * 32768 + 16384 + wn * 64 * 128;
; #pragma unroll
;     for (int ks = 0; ks < 2; ++ks) {
;       bf16x8 wf[4], af[4];
; #pragma unroll
;       for (int j = 0; j < 4; ++j) {
;         wf[j] = *(const bf16x8*)(sb + j * 2048 + foff[ks]);
;         af[j] = *(const bf16x8*)(sa + j * 2048 + foff[ks]);
;       }
; #pragma unroll
;       for (int ni = 0; ni < 4; ++ni)
; #pragma unroll
;         for (int mi = 0; mi < 4; ++mi) acc[ni][mi] = __builtin_amdgcn_mfma_f32_16x16x32_bf16(wf[ni], af[mi], acc[ni][mi], 0, 0, 0);
;     }
;     asm volatile("s_waitcnt vmcnt(0)" ::: "memory");
;     __syncthreads();
;   }
.LBB0_1173:
	s_and_b32 s6, s1, 0x8000
	s_xor_b32 s7, s6, 0x8000
	v_add_u32_e32 v108, s7, v91
	v_add_u32_e32 v116, s6, v89
	v_or_b32_e32 v117, s6, v90
	v_readfirstlane_b32 s6, v108
	v_add_u32_e32 v109, 0x4000, v108
	v_lshl_add_u64 v[92:93], v[66:67], 0, s[4:5]
	v_add_u32_e32 v110, 0x400, v108
	v_readfirstlane_b32 s7, v109
	s_mov_b32 m0, s6
	v_lshl_add_u64 v[94:95], v[68:69], 0, s[4:5]
	v_add_u32_e32 v111, 0x4400, v108
	v_readfirstlane_b32 s8, v110
	global_load_lds_dwordx4 v[92:93], off
	s_mov_b32 m0, s7
	v_lshl_add_u64 v[96:97], v[70:71], 0, s[4:5]
	v_add_u32_e32 v113, 0x800, v108
	v_readfirstlane_b32 s9, v111
	global_load_lds_dwordx4 v[94:95], off
	s_mov_b32 m0, s8
	v_lshl_add_u64 v[98:99], v[72:73], 0, s[4:5]
	v_add_u32_e32 v114, 0x4800, v108
	v_readfirstlane_b32 s10, v113
	global_load_lds_dwordx4 v[96:97], off
	s_mov_b32 m0, s9
	v_lshl_add_u64 v[100:101], v[74:75], 0, s[4:5]
	v_add_u32_e32 v115, 0xc00, v108
	v_readfirstlane_b32 s11, v114
	global_load_lds_dwordx4 v[98:99], off
	s_mov_b32 m0, s10
	v_lshl_add_u64 v[102:103], v[76:77], 0, s[4:5]
	v_add_u32_e32 v108, 0x4c00, v108
	v_readfirstlane_b32 s12, v115
	global_load_lds_dwordx4 v[100:101], off
	s_mov_b32 m0, s11
	v_lshl_add_u64 v[104:105], v[78:79], 0, s[4:5]
	v_readfirstlane_b32 s13, v108
	global_load_lds_dwordx4 v[102:103], off
	s_mov_b32 m0, s12
	v_lshl_add_u64 v[106:107], v[80:81], 0, s[4:5]
	global_load_lds_dwordx4 v[104:105], off
	s_mov_b32 m0, s13
	v_add_u32_e32 v118, v117, v88
	global_load_lds_dwordx4 v[106:107], off
	v_add_u32_e32 v112, v116, v88
	ds_read_b128 v[92:95], v118 offset:16384
	ds_read_b128 v[96:99], v112
	ds_read_b128 v[100:103], v118 offset:18432
	ds_read_b128 v[104:107], v112 offset:2048
	ds_read_b128 v[108:111], v112 offset:4096
	ds_read_b128 v[112:115], v112 offset:6144
	s_waitcnt lgkmcnt(0)
	v_mfma_f32_16x16x32_bf16 v[60:63], v[92:95], v[96:99], v[60:63]
	v_add_u32_e32 v117, v117, v87
	v_add_u32_e32 v116, v116, v87
	s_add_i32 s1, s1, 0x8000
	v_mfma_f32_16x16x32_bf16 v[56:59], v[92:95], v[104:107], v[56:59]
	s_add_u32 s4, s4, 0x80
	s_addc_u32 s5, s5, 0
	s_cmpk_eq_i32 s4, 0x780
	v_mfma_f32_16x16x32_bf16 v[48:51], v[92:95], v[108:111], v[48:51]
	v_mfma_f32_16x16x32_bf16 v[40:43], v[92:95], v[112:115], v[40:43]
	v_mfma_f32_16x16x32_bf16 v[36:39], v[100:103], v[96:99], v[36:39]
	v_mfma_f32_16x16x32_bf16 v[32:35], v[100:103], v[104:107], v[32:35]
	v_mfma_f32_16x16x32_bf16 v[28:31], v[100:103], v[108:111], v[28:31]
	v_mfma_f32_16x16x32_bf16 v[24:27], v[100:103], v[112:115], v[24:27]
	ds_read_b128 v[92:95], v118 offset:20480
	ds_read_b128 v[100:103], v118 offset:22528
	s_waitcnt lgkmcnt(0)
	v_mfma_f32_16x16x32_bf16 v[20:23], v[92:95], v[96:99], v[20:23]
	v_mfma_f32_16x16x32_bf16 v[16:19], v[92:95], v[104:107], v[16:19]
	v_mfma_f32_16x16x32_bf16 v[12:15], v[92:95], v[108:111], v[12:15]
	v_mfma_f32_16x16x32_bf16 v[8:11], v[92:95], v[112:115], v[8:11]
	ds_read_b128 v[92:95], v117 offset:16384
	v_mfma_f32_16x16x32_bf16 v[4:7], v[100:103], v[96:99], v[4:7]
	v_mfma_f32_16x16x32_bf16 v[0:3], v[100:103], v[104:107], v[0:3]
	v_mfma_f32_16x16x32_bf16 v[52:55], v[100:103], v[108:111], v[52:55]
	v_mfma_f32_16x16x32_bf16 v[44:47], v[100:103], v[112:115], v[44:47]
	ds_read_b128 v[96:99], v116
	ds_read_b128 v[100:103], v117 offset:18432
	ds_read_b128 v[104:107], v116 offset:2048
	ds_read_b128 v[108:111], v116 offset:4096
	ds_read_b128 v[112:115], v116 offset:6144
	s_waitcnt lgkmcnt(0)
	v_mfma_f32_16x16x32_bf16 v[60:63], v[92:95], v[96:99], v[60:63]
	v_mfma_f32_16x16x32_bf16 v[56:59], v[92:95], v[104:107], v[56:59]
	v_mfma_f32_16x16x32_bf16 v[48:51], v[92:95], v[108:111], v[48:51]
	v_mfma_f32_16x16x32_bf16 v[40:43], v[92:95], v[112:115], v[40:43]
	v_mfma_f32_16x16x32_bf16 v[36:39], v[100:103], v[96:99], v[36:39]
	v_mfma_f32_16x16x32_bf16 v[32:35], v[100:103], v[104:107], v[32:35]
	v_mfma_f32_16x16x32_bf16 v[28:31], v[100:103], v[108:111], v[28:31]
	v_mfma_f32_16x16x32_bf16 v[24:27], v[100:103], v[112:115], v[24:27]
	ds_read_b128 v[92:95], v117 offset:20480
	ds_read_b128 v[100:103], v117 offset:22528
	s_waitcnt vmcnt(0)
	s_waitcnt vmcnt(0) lgkmcnt(0)
	v_mfma_f32_16x16x32_bf16 v[20:23], v[92:95], v[96:99], v[20:23]
	s_barrier
	v_mfma_f32_16x16x32_bf16 v[16:19], v[92:95], v[104:107], v[16:19]
	v_mfma_f32_16x16x32_bf16 v[12:15], v[92:95], v[108:111], v[12:15]
	v_mfma_f32_16x16x32_bf16 v[8:11], v[92:95], v[112:115], v[8:11]
	v_mfma_f32_16x16x32_bf16 v[4:7], v[100:103], v[96:99], v[4:7]
	v_mfma_f32_16x16x32_bf16 v[0:3], v[100:103], v[104:107], v[0:3]
	v_mfma_f32_16x16x32_bf16 v[52:55], v[100:103], v[108:111], v[52:55]
	v_mfma_f32_16x16x32_bf16 v[44:47], v[100:103], v[112:115], v[44:47]
	s_cbranch_scc0 .LBB0_1173
;   DI u32x2 pack(int, int, float a, float b, float c, float d, float&) const { u32x2 v; v.x = pack2(a, b); v.y = pack2(c, d); return v; }
; template <class ARow, class Epi>
; DI void gemm_tile(const ARow& arow, long a_kstride, const u16* __restrict__ Bt, long ldb, int K, int m0, int n0,
;                   const Epi& epi, char* smem) {
;     ...
; #pragma unroll
;     for (int ks = 0; ks < 2; ++ks) {
;       bf16x8 wf[4], af[4];
; #pragma unroll
;       for (int j = 0; j < 4; ++j) {
;         wf[j] = *(const bf16x8*)(sb + j * 2048 + foff[ks]);
;         af[j] = *(const bf16x8*)(sa + j * 2048 + foff[ks]);
;       }
; #pragma unroll
;       for (int ni = 0; ni < 4; ++ni)
; #pragma unroll
;         for (int mi = 0; mi < 4; ++mi) acc[ni][mi] = __builtin_amdgcn_mfma_f32_16x16x32_bf16(wf[ni], af[mi], acc[ni][mi], 0, 0, 0);
;     }
;     asm volatile("s_waitcnt vmcnt(0)" ::: "memory");
;     __syncthreads();
;   }
;     ...
;   const int nh = n0 + wn * 64;
;   if (epi.packed(nh)) {
; #pragma unroll
;     for (int mi = 0; mi < 4; ++mi) {
;       const int m = m0 + wm * 64 + mi * 16 + fr;
;       float ss = 0.f;
;       u32x2 pk[4];
; #pragma unroll
;       for (int ni = 0; ni < 4; ++ni) pk[ni] = epi.pack(m, nh + ni * 16 + fq * 4, acc[ni][mi][0], acc[ni][mi][1], acc[ni][mi][2], acc[ni][mi][3], ss);
;       epi.finish16(m, nh, ss);
;       u16* rp = epi.rowp(m) + nh;
; #pragma unroll
;       for (int pp = 0; pp < 2; ++pp) {
;         u32x2 a = pk[2 * pp], b = pk[2 * pp + 1];
;         const u32x2 rx = __builtin_amdgcn_permlane16_swap(a.x, b.x, false, false);
;         const u32x2 ry = __builtin_amdgcn_permlane16_swap(a.y, b.y, false, false);
;         const int nst = (fq & 1) ? ((2 * pp + 1) * 16 + (fq - 1) * 4) : ((2 * pp) * 16 + fq * 4);
;         *(u32x4*)(rp + nst) = (u32x4){rx[0], ry[0], rx[1], ry[1]};
;       }
	v_add_u32_e32 v91, v90, v88
	ds_read_b128 v[66:69], v91 offset:49152
	v_add_u32_e32 v88, v89, v88
	ds_read_b128 v[70:73], v88 offset:32768
	ds_read_b128 v[74:77], v88 offset:34816
	ds_read_b128 v[78:81], v88 offset:36864
	ds_read_b128 v[92:95], v88 offset:38912
	v_add_u32_e32 v116, v90, v87
	s_waitcnt lgkmcnt(3)
	v_mfma_f32_16x16x32_bf16 v[60:63], v[66:69], v[70:73], v[60:63]
	s_waitcnt lgkmcnt(2)
	v_mfma_f32_16x16x32_bf16 v[56:59], v[66:69], v[74:77], v[56:59]
	s_waitcnt lgkmcnt(1)
	v_mfma_f32_16x16x32_bf16 v[48:51], v[66:69], v[78:81], v[48:51]
	s_waitcnt lgkmcnt(0)
	v_mfma_f32_16x16x32_bf16 v[40:43], v[66:69], v[92:95], v[40:43]
	ds_read_b128 v[66:69], v91 offset:51200
	s_waitcnt lgkmcnt(0)
	v_mfma_f32_16x16x32_bf16 v[36:39], v[66:69], v[70:73], v[36:39]
	v_mfma_f32_16x16x32_bf16 v[32:35], v[66:69], v[74:77], v[32:35]
	v_mfma_f32_16x16x32_bf16 v[96:99], v[66:69], v[78:81], v[28:31]
	v_mfma_f32_16x16x32_bf16 v[66:69], v[66:69], v[92:95], v[24:27]
	s_nop 2
	ds_read_b128 v[24:27], v91 offset:53248
	s_waitcnt lgkmcnt(0)
	v_mfma_f32_16x16x32_bf16 v[104:107], v[24:27], v[92:95], v[8:11]
	s_nop 2
	ds_read_b128 v[8:11], v91 offset:55296
	v_mfma_f32_16x16x32_bf16 v[20:23], v[24:27], v[70:73], v[20:23]
	s_waitcnt lgkmcnt(0)
	v_mfma_f32_16x16x32_bf16 v[70:73], v[8:11], v[70:73], v[4:7]
	s_nop 2
	ds_read_b128 v[4:7], v116 offset:49152
	v_mfma_f32_16x16x32_bf16 v[100:103], v[24:27], v[78:81], v[12:15]
	s_nop 2
	v_add_u32_e32 v12, v89, v87
	v_mfma_f32_16x16x32_bf16 v[16:19], v[24:27], v[74:77], v[16:19]
	ds_read_b128 v[88:91], v12 offset:32768
	ds_read_b128 v[108:111], v12 offset:36864
	ds_read_b128 v[112:115], v12 offset:38912
	v_mfma_f32_16x16x32_bf16 v[0:3], v[8:11], v[74:77], v[0:3]
	v_mfma_f32_16x16x32_bf16 v[74:77], v[8:11], v[78:81], v[52:55]
	v_mfma_f32_16x16x32_bf16 v[78:81], v[8:11], v[92:95], v[44:47]
	ds_read_b128 v[92:95], v12 offset:34816
	s_waitcnt lgkmcnt(3)
	v_mfma_f32_16x16x32_bf16 v[60:63], v[4:7], v[88:91], v[60:63]
	s_waitcnt lgkmcnt(0)
	v_mfma_f32_16x16x32_bf16 v[44:47], v[4:7], v[92:95], v[56:59]
	v_mfma_f32_16x16x32_bf16 v[28:31], v[4:7], v[108:111], v[48:51]
	v_mfma_f32_16x16x32_bf16 v[12:15], v[4:7], v[112:115], v[40:43]
	ds_read_b128 v[4:7], v116 offset:51200
	s_waitcnt lgkmcnt(0)
	v_mfma_f32_16x16x32_bf16 v[56:59], v[4:7], v[88:91], v[36:39]
	v_mfma_f32_16x16x32_bf16 v[40:43], v[4:7], v[92:95], v[32:35]
	v_mfma_f32_16x16x32_bf16 v[24:27], v[4:7], v[108:111], v[96:99]
	v_mfma_f32_16x16x32_bf16 v[8:11], v[4:7], v[112:115], v[66:69]
	ds_read_b128 v[4:7], v116 offset:53248
	s_nop 0
	ds_read_b128 v[96:99], v116 offset:55296
	s_waitcnt vmcnt(0)
	s_waitcnt lgkmcnt(0)
	v_mfma_f32_16x16x32_bf16 v[32:35], v[96:99], v[92:95], v[0:3]
	s_nop 2
	v_or_b32_e32 v0, s0, v64
	v_lshl_add_u32 v66, v86, 6, v0
	v_lshl_or_b32 v68, v85, 6, s38
	v_mfma_f32_16x16x32_bf16 v[52:55], v[4:7], v[88:91], v[20:23]
	v_cmp_lt_i32_e32 vcc, s33, v68
	s_barrier
	v_mfma_f32_16x16x32_bf16 v[36:39], v[4:7], v[92:95], v[16:19]
	v_mfma_f32_16x16x32_bf16 v[20:23], v[4:7], v[108:111], v[100:103]
	v_mfma_f32_16x16x32_bf16 v[4:7], v[4:7], v[112:115], v[104:107]
	v_mfma_f32_16x16x32_bf16 v[48:51], v[96:99], v[88:91], v[70:73]
	v_mfma_f32_16x16x32_bf16 v[16:19], v[96:99], v[108:111], v[74:77]
	s_nop 1
	v_lshlrev_b32_e32 v72, 2, v84
	v_or_b32_e32 v64, v68, v72
	v_mfma_f32_16x16x32_bf16 v[0:3], v[96:99], v[112:115], v[78:81]
	s_nop 7
	v_readfirstlane_b32 s99, v68
	s_cmpk_ge_u32 s99, 0x800
	s_cbranch_scc0 .Lfe_B_not_plain
	s_cmpk_lt_u32 s99, 0xc00
	s_cbranch_scc0 .Lfe_B_not_plain
	s_load_dwordx2 s[100:101], s[56:57], 0x130
	v_and_b32_e32 v152, 1, v84
	v_mul_u32_u24_e32 v152, 12, v152
	v_lshl_add_u32 v152, v84, 2, v152
	v_add_u32_e32 v152, v152, v68
	v_lshl_add_u32 v152, v66, 12, v152
	v_lshlrev_b32_e32 v152, 1, v152
	v_add_u32_e32 v153, 0x20000, v152
	v_add_u32_e32 v154, 0x40000, v152
	v_add_u32_e32 v155, 0x60000, v152
	s_nop 3
	v_cvt_pk_bf16_f32 v120, v60, v61
	v_cvt_pk_bf16_f32 v121, v62, v63
	v_cvt_pk_bf16_f32 v122, v56, v57
	v_cvt_pk_bf16_f32 v123, v58, v59
	v_cvt_pk_bf16_f32 v124, v52, v53
	v_cvt_pk_bf16_f32 v125, v54, v55
	v_cvt_pk_bf16_f32 v126, v48, v49
	v_cvt_pk_bf16_f32 v127, v50, v51
	s_nop 1
	v_permlane16_swap_b32_e32 v120, v122
	v_permlane16_swap_b32_e32 v121, v123
	v_permlane16_swap_b32_e32 v124, v126
	v_permlane16_swap_b32_e32 v125, v127
	s_waitcnt lgkmcnt(0)
	global_store_dwordx4 v152, v[120:123], s[100:101] sc0 sc1
	global_store_dwordx4 v152, v[124:127], s[100:101] offset:64 sc0 sc1
	v_cvt_pk_bf16_f32 v128, v44, v45
	v_cvt_pk_bf16_f32 v129, v46, v47
	v_cvt_pk_bf16_f32 v130, v40, v41
	v_cvt_pk_bf16_f32 v131, v42, v43
	v_cvt_pk_bf16_f32 v132, v36, v37
	v_cvt_pk_bf16_f32 v133, v38, v39
	v_cvt_pk_bf16_f32 v134, v32, v33
	v_cvt_pk_bf16_f32 v135, v34, v35
	s_nop 1
	v_permlane16_swap_b32_e32 v128, v130
	v_permlane16_swap_b32_e32 v129, v131
	v_permlane16_swap_b32_e32 v132, v134
	v_permlane16_swap_b32_e32 v133, v135
	global_store_dwordx4 v153, v[128:131], s[100:101] sc0 sc1
	global_store_dwordx4 v153, v[132:135], s[100:101] offset:64 sc0 sc1
	v_cvt_pk_bf16_f32 v136, v28, v29
	v_cvt_pk_bf16_f32 v137, v30, v31
	v_cvt_pk_bf16_f32 v138, v24, v25
	v_cvt_pk_bf16_f32 v139, v26, v27
	v_cvt_pk_bf16_f32 v140, v20, v21
	v_cvt_pk_bf16_f32 v141, v22, v23
	v_cvt_pk_bf16_f32 v142, v16, v17
	v_cvt_pk_bf16_f32 v143, v18, v19
	s_nop 1
	v_permlane16_swap_b32_e32 v136, v138
	v_permlane16_swap_b32_e32 v137, v139
	v_permlane16_swap_b32_e32 v140, v142
	v_permlane16_swap_b32_e32 v141, v143
	global_store_dwordx4 v154, v[136:139], s[100:101] sc0 sc1
	global_store_dwordx4 v154, v[140:143], s[100:101] offset:64 sc0 sc1
	v_cvt_pk_bf16_f32 v144, v12, v13
	v_cvt_pk_bf16_f32 v145, v14, v15
	v_cvt_pk_bf16_f32 v146, v8, v9
	v_cvt_pk_bf16_f32 v147, v10, v11
	v_cvt_pk_bf16_f32 v148, v4, v5
	v_cvt_pk_bf16_f32 v149, v6, v7
	v_cvt_pk_bf16_f32 v150, v0, v1
	v_cvt_pk_bf16_f32 v151, v2, v3
	s_nop 1
	v_permlane16_swap_b32_e32 v144, v146
	v_permlane16_swap_b32_e32 v145, v147
	v_permlane16_swap_b32_e32 v148, v150
	v_permlane16_swap_b32_e32 v149, v151
	global_store_dwordx4 v155, v[144:147], s[100:101] sc0 sc1
	global_store_dwordx4 v155, v[148:151], s[100:101] offset:64 sc0 sc1
	s_branch .Lfe_join_B
; DI unsigned pack2(float a, float b) { v2f f = {a, b}; return __builtin_bit_cast(unsigned, __builtin_convertvector(f, v2bf)); }
; DI float silu_f(float v) { return v / (1.f + fexp(-v)); }
;   DI u32x2 pack(int, int, float a, float b, float c, float d, float&) const { u32x2 v; v.x = pack2(a, b); v.y = pack2(c, d); return v; }
; template <class ARow, class Epi>
; DI void gemm_tile(const ARow& arow, long a_kstride, const u16* __restrict__ Bt, long ldb, int K, int m0, int n0,
;                   const Epi& epi, char* smem) {
;     ...
;     for (int mi = 0; mi < 4; ++mi) {
;       const int m = m0 + wm * 64 + mi * 16 + fr;
;       float ss = 0.f;
;       u32x2 pk[4];
; #pragma unroll
;       for (int ni = 0; ni < 4; ++ni) pk[ni] = epi.pack(m, nh + ni * 16 + fq * 4, acc[ni][mi][0], acc[ni][mi][1], acc[ni][mi][2], acc[ni][mi][3], ss);
;       epi.finish16(m, nh, ss);
;       u16* rp = epi.rowp(m) + nh;
; #pragma unroll
;       for (int pp = 0; pp < 2; ++pp) {
;         u32x2 a = pk[2 * pp], b = pk[2 * pp + 1];
;         const u32x2 rx = __builtin_amdgcn_permlane16_swap(a.x, b.x, false, false);
;         const u32x2 ry = __builtin_amdgcn_permlane16_swap(a.y, b.y, false, false);
;         const int nst = (fq & 1) ? ((2 * pp + 1) * 16 + (fq - 1) * 4) : ((2 * pp) * 16 + fq * 4);
;         *(u32x4*)(rp + nst) = (u32x4){rx[0], ry[0], rx[1], ry[1]};
;       }
;   DI u32x2 pack(int m, int n, float a, float b, float c, float d, float& ss) const {
;     if (n < q_end) { a *= qscale; b *= qscale; c *= qscale; d *= qscale; }
;     else if (n >= z_start) { a = silu_f(a); b = silu_f(b); c = silu_f(c); d = silu_f(d); }
;     ss += a * a + b * b + c * c + d * d;
;     u32x2 v; v.x = pack2(a, b); v.y = pack2(c, d);
;     return v;
.Lfe_B_not_plain:
	s_cmpk_lt_u32 s99, 0x400
	s_cbranch_scc0 .Lfe_B_not_q
	s_load_dwordx2 s[100:101], s[56:57], 0x130
	v_and_b32_e32 v152, 1, v84
	v_mul_u32_u24_e32 v152, 12, v152
	v_lshl_add_u32 v152, v84, 2, v152
	v_add_u32_e32 v152, v152, v68
	v_lshl_add_u32 v152, v66, 12, v152
	v_lshlrev_b32_e32 v152, 1, v152
	v_add_u32_e32 v153, 0x20000, v152
	v_add_u32_e32 v154, 0x40000, v152
	v_add_u32_e32 v155, 0x60000, v152
	s_mov_b32 s98, 0x3e38aa3b
	s_nop 3
	v_pk_mul_f32 v[60:61], v[60:61], s[98:99] op_sel_hi:[1,0]
	v_pk_mul_f32 v[62:63], v[62:63], s[98:99] op_sel_hi:[1,0]
	v_pk_mul_f32 v[56:57], v[56:57], s[98:99] op_sel_hi:[1,0]
	v_pk_mul_f32 v[58:59], v[58:59], s[98:99] op_sel_hi:[1,0]
	v_pk_mul_f32 v[52:53], v[52:53], s[98:99] op_sel_hi:[1,0]
	v_pk_mul_f32 v[54:55], v[54:55], s[98:99] op_sel_hi:[1,0]
	v_pk_mul_f32 v[48:49], v[48:49], s[98:99] op_sel_hi:[1,0]
	v_pk_mul_f32 v[50:51], v[50:51], s[98:99] op_sel_hi:[1,0]
	v_cvt_pk_bf16_f32 v120, v60, v61
	v_cvt_pk_bf16_f32 v121, v62, v63
	v_cvt_pk_bf16_f32 v122, v56, v57
	v_cvt_pk_bf16_f32 v123, v58, v59
	v_cvt_pk_bf16_f32 v124, v52, v53
	v_cvt_pk_bf16_f32 v125, v54, v55
	v_cvt_pk_bf16_f32 v126, v48, v49
	v_cvt_pk_bf16_f32 v127, v50, v51
	s_nop 1
	v_permlane16_swap_b32_e32 v120, v122
	v_permlane16_swap_b32_e32 v121, v123
	v_permlane16_swap_b32_e32 v124, v126
	v_permlane16_swap_b32_e32 v125, v127
	s_waitcnt lgkmcnt(0)
	global_store_dwordx4 v152, v[120:123], s[100:101] sc0 sc1
	global_store_dwordx4 v152, v[124:127], s[100:101] offset:64 sc0 sc1
	v_pk_mul_f32 v[44:45], v[44:45], s[98:99] op_sel_hi:[1,0]
	v_pk_mul_f32 v[46:47], v[46:47], s[98:99] op_sel_hi:[1,0]
	v_pk_mul_f32 v[40:41], v[40:41], s[98:99] op_sel_hi:[1,0]
	v_pk_mul_f32 v[42:43], v[42:43], s[98:99] op_sel_hi:[1,0]
	v_pk_mul_f32 v[36:37], v[36:37], s[98:99] op_sel_hi:[1,0]
	v_pk_mul_f32 v[38:39], v[38:39], s[98:99] op_sel_hi:[1,0]
	v_pk_mul_f32 v[32:33], v[32:33], s[98:99] op_sel_hi:[1,0]
	v_pk_mul_f32 v[34:35], v[34:35], s[98:99] op_sel_hi:[1,0]
	v_cvt_pk_bf16_f32 v128, v44, v45
	v_cvt_pk_bf16_f32 v129, v46, v47
	v_cvt_pk_bf16_f32 v130, v40, v41
	v_cvt_pk_bf16_f32 v131, v42, v43
	v_cvt_pk_bf16_f32 v132, v36, v37
	v_cvt_pk_bf16_f32 v133, v38, v39
	v_cvt_pk_bf16_f32 v134, v32, v33
	v_cvt_pk_bf16_f32 v135, v34, v35
	s_nop 1
	v_permlane16_swap_b32_e32 v128, v130
	v_permlane16_swap_b32_e32 v129, v131
	v_permlane16_swap_b32_e32 v132, v134
	v_permlane16_swap_b32_e32 v133, v135
	global_store_dwordx4 v153, v[128:131], s[100:101] sc0 sc1
	global_store_dwordx4 v153, v[132:135], s[100:101] offset:64 sc0 sc1
	v_pk_mul_f32 v[28:29], v[28:29], s[98:99] op_sel_hi:[1,0]
	v_pk_mul_f32 v[30:31], v[30:31], s[98:99] op_sel_hi:[1,0]
	v_pk_mul_f32 v[24:25], v[24:25], s[98:99] op_sel_hi:[1,0]
	v_pk_mul_f32 v[26:27], v[26:27], s[98:99] op_sel_hi:[1,0]
	v_pk_mul_f32 v[20:21], v[20:21], s[98:99] op_sel_hi:[1,0]
	v_pk_mul_f32 v[22:23], v[22:23], s[98:99] op_sel_hi:[1,0]
	v_pk_mul_f32 v[16:17], v[16:17], s[98:99] op_sel_hi:[1,0]
	v_pk_mul_f32 v[18:19], v[18:19], s[98:99] op_sel_hi:[1,0]
	v_cvt_pk_bf16_f32 v136, v28, v29
	v_cvt_pk_bf16_f32 v137, v30, v31
	v_cvt_pk_bf16_f32 v138, v24, v25
	v_cvt_pk_bf16_f32 v139, v26, v27
	v_cvt_pk_bf16_f32 v140, v20, v21
	v_cvt_pk_bf16_f32 v141, v22, v23
	v_cvt_pk_bf16_f32 v142, v16, v17
	v_cvt_pk_bf16_f32 v143, v18, v19
	s_nop 1
	v_permlane16_swap_b32_e32 v136, v138
	v_permlane16_swap_b32_e32 v137, v139
	v_permlane16_swap_b32_e32 v140, v142
	v_permlane16_swap_b32_e32 v141, v143
	global_store_dwordx4 v154, v[136:139], s[100:101] sc0 sc1
	global_store_dwordx4 v154, v[140:143], s[100:101] offset:64 sc0 sc1
	v_pk_mul_f32 v[12:13], v[12:13], s[98:99] op_sel_hi:[1,0]
	v_pk_mul_f32 v[14:15], v[14:15], s[98:99] op_sel_hi:[1,0]
	v_pk_mul_f32 v[8:9], v[8:9], s[98:99] op_sel_hi:[1,0]
	v_pk_mul_f32 v[10:11], v[10:11], s[98:99] op_sel_hi:[1,0]
	v_pk_mul_f32 v[4:5], v[4:5], s[98:99] op_sel_hi:[1,0]
	v_pk_mul_f32 v[6:7], v[6:7], s[98:99] op_sel_hi:[1,0]
	v_pk_mul_f32 v[0:1], v[0:1], s[98:99] op_sel_hi:[1,0]
	v_pk_mul_f32 v[2:3], v[2:3], s[98:99] op_sel_hi:[1,0]
	v_cvt_pk_bf16_f32 v144, v12, v13
	v_cvt_pk_bf16_f32 v145, v14, v15
	v_cvt_pk_bf16_f32 v146, v8, v9
	v_cvt_pk_bf16_f32 v147, v10, v11
	v_cvt_pk_bf16_f32 v148, v4, v5
	v_cvt_pk_bf16_f32 v149, v6, v7
	v_cvt_pk_bf16_f32 v150, v0, v1
	v_cvt_pk_bf16_f32 v151, v2, v3
	s_nop 1
	v_permlane16_swap_b32_e32 v144, v146
	v_permlane16_swap_b32_e32 v145, v147
	v_permlane16_swap_b32_e32 v148, v150
	v_permlane16_swap_b32_e32 v149, v151
	global_store_dwordx4 v155, v[144:147], s[100:101] sc0 sc1
	global_store_dwordx4 v155, v[148:151], s[100:101] offset:64 sc0 sc1
	s_branch .Lfe_join_B
; DI unsigned pack2(float a, float b) { v2f f = {a, b}; return __builtin_bit_cast(unsigned, __builtin_convertvector(f, v2bf)); }
; DI float silu_f(float v) { return v / (1.f + fexp(-v)); }
;   DI u32x2 pack(int, int, float a, float b, float c, float d, float&) const { u32x2 v; v.x = pack2(a, b); v.y = pack2(c, d); return v; }
; template <class ARow, class Epi>
; DI void gemm_tile(const ARow& arow, long a_kstride, const u16* __restrict__ Bt, long ldb, int K, int m0, int n0,
;                   const Epi& epi, char* smem) {
;     ...
;     for (int mi = 0; mi < 4; ++mi) {
;       const int m = m0 + wm * 64 + mi * 16 + fr;
;       float ss = 0.f;
;       u32x2 pk[4];
; #pragma unroll
;       for (int ni = 0; ni < 4; ++ni) pk[ni] = epi.pack(m, nh + ni * 16 + fq * 4, acc[ni][mi][0], acc[ni][mi][1], acc[ni][mi][2], acc[ni][mi][3], ss);
;       epi.finish16(m, nh, ss);
;       u16* rp = epi.rowp(m) + nh;
; #pragma unroll
;       for (int pp = 0; pp < 2; ++pp) {
;         u32x2 a = pk[2 * pp], b = pk[2 * pp + 1];
;         const u32x2 rx = __builtin_amdgcn_permlane16_swap(a.x, b.x, false, false);
;         const u32x2 ry = __builtin_amdgcn_permlane16_swap(a.y, b.y, false, false);
;         const int nst = (fq & 1) ? ((2 * pp + 1) * 16 + (fq - 1) * 4) : ((2 * pp) * 16 + fq * 4);
;         *(u32x4*)(rp + nst) = (u32x4){rx[0], ry[0], rx[1], ry[1]};
;       }
;   DI u32x2 pack(int m, int n, float a, float b, float c, float d, float& ss) const {
;     if (n < q_end) { a *= qscale; b *= qscale; c *= qscale; d *= qscale; }
;     else if (n >= z_start) { a = silu_f(a); b = silu_f(b); c = silu_f(c); d = silu_f(d); }
;     ss += a * a + b * b + c * c + d * d;
;     u32x2 v; v.x = pack2(a, b); v.y = pack2(c, d);
;     return v;
.Lfe_B_not_q:
	s_cmpk_ge_u32 s99, 0xc00
	s_cbranch_scc0 .Lfe_B_not_z
	s_cmpk_lt_u32 s99, 0x1000
	s_cbranch_scc0 .Lfe_B_not_z
	s_load_dwordx2 s[100:101], s[56:57], 0x130
	v_and_b32_e32 v152, 1, v84
	v_mul_u32_u24_e32 v152, 12, v152
	v_lshl_add_u32 v152, v84, 2, v152
	v_add_u32_e32 v152, v152, v68
	v_lshl_add_u32 v152, v66, 12, v152
	v_lshlrev_b32_e32 v152, 1, v152
	v_add_u32_e32 v153, 0x20000, v152
	v_add_u32_e32 v154, 0x40000, v152
	v_add_u32_e32 v155, 0x60000, v152
	s_nop 3
	v_mul_f32_e32 v156, 0xbfb8aa3b, v60
	v_mul_f32_e32 v157, 0xbfb8aa3b, v61
	v_mul_f32_e32 v158, 0xbfb8aa3b, v62
	v_mul_f32_e32 v159, 0xbfb8aa3b, v63
	v_mul_f32_e32 v160, 0xbfb8aa3b, v56
	v_mul_f32_e32 v161, 0xbfb8aa3b, v57
	v_mul_f32_e32 v162, 0xbfb8aa3b, v58
	v_mul_f32_e32 v163, 0xbfb8aa3b, v59
	v_exp_f32_e32 v156, v156
	v_exp_f32_e32 v157, v157
	v_exp_f32_e32 v158, v158
	v_exp_f32_e32 v159, v159
	v_exp_f32_e32 v160, v160
	v_exp_f32_e32 v161, v161
	v_exp_f32_e32 v162, v162
	v_exp_f32_e32 v163, v163
	v_add_f32_e32 v156, 1.0, v156
	v_add_f32_e32 v157, 1.0, v157
	v_add_f32_e32 v158, 1.0, v158
	v_add_f32_e32 v159, 1.0, v159
	v_add_f32_e32 v160, 1.0, v160
	v_add_f32_e32 v161, 1.0, v161
	v_add_f32_e32 v162, 1.0, v162
	v_add_f32_e32 v163, 1.0, v163
	v_rcp_f32_e32 v156, v156
	v_rcp_f32_e32 v157, v157
	v_rcp_f32_e32 v158, v158
	v_rcp_f32_e32 v159, v159
	v_rcp_f32_e32 v160, v160
	v_rcp_f32_e32 v161, v161
	v_rcp_f32_e32 v162, v162
	v_rcp_f32_e32 v163, v163
	v_mul_f32_e32 v60, v60, v156
	v_mul_f32_e32 v61, v61, v157
	v_mul_f32_e32 v62, v62, v158
	v_mul_f32_e32 v63, v63, v159
	v_mul_f32_e32 v56, v56, v160
	v_mul_f32_e32 v57, v57, v161
	v_mul_f32_e32 v58, v58, v162
	v_mul_f32_e32 v59, v59, v163
	v_mul_f32_e32 v156, 0xbfb8aa3b, v52
	v_mul_f32_e32 v157, 0xbfb8aa3b, v53
	v_mul_f32_e32 v158, 0xbfb8aa3b, v54
	v_mul_f32_e32 v159, 0xbfb8aa3b, v55
	v_mul_f32_e32 v160, 0xbfb8aa3b, v48
	v_mul_f32_e32 v161, 0xbfb8aa3b, v49
	v_mul_f32_e32 v162, 0xbfb8aa3b, v50
	v_mul_f32_e32 v163, 0xbfb8aa3b, v51
	v_exp_f32_e32 v156, v156
	v_exp_f32_e32 v157, v157
	v_exp_f32_e32 v158, v158
	v_exp_f32_e32 v159, v159
	v_exp_f32_e32 v160, v160
	v_exp_f32_e32 v161, v161
	v_exp_f32_e32 v162, v162
	v_exp_f32_e32 v163, v163
	v_add_f32_e32 v156, 1.0, v156
	v_add_f32_e32 v157, 1.0, v157
	v_add_f32_e32 v158, 1.0, v158
	v_add_f32_e32 v159, 1.0, v159
	v_add_f32_e32 v160, 1.0, v160
	v_add_f32_e32 v161, 1.0, v161
	v_add_f32_e32 v162, 1.0, v162
	v_add_f32_e32 v163, 1.0, v163
	v_rcp_f32_e32 v156, v156
	v_rcp_f32_e32 v157, v157
	v_rcp_f32_e32 v158, v158
	v_rcp_f32_e32 v159, v159
	v_rcp_f32_e32 v160, v160
	v_rcp_f32_e32 v161, v161
	v_rcp_f32_e32 v162, v162
	v_rcp_f32_e32 v163, v163
	v_mul_f32_e32 v52, v52, v156
	v_mul_f32_e32 v53, v53, v157
	v_mul_f32_e32 v54, v54, v158
	v_mul_f32_e32 v55, v55, v159
	v_mul_f32_e32 v48, v48, v160
	v_mul_f32_e32 v49, v49, v161
	v_mul_f32_e32 v50, v50, v162
	v_mul_f32_e32 v51, v51, v163
	v_cvt_pk_bf16_f32 v120, v60, v61
	v_cvt_pk_bf16_f32 v121, v62, v63
	v_cvt_pk_bf16_f32 v122, v56, v57
	v_cvt_pk_bf16_f32 v123, v58, v59
	v_cvt_pk_bf16_f32 v124, v52, v53
	v_cvt_pk_bf16_f32 v125, v54, v55
	v_cvt_pk_bf16_f32 v126, v48, v49
	v_cvt_pk_bf16_f32 v127, v50, v51
	s_nop 1
	v_permlane16_swap_b32_e32 v120, v122
	v_permlane16_swap_b32_e32 v121, v123
	v_permlane16_swap_b32_e32 v124, v126
	v_permlane16_swap_b32_e32 v125, v127
	s_waitcnt lgkmcnt(0)
	global_store_dwordx4 v152, v[120:123], s[100:101] sc0 sc1
	global_store_dwordx4 v152, v[124:127], s[100:101] offset:64 sc0 sc1
	v_mul_f32_e32 v156, 0xbfb8aa3b, v44
	v_mul_f32_e32 v157, 0xbfb8aa3b, v45
	v_mul_f32_e32 v158, 0xbfb8aa3b, v46
	v_mul_f32_e32 v159, 0xbfb8aa3b, v47
	v_mul_f32_e32 v160, 0xbfb8aa3b, v40
	v_mul_f32_e32 v161, 0xbfb8aa3b, v41
	v_mul_f32_e32 v162, 0xbfb8aa3b, v42
	v_mul_f32_e32 v163, 0xbfb8aa3b, v43
	v_exp_f32_e32 v156, v156
	v_exp_f32_e32 v157, v157
	v_exp_f32_e32 v158, v158
	v_exp_f32_e32 v159, v159
	v_exp_f32_e32 v160, v160
	v_exp_f32_e32 v161, v161
	v_exp_f32_e32 v162, v162
	v_exp_f32_e32 v163, v163
	v_add_f32_e32 v156, 1.0, v156
	v_add_f32_e32 v157, 1.0, v157
	v_add_f32_e32 v158, 1.0, v158
	v_add_f32_e32 v159, 1.0, v159
	v_add_f32_e32 v160, 1.0, v160
	v_add_f32_e32 v161, 1.0, v161
	v_add_f32_e32 v162, 1.0, v162
	v_add_f32_e32 v163, 1.0, v163
	v_rcp_f32_e32 v156, v156
	v_rcp_f32_e32 v157, v157
	v_rcp_f32_e32 v158, v158
	v_rcp_f32_e32 v159, v159
	v_rcp_f32_e32 v160, v160
	v_rcp_f32_e32 v161, v161
	v_rcp_f32_e32 v162, v162
	v_rcp_f32_e32 v163, v163
	v_mul_f32_e32 v44, v44, v156
	v_mul_f32_e32 v45, v45, v157
	v_mul_f32_e32 v46, v46, v158
	v_mul_f32_e32 v47, v47, v159
	v_mul_f32_e32 v40, v40, v160
	v_mul_f32_e32 v41, v41, v161
	v_mul_f32_e32 v42, v42, v162
	v_mul_f32_e32 v43, v43, v163
	v_mul_f32_e32 v156, 0xbfb8aa3b, v36
	v_mul_f32_e32 v157, 0xbfb8aa3b, v37
	v_mul_f32_e32 v158, 0xbfb8aa3b, v38
	v_mul_f32_e32 v159, 0xbfb8aa3b, v39
	v_mul_f32_e32 v160, 0xbfb8aa3b, v32
	v_mul_f32_e32 v161, 0xbfb8aa3b, v33
	v_mul_f32_e32 v162, 0xbfb8aa3b, v34
	v_mul_f32_e32 v163, 0xbfb8aa3b, v35
	v_exp_f32_e32 v156, v156
	v_exp_f32_e32 v157, v157
	v_exp_f32_e32 v158, v158
	v_exp_f32_e32 v159, v159
	v_exp_f32_e32 v160, v160
	v_exp_f32_e32 v161, v161
	v_exp_f32_e32 v162, v162
	v_exp_f32_e32 v163, v163
	v_add_f32_e32 v156, 1.0, v156
	v_add_f32_e32 v157, 1.0, v157
	v_add_f32_e32 v158, 1.0, v158
	v_add_f32_e32 v159, 1.0, v159
	v_add_f32_e32 v160, 1.0, v160
	v_add_f32_e32 v161, 1.0, v161
	v_add_f32_e32 v162, 1.0, v162
	v_add_f32_e32 v163, 1.0, v163
	v_rcp_f32_e32 v156, v156
	v_rcp_f32_e32 v157, v157
	v_rcp_f32_e32 v158, v158
	v_rcp_f32_e32 v159, v159
	v_rcp_f32_e32 v160, v160
	v_rcp_f32_e32 v161, v161
	v_rcp_f32_e32 v162, v162
	v_rcp_f32_e32 v163, v163
	v_mul_f32_e32 v36, v36, v156
; DI unsigned pack2(float a, float b) { v2f f = {a, b}; return __builtin_bit_cast(unsigned, __builtin_convertvector(f, v2bf)); }
; DI float silu_f(float v) { return v / (1.f + fexp(-v)); }
;   DI u32x2 pack(int, int, float a, float b, float c, float d, float&) const { u32x2 v; v.x = pack2(a, b); v.y = pack2(c, d); return v; }
; template <class ARow, class Epi>
; DI void gemm_tile(const ARow& arow, long a_kstride, const u16* __restrict__ Bt, long ldb, int K, int m0, int n0,
;                   const Epi& epi, char* smem) {
;     ...
;     for (int mi = 0; mi < 4; ++mi) {
;       const int m = m0 + wm * 64 + mi * 16 + fr;
;       float ss = 0.f;
;       u32x2 pk[4];
; #pragma unroll
;       for (int ni = 0; ni < 4; ++ni) pk[ni] = epi.pack(m, nh + ni * 16 + fq * 4, acc[ni][mi][0], acc[ni][mi][1], acc[ni][mi][2], acc[ni][mi][3], ss);
;       epi.finish16(m, nh, ss);
;       u16* rp = epi.rowp(m) + nh;
; #pragma unroll
;       for (int pp = 0; pp < 2; ++pp) {
;         u32x2 a = pk[2 * pp], b = pk[2 * pp + 1];
;         const u32x2 rx = __builtin_amdgcn_permlane16_swap(a.x, b.x, false, false);
;         const u32x2 ry = __builtin_amdgcn_permlane16_swap(a.y, b.y, false, false);
;         const int nst = (fq & 1) ? ((2 * pp + 1) * 16 + (fq - 1) * 4) : ((2 * pp) * 16 + fq * 4);
;         *(u32x4*)(rp + nst) = (u32x4){rx[0], ry[0], rx[1], ry[1]};
;       }
;   DI u32x2 pack(int m, int n, float a, float b, float c, float d, float& ss) const {
;     if (n < q_end) { a *= qscale; b *= qscale; c *= qscale; d *= qscale; }
;     else if (n >= z_start) { a = silu_f(a); b = silu_f(b); c = silu_f(c); d = silu_f(d); }
;     ss += a * a + b * b + c * c + d * d;
;     u32x2 v; v.x = pack2(a, b); v.y = pack2(c, d);
;     return v;
	v_mul_f32_e32 v37, v37, v157
	v_mul_f32_e32 v38, v38, v158
	v_mul_f32_e32 v39, v39, v159
	v_mul_f32_e32 v32, v32, v160
	v_mul_f32_e32 v33, v33, v161
	v_mul_f32_e32 v34, v34, v162
	v_mul_f32_e32 v35, v35, v163
	v_cvt_pk_bf16_f32 v128, v44, v45
	v_cvt_pk_bf16_f32 v129, v46, v47
	v_cvt_pk_bf16_f32 v130, v40, v41
	v_cvt_pk_bf16_f32 v131, v42, v43
	v_cvt_pk_bf16_f32 v132, v36, v37
	v_cvt_pk_bf16_f32 v133, v38, v39
	v_cvt_pk_bf16_f32 v134, v32, v33
	v_cvt_pk_bf16_f32 v135, v34, v35
	s_nop 1
	v_permlane16_swap_b32_e32 v128, v130
	v_permlane16_swap_b32_e32 v129, v131
	v_permlane16_swap_b32_e32 v132, v134
	v_permlane16_swap_b32_e32 v133, v135
	global_store_dwordx4 v153, v[128:131], s[100:101] sc0 sc1
	global_store_dwordx4 v153, v[132:135], s[100:101] offset:64 sc0 sc1
	v_mul_f32_e32 v156, 0xbfb8aa3b, v28
	v_mul_f32_e32 v157, 0xbfb8aa3b, v29
	v_mul_f32_e32 v158, 0xbfb8aa3b, v30
	v_mul_f32_e32 v159, 0xbfb8aa3b, v31
	v_mul_f32_e32 v160, 0xbfb8aa3b, v24
	v_mul_f32_e32 v161, 0xbfb8aa3b, v25
	v_mul_f32_e32 v162, 0xbfb8aa3b, v26
	v_mul_f32_e32 v163, 0xbfb8aa3b, v27
	v_exp_f32_e32 v156, v156
	v_exp_f32_e32 v157, v157
	v_exp_f32_e32 v158, v158
	v_exp_f32_e32 v159, v159
	v_exp_f32_e32 v160, v160
	v_exp_f32_e32 v161, v161
	v_exp_f32_e32 v162, v162
	v_exp_f32_e32 v163, v163
	v_add_f32_e32 v156, 1.0, v156
	v_add_f32_e32 v157, 1.0, v157
	v_add_f32_e32 v158, 1.0, v158
	v_add_f32_e32 v159, 1.0, v159
	v_add_f32_e32 v160, 1.0, v160
	v_add_f32_e32 v161, 1.0, v161
	v_add_f32_e32 v162, 1.0, v162
	v_add_f32_e32 v163, 1.0, v163
	v_rcp_f32_e32 v156, v156
	v_rcp_f32_e32 v157, v157
	v_rcp_f32_e32 v158, v158
	v_rcp_f32_e32 v159, v159
	v_rcp_f32_e32 v160, v160
	v_rcp_f32_e32 v161, v161
	v_rcp_f32_e32 v162, v162
	v_rcp_f32_e32 v163, v163
	v_mul_f32_e32 v28, v28, v156
	v_mul_f32_e32 v29, v29, v157
	v_mul_f32_e32 v30, v30, v158
	v_mul_f32_e32 v31, v31, v159
	v_mul_f32_e32 v24, v24, v160
	v_mul_f32_e32 v25, v25, v161
	v_mul_f32_e32 v26, v26, v162
	v_mul_f32_e32 v27, v27, v163
	v_mul_f32_e32 v156, 0xbfb8aa3b, v20
	v_mul_f32_e32 v157, 0xbfb8aa3b, v21
	v_mul_f32_e32 v158, 0xbfb8aa3b, v22
	v_mul_f32_e32 v159, 0xbfb8aa3b, v23
	v_mul_f32_e32 v160, 0xbfb8aa3b, v16
	v_mul_f32_e32 v161, 0xbfb8aa3b, v17
	v_mul_f32_e32 v162, 0xbfb8aa3b, v18
	v_mul_f32_e32 v163, 0xbfb8aa3b, v19
	v_exp_f32_e32 v156, v156
	v_exp_f32_e32 v157, v157
	v_exp_f32_e32 v158, v158
	v_exp_f32_e32 v159, v159
	v_exp_f32_e32 v160, v160
	v_exp_f32_e32 v161, v161
	v_exp_f32_e32 v162, v162
	v_exp_f32_e32 v163, v163
	v_add_f32_e32 v156, 1.0, v156
	v_add_f32_e32 v157, 1.0, v157
	v_add_f32_e32 v158, 1.0, v158
	v_add_f32_e32 v159, 1.0, v159
	v_add_f32_e32 v160, 1.0, v160
	v_add_f32_e32 v161, 1.0, v161
	v_add_f32_e32 v162, 1.0, v162
	v_add_f32_e32 v163, 1.0, v163
	v_rcp_f32_e32 v156, v156
	v_rcp_f32_e32 v157, v157
	v_rcp_f32_e32 v158, v158
	v_rcp_f32_e32 v159, v159
	v_rcp_f32_e32 v160, v160
	v_rcp_f32_e32 v161, v161
	v_rcp_f32_e32 v162, v162
	v_rcp_f32_e32 v163, v163
	v_mul_f32_e32 v20, v20, v156
	v_mul_f32_e32 v21, v21, v157
	v_mul_f32_e32 v22, v22, v158
	v_mul_f32_e32 v23, v23, v159
	v_mul_f32_e32 v16, v16, v160
	v_mul_f32_e32 v17, v17, v161
	v_mul_f32_e32 v18, v18, v162
	v_mul_f32_e32 v19, v19, v163
	v_cvt_pk_bf16_f32 v136, v28, v29
	v_cvt_pk_bf16_f32 v137, v30, v31
	v_cvt_pk_bf16_f32 v138, v24, v25
	v_cvt_pk_bf16_f32 v139, v26, v27
	v_cvt_pk_bf16_f32 v140, v20, v21
	v_cvt_pk_bf16_f32 v141, v22, v23
	v_cvt_pk_bf16_f32 v142, v16, v17
	v_cvt_pk_bf16_f32 v143, v18, v19
	s_nop 1
	v_permlane16_swap_b32_e32 v136, v138
	v_permlane16_swap_b32_e32 v137, v139
	v_permlane16_swap_b32_e32 v140, v142
	v_permlane16_swap_b32_e32 v141, v143
	global_store_dwordx4 v154, v[136:139], s[100:101] sc0 sc1
	global_store_dwordx4 v154, v[140:143], s[100:101] offset:64 sc0 sc1
	v_mul_f32_e32 v156, 0xbfb8aa3b, v12
	v_mul_f32_e32 v157, 0xbfb8aa3b, v13
	v_mul_f32_e32 v158, 0xbfb8aa3b, v14
	v_mul_f32_e32 v159, 0xbfb8aa3b, v15
	v_mul_f32_e32 v160, 0xbfb8aa3b, v8
	v_mul_f32_e32 v161, 0xbfb8aa3b, v9
	v_mul_f32_e32 v162, 0xbfb8aa3b, v10
	v_mul_f32_e32 v163, 0xbfb8aa3b, v11
	v_exp_f32_e32 v156, v156
	v_exp_f32_e32 v157, v157
	v_exp_f32_e32 v158, v158
	v_exp_f32_e32 v159, v159
	v_exp_f32_e32 v160, v160
	v_exp_f32_e32 v161, v161
	v_exp_f32_e32 v162, v162
	v_exp_f32_e32 v163, v163
	v_add_f32_e32 v156, 1.0, v156
	v_add_f32_e32 v157, 1.0, v157
	v_add_f32_e32 v158, 1.0, v158
	v_add_f32_e32 v159, 1.0, v159
	v_add_f32_e32 v160, 1.0, v160
	v_add_f32_e32 v161, 1.0, v161
	v_add_f32_e32 v162, 1.0, v162
	v_add_f32_e32 v163, 1.0, v163
	v_rcp_f32_e32 v156, v156
	v_rcp_f32_e32 v157, v157
	v_rcp_f32_e32 v158, v158
	v_rcp_f32_e32 v159, v159
	v_rcp_f32_e32 v160, v160
	v_rcp_f32_e32 v161, v161
	v_rcp_f32_e32 v162, v162
	v_rcp_f32_e32 v163, v163
	v_mul_f32_e32 v12, v12, v156
	v_mul_f32_e32 v13, v13, v157
	v_mul_f32_e32 v14, v14, v158
	v_mul_f32_e32 v15, v15, v159
	v_mul_f32_e32 v8, v8, v160
	v_mul_f32_e32 v9, v9, v161
	v_mul_f32_e32 v10, v10, v162
	v_mul_f32_e32 v11, v11, v163
	v_mul_f32_e32 v156, 0xbfb8aa3b, v4
	v_mul_f32_e32 v157, 0xbfb8aa3b, v5
	v_mul_f32_e32 v158, 0xbfb8aa3b, v6
	v_mul_f32_e32 v159, 0xbfb8aa3b, v7
	v_mul_f32_e32 v160, 0xbfb8aa3b, v0
	v_mul_f32_e32 v161, 0xbfb8aa3b, v1
	v_mul_f32_e32 v162, 0xbfb8aa3b, v2
	v_mul_f32_e32 v163, 0xbfb8aa3b, v3
	v_exp_f32_e32 v156, v156
	v_exp_f32_e32 v157, v157
	v_exp_f32_e32 v158, v158
	v_exp_f32_e32 v159, v159
	v_exp_f32_e32 v160, v160
	v_exp_f32_e32 v161, v161
	v_exp_f32_e32 v162, v162
	v_exp_f32_e32 v163, v163
	v_add_f32_e32 v156, 1.0, v156
	v_add_f32_e32 v157, 1.0, v157
	v_add_f32_e32 v158, 1.0, v158
	v_add_f32_e32 v159, 1.0, v159
	v_add_f32_e32 v160, 1.0, v160
	v_add_f32_e32 v161, 1.0, v161
	v_add_f32_e32 v162, 1.0, v162
	v_add_f32_e32 v163, 1.0, v163
	v_rcp_f32_e32 v156, v156
	v_rcp_f32_e32 v157, v157
	v_rcp_f32_e32 v158, v158
	v_rcp_f32_e32 v159, v159
	v_rcp_f32_e32 v160, v160
	v_rcp_f32_e32 v161, v161
	v_rcp_f32_e32 v162, v162
	v_rcp_f32_e32 v163, v163
	v_mul_f32_e32 v4, v4, v156
	v_mul_f32_e32 v5, v5, v157
	v_mul_f32_e32 v6, v6, v158
	v_mul_f32_e32 v7, v7, v159
	v_mul_f32_e32 v0, v0, v160
	v_mul_f32_e32 v1, v1, v161
	v_mul_f32_e32 v2, v2, v162
	v_mul_f32_e32 v3, v3, v163
	v_cvt_pk_bf16_f32 v144, v12, v13
	v_cvt_pk_bf16_f32 v145, v14, v15
	v_cvt_pk_bf16_f32 v146, v8, v9
	v_cvt_pk_bf16_f32 v147, v10, v11
	v_cvt_pk_bf16_f32 v148, v4, v5
	v_cvt_pk_bf16_f32 v149, v6, v7
	v_cvt_pk_bf16_f32 v150, v0, v1
	v_cvt_pk_bf16_f32 v151, v2, v3
	s_nop 1
	v_permlane16_swap_b32_e32 v144, v146
	v_permlane16_swap_b32_e32 v145, v147
	v_permlane16_swap_b32_e32 v148, v150
	v_permlane16_swap_b32_e32 v149, v151
	global_store_dwordx4 v155, v[144:147], s[100:101] sc0 sc1
	global_store_dwordx4 v155, v[148:151], s[100:101] offset:64 sc0 sc1
	s_branch .Lfe_join_B
; DI unsigned pack2(float a, float b) { v2f f = {a, b}; return __builtin_bit_cast(unsigned, __builtin_convertvector(f, v2bf)); }
; DI float silu_f(float v) { return v / (1.f + fexp(-v)); }
; DI int ltid() { int x = threadIdx.x; asm volatile("" : "+v"(x)); return x; }
;   DI u32x2 pack(int, int, float a, float b, float c, float d, float&) const { u32x2 v; v.x = pack2(a, b); v.y = pack2(c, d); return v; }
; template <class ARow, class Epi>
; DI void gemm_tile(const ARow& arow, long a_kstride, const u16* __restrict__ Bt, long ldb, int K, int m0, int n0,
;                   const Epi& epi, char* smem) {
;     ...
;     for (int mi = 0; mi < 4; ++mi) {
;       const int m = m0 + wm * 64 + mi * 16 + fr;
;       float ss = 0.f;
;       u32x2 pk[4];
; #pragma unroll
;       for (int ni = 0; ni < 4; ++ni) pk[ni] = epi.pack(m, nh + ni * 16 + fq * 4, acc[ni][mi][0], acc[ni][mi][1], acc[ni][mi][2], acc[ni][mi][3], ss);
;       epi.finish16(m, nh, ss);
;       u16* rp = epi.rowp(m) + nh;
; #pragma unroll
;       for (int pp = 0; pp < 2; ++pp) {
;         u32x2 a = pk[2 * pp], b = pk[2 * pp + 1];
;         const u32x2 rx = __builtin_amdgcn_permlane16_swap(a.x, b.x, false, false);
;         const u32x2 ry = __builtin_amdgcn_permlane16_swap(a.y, b.y, false, false);
;         const int nst = (fq & 1) ? ((2 * pp + 1) * 16 + (fq - 1) * 4) : ((2 * pp) * 16 + fq * 4);
;         *(u32x4*)(rp + nst) = (u32x4){rx[0], ry[0], rx[1], ry[1]};
;       }
;   DI u32x2 pack(int m, int n, float a, float b, float c, float d, float& ss) const {
;     if (n < q_end) { a *= qscale; b *= qscale; c *= qscale; d *= qscale; }
;     else if (n >= z_start) { a = silu_f(a); b = silu_f(b); c = silu_f(c); d = silu_f(d); }
;     ss += a * a + b * b + c * c + d * d;
;     u32x2 v; v.x = pack2(a, b); v.y = pack2(c, d);
;     return v;
;   }
;   DI void finish16(int m, int nh, float ss) const {
;     if (nh >= kn_lo && nh < kn_hi) {
;       ss += __shfl_xor(ss, 16); ss += __shfl_xor(ss, 32);
; #pragma unroll
;       for (int o = 8; o > 0; o >>= 1) ss = fmaxf(ss, __shfl_xor(ss, o));
;       if ((ltid() & 63) == 0) atomicMax(kmax2 + (m >> 13) * 64 + (nh >> 6), __float_as_uint(ss));
;     }
.Lfe_B_not_z:
	s_cmpk_ge_u32 s99, 0x400
	s_cbranch_scc0 .Lfe_B_not_k
	s_cmpk_lt_u32 s99, 0x800
	s_cbranch_scc0 .Lfe_B_not_k
	s_load_dwordx2 s[100:101], s[56:57], 0x130
	v_and_b32_e32 v152, 1, v84
	v_mul_u32_u24_e32 v152, 12, v152
	v_lshl_add_u32 v152, v84, 2, v152
	v_add_u32_e32 v152, v152, v68
	v_lshl_add_u32 v152, v66, 12, v152
	v_lshlrev_b32_e32 v152, 1, v152
	v_add_u32_e32 v153, 0x20000, v152
	v_add_u32_e32 v154, 0x40000, v152
	v_add_u32_e32 v155, 0x60000, v152
	s_load_dwordx2 s[98:99], s[56:57], 0x100
	v_lshrrev_b32_e32 v174, 6, v68
	v_lshrrev_b32_e32 v175, 13, v66
	v_lshl_add_u32 v174, v175, 6, v174
	v_lshlrev_b32_e32 v174, 2, v174
	s_nop 3
	v_pk_mul_f32 v[156:157], v[60:61], v[60:61]
	v_pk_mul_f32 v[158:159], v[62:63], v[62:63]
	v_pk_mul_f32 v[160:161], v[56:57], v[56:57]
	v_pk_mul_f32 v[162:163], v[58:59], v[58:59]
	v_pk_mul_f32 v[164:165], v[52:53], v[52:53]
	v_pk_mul_f32 v[166:167], v[54:55], v[54:55]
	v_pk_mul_f32 v[168:169], v[48:49], v[48:49]
	v_pk_mul_f32 v[170:171], v[50:51], v[50:51]
	v_add_f32_e32 v172, v157, v156
	v_add_f32_e32 v172, v158, v172
	v_add_f32_e32 v172, v159, v172
	v_add_f32_e32 v173, v161, v160
	v_add_f32_e32 v173, v162, v173
	v_add_f32_e32 v173, v163, v173
	v_add_f32_e32 v172, v172, v173
	v_add_f32_e32 v173, v165, v164
	v_add_f32_e32 v173, v166, v173
	v_add_f32_e32 v173, v167, v173
	v_add_f32_e32 v172, v172, v173
	v_add_f32_e32 v173, v169, v168
	v_add_f32_e32 v173, v170, v173
	v_add_f32_e32 v173, v171, v173
	v_add_f32_e32 v172, v172, v173
	v_mov_b32_e32 v173, v172
	s_nop 1
	v_permlane16_swap_b32_e32 v173, v172
	v_add_f32_e32 v172, v172, v173
	v_mov_b32_e32 v173, v172
	s_nop 1
	v_permlane32_swap_b32_e32 v173, v172
	v_add_f32_e32 v172, v172, v173
	s_nop 1
	v_max_f32_dpp v172, v172, v172 row_ror:8 row_mask:0xf bank_mask:0xf
	s_nop 1
	v_max_f32_dpp v173, v172, v172 row_shl:4 row_mask:0xf bank_mask:0x5
	v_max_f32_dpp v173, v172, v172 row_shr:4 row_mask:0xf bank_mask:0xa
	s_nop 1
	v_max_f32_dpp v172, v173, v173 quad_perm:[2,3,0,1] row_mask:0xf bank_mask:0xf
	s_nop 1
	v_max_f32_dpp v172, v172, v172 quad_perm:[1,0,3,2] row_mask:0xf bank_mask:0xf
	v_mov_b32_e32 v176, v172
	v_pk_mul_f32 v[156:157], v[44:45], v[44:45]
	v_pk_mul_f32 v[158:159], v[46:47], v[46:47]
	v_pk_mul_f32 v[160:161], v[40:41], v[40:41]
	v_pk_mul_f32 v[162:163], v[42:43], v[42:43]
	v_pk_mul_f32 v[164:165], v[36:37], v[36:37]
	v_pk_mul_f32 v[166:167], v[38:39], v[38:39]
	v_pk_mul_f32 v[168:169], v[32:33], v[32:33]
	v_pk_mul_f32 v[170:171], v[34:35], v[34:35]
	v_add_f32_e32 v172, v157, v156
	v_add_f32_e32 v172, v158, v172
	v_add_f32_e32 v172, v159, v172
	v_add_f32_e32 v173, v161, v160
	v_add_f32_e32 v173, v162, v173
	v_add_f32_e32 v173, v163, v173
	v_add_f32_e32 v172, v172, v173
	v_add_f32_e32 v173, v165, v164
	v_add_f32_e32 v173, v166, v173
	v_add_f32_e32 v173, v167, v173
	v_add_f32_e32 v172, v172, v173
	v_add_f32_e32 v173, v169, v168
	v_add_f32_e32 v173, v170, v173
	v_add_f32_e32 v173, v171, v173
	v_add_f32_e32 v172, v172, v173
	v_mov_b32_e32 v173, v172
	s_nop 1
	v_permlane16_swap_b32_e32 v173, v172
	v_add_f32_e32 v172, v172, v173
	v_mov_b32_e32 v173, v172
	s_nop 1
	v_permlane32_swap_b32_e32 v173, v172
	v_add_f32_e32 v172, v172, v173
	s_nop 1
	v_max_f32_dpp v172, v172, v172 row_ror:8 row_mask:0xf bank_mask:0xf
	s_nop 1
	v_max_f32_dpp v173, v172, v172 row_shl:4 row_mask:0xf bank_mask:0x5
	v_max_f32_dpp v173, v172, v172 row_shr:4 row_mask:0xf bank_mask:0xa
	s_nop 1
	v_max_f32_dpp v172, v173, v173 quad_perm:[2,3,0,1] row_mask:0xf bank_mask:0xf
	s_nop 1
	v_max_f32_dpp v172, v172, v172 quad_perm:[1,0,3,2] row_mask:0xf bank_mask:0xf
	v_max_f32_e32 v176, v176, v172
	v_pk_mul_f32 v[156:157], v[28:29], v[28:29]
	v_pk_mul_f32 v[158:159], v[30:31], v[30:31]
	v_pk_mul_f32 v[160:161], v[24:25], v[24:25]
	v_pk_mul_f32 v[162:163], v[26:27], v[26:27]
	v_pk_mul_f32 v[164:165], v[20:21], v[20:21]
	v_pk_mul_f32 v[166:167], v[22:23], v[22:23]
	v_pk_mul_f32 v[168:169], v[16:17], v[16:17]
	v_pk_mul_f32 v[170:171], v[18:19], v[18:19]
	v_add_f32_e32 v172, v157, v156
	v_add_f32_e32 v172, v158, v172
	v_add_f32_e32 v172, v159, v172
	v_add_f32_e32 v173, v161, v160
	v_add_f32_e32 v173, v162, v173
	v_add_f32_e32 v173, v163, v173
	v_add_f32_e32 v172, v172, v173
	v_add_f32_e32 v173, v165, v164
	v_add_f32_e32 v173, v166, v173
	v_add_f32_e32 v173, v167, v173
	v_add_f32_e32 v172, v172, v173
	v_add_f32_e32 v173, v169, v168
	v_add_f32_e32 v173, v170, v173
	v_add_f32_e32 v173, v171, v173
	v_add_f32_e32 v172, v172, v173
	v_mov_b32_e32 v173, v172
	s_nop 1
	v_permlane16_swap_b32_e32 v173, v172
	v_add_f32_e32 v172, v172, v173
	v_mov_b32_e32 v173, v172
	s_nop 1
	v_permlane32_swap_b32_e32 v173, v172
	v_add_f32_e32 v172, v172, v173
	s_nop 1
	v_max_f32_dpp v172, v172, v172 row_ror:8 row_mask:0xf bank_mask:0xf
	s_nop 1
	v_max_f32_dpp v173, v172, v172 row_shl:4 row_mask:0xf bank_mask:0x5
	v_max_f32_dpp v173, v172, v172 row_shr:4 row_mask:0xf bank_mask:0xa
	s_nop 1
	v_max_f32_dpp v172, v173, v173 quad_perm:[2,3,0,1] row_mask:0xf bank_mask:0xf
	s_nop 1
	v_max_f32_dpp v172, v172, v172 quad_perm:[1,0,3,2] row_mask:0xf bank_mask:0xf
	v_max_f32_e32 v176, v176, v172
	v_pk_mul_f32 v[156:157], v[12:13], v[12:13]
	v_pk_mul_f32 v[158:159], v[14:15], v[14:15]
	v_pk_mul_f32 v[160:161], v[8:9], v[8:9]
	v_pk_mul_f32 v[162:163], v[10:11], v[10:11]
	v_pk_mul_f32 v[164:165], v[4:5], v[4:5]
	v_pk_mul_f32 v[166:167], v[6:7], v[6:7]
	v_pk_mul_f32 v[168:169], v[0:1], v[0:1]
	v_pk_mul_f32 v[170:171], v[2:3], v[2:3]
	v_add_f32_e32 v172, v157, v156
	v_add_f32_e32 v172, v158, v172
	v_add_f32_e32 v172, v159, v172
	v_add_f32_e32 v173, v161, v160
	v_add_f32_e32 v173, v162, v173
	v_add_f32_e32 v173, v163, v173
	v_add_f32_e32 v172, v172, v173
	v_add_f32_e32 v173, v165, v164
	v_add_f32_e32 v173, v166, v173
	v_add_f32_e32 v173, v167, v173
	v_add_f32_e32 v172, v172, v173
	v_add_f32_e32 v173, v169, v168
	v_add_f32_e32 v173, v170, v173
	v_add_f32_e32 v173, v171, v173
	v_add_f32_e32 v172, v172, v173
	v_mov_b32_e32 v173, v172
	s_nop 1
	v_permlane16_swap_b32_e32 v173, v172
	v_add_f32_e32 v172, v172, v173
	v_mov_b32_e32 v173, v172
	s_nop 1
	v_permlane32_swap_b32_e32 v173, v172
	v_add_f32_e32 v172, v172, v173
	s_nop 1
	v_max_f32_dpp v172, v172, v172 row_ror:8 row_mask:0xf bank_mask:0xf
	s_nop 1
	v_max_f32_dpp v173, v172, v172 row_shl:4 row_mask:0xf bank_mask:0x5
	v_max_f32_dpp v173, v172, v172 row_shr:4 row_mask:0xf bank_mask:0xa
	s_nop 1
	v_max_f32_dpp v172, v173, v173 quad_perm:[2,3,0,1] row_mask:0xf bank_mask:0xf
	s_nop 1
	v_max_f32_dpp v172, v172, v172 quad_perm:[1,0,3,2] row_mask:0xf bank_mask:0xf
	v_max_f32_e32 v176, v176, v172
	v_and_b32_e32 v175, 63, v222
	v_cmp_eq_u32_e32 vcc, 0, v175
	s_waitcnt lgkmcnt(0)
; DI int ltid() { int x = threadIdx.x; asm volatile("" : "+v"(x)); return x; }
;   DI u32x2 pack(int, int, float a, float b, float c, float d, float&) const { u32x2 v; v.x = pack2(a, b); v.y = pack2(c, d); return v; }
; template <class ARow, class Epi>
; DI void gemm_tile(const ARow& arow, long a_kstride, const u16* __restrict__ Bt, long ldb, int K, int m0, int n0,
;                   const Epi& epi, char* smem) {
;     ...
;     for (int mi = 0; mi < 4; ++mi) {
;       const int m = m0 + wm * 64 + mi * 16 + fr;
;       float ss = 0.f;
;       u32x2 pk[4];
; #pragma unroll
;       for (int ni = 0; ni < 4; ++ni) pk[ni] = epi.pack(m, nh + ni * 16 + fq * 4, acc[ni][mi][0], acc[ni][mi][1], acc[ni][mi][2], acc[ni][mi][3], ss);
;       epi.finish16(m, nh, ss);
;       u16* rp = epi.rowp(m) + nh;
; #pragma unroll
;       for (int pp = 0; pp < 2; ++pp) {
;         u32x2 a = pk[2 * pp], b = pk[2 * pp + 1];
;         const u32x2 rx = __builtin_amdgcn_permlane16_swap(a.x, b.x, false, false);
;         const u32x2 ry = __builtin_amdgcn_permlane16_swap(a.y, b.y, false, false);
;         const int nst = (fq & 1) ? ((2 * pp + 1) * 16 + (fq - 1) * 4) : ((2 * pp) * 16 + fq * 4);
;         *(u32x4*)(rp + nst) = (u32x4){rx[0], ry[0], rx[1], ry[1]};
;       }
;   DI void finish16(int m, int nh, float ss) const {
;     if (nh >= kn_lo && nh < kn_hi) {
;       ss += __shfl_xor(ss, 16); ss += __shfl_xor(ss, 32);
; #pragma unroll
;       for (int o = 8; o > 0; o >>= 1) ss = fmaxf(ss, __shfl_xor(ss, o));
;       if ((ltid() & 63) == 0) atomicMax(kmax2 + (m >> 13) * 64 + (nh >> 6), __float_as_uint(ss));
;     }
	s_and_b64 exec, exec, vcc
	global_atomic_umax v174, v176, s[98:99] offset:512
	s_mov_b64 exec, -1
	s_nop 3
	v_cvt_pk_bf16_f32 v120, v60, v61
	v_cvt_pk_bf16_f32 v121, v62, v63
	v_cvt_pk_bf16_f32 v122, v56, v57
	v_cvt_pk_bf16_f32 v123, v58, v59
	v_cvt_pk_bf16_f32 v124, v52, v53
	v_cvt_pk_bf16_f32 v125, v54, v55
	v_cvt_pk_bf16_f32 v126, v48, v49
	v_cvt_pk_bf16_f32 v127, v50, v51
	s_nop 1
	v_permlane16_swap_b32_e32 v120, v122
	v_permlane16_swap_b32_e32 v121, v123
	v_permlane16_swap_b32_e32 v124, v126
	v_permlane16_swap_b32_e32 v125, v127
	s_waitcnt lgkmcnt(0)
	global_store_dwordx4 v152, v[120:123], s[100:101] sc0 sc1
	global_store_dwordx4 v152, v[124:127], s[100:101] offset:64 sc0 sc1
	v_cvt_pk_bf16_f32 v128, v44, v45
	v_cvt_pk_bf16_f32 v129, v46, v47
	v_cvt_pk_bf16_f32 v130, v40, v41
	v_cvt_pk_bf16_f32 v131, v42, v43
	v_cvt_pk_bf16_f32 v132, v36, v37
	v_cvt_pk_bf16_f32 v133, v38, v39
	v_cvt_pk_bf16_f32 v134, v32, v33
	v_cvt_pk_bf16_f32 v135, v34, v35
	s_nop 1
	v_permlane16_swap_b32_e32 v128, v130
	v_permlane16_swap_b32_e32 v129, v131
	v_permlane16_swap_b32_e32 v132, v134
	v_permlane16_swap_b32_e32 v133, v135
	global_store_dwordx4 v153, v[128:131], s[100:101] sc0 sc1
	global_store_dwordx4 v153, v[132:135], s[100:101] offset:64 sc0 sc1
	v_cvt_pk_bf16_f32 v136, v28, v29
	v_cvt_pk_bf16_f32 v137, v30, v31
	v_cvt_pk_bf16_f32 v138, v24, v25
	v_cvt_pk_bf16_f32 v139, v26, v27
	v_cvt_pk_bf16_f32 v140, v20, v21
	v_cvt_pk_bf16_f32 v141, v22, v23
	v_cvt_pk_bf16_f32 v142, v16, v17
	v_cvt_pk_bf16_f32 v143, v18, v19
	s_nop 1
	v_permlane16_swap_b32_e32 v136, v138
	v_permlane16_swap_b32_e32 v137, v139
	v_permlane16_swap_b32_e32 v140, v142
	v_permlane16_swap_b32_e32 v141, v143
	global_store_dwordx4 v154, v[136:139], s[100:101] sc0 sc1
	global_store_dwordx4 v154, v[140:143], s[100:101] offset:64 sc0 sc1
	v_cvt_pk_bf16_f32 v144, v12, v13
	v_cvt_pk_bf16_f32 v145, v14, v15
	v_cvt_pk_bf16_f32 v146, v8, v9
	v_cvt_pk_bf16_f32 v147, v10, v11
	v_cvt_pk_bf16_f32 v148, v4, v5
	v_cvt_pk_bf16_f32 v149, v6, v7
	v_cvt_pk_bf16_f32 v150, v0, v1
	v_cvt_pk_bf16_f32 v151, v2, v3
	s_nop 1
	v_permlane16_swap_b32_e32 v144, v146
	v_permlane16_swap_b32_e32 v145, v147
	v_permlane16_swap_b32_e32 v148, v150
	v_permlane16_swap_b32_e32 v149, v151
	global_store_dwordx4 v155, v[144:147], s[100:101] sc0 sc1
	global_store_dwordx4 v155, v[148:151], s[100:101] offset:64 sc0 sc1
	s_branch .Lfe_join_B

; DI unsigned pack2(float a, float b) { v2f f = {a, b}; return __builtin_bit_cast(unsigned, __builtin_convertvector(f, v2bf)); }
; DI float silu_f(float v) { return v / (1.f + fexp(-v)); }
;   DI u32x2 pack(int, int, float a, float b, float c, float d, float&) const { u32x2 v; v.x = pack2(a, b); v.y = pack2(c, d); return v; }
; template <class ARow, class Epi>
; DI void gemm_tile(const ARow& arow, long a_kstride, const u16* __restrict__ Bt, long ldb, int K, int m0, int n0,
;                   const Epi& epi, char* smem) {
;     ...
;     for (int mi = 0; mi < 4; ++mi) {
;       const int m = m0 + wm * 64 + mi * 16 + fr;
;       float ss = 0.f;
;       u32x2 pk[4];
; #pragma unroll
;       for (int ni = 0; ni < 4; ++ni) pk[ni] = epi.pack(m, nh + ni * 16 + fq * 4, acc[ni][mi][0], acc[ni][mi][1], acc[ni][mi][2], acc[ni][mi][3], ss);
;       epi.finish16(m, nh, ss);
;       u16* rp = epi.rowp(m) + nh;
; #pragma unroll
;       for (int pp = 0; pp < 2; ++pp) {
;         u32x2 a = pk[2 * pp], b = pk[2 * pp + 1];
;         const u32x2 rx = __builtin_amdgcn_permlane16_swap(a.x, b.x, false, false);
;         const u32x2 ry = __builtin_amdgcn_permlane16_swap(a.y, b.y, false, false);
;         const int nst = (fq & 1) ? ((2 * pp + 1) * 16 + (fq - 1) * 4) : ((2 * pp) * 16 + fq * 4);
;         *(u32x4*)(rp + nst) = (u32x4){rx[0], ry[0], rx[1], ry[1]};
;       }
;   DI u32x2 pack(int m, int n, float a, float b, float c, float d, float& ss) const {
;     if (n < q_end) { a *= qscale; b *= qscale; c *= qscale; d *= qscale; }
;     else if (n >= z_start) { a = silu_f(a); b = silu_f(b); c = silu_f(c); d = silu_f(d); }
;     ss += a * a + b * b + c * c + d * d;
;     u32x2 v; v.x = pack2(a, b); v.y = pack2(c, d);
;     return v;
.LBB0_1345:
	v_cvt_pk_bf16_f32 v75, v54, v55
	v_and_b32_e32 v54, 16, v83
	s_waitcnt lgkmcnt(0)
	v_ashrrev_i32_e32 v67, 31, v66
	v_cvt_pk_bf16_f32 v74, v52, v53
	v_lshlrev_b64 v[52:53], 13, v[66:67]
	v_add_u32_e32 v55, 12, v72
	v_cmp_eq_u32_e32 vcc, 0, v54
	v_ashrrev_i32_e32 v69, 31, v68
	v_lshl_add_u64 v[52:53], s[18:19], 0, v[52:53]
	v_cndmask_b32_e32 v54, v55, v72, vcc
	v_cvt_pk_bf16_f32 v76, v48, v49
	v_cvt_pk_bf16_f32 v77, v50, v51
	v_cvt_pk_bf16_f32 v50, v56, v57
	v_cvt_pk_bf16_f32 v51, v58, v59
	v_cvt_pk_bf16_f32 v48, v60, v61
	v_cvt_pk_bf16_f32 v49, v62, v63
	v_lshl_add_u64 v[52:53], v[68:69], 1, v[52:53]
	v_lshlrev_b32_e32 v64, 1, v54
	v_permlane16_swap_b32_e32 v48, v50
	v_permlane16_swap_b32_e32 v49, v51
	v_lshl_add_u64 v[54:55], v[52:53], 0, v[64:65]
	global_store_dwordx4 v[54:55], v[48:51], off sc0 sc1
	v_permlane16_swap_b32_e32 v74, v76
	s_nop 0
	v_add_u32_e32 v48, 44, v72
	v_or_b32_e32 v49, 32, v72
	v_cndmask_b32_e32 v48, v48, v49, vcc
	v_lshlrev_b32_e32 v48, 1, v48
	v_mov_b32_e32 v49, v65
	v_permlane16_swap_b32_e32 v75, v77
	v_lshl_add_u64 v[50:51], v[52:53], 0, v[48:49]
	global_store_dwordx4 v[50:51], v[74:77], off sc0 sc1
	s_and_saveexec_b64 s[0:1], s[4:5]
	s_xor_b64 s[0:1], exec, s[0:1]
	s_cbranch_execz .LBB0_1348
	s_cmpk_lt_u32 s38, 0xc00
	s_cbranch_scc1 .LBB0_1348
	v_mul_f32_e32 v49, 0xbfb8aa3b, v44
	v_exp_f32_e32 v50, v49
	v_mul_f32_e32 v49, 0xbfb8aa3b, v45
	v_exp_f32_e32 v51, v49
	s_nop 0
	v_pk_add_f32 v[50:51], v[50:51], 1.0 op_sel_hi:[1,0]
	s_nop 0
	v_rcp_f32_e32 v49, v50
	v_mul_f32_e32 v52, 0xbfb8aa3b, v46
	v_mul_f32_e32 v53, 0xbfb8aa3b, v47
	v_exp_f32_e32 v52, v52
	v_exp_f32_e32 v53, v53
	v_mul_f32_e32 v44, v44, v49
	v_pk_add_f32 v[52:53], v[52:53], 1.0 op_sel_hi:[1,0]
	v_rcp_f32_e32 v49, v51
	s_nop 0
	v_mul_f32_e32 v45, v45, v49
	v_rcp_f32_e32 v49, v52
	s_nop 0
	v_mul_f32_e32 v46, v46, v49
	v_rcp_f32_e32 v49, v53
	s_nop 0
	v_mul_f32_e32 v47, v47, v49

; DI unsigned pack2(float a, float b) { v2f f = {a, b}; return __builtin_bit_cast(unsigned, __builtin_convertvector(f, v2bf)); }
; DI float silu_f(float v) { return v / (1.f + fexp(-v)); }
;   DI u32x2 pack(int, int, float a, float b, float c, float d, float&) const { u32x2 v; v.x = pack2(a, b); v.y = pack2(c, d); return v; }
; template <class ARow, class Epi>
; DI void gemm_tile(const ARow& arow, long a_kstride, const u16* __restrict__ Bt, long ldb, int K, int m0, int n0,
;                   const Epi& epi, char* smem) {
;     ...
;     for (int mi = 0; mi < 4; ++mi) {
;       const int m = m0 + wm * 64 + mi * 16 + fr;
;       float ss = 0.f;
;       u32x2 pk[4];
; #pragma unroll
;       for (int ni = 0; ni < 4; ++ni) pk[ni] = epi.pack(m, nh + ni * 16 + fq * 4, acc[ni][mi][0], acc[ni][mi][1], acc[ni][mi][2], acc[ni][mi][3], ss);
;       epi.finish16(m, nh, ss);
;       u16* rp = epi.rowp(m) + nh;
; #pragma unroll
;       for (int pp = 0; pp < 2; ++pp) {
;         u32x2 a = pk[2 * pp], b = pk[2 * pp + 1];
;         const u32x2 rx = __builtin_amdgcn_permlane16_swap(a.x, b.x, false, false);
;         const u32x2 ry = __builtin_amdgcn_permlane16_swap(a.y, b.y, false, false);
;         const int nst = (fq & 1) ? ((2 * pp + 1) * 16 + (fq - 1) * 4) : ((2 * pp) * 16 + fq * 4);
;         *(u32x4*)(rp + nst) = (u32x4){rx[0], ry[0], rx[1], ry[1]};
;       }
;   DI u32x2 pack(int m, int n, float a, float b, float c, float d, float& ss) const {
;     if (n < q_end) { a *= qscale; b *= qscale; c *= qscale; d *= qscale; }
;     else if (n >= z_start) { a = silu_f(a); b = silu_f(b); c = silu_f(c); d = silu_f(d); }
;     ss += a * a + b * b + c * c + d * d;
;     u32x2 v; v.x = pack2(a, b); v.y = pack2(c, d);
;     return v;
.LBB0_1369:
	v_or_b32_e32 v54, 16, v66
	v_ashrrev_i32_e32 v55, 31, v54
	s_waitcnt lgkmcnt(0)
	v_cvt_pk_bf16_f32 v50, v36, v37
	v_lshlrev_b64 v[36:37], 13, v[54:55]
	v_lshl_add_u64 v[36:37], s[18:19], 0, v[36:37]
	v_cvt_pk_bf16_f32 v52, v32, v33
	v_cvt_pk_bf16_f32 v53, v34, v35
	v_cvt_pk_bf16_f32 v34, v40, v41
	v_cvt_pk_bf16_f32 v35, v42, v43
	v_cvt_pk_bf16_f32 v32, v44, v45
	v_cvt_pk_bf16_f32 v33, v46, v47
	v_lshl_add_u64 v[36:37], v[68:69], 1, v[36:37]
	v_cvt_pk_bf16_f32 v51, v38, v39
	v_permlane16_swap_b32_e32 v32, v34
	v_permlane16_swap_b32_e32 v33, v35
	v_lshl_add_u64 v[38:39], v[36:37], 0, v[64:65]
	v_mov_b32_e32 v49, v65
	global_store_dwordx4 v[38:39], v[32:35], off sc0 sc1
	v_permlane16_swap_b32_e32 v50, v52
	v_permlane16_swap_b32_e32 v51, v53
	v_lshl_add_u64 v[32:33], v[36:37], 0, v[48:49]
	global_store_dwordx4 v[32:33], v[50:53], off sc0 sc1
	s_and_saveexec_b64 s[0:1], s[4:5]
	s_xor_b64 s[0:1], exec, s[0:1]
	s_cbranch_execz .LBB0_1372
	s_cmpk_lt_u32 s38, 0xc00
	s_cbranch_scc1 .LBB0_1372
	v_mul_f32_e32 v32, 0xbfb8aa3b, v28
	v_mul_f32_e32 v33, 0xbfb8aa3b, v29
	v_exp_f32_e32 v32, v32
	v_exp_f32_e32 v33, v33
	s_nop 0
	v_pk_add_f32 v[32:33], v[32:33], 1.0 op_sel_hi:[1,0]
	s_nop 0
	v_rcp_f32_e32 v34, v32
	s_nop 0
	v_mul_f32_e32 v28, v28, v34
	v_mul_f32_e32 v34, 0xbfb8aa3b, v30
	v_mul_f32_e32 v35, 0xbfb8aa3b, v31
	v_exp_f32_e32 v34, v34
	v_exp_f32_e32 v35, v35
	s_nop 0
	v_pk_add_f32 v[34:35], v[34:35], 1.0 op_sel_hi:[1,0]
	v_rcp_f32_e32 v32, v33
	s_nop 0
	v_mul_f32_e32 v29, v29, v32
	v_rcp_f32_e32 v32, v34
	s_nop 0
	v_mul_f32_e32 v30, v30, v32
	v_rcp_f32_e32 v32, v35
	s_nop 0
	v_mul_f32_e32 v31, v31, v32

; DI unsigned pack2(float a, float b) { v2f f = {a, b}; return __builtin_bit_cast(unsigned, __builtin_convertvector(f, v2bf)); }
; DI float silu_f(float v) { return v / (1.f + fexp(-v)); }
;   DI u32x2 pack(int, int, float a, float b, float c, float d, float&) const { u32x2 v; v.x = pack2(a, b); v.y = pack2(c, d); return v; }
; template <class ARow, class Epi>
; DI void gemm_tile(const ARow& arow, long a_kstride, const u16* __restrict__ Bt, long ldb, int K, int m0, int n0,
;                   const Epi& epi, char* smem) {
;     ...
;     for (int mi = 0; mi < 4; ++mi) {
;       const int m = m0 + wm * 64 + mi * 16 + fr;
;       float ss = 0.f;
;       u32x2 pk[4];
; #pragma unroll
;       for (int ni = 0; ni < 4; ++ni) pk[ni] = epi.pack(m, nh + ni * 16 + fq * 4, acc[ni][mi][0], acc[ni][mi][1], acc[ni][mi][2], acc[ni][mi][3], ss);
;       epi.finish16(m, nh, ss);
;       u16* rp = epi.rowp(m) + nh;
; #pragma unroll
;       for (int pp = 0; pp < 2; ++pp) {
;         u32x2 a = pk[2 * pp], b = pk[2 * pp + 1];
;         const u32x2 rx = __builtin_amdgcn_permlane16_swap(a.x, b.x, false, false);
;         const u32x2 ry = __builtin_amdgcn_permlane16_swap(a.y, b.y, false, false);
;         const int nst = (fq & 1) ? ((2 * pp + 1) * 16 + (fq - 1) * 4) : ((2 * pp) * 16 + fq * 4);
;         *(u32x4*)(rp + nst) = (u32x4){rx[0], ry[0], rx[1], ry[1]};
;       }
;   DI u32x2 pack(int m, int n, float a, float b, float c, float d, float& ss) const {
;     if (n < q_end) { a *= qscale; b *= qscale; c *= qscale; d *= qscale; }
;     else if (n >= z_start) { a = silu_f(a); b = silu_f(b); c = silu_f(c); d = silu_f(d); }
;     ss += a * a + b * b + c * c + d * d;
;     u32x2 v; v.x = pack2(a, b); v.y = pack2(c, d);
;     return v;
.LBB0_1393:
	v_or_b32_e32 v36, 32, v66
	v_ashrrev_i32_e32 v37, 31, v36
	v_cvt_pk_bf16_f32 v32, v20, v21
	v_lshlrev_b64 v[20:21], 13, v[36:37]
	v_lshl_add_u64 v[20:21], s[18:19], 0, v[20:21]
	v_cvt_pk_bf16_f32 v34, v16, v17
	v_cvt_pk_bf16_f32 v35, v18, v19
	v_cvt_pk_bf16_f32 v18, v24, v25
	v_cvt_pk_bf16_f32 v19, v26, v27
	v_cvt_pk_bf16_f32 v16, v28, v29
	v_cvt_pk_bf16_f32 v17, v30, v31
	v_lshl_add_u64 v[20:21], v[68:69], 1, v[20:21]
	s_waitcnt lgkmcnt(0)
	v_cvt_pk_bf16_f32 v33, v22, v23
	v_permlane16_swap_b32_e32 v16, v18
	v_permlane16_swap_b32_e32 v17, v19
	v_lshl_add_u64 v[22:23], v[20:21], 0, v[64:65]
	v_mov_b32_e32 v49, v65
	global_store_dwordx4 v[22:23], v[16:19], off sc0 sc1
	v_permlane16_swap_b32_e32 v32, v34
	v_permlane16_swap_b32_e32 v33, v35
	v_lshl_add_u64 v[16:17], v[20:21], 0, v[48:49]
	global_store_dwordx4 v[16:17], v[32:35], off sc0 sc1
	s_and_saveexec_b64 s[0:1], s[4:5]
	s_xor_b64 s[0:1], exec, s[0:1]
	s_cbranch_execz .LBB0_1396
	s_cmpk_lt_u32 s38, 0xc00
	s_cbranch_scc1 .LBB0_1396
	v_mul_f32_e32 v16, 0xbfb8aa3b, v12
	v_mul_f32_e32 v17, 0xbfb8aa3b, v13
	v_exp_f32_e32 v16, v16
	v_exp_f32_e32 v17, v17
	s_nop 0
	v_pk_add_f32 v[16:17], v[16:17], 1.0 op_sel_hi:[1,0]
	s_nop 0
	v_rcp_f32_e32 v18, v16
	s_nop 0
	v_mul_f32_e32 v12, v12, v18
	v_mul_f32_e32 v18, 0xbfb8aa3b, v14
	v_mul_f32_e32 v19, 0xbfb8aa3b, v15
	v_exp_f32_e32 v18, v18
	v_exp_f32_e32 v19, v19
	s_nop 0
	v_pk_add_f32 v[18:19], v[18:19], 1.0 op_sel_hi:[1,0]
	v_rcp_f32_e32 v16, v17
	s_nop 0
	v_mul_f32_e32 v13, v13, v16
	v_rcp_f32_e32 v16, v18
	s_nop 0
	v_mul_f32_e32 v14, v14, v16
	v_rcp_f32_e32 v16, v19
	s_nop 0
	v_mul_f32_e32 v15, v15, v16

; template <class ARow, class Epi>
; DI void gemm_tile(const ARow& arow, long a_kstride, const u16* __restrict__ Bt, long ldb, int K, int m0, int n0,
;                   const Epi& epi, char* smem) {
;     ...
;       u16* rp = epi.rowp(m) + nh;
; #pragma unroll
;       for (int pp = 0; pp < 2; ++pp) {
;         u32x2 a = pk[2 * pp], b = pk[2 * pp + 1];
;         const u32x2 rx = __builtin_amdgcn_permlane16_swap(a.x, b.x, false, false);
;         const u32x2 ry = __builtin_amdgcn_permlane16_swap(a.y, b.y, false, false);
;         const int nst = (fq & 1) ? ((2 * pp + 1) * 16 + (fq - 1) * 4) : ((2 * pp) * 16 + fq * 4);
;         *(u32x4*)(rp + nst) = (u32x4){rx[0], ry[0], rx[1], ry[1]};
;       }
.LBB0_1699:
	s_or_b64 exec, exec, s[0:1]
	v_cvt_pk_bf16_f32 v4, v4, v5
	v_cvt_pk_bf16_f32 v5, v6, v7
	v_cvt_pk_bf16_f32 v6, v0, v1
	v_cvt_pk_bf16_f32 v7, v2, v3
	v_or_b32_e32 v2, 48, v74
	v_mov_b64_e32 v[0:1], s[14:15]
	v_mad_i64_i32 v[0:1], s[0:1], v2, s34, v[0:1]
	v_cvt_pk_bf16_f32 v18, v8, v9
	v_cvt_pk_bf16_f32 v19, v10, v11
	v_cvt_pk_bf16_f32 v16, v12, v13
	v_cvt_pk_bf16_f32 v17, v14, v15
	v_lshl_add_u64 v[0:1], v[66:67], 1, v[0:1]
	v_mov_b32_e32 v49, v65
	v_permlane16_swap_b32_e32 v16, v18
	v_permlane16_swap_b32_e32 v17, v19
	v_lshl_add_u64 v[2:3], v[0:1], 0, v[64:65]
	v_permlane16_swap_b32_e32 v4, v6
	v_permlane16_swap_b32_e32 v5, v7
	v_lshl_add_u64 v[0:1], v[0:1], 0, v[48:49]
	global_store_dwordx4 v[2:3], v[16:19], off sc0 sc1
	global_store_dwordx4 v[0:1], v[4:7], off sc0 sc1

; template <class ARow, class Epi>
; DI void gemm_tile(const ARow& arow, long a_kstride, const u16* __restrict__ Bt, long ldb, int K, int m0, int n0,
;                   const Epi& epi, char* smem) {
;     ...
;   const int fr = lane & 15, fq = lane >> 4;
;   int foff[2];
; #pragma unroll
;   for (int ks = 0; ks < 2; ++ks) foff[ks] = fr * 128 + ((((4 * ks + fq) ^ ((fr >> 1) & 7))) << 4);
;   f32x4 acc[4][4];
; #pragma unroll
;   for (int a = 0; a < 4; ++a)
; #pragma unroll
;     for (int b = 0; b < 4; ++b) acc[a][b] = (f32x4){0.f, 0.f, 0.f, 0.f};
;   const int KT = K >> 6;
;   GEMM_STAGE(0, 0);
;   asm volatile("s_waitcnt vmcnt(0)" ::: "memory");
;   __syncthreads();
;   for (int kt = 0; kt < KT; ++kt) {
;     const int cur = kt & 1;
;     if (kt + 1 < KT) GEMM_STAGE(cur ^ 1, kt + 1);
;     const char* sa = smem + cur * 32768 + wm * 64 * 128;
;     const char* sb = smem + cur * 32768 + 16384 + wn * 64 * 128;
; #pragma unroll
;     for (int ks = 0; ks < 2; ++ks) {
;       bf16x8 wf[4], af[4];
; #pragma unroll
;       for (int j = 0; j < 4; ++j) {
;         wf[j] = *(const bf16x8*)(sb + j * 2048 + foff[ks]);
;         af[j] = *(const bf16x8*)(sa + j * 2048 + foff[ks]);
;       }
; #pragma unroll
;       for (int ni = 0; ni < 4; ++ni)
; #pragma unroll
;         for (int mi = 0; mi < 4; ++mi) acc[ni][mi] = __builtin_amdgcn_mfma_f32_16x16x32_bf16(wf[ni], af[mi], acc[ni][mi], 0, 0, 0);
;     }
;     asm volatile("s_waitcnt vmcnt(0)" ::: "memory");
;     __syncthreads();
;   }
.LBB0_1702:
	s_and_b32 s6, s1, 0x8000
	s_xor_b32 s7, s6, 0x8000
	v_add_u32_e32 v108, s7, v90
	v_add_u32_e32 v91, s6, v88
	v_or_b32_e32 v116, s6, v89
	v_readfirstlane_b32 s6, v108
	v_add_u32_e32 v109, 0x4000, v108
	v_lshl_add_u64 v[92:93], v[66:67], 0, s[4:5]
	v_add_u32_e32 v110, 0x400, v108
	v_readfirstlane_b32 s7, v109
	s_mov_b32 m0, s6
	v_lshl_add_u64 v[94:95], v[68:69], 0, s[4:5]
	v_add_u32_e32 v111, 0x4400, v108
	v_readfirstlane_b32 s8, v110
	global_load_lds_dwordx4 v[92:93], off
	s_mov_b32 m0, s7
	v_lshl_add_u64 v[96:97], v[70:71], 0, s[4:5]
	v_add_u32_e32 v113, 0x800, v108
	v_readfirstlane_b32 s9, v111
	global_load_lds_dwordx4 v[94:95], off
	s_mov_b32 m0, s8
	v_lshl_add_u64 v[98:99], v[72:73], 0, s[4:5]
	v_add_u32_e32 v114, 0x4800, v108
	v_readfirstlane_b32 s10, v113
	global_load_lds_dwordx4 v[96:97], off
	s_mov_b32 m0, s9
	v_lshl_add_u64 v[100:101], v[74:75], 0, s[4:5]
	v_add_u32_e32 v115, 0xc00, v108
	v_readfirstlane_b32 s11, v114
	global_load_lds_dwordx4 v[98:99], off
	s_mov_b32 m0, s10
	v_lshl_add_u64 v[102:103], v[76:77], 0, s[4:5]
	v_add_u32_e32 v108, 0x4c00, v108
	v_readfirstlane_b32 s26, v115
	global_load_lds_dwordx4 v[100:101], off
	s_mov_b32 m0, s11
	v_lshl_add_u64 v[104:105], v[78:79], 0, s[4:5]
	v_readfirstlane_b32 s27, v108
	global_load_lds_dwordx4 v[102:103], off
	s_mov_b32 m0, s26
	v_lshl_add_u64 v[106:107], v[80:81], 0, s[4:5]
	global_load_lds_dwordx4 v[104:105], off
	s_mov_b32 m0, s27
	v_add_u32_e32 v117, v116, v87
	global_load_lds_dwordx4 v[106:107], off
	v_add_u32_e32 v112, v91, v87
	ds_read_b128 v[92:95], v117 offset:16384
	ds_read_b128 v[96:99], v112
	ds_read_b128 v[100:103], v117 offset:18432
	ds_read_b128 v[104:107], v112 offset:2048
	ds_read_b128 v[108:111], v112 offset:4096
	ds_read_b128 v[112:115], v112 offset:6144
	s_waitcnt lgkmcnt(0)
	v_mfma_f32_16x16x32_bf16 v[60:63], v[92:95], v[96:99], v[60:63]
	v_add_u32_e32 v116, v116, v86
	v_add_u32_e32 v91, v91, v86
	s_add_i32 s1, s1, 0x8000
	v_mfma_f32_16x16x32_bf16 v[56:59], v[92:95], v[104:107], v[56:59]
	s_add_u32 s4, s4, 0x80
	s_addc_u32 s5, s5, 0
	s_cmpk_eq_i32 s4, 0x780
	v_mfma_f32_16x16x32_bf16 v[48:51], v[92:95], v[108:111], v[48:51]
	v_mfma_f32_16x16x32_bf16 v[40:43], v[92:95], v[112:115], v[40:43]
	v_mfma_f32_16x16x32_bf16 v[36:39], v[100:103], v[96:99], v[36:39]
	v_mfma_f32_16x16x32_bf16 v[32:35], v[100:103], v[104:107], v[32:35]
	v_mfma_f32_16x16x32_bf16 v[28:31], v[100:103], v[108:111], v[28:31]
	v_mfma_f32_16x16x32_bf16 v[24:27], v[100:103], v[112:115], v[24:27]
	ds_read_b128 v[92:95], v117 offset:20480
	ds_read_b128 v[100:103], v117 offset:22528
	s_waitcnt lgkmcnt(0)
	v_mfma_f32_16x16x32_bf16 v[20:23], v[92:95], v[96:99], v[20:23]
	v_mfma_f32_16x16x32_bf16 v[16:19], v[92:95], v[104:107], v[16:19]
	v_mfma_f32_16x16x32_bf16 v[12:15], v[92:95], v[108:111], v[12:15]
	v_mfma_f32_16x16x32_bf16 v[8:11], v[92:95], v[112:115], v[8:11]
	ds_read_b128 v[92:95], v116 offset:16384
	v_mfma_f32_16x16x32_bf16 v[4:7], v[100:103], v[96:99], v[4:7]
	v_mfma_f32_16x16x32_bf16 v[0:3], v[100:103], v[104:107], v[0:3]
	v_mfma_f32_16x16x32_bf16 v[52:55], v[100:103], v[108:111], v[52:55]
	v_mfma_f32_16x16x32_bf16 v[44:47], v[100:103], v[112:115], v[44:47]
	ds_read_b128 v[96:99], v91
	ds_read_b128 v[100:103], v116 offset:18432
	ds_read_b128 v[104:107], v91 offset:2048
	ds_read_b128 v[108:111], v91 offset:4096
	ds_read_b128 v[112:115], v91 offset:6144
	s_waitcnt lgkmcnt(0)
	v_mfma_f32_16x16x32_bf16 v[60:63], v[92:95], v[96:99], v[60:63]
	v_mfma_f32_16x16x32_bf16 v[56:59], v[92:95], v[104:107], v[56:59]
	v_mfma_f32_16x16x32_bf16 v[48:51], v[92:95], v[108:111], v[48:51]
	v_mfma_f32_16x16x32_bf16 v[40:43], v[92:95], v[112:115], v[40:43]
	v_mfma_f32_16x16x32_bf16 v[36:39], v[100:103], v[96:99], v[36:39]
	v_mfma_f32_16x16x32_bf16 v[32:35], v[100:103], v[104:107], v[32:35]
	v_mfma_f32_16x16x32_bf16 v[28:31], v[100:103], v[108:111], v[28:31]
	v_mfma_f32_16x16x32_bf16 v[24:27], v[100:103], v[112:115], v[24:27]
	ds_read_b128 v[92:95], v116 offset:20480
	ds_read_b128 v[100:103], v116 offset:22528
	s_waitcnt vmcnt(0)
	s_waitcnt vmcnt(0) lgkmcnt(0)
	v_mfma_f32_16x16x32_bf16 v[20:23], v[92:95], v[96:99], v[20:23]
	s_barrier
	v_mfma_f32_16x16x32_bf16 v[16:19], v[92:95], v[104:107], v[16:19]
	v_mfma_f32_16x16x32_bf16 v[12:15], v[92:95], v[108:111], v[12:15]
	v_mfma_f32_16x16x32_bf16 v[8:11], v[92:95], v[112:115], v[8:11]
	v_mfma_f32_16x16x32_bf16 v[4:7], v[100:103], v[96:99], v[4:7]
	v_mfma_f32_16x16x32_bf16 v[0:3], v[100:103], v[104:107], v[0:3]
	v_mfma_f32_16x16x32_bf16 v[52:55], v[100:103], v[108:111], v[52:55]
	v_mfma_f32_16x16x32_bf16 v[44:47], v[100:103], v[112:115], v[44:47]
	s_cbranch_scc0 .LBB0_1702
;   DI u32x2 pack(int, int, float a, float b, float c, float d, float&) const { u32x2 v; v.x = pack2(a, b); v.y = pack2(c, d); return v; }
; template <class ARow, class Epi>
; DI void gemm_tile(const ARow& arow, long a_kstride, const u16* __restrict__ Bt, long ldb, int K, int m0, int n0,
;                   const Epi& epi, char* smem) {
;     ...
; #pragma unroll
;     for (int ks = 0; ks < 2; ++ks) {
;       bf16x8 wf[4], af[4];
; #pragma unroll
;       for (int j = 0; j < 4; ++j) {
;         wf[j] = *(const bf16x8*)(sb + j * 2048 + foff[ks]);
;         af[j] = *(const bf16x8*)(sa + j * 2048 + foff[ks]);
;       }
; #pragma unroll
;       for (int ni = 0; ni < 4; ++ni)
; #pragma unroll
;         for (int mi = 0; mi < 4; ++mi) acc[ni][mi] = __builtin_amdgcn_mfma_f32_16x16x32_bf16(wf[ni], af[mi], acc[ni][mi], 0, 0, 0);
;     }
;     asm volatile("s_waitcnt vmcnt(0)" ::: "memory");
;     __syncthreads();
;   }
;     ...
;   const int nh = n0 + wn * 64;
;   if (epi.packed(nh)) {
; #pragma unroll
;     for (int mi = 0; mi < 4; ++mi) {
;       const int m = m0 + wm * 64 + mi * 16 + fr;
;       float ss = 0.f;
;       u32x2 pk[4];
; #pragma unroll
;       for (int ni = 0; ni < 4; ++ni) pk[ni] = epi.pack(m, nh + ni * 16 + fq * 4, acc[ni][mi][0], acc[ni][mi][1], acc[ni][mi][2], acc[ni][mi][3], ss);
;       epi.finish16(m, nh, ss);
;       u16* rp = epi.rowp(m) + nh;
; #pragma unroll
;       for (int pp = 0; pp < 2; ++pp) {
;         u32x2 a = pk[2 * pp], b = pk[2 * pp + 1];
;         const u32x2 rx = __builtin_amdgcn_permlane16_swap(a.x, b.x, false, false);
;         const u32x2 ry = __builtin_amdgcn_permlane16_swap(a.y, b.y, false, false);
;         const int nst = (fq & 1) ? ((2 * pp + 1) * 16 + (fq - 1) * 4) : ((2 * pp) * 16 + fq * 4);
;         *(u32x4*)(rp + nst) = (u32x4){rx[0], ry[0], rx[1], ry[1]};
;       }
	v_add_u32_e32 v106, v89, v87
	ds_read_b128 v[66:69], v106 offset:49152
	v_add_u32_e32 v87, v88, v87
	ds_read_b128 v[70:73], v87 offset:32768
	ds_read_b128 v[74:77], v87 offset:34816
	ds_read_b128 v[78:81], v87 offset:36864
	ds_read_b128 v[90:93], v87 offset:38912
	v_add_u32_e32 v114, v89, v86
	s_waitcnt lgkmcnt(3)
	v_mfma_f32_16x16x32_bf16 v[60:63], v[66:69], v[70:73], v[60:63]
	s_waitcnt lgkmcnt(2)
	v_mfma_f32_16x16x32_bf16 v[56:59], v[66:69], v[74:77], v[56:59]
	s_waitcnt lgkmcnt(1)
	v_mfma_f32_16x16x32_bf16 v[48:51], v[66:69], v[78:81], v[48:51]
	s_waitcnt lgkmcnt(0)
	v_mfma_f32_16x16x32_bf16 v[40:43], v[66:69], v[90:93], v[40:43]
	ds_read_b128 v[66:69], v106 offset:51200
	s_waitcnt lgkmcnt(0)
	v_mfma_f32_16x16x32_bf16 v[36:39], v[66:69], v[70:73], v[36:39]
	v_mfma_f32_16x16x32_bf16 v[32:35], v[66:69], v[74:77], v[32:35]
	v_mfma_f32_16x16x32_bf16 v[94:97], v[66:69], v[78:81], v[28:31]
	v_mfma_f32_16x16x32_bf16 v[66:69], v[66:69], v[90:93], v[24:27]
	s_nop 2
	ds_read_b128 v[24:27], v106 offset:53248
	s_waitcnt lgkmcnt(0)
	v_mfma_f32_16x16x32_bf16 v[102:105], v[24:27], v[90:93], v[8:11]
	s_nop 2
	ds_read_b128 v[8:11], v106 offset:55296
	v_mfma_f32_16x16x32_bf16 v[20:23], v[24:27], v[70:73], v[20:23]
	s_waitcnt lgkmcnt(0)
	v_mfma_f32_16x16x32_bf16 v[70:73], v[8:11], v[70:73], v[4:7]
	s_nop 2
	ds_read_b128 v[4:7], v114 offset:49152
	v_mfma_f32_16x16x32_bf16 v[98:101], v[24:27], v[78:81], v[12:15]
	s_nop 2
	v_add_u32_e32 v12, v88, v86
	v_mfma_f32_16x16x32_bf16 v[16:19], v[24:27], v[74:77], v[16:19]
	ds_read_b128 v[86:89], v12 offset:32768
	ds_read_b128 v[106:109], v12 offset:36864
	ds_read_b128 v[110:113], v12 offset:38912
	v_mfma_f32_16x16x32_bf16 v[0:3], v[8:11], v[74:77], v[0:3]
	v_mfma_f32_16x16x32_bf16 v[74:77], v[8:11], v[78:81], v[52:55]
	v_mfma_f32_16x16x32_bf16 v[78:81], v[8:11], v[90:93], v[44:47]
	ds_read_b128 v[90:93], v12 offset:34816
	s_waitcnt lgkmcnt(3)
	v_mfma_f32_16x16x32_bf16 v[60:63], v[4:7], v[86:89], v[60:63]
	s_waitcnt lgkmcnt(0)
	v_mfma_f32_16x16x32_bf16 v[44:47], v[4:7], v[90:93], v[56:59]
	v_mfma_f32_16x16x32_bf16 v[28:31], v[4:7], v[106:109], v[48:51]
	v_mfma_f32_16x16x32_bf16 v[12:15], v[4:7], v[110:113], v[40:43]
	ds_read_b128 v[4:7], v114 offset:51200
	s_waitcnt lgkmcnt(0)
	v_mfma_f32_16x16x32_bf16 v[56:59], v[4:7], v[86:89], v[36:39]
	v_mfma_f32_16x16x32_bf16 v[40:43], v[4:7], v[90:93], v[32:35]
	v_mfma_f32_16x16x32_bf16 v[24:27], v[4:7], v[106:109], v[94:97]
	v_mfma_f32_16x16x32_bf16 v[8:11], v[4:7], v[110:113], v[66:69]
	ds_read_b128 v[4:7], v114 offset:53248
	s_nop 0
	ds_read_b128 v[94:97], v114 offset:55296
	s_waitcnt vmcnt(0)
	s_waitcnt lgkmcnt(0)
	v_mfma_f32_16x16x32_bf16 v[32:35], v[94:97], v[90:93], v[0:3]
	s_nop 2
	v_or_b32_e32 v0, s0, v64
	v_lshl_or_b32 v66, v84, 6, s35
	v_lshlrev_b32_e32 v68, 2, v83
	v_mfma_f32_16x16x32_bf16 v[52:55], v[4:7], v[86:89], v[20:23]
	v_cmp_lt_i32_e32 vcc, s30, v66
	v_or_b32_e32 v64, v66, v68
	v_mfma_f32_16x16x32_bf16 v[36:39], v[4:7], v[90:93], v[16:19]
	s_barrier
	v_mfma_f32_16x16x32_bf16 v[20:23], v[4:7], v[106:109], v[98:101]
	v_mfma_f32_16x16x32_bf16 v[4:7], v[4:7], v[110:113], v[102:105]
	v_mfma_f32_16x16x32_bf16 v[48:51], v[94:97], v[86:89], v[70:73]
	v_mfma_f32_16x16x32_bf16 v[16:19], v[94:97], v[106:109], v[74:77]
	s_nop 2
	v_lshl_add_u32 v74, v85, 6, v0
	v_mfma_f32_16x16x32_bf16 v[0:3], v[94:97], v[110:113], v[78:81]
	s_nop 7
	v_readfirstlane_b32 s99, v66
	s_cmpk_ge_u32 s99, 0x300
	s_cbranch_scc0 .Lfe_C_not_plain
	s_cmpk_lt_u32 s99, 0xa00
	s_cbranch_scc0 .Lfe_C_not_plain
	s_load_dwordx2 s[100:101], s[56:57], 0x130
	v_and_b32_e32 v152, 1, v83
	v_mul_u32_u24_e32 v152, 12, v152
	v_lshl_add_u32 v152, v83, 2, v152
	v_add_u32_e32 v152, v152, v66
	v_mul_u32_u24_e32 v153, 0xe00, v74
	v_add_u32_e32 v152, v152, v153
	v_lshlrev_b32_e32 v152, 1, v152
	v_add_u32_e32 v153, 0x1c000, v152
	v_add_u32_e32 v154, 0x38000, v152
	v_add_u32_e32 v155, 0x54000, v152
	s_nop 3
	v_cvt_pk_bf16_f32 v120, v60, v61
	v_cvt_pk_bf16_f32 v121, v62, v63
	v_cvt_pk_bf16_f32 v122, v56, v57
	v_cvt_pk_bf16_f32 v123, v58, v59
	v_cvt_pk_bf16_f32 v124, v52, v53
	v_cvt_pk_bf16_f32 v125, v54, v55
	v_cvt_pk_bf16_f32 v126, v48, v49
	v_cvt_pk_bf16_f32 v127, v50, v51
	s_nop 1
	v_permlane16_swap_b32_e32 v120, v122
	v_permlane16_swap_b32_e32 v121, v123
	v_permlane16_swap_b32_e32 v124, v126
	v_permlane16_swap_b32_e32 v125, v127
	s_waitcnt lgkmcnt(0)
	global_store_dwordx4 v152, v[120:123], s[100:101] sc0 sc1
	global_store_dwordx4 v152, v[124:127], s[100:101] offset:64 sc0 sc1
	v_cvt_pk_bf16_f32 v128, v44, v45
	v_cvt_pk_bf16_f32 v129, v46, v47
	v_cvt_pk_bf16_f32 v130, v40, v41
	v_cvt_pk_bf16_f32 v131, v42, v43
	v_cvt_pk_bf16_f32 v132, v36, v37
	v_cvt_pk_bf16_f32 v133, v38, v39
	v_cvt_pk_bf16_f32 v134, v32, v33
	v_cvt_pk_bf16_f32 v135, v34, v35
	s_nop 1
	v_permlane16_swap_b32_e32 v128, v130
	v_permlane16_swap_b32_e32 v129, v131
	v_permlane16_swap_b32_e32 v132, v134
	v_permlane16_swap_b32_e32 v133, v135
	global_store_dwordx4 v153, v[128:131], s[100:101] sc0 sc1
	global_store_dwordx4 v153, v[132:135], s[100:101] offset:64 sc0 sc1
	v_cvt_pk_bf16_f32 v136, v28, v29
	v_cvt_pk_bf16_f32 v137, v30, v31
	v_cvt_pk_bf16_f32 v138, v24, v25
	v_cvt_pk_bf16_f32 v139, v26, v27
	v_cvt_pk_bf16_f32 v140, v20, v21
	v_cvt_pk_bf16_f32 v141, v22, v23
	v_cvt_pk_bf16_f32 v142, v16, v17
	v_cvt_pk_bf16_f32 v143, v18, v19
	s_nop 1
	v_permlane16_swap_b32_e32 v136, v138
	v_permlane16_swap_b32_e32 v137, v139
	v_permlane16_swap_b32_e32 v140, v142
	v_permlane16_swap_b32_e32 v141, v143
	global_store_dwordx4 v154, v[136:139], s[100:101] sc0 sc1
	global_store_dwordx4 v154, v[140:143], s[100:101] offset:64 sc0 sc1
	v_cvt_pk_bf16_f32 v144, v12, v13
	v_cvt_pk_bf16_f32 v145, v14, v15
	v_cvt_pk_bf16_f32 v146, v8, v9
	v_cvt_pk_bf16_f32 v147, v10, v11
	v_cvt_pk_bf16_f32 v148, v4, v5
	v_cvt_pk_bf16_f32 v149, v6, v7
	v_cvt_pk_bf16_f32 v150, v0, v1
	v_cvt_pk_bf16_f32 v151, v2, v3
	s_nop 1
	v_permlane16_swap_b32_e32 v144, v146
	v_permlane16_swap_b32_e32 v145, v147
	v_permlane16_swap_b32_e32 v148, v150
	v_permlane16_swap_b32_e32 v149, v151
	global_store_dwordx4 v155, v[144:147], s[100:101] sc0 sc1
	global_store_dwordx4 v155, v[148:151], s[100:101] offset:64 sc0 sc1
	s_branch .Lfe_join_C
; DI unsigned pack2(float a, float b) { v2f f = {a, b}; return __builtin_bit_cast(unsigned, __builtin_convertvector(f, v2bf)); }
; DI float silu_f(float v) { return v / (1.f + fexp(-v)); }
;   DI u32x2 pack(int, int, float a, float b, float c, float d, float&) const { u32x2 v; v.x = pack2(a, b); v.y = pack2(c, d); return v; }
; template <class ARow, class Epi>
; DI void gemm_tile(const ARow& arow, long a_kstride, const u16* __restrict__ Bt, long ldb, int K, int m0, int n0,
;                   const Epi& epi, char* smem) {
;     ...
;     for (int mi = 0; mi < 4; ++mi) {
;       const int m = m0 + wm * 64 + mi * 16 + fr;
;       float ss = 0.f;
;       u32x2 pk[4];
; #pragma unroll
;       for (int ni = 0; ni < 4; ++ni) pk[ni] = epi.pack(m, nh + ni * 16 + fq * 4, acc[ni][mi][0], acc[ni][mi][1], acc[ni][mi][2], acc[ni][mi][3], ss);
;       epi.finish16(m, nh, ss);
;       u16* rp = epi.rowp(m) + nh;
; #pragma unroll
;       for (int pp = 0; pp < 2; ++pp) {
;         u32x2 a = pk[2 * pp], b = pk[2 * pp + 1];
;         const u32x2 rx = __builtin_amdgcn_permlane16_swap(a.x, b.x, false, false);
;         const u32x2 ry = __builtin_amdgcn_permlane16_swap(a.y, b.y, false, false);
;         const int nst = (fq & 1) ? ((2 * pp + 1) * 16 + (fq - 1) * 4) : ((2 * pp) * 16 + fq * 4);
;         *(u32x4*)(rp + nst) = (u32x4){rx[0], ry[0], rx[1], ry[1]};
;       }
;   DI u32x2 pack(int m, int n, float a, float b, float c, float d, float& ss) const {
;     if (n < q_end) { a *= qscale; b *= qscale; c *= qscale; d *= qscale; }
;     else if (n >= z_start) { a = silu_f(a); b = silu_f(b); c = silu_f(c); d = silu_f(d); }
;     ss += a * a + b * b + c * c + d * d;
;     u32x2 v; v.x = pack2(a, b); v.y = pack2(c, d);
;     return v;
.Lfe_C_not_plain:
	s_cmpk_lt_u32 s99, 0x300
	s_cbranch_scc0 .Lfe_C_not_q
	s_load_dwordx2 s[100:101], s[56:57], 0x130
	v_and_b32_e32 v152, 1, v83
	v_mul_u32_u24_e32 v152, 12, v152
	v_lshl_add_u32 v152, v83, 2, v152
	v_add_u32_e32 v152, v152, v66
	v_mul_u32_u24_e32 v153, 0xe00, v74
	v_add_u32_e32 v152, v152, v153
	v_lshlrev_b32_e32 v152, 1, v152
	v_add_u32_e32 v153, 0x1c000, v152
	v_add_u32_e32 v154, 0x38000, v152
	v_add_u32_e32 v155, 0x54000, v152
	s_mov_b32 s98, 0x3e38aa3b
	s_nop 3
	v_pk_mul_f32 v[60:61], v[60:61], s[98:99] op_sel_hi:[1,0]
	v_pk_mul_f32 v[62:63], v[62:63], s[98:99] op_sel_hi:[1,0]
	v_pk_mul_f32 v[56:57], v[56:57], s[98:99] op_sel_hi:[1,0]
	v_pk_mul_f32 v[58:59], v[58:59], s[98:99] op_sel_hi:[1,0]
	v_pk_mul_f32 v[52:53], v[52:53], s[98:99] op_sel_hi:[1,0]
	v_pk_mul_f32 v[54:55], v[54:55], s[98:99] op_sel_hi:[1,0]
	v_pk_mul_f32 v[48:49], v[48:49], s[98:99] op_sel_hi:[1,0]
	v_pk_mul_f32 v[50:51], v[50:51], s[98:99] op_sel_hi:[1,0]
	v_cvt_pk_bf16_f32 v120, v60, v61
	v_cvt_pk_bf16_f32 v121, v62, v63
	v_cvt_pk_bf16_f32 v122, v56, v57
	v_cvt_pk_bf16_f32 v123, v58, v59
	v_cvt_pk_bf16_f32 v124, v52, v53
	v_cvt_pk_bf16_f32 v125, v54, v55
	v_cvt_pk_bf16_f32 v126, v48, v49
	v_cvt_pk_bf16_f32 v127, v50, v51
	s_nop 1
	v_permlane16_swap_b32_e32 v120, v122
	v_permlane16_swap_b32_e32 v121, v123
	v_permlane16_swap_b32_e32 v124, v126
	v_permlane16_swap_b32_e32 v125, v127
	s_waitcnt lgkmcnt(0)
	global_store_dwordx4 v152, v[120:123], s[100:101] sc0 sc1
	global_store_dwordx4 v152, v[124:127], s[100:101] offset:64 sc0 sc1
	v_pk_mul_f32 v[44:45], v[44:45], s[98:99] op_sel_hi:[1,0]
	v_pk_mul_f32 v[46:47], v[46:47], s[98:99] op_sel_hi:[1,0]
	v_pk_mul_f32 v[40:41], v[40:41], s[98:99] op_sel_hi:[1,0]
	v_pk_mul_f32 v[42:43], v[42:43], s[98:99] op_sel_hi:[1,0]
	v_pk_mul_f32 v[36:37], v[36:37], s[98:99] op_sel_hi:[1,0]
	v_pk_mul_f32 v[38:39], v[38:39], s[98:99] op_sel_hi:[1,0]
	v_pk_mul_f32 v[32:33], v[32:33], s[98:99] op_sel_hi:[1,0]
	v_pk_mul_f32 v[34:35], v[34:35], s[98:99] op_sel_hi:[1,0]
	v_cvt_pk_bf16_f32 v128, v44, v45
	v_cvt_pk_bf16_f32 v129, v46, v47
	v_cvt_pk_bf16_f32 v130, v40, v41
	v_cvt_pk_bf16_f32 v131, v42, v43
	v_cvt_pk_bf16_f32 v132, v36, v37
	v_cvt_pk_bf16_f32 v133, v38, v39
	v_cvt_pk_bf16_f32 v134, v32, v33
	v_cvt_pk_bf16_f32 v135, v34, v35
	s_nop 1
	v_permlane16_swap_b32_e32 v128, v130
	v_permlane16_swap_b32_e32 v129, v131
	v_permlane16_swap_b32_e32 v132, v134
	v_permlane16_swap_b32_e32 v133, v135
	global_store_dwordx4 v153, v[128:131], s[100:101] sc0 sc1
	global_store_dwordx4 v153, v[132:135], s[100:101] offset:64 sc0 sc1
	v_pk_mul_f32 v[28:29], v[28:29], s[98:99] op_sel_hi:[1,0]
	v_pk_mul_f32 v[30:31], v[30:31], s[98:99] op_sel_hi:[1,0]
	v_pk_mul_f32 v[24:25], v[24:25], s[98:99] op_sel_hi:[1,0]
	v_pk_mul_f32 v[26:27], v[26:27], s[98:99] op_sel_hi:[1,0]
	v_pk_mul_f32 v[20:21], v[20:21], s[98:99] op_sel_hi:[1,0]
	v_pk_mul_f32 v[22:23], v[22:23], s[98:99] op_sel_hi:[1,0]
	v_pk_mul_f32 v[16:17], v[16:17], s[98:99] op_sel_hi:[1,0]
	v_pk_mul_f32 v[18:19], v[18:19], s[98:99] op_sel_hi:[1,0]
	v_cvt_pk_bf16_f32 v136, v28, v29
	v_cvt_pk_bf16_f32 v137, v30, v31
	v_cvt_pk_bf16_f32 v138, v24, v25
	v_cvt_pk_bf16_f32 v139, v26, v27
	v_cvt_pk_bf16_f32 v140, v20, v21
	v_cvt_pk_bf16_f32 v141, v22, v23
	v_cvt_pk_bf16_f32 v142, v16, v17
	v_cvt_pk_bf16_f32 v143, v18, v19
	s_nop 1
	v_permlane16_swap_b32_e32 v136, v138
	v_permlane16_swap_b32_e32 v137, v139
	v_permlane16_swap_b32_e32 v140, v142
	v_permlane16_swap_b32_e32 v141, v143
	global_store_dwordx4 v154, v[136:139], s[100:101] sc0 sc1
	global_store_dwordx4 v154, v[140:143], s[100:101] offset:64 sc0 sc1
	v_pk_mul_f32 v[12:13], v[12:13], s[98:99] op_sel_hi:[1,0]
	v_pk_mul_f32 v[14:15], v[14:15], s[98:99] op_sel_hi:[1,0]
	v_pk_mul_f32 v[8:9], v[8:9], s[98:99] op_sel_hi:[1,0]
	v_pk_mul_f32 v[10:11], v[10:11], s[98:99] op_sel_hi:[1,0]
	v_pk_mul_f32 v[4:5], v[4:5], s[98:99] op_sel_hi:[1,0]
	v_pk_mul_f32 v[6:7], v[6:7], s[98:99] op_sel_hi:[1,0]
	v_pk_mul_f32 v[0:1], v[0:1], s[98:99] op_sel_hi:[1,0]
	v_pk_mul_f32 v[2:3], v[2:3], s[98:99] op_sel_hi:[1,0]
	v_cvt_pk_bf16_f32 v144, v12, v13
	v_cvt_pk_bf16_f32 v145, v14, v15
	v_cvt_pk_bf16_f32 v146, v8, v9
	v_cvt_pk_bf16_f32 v147, v10, v11
	v_cvt_pk_bf16_f32 v148, v4, v5
	v_cvt_pk_bf16_f32 v149, v6, v7
	v_cvt_pk_bf16_f32 v150, v0, v1
	v_cvt_pk_bf16_f32 v151, v2, v3
	s_nop 1
	v_permlane16_swap_b32_e32 v144, v146
	v_permlane16_swap_b32_e32 v145, v147
	v_permlane16_swap_b32_e32 v148, v150
	v_permlane16_swap_b32_e32 v149, v151
	global_store_dwordx4 v155, v[144:147], s[100:101] sc0 sc1
	global_store_dwordx4 v155, v[148:151], s[100:101] offset:64 sc0 sc1
	s_branch .Lfe_join_C
; DI unsigned pack2(float a, float b) { v2f f = {a, b}; return __builtin_bit_cast(unsigned, __builtin_convertvector(f, v2bf)); }
; DI float silu_f(float v) { return v / (1.f + fexp(-v)); }
;   DI u32x2 pack(int, int, float a, float b, float c, float d, float&) const { u32x2 v; v.x = pack2(a, b); v.y = pack2(c, d); return v; }
; template <class ARow, class Epi>
; DI void gemm_tile(const ARow& arow, long a_kstride, const u16* __restrict__ Bt, long ldb, int K, int m0, int n0,
;                   const Epi& epi, char* smem) {
;     ...
;     for (int mi = 0; mi < 4; ++mi) {
;       const int m = m0 + wm * 64 + mi * 16 + fr;
;       float ss = 0.f;
;       u32x2 pk[4];
; #pragma unroll
;       for (int ni = 0; ni < 4; ++ni) pk[ni] = epi.pack(m, nh + ni * 16 + fq * 4, acc[ni][mi][0], acc[ni][mi][1], acc[ni][mi][2], acc[ni][mi][3], ss);
;       epi.finish16(m, nh, ss);
;       u16* rp = epi.rowp(m) + nh;
; #pragma unroll
;       for (int pp = 0; pp < 2; ++pp) {
;         u32x2 a = pk[2 * pp], b = pk[2 * pp + 1];
;         const u32x2 rx = __builtin_amdgcn_permlane16_swap(a.x, b.x, false, false);
;         const u32x2 ry = __builtin_amdgcn_permlane16_swap(a.y, b.y, false, false);
;         const int nst = (fq & 1) ? ((2 * pp + 1) * 16 + (fq - 1) * 4) : ((2 * pp) * 16 + fq * 4);
;         *(u32x4*)(rp + nst) = (u32x4){rx[0], ry[0], rx[1], ry[1]};
;       }
;   DI u32x2 pack(int m, int n, float a, float b, float c, float d, float& ss) const {
;     if (n < q_end) { a *= qscale; b *= qscale; c *= qscale; d *= qscale; }
;     else if (n >= z_start) { a = silu_f(a); b = silu_f(b); c = silu_f(c); d = silu_f(d); }
;     ss += a * a + b * b + c * c + d * d;
;     u32x2 v; v.x = pack2(a, b); v.y = pack2(c, d);
;     return v;
.Lfe_C_not_q:
	s_cmpk_ge_u32 s99, 0xa00
	s_cbranch_scc0 .Lfe_C_not_z
	s_cmpk_lt_u32 s99, 0xe00
	s_cbranch_scc0 .Lfe_C_not_z
	s_load_dwordx2 s[100:101], s[56:57], 0x130
	v_and_b32_e32 v152, 1, v83
	v_mul_u32_u24_e32 v152, 12, v152
	v_lshl_add_u32 v152, v83, 2, v152
	v_add_u32_e32 v152, v152, v66
	v_mul_u32_u24_e32 v153, 0xe00, v74
	v_add_u32_e32 v152, v152, v153
	v_lshlrev_b32_e32 v152, 1, v152
	v_add_u32_e32 v153, 0x1c000, v152
	v_add_u32_e32 v154, 0x38000, v152
	v_add_u32_e32 v155, 0x54000, v152
	s_nop 3
	v_mul_f32_e32 v156, 0xbfb8aa3b, v60
	v_mul_f32_e32 v157, 0xbfb8aa3b, v61
	v_mul_f32_e32 v158, 0xbfb8aa3b, v62
	v_mul_f32_e32 v159, 0xbfb8aa3b, v63
	v_mul_f32_e32 v160, 0xbfb8aa3b, v56
	v_mul_f32_e32 v161, 0xbfb8aa3b, v57
	v_mul_f32_e32 v162, 0xbfb8aa3b, v58
	v_mul_f32_e32 v163, 0xbfb8aa3b, v59
	v_exp_f32_e32 v156, v156
	v_exp_f32_e32 v157, v157
	v_exp_f32_e32 v158, v158
	v_exp_f32_e32 v159, v159
	v_exp_f32_e32 v160, v160
	v_exp_f32_e32 v161, v161
	v_exp_f32_e32 v162, v162
	v_exp_f32_e32 v163, v163
	v_add_f32_e32 v156, 1.0, v156
	v_add_f32_e32 v157, 1.0, v157
	v_add_f32_e32 v158, 1.0, v158
	v_add_f32_e32 v159, 1.0, v159
	v_add_f32_e32 v160, 1.0, v160
	v_add_f32_e32 v161, 1.0, v161
	v_add_f32_e32 v162, 1.0, v162
	v_add_f32_e32 v163, 1.0, v163
	v_rcp_f32_e32 v156, v156
	v_rcp_f32_e32 v157, v157
	v_rcp_f32_e32 v158, v158
	v_rcp_f32_e32 v159, v159
	v_rcp_f32_e32 v160, v160
	v_rcp_f32_e32 v161, v161
	v_rcp_f32_e32 v162, v162
	v_rcp_f32_e32 v163, v163
	v_mul_f32_e32 v60, v60, v156
	v_mul_f32_e32 v61, v61, v157
	v_mul_f32_e32 v62, v62, v158
	v_mul_f32_e32 v63, v63, v159
	v_mul_f32_e32 v56, v56, v160
	v_mul_f32_e32 v57, v57, v161
	v_mul_f32_e32 v58, v58, v162
	v_mul_f32_e32 v59, v59, v163
	v_mul_f32_e32 v156, 0xbfb8aa3b, v52
	v_mul_f32_e32 v157, 0xbfb8aa3b, v53
	v_mul_f32_e32 v158, 0xbfb8aa3b, v54
	v_mul_f32_e32 v159, 0xbfb8aa3b, v55
	v_mul_f32_e32 v160, 0xbfb8aa3b, v48
	v_mul_f32_e32 v161, 0xbfb8aa3b, v49
	v_mul_f32_e32 v162, 0xbfb8aa3b, v50
	v_mul_f32_e32 v163, 0xbfb8aa3b, v51
	v_exp_f32_e32 v156, v156
	v_exp_f32_e32 v157, v157
	v_exp_f32_e32 v158, v158
	v_exp_f32_e32 v159, v159
	v_exp_f32_e32 v160, v160
	v_exp_f32_e32 v161, v161
	v_exp_f32_e32 v162, v162
	v_exp_f32_e32 v163, v163
	v_add_f32_e32 v156, 1.0, v156
	v_add_f32_e32 v157, 1.0, v157
	v_add_f32_e32 v158, 1.0, v158
	v_add_f32_e32 v159, 1.0, v159
	v_add_f32_e32 v160, 1.0, v160
	v_add_f32_e32 v161, 1.0, v161
	v_add_f32_e32 v162, 1.0, v162
	v_add_f32_e32 v163, 1.0, v163
	v_rcp_f32_e32 v156, v156
	v_rcp_f32_e32 v157, v157
	v_rcp_f32_e32 v158, v158
	v_rcp_f32_e32 v159, v159
	v_rcp_f32_e32 v160, v160
	v_rcp_f32_e32 v161, v161
	v_rcp_f32_e32 v162, v162
	v_rcp_f32_e32 v163, v163
	v_mul_f32_e32 v52, v52, v156
	v_mul_f32_e32 v53, v53, v157
	v_mul_f32_e32 v54, v54, v158
	v_mul_f32_e32 v55, v55, v159
	v_mul_f32_e32 v48, v48, v160
	v_mul_f32_e32 v49, v49, v161
	v_mul_f32_e32 v50, v50, v162
	v_mul_f32_e32 v51, v51, v163
	v_cvt_pk_bf16_f32 v120, v60, v61
	v_cvt_pk_bf16_f32 v121, v62, v63
	v_cvt_pk_bf16_f32 v122, v56, v57
	v_cvt_pk_bf16_f32 v123, v58, v59
	v_cvt_pk_bf16_f32 v124, v52, v53
	v_cvt_pk_bf16_f32 v125, v54, v55
	v_cvt_pk_bf16_f32 v126, v48, v49
	v_cvt_pk_bf16_f32 v127, v50, v51
	s_nop 1
	v_permlane16_swap_b32_e32 v120, v122
	v_permlane16_swap_b32_e32 v121, v123
	v_permlane16_swap_b32_e32 v124, v126
	v_permlane16_swap_b32_e32 v125, v127
	s_waitcnt lgkmcnt(0)
	global_store_dwordx4 v152, v[120:123], s[100:101] sc0 sc1
	global_store_dwordx4 v152, v[124:127], s[100:101] offset:64 sc0 sc1
	v_mul_f32_e32 v156, 0xbfb8aa3b, v44
	v_mul_f32_e32 v157, 0xbfb8aa3b, v45
	v_mul_f32_e32 v158, 0xbfb8aa3b, v46
	v_mul_f32_e32 v159, 0xbfb8aa3b, v47
	v_mul_f32_e32 v160, 0xbfb8aa3b, v40
	v_mul_f32_e32 v161, 0xbfb8aa3b, v41
	v_mul_f32_e32 v162, 0xbfb8aa3b, v42
	v_mul_f32_e32 v163, 0xbfb8aa3b, v43
	v_exp_f32_e32 v156, v156
	v_exp_f32_e32 v157, v157
	v_exp_f32_e32 v158, v158
	v_exp_f32_e32 v159, v159
	v_exp_f32_e32 v160, v160
	v_exp_f32_e32 v161, v161
	v_exp_f32_e32 v162, v162
	v_exp_f32_e32 v163, v163
	v_add_f32_e32 v156, 1.0, v156
	v_add_f32_e32 v157, 1.0, v157
	v_add_f32_e32 v158, 1.0, v158
	v_add_f32_e32 v159, 1.0, v159
	v_add_f32_e32 v160, 1.0, v160
	v_add_f32_e32 v161, 1.0, v161
	v_add_f32_e32 v162, 1.0, v162
	v_add_f32_e32 v163, 1.0, v163
	v_rcp_f32_e32 v156, v156
	v_rcp_f32_e32 v157, v157
	v_rcp_f32_e32 v158, v158
	v_rcp_f32_e32 v159, v159
	v_rcp_f32_e32 v160, v160
	v_rcp_f32_e32 v161, v161
	v_rcp_f32_e32 v162, v162
	v_rcp_f32_e32 v163, v163
	v_mul_f32_e32 v44, v44, v156
	v_mul_f32_e32 v45, v45, v157
	v_mul_f32_e32 v46, v46, v158
	v_mul_f32_e32 v47, v47, v159
	v_mul_f32_e32 v40, v40, v160
	v_mul_f32_e32 v41, v41, v161
	v_mul_f32_e32 v42, v42, v162
	v_mul_f32_e32 v43, v43, v163
	v_mul_f32_e32 v156, 0xbfb8aa3b, v36
	v_mul_f32_e32 v157, 0xbfb8aa3b, v37
	v_mul_f32_e32 v158, 0xbfb8aa3b, v38
	v_mul_f32_e32 v159, 0xbfb8aa3b, v39
	v_mul_f32_e32 v160, 0xbfb8aa3b, v32
	v_mul_f32_e32 v161, 0xbfb8aa3b, v33
	v_mul_f32_e32 v162, 0xbfb8aa3b, v34
	v_mul_f32_e32 v163, 0xbfb8aa3b, v35
	v_exp_f32_e32 v156, v156
	v_exp_f32_e32 v157, v157
	v_exp_f32_e32 v158, v158
	v_exp_f32_e32 v159, v159
	v_exp_f32_e32 v160, v160
	v_exp_f32_e32 v161, v161
	v_exp_f32_e32 v162, v162
	v_exp_f32_e32 v163, v163
	v_add_f32_e32 v156, 1.0, v156
	v_add_f32_e32 v157, 1.0, v157
	v_add_f32_e32 v158, 1.0, v158
	v_add_f32_e32 v159, 1.0, v159
	v_add_f32_e32 v160, 1.0, v160
	v_add_f32_e32 v161, 1.0, v161
	v_add_f32_e32 v162, 1.0, v162
	v_add_f32_e32 v163, 1.0, v163
	v_rcp_f32_e32 v156, v156
	v_rcp_f32_e32 v157, v157
	v_rcp_f32_e32 v158, v158
	v_rcp_f32_e32 v159, v159
	v_rcp_f32_e32 v160, v160
	v_rcp_f32_e32 v161, v161
	v_rcp_f32_e32 v162, v162
; DI unsigned pack2(float a, float b) { v2f f = {a, b}; return __builtin_bit_cast(unsigned, __builtin_convertvector(f, v2bf)); }
; DI float silu_f(float v) { return v / (1.f + fexp(-v)); }
;   DI u32x2 pack(int, int, float a, float b, float c, float d, float&) const { u32x2 v; v.x = pack2(a, b); v.y = pack2(c, d); return v; }
; template <class ARow, class Epi>
; DI void gemm_tile(const ARow& arow, long a_kstride, const u16* __restrict__ Bt, long ldb, int K, int m0, int n0,
;                   const Epi& epi, char* smem) {
;     ...
;     for (int mi = 0; mi < 4; ++mi) {
;       const int m = m0 + wm * 64 + mi * 16 + fr;
;       float ss = 0.f;
;       u32x2 pk[4];
; #pragma unroll
;       for (int ni = 0; ni < 4; ++ni) pk[ni] = epi.pack(m, nh + ni * 16 + fq * 4, acc[ni][mi][0], acc[ni][mi][1], acc[ni][mi][2], acc[ni][mi][3], ss);
;       epi.finish16(m, nh, ss);
;       u16* rp = epi.rowp(m) + nh;
; #pragma unroll
;       for (int pp = 0; pp < 2; ++pp) {
;         u32x2 a = pk[2 * pp], b = pk[2 * pp + 1];
;         const u32x2 rx = __builtin_amdgcn_permlane16_swap(a.x, b.x, false, false);
;         const u32x2 ry = __builtin_amdgcn_permlane16_swap(a.y, b.y, false, false);
;         const int nst = (fq & 1) ? ((2 * pp + 1) * 16 + (fq - 1) * 4) : ((2 * pp) * 16 + fq * 4);
;         *(u32x4*)(rp + nst) = (u32x4){rx[0], ry[0], rx[1], ry[1]};
;       }
;   DI u32x2 pack(int m, int n, float a, float b, float c, float d, float& ss) const {
;     if (n < q_end) { a *= qscale; b *= qscale; c *= qscale; d *= qscale; }
;     else if (n >= z_start) { a = silu_f(a); b = silu_f(b); c = silu_f(c); d = silu_f(d); }
;     ss += a * a + b * b + c * c + d * d;
;     u32x2 v; v.x = pack2(a, b); v.y = pack2(c, d);
;     return v;
	v_rcp_f32_e32 v163, v163
	v_mul_f32_e32 v36, v36, v156
	v_mul_f32_e32 v37, v37, v157
	v_mul_f32_e32 v38, v38, v158
	v_mul_f32_e32 v39, v39, v159
	v_mul_f32_e32 v32, v32, v160
	v_mul_f32_e32 v33, v33, v161
	v_mul_f32_e32 v34, v34, v162
	v_mul_f32_e32 v35, v35, v163
	v_cvt_pk_bf16_f32 v128, v44, v45
	v_cvt_pk_bf16_f32 v129, v46, v47
	v_cvt_pk_bf16_f32 v130, v40, v41
	v_cvt_pk_bf16_f32 v131, v42, v43
	v_cvt_pk_bf16_f32 v132, v36, v37
	v_cvt_pk_bf16_f32 v133, v38, v39
	v_cvt_pk_bf16_f32 v134, v32, v33
	v_cvt_pk_bf16_f32 v135, v34, v35
	s_nop 1
	v_permlane16_swap_b32_e32 v128, v130
	v_permlane16_swap_b32_e32 v129, v131
	v_permlane16_swap_b32_e32 v132, v134
	v_permlane16_swap_b32_e32 v133, v135
	global_store_dwordx4 v153, v[128:131], s[100:101] sc0 sc1
	global_store_dwordx4 v153, v[132:135], s[100:101] offset:64 sc0 sc1
	v_mul_f32_e32 v156, 0xbfb8aa3b, v28
	v_mul_f32_e32 v157, 0xbfb8aa3b, v29
	v_mul_f32_e32 v158, 0xbfb8aa3b, v30
	v_mul_f32_e32 v159, 0xbfb8aa3b, v31
	v_mul_f32_e32 v160, 0xbfb8aa3b, v24
	v_mul_f32_e32 v161, 0xbfb8aa3b, v25
	v_mul_f32_e32 v162, 0xbfb8aa3b, v26
	v_mul_f32_e32 v163, 0xbfb8aa3b, v27
	v_exp_f32_e32 v156, v156
	v_exp_f32_e32 v157, v157
	v_exp_f32_e32 v158, v158
	v_exp_f32_e32 v159, v159
	v_exp_f32_e32 v160, v160
	v_exp_f32_e32 v161, v161
	v_exp_f32_e32 v162, v162
	v_exp_f32_e32 v163, v163
	v_add_f32_e32 v156, 1.0, v156
	v_add_f32_e32 v157, 1.0, v157
	v_add_f32_e32 v158, 1.0, v158
	v_add_f32_e32 v159, 1.0, v159
	v_add_f32_e32 v160, 1.0, v160
	v_add_f32_e32 v161, 1.0, v161
	v_add_f32_e32 v162, 1.0, v162
	v_add_f32_e32 v163, 1.0, v163
	v_rcp_f32_e32 v156, v156
	v_rcp_f32_e32 v157, v157
	v_rcp_f32_e32 v158, v158
	v_rcp_f32_e32 v159, v159
	v_rcp_f32_e32 v160, v160
	v_rcp_f32_e32 v161, v161
	v_rcp_f32_e32 v162, v162
	v_rcp_f32_e32 v163, v163
	v_mul_f32_e32 v28, v28, v156
	v_mul_f32_e32 v29, v29, v157
	v_mul_f32_e32 v30, v30, v158
	v_mul_f32_e32 v31, v31, v159
	v_mul_f32_e32 v24, v24, v160
	v_mul_f32_e32 v25, v25, v161
	v_mul_f32_e32 v26, v26, v162
	v_mul_f32_e32 v27, v27, v163
	v_mul_f32_e32 v156, 0xbfb8aa3b, v20
	v_mul_f32_e32 v157, 0xbfb8aa3b, v21
	v_mul_f32_e32 v158, 0xbfb8aa3b, v22
	v_mul_f32_e32 v159, 0xbfb8aa3b, v23
	v_mul_f32_e32 v160, 0xbfb8aa3b, v16
	v_mul_f32_e32 v161, 0xbfb8aa3b, v17
	v_mul_f32_e32 v162, 0xbfb8aa3b, v18
	v_mul_f32_e32 v163, 0xbfb8aa3b, v19
	v_exp_f32_e32 v156, v156
	v_exp_f32_e32 v157, v157
	v_exp_f32_e32 v158, v158
	v_exp_f32_e32 v159, v159
	v_exp_f32_e32 v160, v160
	v_exp_f32_e32 v161, v161
	v_exp_f32_e32 v162, v162
	v_exp_f32_e32 v163, v163
	v_add_f32_e32 v156, 1.0, v156
	v_add_f32_e32 v157, 1.0, v157
	v_add_f32_e32 v158, 1.0, v158
	v_add_f32_e32 v159, 1.0, v159
	v_add_f32_e32 v160, 1.0, v160
	v_add_f32_e32 v161, 1.0, v161
	v_add_f32_e32 v162, 1.0, v162
	v_add_f32_e32 v163, 1.0, v163
	v_rcp_f32_e32 v156, v156
	v_rcp_f32_e32 v157, v157
	v_rcp_f32_e32 v158, v158
	v_rcp_f32_e32 v159, v159
	v_rcp_f32_e32 v160, v160
	v_rcp_f32_e32 v161, v161
	v_rcp_f32_e32 v162, v162
	v_rcp_f32_e32 v163, v163
	v_mul_f32_e32 v20, v20, v156
	v_mul_f32_e32 v21, v21, v157
	v_mul_f32_e32 v22, v22, v158
	v_mul_f32_e32 v23, v23, v159
	v_mul_f32_e32 v16, v16, v160
	v_mul_f32_e32 v17, v17, v161
	v_mul_f32_e32 v18, v18, v162
	v_mul_f32_e32 v19, v19, v163
	v_cvt_pk_bf16_f32 v136, v28, v29
	v_cvt_pk_bf16_f32 v137, v30, v31
	v_cvt_pk_bf16_f32 v138, v24, v25
	v_cvt_pk_bf16_f32 v139, v26, v27
	v_cvt_pk_bf16_f32 v140, v20, v21
	v_cvt_pk_bf16_f32 v141, v22, v23
	v_cvt_pk_bf16_f32 v142, v16, v17
	v_cvt_pk_bf16_f32 v143, v18, v19
	s_nop 1
	v_permlane16_swap_b32_e32 v136, v138
	v_permlane16_swap_b32_e32 v137, v139
	v_permlane16_swap_b32_e32 v140, v142
	v_permlane16_swap_b32_e32 v141, v143
	global_store_dwordx4 v154, v[136:139], s[100:101] sc0 sc1
	global_store_dwordx4 v154, v[140:143], s[100:101] offset:64 sc0 sc1
	v_mul_f32_e32 v156, 0xbfb8aa3b, v12
	v_mul_f32_e32 v157, 0xbfb8aa3b, v13
	v_mul_f32_e32 v158, 0xbfb8aa3b, v14
	v_mul_f32_e32 v159, 0xbfb8aa3b, v15
	v_mul_f32_e32 v160, 0xbfb8aa3b, v8
	v_mul_f32_e32 v161, 0xbfb8aa3b, v9
	v_mul_f32_e32 v162, 0xbfb8aa3b, v10
	v_mul_f32_e32 v163, 0xbfb8aa3b, v11
	v_exp_f32_e32 v156, v156
	v_exp_f32_e32 v157, v157
	v_exp_f32_e32 v158, v158
	v_exp_f32_e32 v159, v159
	v_exp_f32_e32 v160, v160
	v_exp_f32_e32 v161, v161
	v_exp_f32_e32 v162, v162
	v_exp_f32_e32 v163, v163
	v_add_f32_e32 v156, 1.0, v156
	v_add_f32_e32 v157, 1.0, v157
	v_add_f32_e32 v158, 1.0, v158
	v_add_f32_e32 v159, 1.0, v159
	v_add_f32_e32 v160, 1.0, v160
	v_add_f32_e32 v161, 1.0, v161
	v_add_f32_e32 v162, 1.0, v162
	v_add_f32_e32 v163, 1.0, v163
	v_rcp_f32_e32 v156, v156
	v_rcp_f32_e32 v157, v157
	v_rcp_f32_e32 v158, v158
	v_rcp_f32_e32 v159, v159
	v_rcp_f32_e32 v160, v160
	v_rcp_f32_e32 v161, v161
	v_rcp_f32_e32 v162, v162
	v_rcp_f32_e32 v163, v163
	v_mul_f32_e32 v12, v12, v156
	v_mul_f32_e32 v13, v13, v157
	v_mul_f32_e32 v14, v14, v158
	v_mul_f32_e32 v15, v15, v159
	v_mul_f32_e32 v8, v8, v160
	v_mul_f32_e32 v9, v9, v161
	v_mul_f32_e32 v10, v10, v162
	v_mul_f32_e32 v11, v11, v163
	v_mul_f32_e32 v156, 0xbfb8aa3b, v4
	v_mul_f32_e32 v157, 0xbfb8aa3b, v5
	v_mul_f32_e32 v158, 0xbfb8aa3b, v6
	v_mul_f32_e32 v159, 0xbfb8aa3b, v7
	v_mul_f32_e32 v160, 0xbfb8aa3b, v0
	v_mul_f32_e32 v161, 0xbfb8aa3b, v1
	v_mul_f32_e32 v162, 0xbfb8aa3b, v2
	v_mul_f32_e32 v163, 0xbfb8aa3b, v3
	v_exp_f32_e32 v156, v156
	v_exp_f32_e32 v157, v157
	v_exp_f32_e32 v158, v158
	v_exp_f32_e32 v159, v159
	v_exp_f32_e32 v160, v160
	v_exp_f32_e32 v161, v161
	v_exp_f32_e32 v162, v162
	v_exp_f32_e32 v163, v163
	v_add_f32_e32 v156, 1.0, v156
	v_add_f32_e32 v157, 1.0, v157
	v_add_f32_e32 v158, 1.0, v158
	v_add_f32_e32 v159, 1.0, v159
	v_add_f32_e32 v160, 1.0, v160
	v_add_f32_e32 v161, 1.0, v161
	v_add_f32_e32 v162, 1.0, v162
	v_add_f32_e32 v163, 1.0, v163
	v_rcp_f32_e32 v156, v156
	v_rcp_f32_e32 v157, v157
	v_rcp_f32_e32 v158, v158
	v_rcp_f32_e32 v159, v159
	v_rcp_f32_e32 v160, v160
	v_rcp_f32_e32 v161, v161
	v_rcp_f32_e32 v162, v162
	v_rcp_f32_e32 v163, v163
	v_mul_f32_e32 v4, v4, v156
	v_mul_f32_e32 v5, v5, v157
	v_mul_f32_e32 v6, v6, v158
	v_mul_f32_e32 v7, v7, v159
	v_mul_f32_e32 v0, v0, v160
	v_mul_f32_e32 v1, v1, v161
	v_mul_f32_e32 v2, v2, v162
	v_mul_f32_e32 v3, v3, v163
	v_cvt_pk_bf16_f32 v144, v12, v13
	v_cvt_pk_bf16_f32 v145, v14, v15
	v_cvt_pk_bf16_f32 v146, v8, v9
	v_cvt_pk_bf16_f32 v147, v10, v11
	v_cvt_pk_bf16_f32 v148, v4, v5
	v_cvt_pk_bf16_f32 v149, v6, v7
	v_cvt_pk_bf16_f32 v150, v0, v1
	v_cvt_pk_bf16_f32 v151, v2, v3
	s_nop 1
	v_permlane16_swap_b32_e32 v144, v146
	v_permlane16_swap_b32_e32 v145, v147
	v_permlane16_swap_b32_e32 v148, v150
	v_permlane16_swap_b32_e32 v149, v151
	global_store_dwordx4 v155, v[144:147], s[100:101] sc0 sc1
	global_store_dwordx4 v155, v[148:151], s[100:101] offset:64 sc0 sc1
	s_branch .Lfe_join_C

; DI unsigned pack2(float a, float b) { v2f f = {a, b}; return __builtin_bit_cast(unsigned, __builtin_convertvector(f, v2bf)); }
; DI float silu_f(float v) { return v / (1.f + fexp(-v)); }
;   DI u32x2 pack(int, int, float a, float b, float c, float d, float&) const { u32x2 v; v.x = pack2(a, b); v.y = pack2(c, d); return v; }
; template <class ARow, class Epi>
; DI void gemm_tile(const ARow& arow, long a_kstride, const u16* __restrict__ Bt, long ldb, int K, int m0, int n0,
;                   const Epi& epi, char* smem) {
;     ...
;     for (int mi = 0; mi < 4; ++mi) {
;       const int m = m0 + wm * 64 + mi * 16 + fr;
;       float ss = 0.f;
;       u32x2 pk[4];
; #pragma unroll
;       for (int ni = 0; ni < 4; ++ni) pk[ni] = epi.pack(m, nh + ni * 16 + fq * 4, acc[ni][mi][0], acc[ni][mi][1], acc[ni][mi][2], acc[ni][mi][3], ss);
;       epi.finish16(m, nh, ss);
;       u16* rp = epi.rowp(m) + nh;
; #pragma unroll
;       for (int pp = 0; pp < 2; ++pp) {
;         u32x2 a = pk[2 * pp], b = pk[2 * pp + 1];
;         const u32x2 rx = __builtin_amdgcn_permlane16_swap(a.x, b.x, false, false);
;         const u32x2 ry = __builtin_amdgcn_permlane16_swap(a.y, b.y, false, false);
;         const int nst = (fq & 1) ? ((2 * pp + 1) * 16 + (fq - 1) * 4) : ((2 * pp) * 16 + fq * 4);
;         *(u32x4*)(rp + nst) = (u32x4){rx[0], ry[0], rx[1], ry[1]};
;       }
;   DI u32x2 pack(int m, int n, float a, float b, float c, float d, float& ss) const {
;     if (n < q_end) { a *= qscale; b *= qscale; c *= qscale; d *= qscale; }
;     else if (n >= z_start) { a = silu_f(a); b = silu_f(b); c = silu_f(c); d = silu_f(d); }
;     ss += a * a + b * b + c * c + d * d;
;     u32x2 v; v.x = pack2(a, b); v.y = pack2(c, d);
;     return v;
.LBB0_1868:
	s_andn2_saveexec_b64 s[0:1], s[0:1]
	v_pk_mul_f32 v[48:49], v[48:49], s[24:25] op_sel_hi:[1,0]
	v_pk_mul_f32 v[50:51], v[50:51], s[24:25] op_sel_hi:[1,0]
	s_or_b64 exec, exec, s[0:1]
	v_cvt_pk_bf16_f32 v52, v52, v53
	v_cvt_pk_bf16_f32 v53, v54, v55
	v_cvt_pk_bf16_f32 v54, v48, v49
	v_mov_b64_e32 v[48:49], s[14:15]
	v_cvt_pk_bf16_f32 v72, v56, v57
	v_ashrrev_i32_e32 v67, 31, v66
	v_and_b32_e32 v56, 16, v82
	v_mad_i64_i32 v[48:49], s[0:1], v74, s34, v[48:49]
	v_cvt_pk_bf16_f32 v55, v50, v51
	v_lshl_add_u64 v[50:51], v[66:67], 1, v[48:49]
	v_add_u32_e32 v48, 12, v68
	v_cmp_eq_u32_e32 vcc, 0, v56
	v_cvt_pk_bf16_f32 v73, v58, v59
	v_cvt_pk_bf16_f32 v70, v60, v61
	v_cndmask_b32_e32 v48, v48, v68, vcc
	v_cvt_pk_bf16_f32 v71, v62, v63
	v_lshlrev_b32_e32 v64, 1, v48
	v_permlane16_swap_b32_e32 v70, v72
	v_permlane16_swap_b32_e32 v71, v73
	v_lshl_add_u64 v[48:49], v[50:51], 0, v[64:65]
	global_store_dwordx4 v[48:49], v[70:73], off sc0 sc1
	v_add_u32_e32 v48, 44, v68
	v_or_b32_e32 v49, 32, v68
	v_cndmask_b32_e32 v48, v48, v49, vcc
	v_lshlrev_b32_e32 v48, 1, v48
	v_mov_b32_e32 v49, v65
	v_permlane16_swap_b32_e32 v52, v54
	v_permlane16_swap_b32_e32 v53, v55
	v_lshl_add_u64 v[50:51], v[50:51], 0, v[48:49]
	global_store_dwordx4 v[50:51], v[52:55], off sc0 sc1
	s_and_saveexec_b64 s[0:1], s[4:5]
	s_xor_b64 s[0:1], exec, s[0:1]
	s_cbranch_execz .LBB0_1873
	s_cmpk_lt_u32 s35, 0xa00
	s_cbranch_scc1 .LBB0_1873
	v_mul_f32_e32 v49, 0xbfb8aa3b, v44
	v_exp_f32_e32 v50, v49
	v_mul_f32_e32 v49, 0xbfb8aa3b, v45
	v_exp_f32_e32 v51, v49
	s_nop 0
	v_pk_add_f32 v[50:51], v[50:51], 1.0 op_sel_hi:[1,0]
	s_nop 0
	v_rcp_f32_e32 v49, v50
	v_mul_f32_e32 v52, 0xbfb8aa3b, v46
	v_mul_f32_e32 v53, 0xbfb8aa3b, v47
	v_exp_f32_e32 v52, v52
	v_exp_f32_e32 v53, v53
	v_mul_f32_e32 v44, v44, v49
	v_pk_add_f32 v[52:53], v[52:53], 1.0 op_sel_hi:[1,0]
	v_rcp_f32_e32 v49, v51
	s_nop 0
	v_mul_f32_e32 v45, v45, v49
	v_rcp_f32_e32 v49, v52
	s_nop 0
	v_mul_f32_e32 v46, v46, v49
	v_rcp_f32_e32 v49, v53
	s_nop 0
	v_mul_f32_e32 v47, v47, v49

; DI unsigned pack2(float a, float b) { v2f f = {a, b}; return __builtin_bit_cast(unsigned, __builtin_convertvector(f, v2bf)); }
; DI float silu_f(float v) { return v / (1.f + fexp(-v)); }
;   DI u32x2 pack(int, int, float a, float b, float c, float d, float&) const { u32x2 v; v.x = pack2(a, b); v.y = pack2(c, d); return v; }
; template <class ARow, class Epi>
; DI void gemm_tile(const ARow& arow, long a_kstride, const u16* __restrict__ Bt, long ldb, int K, int m0, int n0,
;                   const Epi& epi, char* smem) {
;     ...
;     for (int mi = 0; mi < 4; ++mi) {
;       const int m = m0 + wm * 64 + mi * 16 + fr;
;       float ss = 0.f;
;       u32x2 pk[4];
; #pragma unroll
;       for (int ni = 0; ni < 4; ++ni) pk[ni] = epi.pack(m, nh + ni * 16 + fq * 4, acc[ni][mi][0], acc[ni][mi][1], acc[ni][mi][2], acc[ni][mi][3], ss);
;       epi.finish16(m, nh, ss);
;       u16* rp = epi.rowp(m) + nh;
; #pragma unroll
;       for (int pp = 0; pp < 2; ++pp) {
;         u32x2 a = pk[2 * pp], b = pk[2 * pp + 1];
;         const u32x2 rx = __builtin_amdgcn_permlane16_swap(a.x, b.x, false, false);
;         const u32x2 ry = __builtin_amdgcn_permlane16_swap(a.y, b.y, false, false);
;         const int nst = (fq & 1) ? ((2 * pp + 1) * 16 + (fq - 1) * 4) : ((2 * pp) * 16 + fq * 4);
;         *(u32x4*)(rp + nst) = (u32x4){rx[0], ry[0], rx[1], ry[1]};
;       }
;   DI u32x2 pack(int m, int n, float a, float b, float c, float d, float& ss) const {
;     if (n < q_end) { a *= qscale; b *= qscale; c *= qscale; d *= qscale; }
;     else if (n >= z_start) { a = silu_f(a); b = silu_f(b); c = silu_f(c); d = silu_f(d); }
;     ss += a * a + b * b + c * c + d * d;
;     u32x2 v; v.x = pack2(a, b); v.y = pack2(c, d);
;     return v;
.LBB0_1888:
	s_andn2_saveexec_b64 s[0:1], s[0:1]
	v_pk_mul_f32 v[32:33], v[32:33], s[24:25] op_sel_hi:[1,0]
	v_pk_mul_f32 v[34:35], v[34:35], s[24:25] op_sel_hi:[1,0]
	s_or_b64 exec, exec, s[0:1]
	v_cvt_pk_bf16_f32 v36, v36, v37
	v_cvt_pk_bf16_f32 v37, v38, v39
	v_cvt_pk_bf16_f32 v38, v32, v33
	v_cvt_pk_bf16_f32 v39, v34, v35
	v_or_b32_e32 v34, 16, v74
	v_mov_b64_e32 v[32:33], s[14:15]
	v_mad_i64_i32 v[32:33], s[0:1], v34, s34, v[32:33]
	v_cvt_pk_bf16_f32 v52, v40, v41
	v_cvt_pk_bf16_f32 v53, v42, v43
	v_cvt_pk_bf16_f32 v50, v44, v45
	v_cvt_pk_bf16_f32 v51, v46, v47
	v_lshl_add_u64 v[32:33], v[66:67], 1, v[32:33]
	v_mov_b32_e32 v49, v65
	v_permlane16_swap_b32_e32 v50, v52
	v_permlane16_swap_b32_e32 v51, v53
	v_lshl_add_u64 v[34:35], v[32:33], 0, v[64:65]
	v_permlane16_swap_b32_e32 v36, v38
	v_permlane16_swap_b32_e32 v37, v39
	v_lshl_add_u64 v[32:33], v[32:33], 0, v[48:49]
	global_store_dwordx4 v[34:35], v[50:53], off sc0 sc1
	global_store_dwordx4 v[32:33], v[36:39], off sc0 sc1
	s_and_saveexec_b64 s[0:1], s[4:5]
	s_xor_b64 s[0:1], exec, s[0:1]
	s_cbranch_execz .LBB0_1893
	s_cmpk_lt_u32 s35, 0xa00
	s_cbranch_scc1 .LBB0_1893
	v_mul_f32_e32 v32, 0xbfb8aa3b, v28
	v_mul_f32_e32 v33, 0xbfb8aa3b, v29
	v_exp_f32_e32 v32, v32
	v_exp_f32_e32 v33, v33
	s_nop 0
	v_pk_add_f32 v[32:33], v[32:33], 1.0 op_sel_hi:[1,0]
	s_nop 0
	v_rcp_f32_e32 v34, v32
	s_nop 0
	v_mul_f32_e32 v28, v28, v34
	v_mul_f32_e32 v34, 0xbfb8aa3b, v30
	v_mul_f32_e32 v35, 0xbfb8aa3b, v31
	v_exp_f32_e32 v34, v34
	v_exp_f32_e32 v35, v35
	s_nop 0
	v_pk_add_f32 v[34:35], v[34:35], 1.0 op_sel_hi:[1,0]
	v_rcp_f32_e32 v32, v33
	s_nop 0
	v_mul_f32_e32 v29, v29, v32
	v_rcp_f32_e32 v32, v34
	s_nop 0
	v_mul_f32_e32 v30, v30, v32
	v_rcp_f32_e32 v32, v35
	s_nop 0
	v_mul_f32_e32 v31, v31, v32

; DI unsigned pack2(float a, float b) { v2f f = {a, b}; return __builtin_bit_cast(unsigned, __builtin_convertvector(f, v2bf)); }
; DI float silu_f(float v) { return v / (1.f + fexp(-v)); }
;   DI u32x2 pack(int, int, float a, float b, float c, float d, float&) const { u32x2 v; v.x = pack2(a, b); v.y = pack2(c, d); return v; }
; template <class ARow, class Epi>
; DI void gemm_tile(const ARow& arow, long a_kstride, const u16* __restrict__ Bt, long ldb, int K, int m0, int n0,
;                   const Epi& epi, char* smem) {
;     ...
;     for (int mi = 0; mi < 4; ++mi) {
;       const int m = m0 + wm * 64 + mi * 16 + fr;
;       float ss = 0.f;
;       u32x2 pk[4];
; #pragma unroll
;       for (int ni = 0; ni < 4; ++ni) pk[ni] = epi.pack(m, nh + ni * 16 + fq * 4, acc[ni][mi][0], acc[ni][mi][1], acc[ni][mi][2], acc[ni][mi][3], ss);
;       epi.finish16(m, nh, ss);
;       u16* rp = epi.rowp(m) + nh;
; #pragma unroll
;       for (int pp = 0; pp < 2; ++pp) {
;         u32x2 a = pk[2 * pp], b = pk[2 * pp + 1];
;         const u32x2 rx = __builtin_amdgcn_permlane16_swap(a.x, b.x, false, false);
;         const u32x2 ry = __builtin_amdgcn_permlane16_swap(a.y, b.y, false, false);
;         const int nst = (fq & 1) ? ((2 * pp + 1) * 16 + (fq - 1) * 4) : ((2 * pp) * 16 + fq * 4);
;         *(u32x4*)(rp + nst) = (u32x4){rx[0], ry[0], rx[1], ry[1]};
;       }
;   DI u32x2 pack(int m, int n, float a, float b, float c, float d, float& ss) const {
;     if (n < q_end) { a *= qscale; b *= qscale; c *= qscale; d *= qscale; }
;     else if (n >= z_start) { a = silu_f(a); b = silu_f(b); c = silu_f(c); d = silu_f(d); }
;     ss += a * a + b * b + c * c + d * d;
;     u32x2 v; v.x = pack2(a, b); v.y = pack2(c, d);
;     return v;
.LBB0_1908:
	s_andn2_saveexec_b64 s[0:1], s[0:1]
	v_pk_mul_f32 v[16:17], v[16:17], s[24:25] op_sel_hi:[1,0]
	v_pk_mul_f32 v[18:19], v[18:19], s[24:25] op_sel_hi:[1,0]
	s_or_b64 exec, exec, s[0:1]
	v_cvt_pk_bf16_f32 v20, v20, v21
	v_cvt_pk_bf16_f32 v21, v22, v23
	v_cvt_pk_bf16_f32 v22, v16, v17
	v_cvt_pk_bf16_f32 v23, v18, v19
	v_or_b32_e32 v18, 32, v74
	v_mov_b64_e32 v[16:17], s[14:15]
	v_mad_i64_i32 v[16:17], s[0:1], v18, s34, v[16:17]
	v_cvt_pk_bf16_f32 v34, v24, v25
	v_cvt_pk_bf16_f32 v35, v26, v27
	v_cvt_pk_bf16_f32 v32, v28, v29
	v_cvt_pk_bf16_f32 v33, v30, v31
	v_lshl_add_u64 v[16:17], v[66:67], 1, v[16:17]
	v_mov_b32_e32 v49, v65
	v_permlane16_swap_b32_e32 v32, v34
	v_permlane16_swap_b32_e32 v33, v35
	v_lshl_add_u64 v[18:19], v[16:17], 0, v[64:65]
	v_permlane16_swap_b32_e32 v20, v22
	v_permlane16_swap_b32_e32 v21, v23
	v_lshl_add_u64 v[16:17], v[16:17], 0, v[48:49]
	global_store_dwordx4 v[18:19], v[32:35], off sc0 sc1
	global_store_dwordx4 v[16:17], v[20:23], off sc0 sc1
	s_and_saveexec_b64 s[0:1], s[4:5]
	s_xor_b64 s[0:1], exec, s[0:1]
	s_cbranch_execz .LBB0_1913
	s_cmpk_lt_u32 s35, 0xa00
	s_cbranch_scc1 .LBB0_1913
	v_mul_f32_e32 v16, 0xbfb8aa3b, v12
	v_mul_f32_e32 v17, 0xbfb8aa3b, v13
	v_exp_f32_e32 v16, v16
	v_exp_f32_e32 v17, v17
	s_nop 0
	v_pk_add_f32 v[16:17], v[16:17], 1.0 op_sel_hi:[1,0]
	s_nop 0
	v_rcp_f32_e32 v18, v16
	s_nop 0
	v_mul_f32_e32 v12, v12, v18
	v_mul_f32_e32 v18, 0xbfb8aa3b, v14
	v_mul_f32_e32 v19, 0xbfb8aa3b, v15
	v_exp_f32_e32 v18, v18
	v_exp_f32_e32 v19, v19
	s_nop 0
	v_pk_add_f32 v[18:19], v[18:19], 1.0 op_sel_hi:[1,0]
	v_rcp_f32_e32 v16, v17
	s_nop 0
	v_mul_f32_e32 v13, v13, v16
	v_rcp_f32_e32 v16, v18
	s_nop 0
	v_mul_f32_e32 v14, v14, v16
	v_rcp_f32_e32 v16, v19
	s_nop 0
	v_mul_f32_e32 v15, v15, v16

; template <class ARow, class Epi>
; DI void gemm_tile(const ARow& arow, long a_kstride, const u16* __restrict__ Bt, long ldb, int K, int m0, int n0,
;                   const Epi& epi, char* smem) {
;     ...
;       u16* rp = epi.rowp(m) + nh;
; #pragma unroll
;       for (int pp = 0; pp < 2; ++pp) {
;         u32x2 a = pk[2 * pp], b = pk[2 * pp + 1];
;         const u32x2 rx = __builtin_amdgcn_permlane16_swap(a.x, b.x, false, false);
;         const u32x2 ry = __builtin_amdgcn_permlane16_swap(a.y, b.y, false, false);
;         const int nst = (fq & 1) ? ((2 * pp + 1) * 16 + (fq - 1) * 4) : ((2 * pp) * 16 + fq * 4);
;         *(u32x4*)(rp + nst) = (u32x4){rx[0], ry[0], rx[1], ry[1]};
;       }
.LBB0_2311:
	s_or_b64 exec, exec, s[0:1]
	v_cvt_pk_bf16_f32 v4, v4, v5
	v_cvt_pk_bf16_f32 v5, v6, v7
	v_cvt_pk_bf16_f32 v6, v0, v1
	v_or_b32_e32 v0, 48, v66
	v_ashrrev_i32_e32 v1, 31, v0
	v_lshlrev_b64 v[0:1], 13, v[0:1]
	v_lshl_add_u64 v[0:1], s[14:15], 0, v[0:1]
	v_cvt_pk_bf16_f32 v18, v8, v9
	v_cvt_pk_bf16_f32 v19, v10, v11
	v_cvt_pk_bf16_f32 v16, v12, v13
	v_cvt_pk_bf16_f32 v17, v14, v15
	v_cvt_pk_bf16_f32 v7, v2, v3
	v_lshl_add_u64 v[0:1], v[68:69], 1, v[0:1]
	v_mov_b32_e32 v49, v65
	v_permlane16_swap_b32_e32 v16, v18
	v_permlane16_swap_b32_e32 v17, v19
	v_lshl_add_u64 v[2:3], v[0:1], 0, v[64:65]
	v_permlane16_swap_b32_e32 v4, v6
	v_permlane16_swap_b32_e32 v5, v7
	v_lshl_add_u64 v[0:1], v[0:1], 0, v[48:49]
	global_store_dwordx4 v[2:3], v[16:19], off sc0 sc1
	global_store_dwordx4 v[0:1], v[4:7], off sc0 sc1

; template <class ARow, class Epi>
; DI void gemm_tile(const ARow& arow, long a_kstride, const u16* __restrict__ Bt, long ldb, int K, int m0, int n0,
;                   const Epi& epi, char* smem) {
;     ...
;   const int fr = lane & 15, fq = lane >> 4;
;   int foff[2];
; #pragma unroll
;   for (int ks = 0; ks < 2; ++ks) foff[ks] = fr * 128 + ((((4 * ks + fq) ^ ((fr >> 1) & 7))) << 4);
;   f32x4 acc[4][4];
; #pragma unroll
;   for (int a = 0; a < 4; ++a)
; #pragma unroll
;     for (int b = 0; b < 4; ++b) acc[a][b] = (f32x4){0.f, 0.f, 0.f, 0.f};
;   const int KT = K >> 6;
;   GEMM_STAGE(0, 0);
;   asm volatile("s_waitcnt vmcnt(0)" ::: "memory");
;   __syncthreads();
;   for (int kt = 0; kt < KT; ++kt) {
;     const int cur = kt & 1;
;     if (kt + 1 < KT) GEMM_STAGE(cur ^ 1, kt + 1);
;     const char* sa = smem + cur * 32768 + wm * 64 * 128;
;     const char* sb = smem + cur * 32768 + 16384 + wn * 64 * 128;
; #pragma unroll
;     for (int ks = 0; ks < 2; ++ks) {
;       bf16x8 wf[4], af[4];
; #pragma unroll
;       for (int j = 0; j < 4; ++j) {
;         wf[j] = *(const bf16x8*)(sb + j * 2048 + foff[ks]);
;         af[j] = *(const bf16x8*)(sa + j * 2048 + foff[ks]);
;       }
; #pragma unroll
;       for (int ni = 0; ni < 4; ++ni)
; #pragma unroll
;         for (int mi = 0; mi < 4; ++mi) acc[ni][mi] = __builtin_amdgcn_mfma_f32_16x16x32_bf16(wf[ni], af[mi], acc[ni][mi], 0, 0, 0);
;     }
;     asm volatile("s_waitcnt vmcnt(0)" ::: "memory");
;     __syncthreads();
;   }
.LBB0_2314:
	s_and_b32 s6, s1, 0x8000
	s_xor_b32 s7, s6, 0x8000
	v_add_u32_e32 v108, s7, v90
	v_add_u32_e32 v91, s6, v88
	v_or_b32_e32 v116, s6, v89
	v_readfirstlane_b32 s6, v108
	v_add_u32_e32 v109, 0x4000, v108
	v_lshl_add_u64 v[92:93], v[66:67], 0, s[4:5]
	v_add_u32_e32 v110, 0x400, v108
	v_readfirstlane_b32 s7, v109
	s_mov_b32 m0, s6
	v_lshl_add_u64 v[94:95], v[68:69], 0, s[4:5]
	v_add_u32_e32 v111, 0x4400, v108
	v_readfirstlane_b32 s8, v110
	global_load_lds_dwordx4 v[92:93], off
	s_mov_b32 m0, s7
	v_lshl_add_u64 v[96:97], v[70:71], 0, s[4:5]
	v_add_u32_e32 v113, 0x800, v108
	v_readfirstlane_b32 s9, v111
	global_load_lds_dwordx4 v[94:95], off
	s_mov_b32 m0, s8
	v_lshl_add_u64 v[98:99], v[72:73], 0, s[4:5]
	v_add_u32_e32 v114, 0x4800, v108
	v_readfirstlane_b32 s10, v113
	global_load_lds_dwordx4 v[96:97], off
	s_mov_b32 m0, s9
	v_lshl_add_u64 v[100:101], v[74:75], 0, s[4:5]
	v_add_u32_e32 v115, 0xc00, v108
	v_readfirstlane_b32 s11, v114
	global_load_lds_dwordx4 v[98:99], off
	s_mov_b32 m0, s10
	v_lshl_add_u64 v[102:103], v[76:77], 0, s[4:5]
	v_add_u32_e32 v108, 0x4c00, v108
	v_readfirstlane_b32 s26, v115
	global_load_lds_dwordx4 v[100:101], off
	s_mov_b32 m0, s11
	v_lshl_add_u64 v[104:105], v[78:79], 0, s[4:5]
	v_readfirstlane_b32 s27, v108
	global_load_lds_dwordx4 v[102:103], off
	s_mov_b32 m0, s26
	v_lshl_add_u64 v[106:107], v[80:81], 0, s[4:5]
	global_load_lds_dwordx4 v[104:105], off
	s_mov_b32 m0, s27
	v_add_u32_e32 v117, v116, v87
	global_load_lds_dwordx4 v[106:107], off
	v_add_u32_e32 v112, v91, v87
	ds_read_b128 v[92:95], v117 offset:16384
	ds_read_b128 v[96:99], v112
	ds_read_b128 v[100:103], v117 offset:18432
	ds_read_b128 v[104:107], v112 offset:2048
	ds_read_b128 v[108:111], v112 offset:4096
	ds_read_b128 v[112:115], v112 offset:6144
	s_waitcnt lgkmcnt(0)
	v_mfma_f32_16x16x32_bf16 v[60:63], v[92:95], v[96:99], v[60:63]
	v_add_u32_e32 v116, v116, v86
	v_add_u32_e32 v91, v91, v86
	s_add_i32 s1, s1, 0x8000
	v_mfma_f32_16x16x32_bf16 v[56:59], v[92:95], v[104:107], v[56:59]
	s_add_u32 s4, s4, 0x80
	s_addc_u32 s5, s5, 0
	s_cmpk_eq_i32 s4, 0x780
	v_mfma_f32_16x16x32_bf16 v[48:51], v[92:95], v[108:111], v[48:51]
	v_mfma_f32_16x16x32_bf16 v[40:43], v[92:95], v[112:115], v[40:43]
	v_mfma_f32_16x16x32_bf16 v[36:39], v[100:103], v[96:99], v[36:39]
	v_mfma_f32_16x16x32_bf16 v[32:35], v[100:103], v[104:107], v[32:35]
	v_mfma_f32_16x16x32_bf16 v[28:31], v[100:103], v[108:111], v[28:31]
	v_mfma_f32_16x16x32_bf16 v[24:27], v[100:103], v[112:115], v[24:27]
	ds_read_b128 v[92:95], v117 offset:20480
	ds_read_b128 v[100:103], v117 offset:22528
	s_waitcnt lgkmcnt(0)
	v_mfma_f32_16x16x32_bf16 v[20:23], v[92:95], v[96:99], v[20:23]
	v_mfma_f32_16x16x32_bf16 v[16:19], v[92:95], v[104:107], v[16:19]
	v_mfma_f32_16x16x32_bf16 v[12:15], v[92:95], v[108:111], v[12:15]
	v_mfma_f32_16x16x32_bf16 v[8:11], v[92:95], v[112:115], v[8:11]
	ds_read_b128 v[92:95], v116 offset:16384
	v_mfma_f32_16x16x32_bf16 v[4:7], v[100:103], v[96:99], v[4:7]
	v_mfma_f32_16x16x32_bf16 v[0:3], v[100:103], v[104:107], v[0:3]
	v_mfma_f32_16x16x32_bf16 v[52:55], v[100:103], v[108:111], v[52:55]
	v_mfma_f32_16x16x32_bf16 v[44:47], v[100:103], v[112:115], v[44:47]
	ds_read_b128 v[96:99], v91
	ds_read_b128 v[100:103], v116 offset:18432
	ds_read_b128 v[104:107], v91 offset:2048
	ds_read_b128 v[108:111], v91 offset:4096
	ds_read_b128 v[112:115], v91 offset:6144
	s_waitcnt lgkmcnt(0)
	v_mfma_f32_16x16x32_bf16 v[60:63], v[92:95], v[96:99], v[60:63]
	v_mfma_f32_16x16x32_bf16 v[56:59], v[92:95], v[104:107], v[56:59]
	v_mfma_f32_16x16x32_bf16 v[48:51], v[92:95], v[108:111], v[48:51]
	v_mfma_f32_16x16x32_bf16 v[40:43], v[92:95], v[112:115], v[40:43]
	v_mfma_f32_16x16x32_bf16 v[36:39], v[100:103], v[96:99], v[36:39]
	v_mfma_f32_16x16x32_bf16 v[32:35], v[100:103], v[104:107], v[32:35]
	v_mfma_f32_16x16x32_bf16 v[28:31], v[100:103], v[108:111], v[28:31]
	v_mfma_f32_16x16x32_bf16 v[24:27], v[100:103], v[112:115], v[24:27]
	ds_read_b128 v[92:95], v116 offset:20480
	ds_read_b128 v[100:103], v116 offset:22528
	s_waitcnt vmcnt(0)
	s_waitcnt vmcnt(0) lgkmcnt(0)
	v_mfma_f32_16x16x32_bf16 v[20:23], v[92:95], v[96:99], v[20:23]
	s_barrier
	v_mfma_f32_16x16x32_bf16 v[16:19], v[92:95], v[104:107], v[16:19]
	v_mfma_f32_16x16x32_bf16 v[12:15], v[92:95], v[108:111], v[12:15]
	v_mfma_f32_16x16x32_bf16 v[8:11], v[92:95], v[112:115], v[8:11]
	v_mfma_f32_16x16x32_bf16 v[4:7], v[100:103], v[96:99], v[4:7]
	v_mfma_f32_16x16x32_bf16 v[0:3], v[100:103], v[104:107], v[0:3]
	v_mfma_f32_16x16x32_bf16 v[52:55], v[100:103], v[108:111], v[52:55]
	v_mfma_f32_16x16x32_bf16 v[44:47], v[100:103], v[112:115], v[44:47]
	s_cbranch_scc0 .LBB0_2314
;   DI u32x2 pack(int, int, float a, float b, float c, float d, float&) const { u32x2 v; v.x = pack2(a, b); v.y = pack2(c, d); return v; }
; template <class ARow, class Epi>
; DI void gemm_tile(const ARow& arow, long a_kstride, const u16* __restrict__ Bt, long ldb, int K, int m0, int n0,
;                   const Epi& epi, char* smem) {
;     ...
; #pragma unroll
;     for (int ks = 0; ks < 2; ++ks) {
;       bf16x8 wf[4], af[4];
; #pragma unroll
;       for (int j = 0; j < 4; ++j) {
;         wf[j] = *(const bf16x8*)(sb + j * 2048 + foff[ks]);
;         af[j] = *(const bf16x8*)(sa + j * 2048 + foff[ks]);
;       }
; #pragma unroll
;       for (int ni = 0; ni < 4; ++ni)
; #pragma unroll
;         for (int mi = 0; mi < 4; ++mi) acc[ni][mi] = __builtin_amdgcn_mfma_f32_16x16x32_bf16(wf[ni], af[mi], acc[ni][mi], 0, 0, 0);
;     }
;     asm volatile("s_waitcnt vmcnt(0)" ::: "memory");
;     __syncthreads();
;   }
;     ...
;   const int nh = n0 + wn * 64;
;   if (epi.packed(nh)) {
; #pragma unroll
;     for (int mi = 0; mi < 4; ++mi) {
;       const int m = m0 + wm * 64 + mi * 16 + fr;
;       float ss = 0.f;
;       u32x2 pk[4];
; #pragma unroll
;       for (int ni = 0; ni < 4; ++ni) pk[ni] = epi.pack(m, nh + ni * 16 + fq * 4, acc[ni][mi][0], acc[ni][mi][1], acc[ni][mi][2], acc[ni][mi][3], ss);
;       epi.finish16(m, nh, ss);
;       u16* rp = epi.rowp(m) + nh;
; #pragma unroll
;       for (int pp = 0; pp < 2; ++pp) {
;         u32x2 a = pk[2 * pp], b = pk[2 * pp + 1];
;         const u32x2 rx = __builtin_amdgcn_permlane16_swap(a.x, b.x, false, false);
;         const u32x2 ry = __builtin_amdgcn_permlane16_swap(a.y, b.y, false, false);
;         const int nst = (fq & 1) ? ((2 * pp + 1) * 16 + (fq - 1) * 4) : ((2 * pp) * 16 + fq * 4);
;         *(u32x4*)(rp + nst) = (u32x4){rx[0], ry[0], rx[1], ry[1]};
;       }
	v_add_u32_e32 v106, v89, v87
	ds_read_b128 v[66:69], v106 offset:49152
	v_add_u32_e32 v87, v88, v87
	ds_read_b128 v[70:73], v87 offset:32768
	ds_read_b128 v[74:77], v87 offset:34816
	ds_read_b128 v[78:81], v87 offset:36864
	ds_read_b128 v[90:93], v87 offset:38912
	v_add_u32_e32 v114, v89, v86
	s_waitcnt lgkmcnt(3)
	v_mfma_f32_16x16x32_bf16 v[60:63], v[66:69], v[70:73], v[60:63]
	s_waitcnt lgkmcnt(2)
	v_mfma_f32_16x16x32_bf16 v[56:59], v[66:69], v[74:77], v[56:59]
	s_waitcnt lgkmcnt(1)
	v_mfma_f32_16x16x32_bf16 v[48:51], v[66:69], v[78:81], v[48:51]
	s_waitcnt lgkmcnt(0)
	v_mfma_f32_16x16x32_bf16 v[40:43], v[66:69], v[90:93], v[40:43]
	ds_read_b128 v[66:69], v106 offset:51200
	s_waitcnt lgkmcnt(0)
	v_mfma_f32_16x16x32_bf16 v[36:39], v[66:69], v[70:73], v[36:39]
	v_mfma_f32_16x16x32_bf16 v[32:35], v[66:69], v[74:77], v[32:35]
	v_mfma_f32_16x16x32_bf16 v[94:97], v[66:69], v[78:81], v[28:31]
	v_mfma_f32_16x16x32_bf16 v[66:69], v[66:69], v[90:93], v[24:27]
	s_nop 2
	ds_read_b128 v[24:27], v106 offset:53248
	s_waitcnt lgkmcnt(0)
	v_mfma_f32_16x16x32_bf16 v[102:105], v[24:27], v[90:93], v[8:11]
	s_nop 2
	ds_read_b128 v[8:11], v106 offset:55296
	v_mfma_f32_16x16x32_bf16 v[20:23], v[24:27], v[70:73], v[20:23]
	s_waitcnt lgkmcnt(0)
	v_mfma_f32_16x16x32_bf16 v[70:73], v[8:11], v[70:73], v[4:7]
	s_nop 2
	ds_read_b128 v[4:7], v114 offset:49152
	v_mfma_f32_16x16x32_bf16 v[98:101], v[24:27], v[78:81], v[12:15]
	s_nop 2
	v_add_u32_e32 v12, v88, v86
	v_mfma_f32_16x16x32_bf16 v[16:19], v[24:27], v[74:77], v[16:19]
	ds_read_b128 v[86:89], v12 offset:32768
	ds_read_b128 v[106:109], v12 offset:36864
	ds_read_b128 v[110:113], v12 offset:38912
	v_mfma_f32_16x16x32_bf16 v[0:3], v[8:11], v[74:77], v[0:3]
	v_mfma_f32_16x16x32_bf16 v[74:77], v[8:11], v[78:81], v[52:55]
	v_mfma_f32_16x16x32_bf16 v[78:81], v[8:11], v[90:93], v[44:47]
	ds_read_b128 v[90:93], v12 offset:34816
	s_waitcnt lgkmcnt(3)
	v_mfma_f32_16x16x32_bf16 v[60:63], v[4:7], v[86:89], v[60:63]
	s_waitcnt lgkmcnt(0)
	v_mfma_f32_16x16x32_bf16 v[44:47], v[4:7], v[90:93], v[56:59]
	v_mfma_f32_16x16x32_bf16 v[28:31], v[4:7], v[106:109], v[48:51]
	v_mfma_f32_16x16x32_bf16 v[12:15], v[4:7], v[110:113], v[40:43]
	ds_read_b128 v[4:7], v114 offset:51200
	s_waitcnt lgkmcnt(0)
	v_mfma_f32_16x16x32_bf16 v[56:59], v[4:7], v[86:89], v[36:39]
	v_mfma_f32_16x16x32_bf16 v[40:43], v[4:7], v[90:93], v[32:35]
	v_mfma_f32_16x16x32_bf16 v[24:27], v[4:7], v[106:109], v[94:97]
	v_mfma_f32_16x16x32_bf16 v[8:11], v[4:7], v[110:113], v[66:69]
	ds_read_b128 v[4:7], v114 offset:53248
	s_nop 0
	ds_read_b128 v[94:97], v114 offset:55296
	s_waitcnt vmcnt(0)
	s_waitcnt lgkmcnt(0)
	v_mfma_f32_16x16x32_bf16 v[32:35], v[94:97], v[90:93], v[0:3]
	s_nop 2
	v_or_b32_e32 v0, s0, v64
	v_lshl_add_u32 v66, v85, 6, v0
	v_lshl_or_b32 v68, v84, 6, s34
	v_mfma_f32_16x16x32_bf16 v[52:55], v[4:7], v[86:89], v[20:23]
	v_cmp_lt_i32_e32 vcc, s30, v68
	s_barrier
	v_mfma_f32_16x16x32_bf16 v[36:39], v[4:7], v[90:93], v[16:19]
	v_mfma_f32_16x16x32_bf16 v[20:23], v[4:7], v[106:109], v[98:101]
	v_mfma_f32_16x16x32_bf16 v[4:7], v[4:7], v[110:113], v[102:105]
	v_mfma_f32_16x16x32_bf16 v[48:51], v[94:97], v[86:89], v[70:73]
	v_mfma_f32_16x16x32_bf16 v[16:19], v[94:97], v[106:109], v[74:77]
	s_nop 1
	v_lshlrev_b32_e32 v70, 2, v83
	v_or_b32_e32 v64, v68, v70
	v_mfma_f32_16x16x32_bf16 v[0:3], v[94:97], v[110:113], v[78:81]
	s_nop 7
	v_readfirstlane_b32 s99, v68
	s_cmpk_ge_u32 s99, 0x400
	s_cbranch_scc0 .Lfe_D_not_plain
	s_cmpk_lt_u32 s99, 0xc00
	s_cbranch_scc0 .Lfe_D_not_plain
	s_load_dwordx2 s[100:101], s[56:57], 0x130
	v_and_b32_e32 v152, 1, v83
	v_mul_u32_u24_e32 v152, 12, v152
	v_lshl_add_u32 v152, v83, 2, v152
	v_add_u32_e32 v152, v152, v68
	v_lshl_add_u32 v152, v66, 12, v152
	v_lshlrev_b32_e32 v152, 1, v152
	v_add_u32_e32 v153, 0x20000, v152
	v_add_u32_e32 v154, 0x40000, v152
	v_add_u32_e32 v155, 0x60000, v152
	s_nop 3
	v_cvt_pk_bf16_f32 v120, v60, v61
	v_cvt_pk_bf16_f32 v121, v62, v63
	v_cvt_pk_bf16_f32 v122, v56, v57
	v_cvt_pk_bf16_f32 v123, v58, v59
	v_cvt_pk_bf16_f32 v124, v52, v53
	v_cvt_pk_bf16_f32 v125, v54, v55
	v_cvt_pk_bf16_f32 v126, v48, v49
	v_cvt_pk_bf16_f32 v127, v50, v51
	s_nop 1
	v_permlane16_swap_b32_e32 v120, v122
	v_permlane16_swap_b32_e32 v121, v123
	v_permlane16_swap_b32_e32 v124, v126
	v_permlane16_swap_b32_e32 v125, v127
	s_waitcnt lgkmcnt(0)
	global_store_dwordx4 v152, v[120:123], s[100:101] sc0 sc1
	global_store_dwordx4 v152, v[124:127], s[100:101] offset:64 sc0 sc1
	v_cvt_pk_bf16_f32 v128, v44, v45
	v_cvt_pk_bf16_f32 v129, v46, v47
	v_cvt_pk_bf16_f32 v130, v40, v41
	v_cvt_pk_bf16_f32 v131, v42, v43
	v_cvt_pk_bf16_f32 v132, v36, v37
	v_cvt_pk_bf16_f32 v133, v38, v39
	v_cvt_pk_bf16_f32 v134, v32, v33
	v_cvt_pk_bf16_f32 v135, v34, v35
	s_nop 1
	v_permlane16_swap_b32_e32 v128, v130
	v_permlane16_swap_b32_e32 v129, v131
	v_permlane16_swap_b32_e32 v132, v134
	v_permlane16_swap_b32_e32 v133, v135
	global_store_dwordx4 v153, v[128:131], s[100:101] sc0 sc1
	global_store_dwordx4 v153, v[132:135], s[100:101] offset:64 sc0 sc1
	v_cvt_pk_bf16_f32 v136, v28, v29
	v_cvt_pk_bf16_f32 v137, v30, v31
	v_cvt_pk_bf16_f32 v138, v24, v25
	v_cvt_pk_bf16_f32 v139, v26, v27
	v_cvt_pk_bf16_f32 v140, v20, v21
	v_cvt_pk_bf16_f32 v141, v22, v23
	v_cvt_pk_bf16_f32 v142, v16, v17
	v_cvt_pk_bf16_f32 v143, v18, v19
	s_nop 1
	v_permlane16_swap_b32_e32 v136, v138
	v_permlane16_swap_b32_e32 v137, v139
	v_permlane16_swap_b32_e32 v140, v142
	v_permlane16_swap_b32_e32 v141, v143
	global_store_dwordx4 v154, v[136:139], s[100:101] sc0 sc1
	global_store_dwordx4 v154, v[140:143], s[100:101] offset:64 sc0 sc1
	v_cvt_pk_bf16_f32 v144, v12, v13
	v_cvt_pk_bf16_f32 v145, v14, v15
	v_cvt_pk_bf16_f32 v146, v8, v9
	v_cvt_pk_bf16_f32 v147, v10, v11
	v_cvt_pk_bf16_f32 v148, v4, v5
	v_cvt_pk_bf16_f32 v149, v6, v7
	v_cvt_pk_bf16_f32 v150, v0, v1
	v_cvt_pk_bf16_f32 v151, v2, v3
	s_nop 1
	v_permlane16_swap_b32_e32 v144, v146
	v_permlane16_swap_b32_e32 v145, v147
	v_permlane16_swap_b32_e32 v148, v150
	v_permlane16_swap_b32_e32 v149, v151
	global_store_dwordx4 v155, v[144:147], s[100:101] sc0 sc1
	global_store_dwordx4 v155, v[148:151], s[100:101] offset:64 sc0 sc1
	s_branch .Lfe_join_D
; DI unsigned pack2(float a, float b) { v2f f = {a, b}; return __builtin_bit_cast(unsigned, __builtin_convertvector(f, v2bf)); }
; DI float silu_f(float v) { return v / (1.f + fexp(-v)); }
;   DI u32x2 pack(int, int, float a, float b, float c, float d, float&) const { u32x2 v; v.x = pack2(a, b); v.y = pack2(c, d); return v; }
; template <class ARow, class Epi>
; DI void gemm_tile(const ARow& arow, long a_kstride, const u16* __restrict__ Bt, long ldb, int K, int m0, int n0,
;                   const Epi& epi, char* smem) {
;     ...
;     for (int mi = 0; mi < 4; ++mi) {
;       const int m = m0 + wm * 64 + mi * 16 + fr;
;       float ss = 0.f;
;       u32x2 pk[4];
; #pragma unroll
;       for (int ni = 0; ni < 4; ++ni) pk[ni] = epi.pack(m, nh + ni * 16 + fq * 4, acc[ni][mi][0], acc[ni][mi][1], acc[ni][mi][2], acc[ni][mi][3], ss);
;       epi.finish16(m, nh, ss);
;       u16* rp = epi.rowp(m) + nh;
; #pragma unroll
;       for (int pp = 0; pp < 2; ++pp) {
;         u32x2 a = pk[2 * pp], b = pk[2 * pp + 1];
;         const u32x2 rx = __builtin_amdgcn_permlane16_swap(a.x, b.x, false, false);
;         const u32x2 ry = __builtin_amdgcn_permlane16_swap(a.y, b.y, false, false);
;         const int nst = (fq & 1) ? ((2 * pp + 1) * 16 + (fq - 1) * 4) : ((2 * pp) * 16 + fq * 4);
;         *(u32x4*)(rp + nst) = (u32x4){rx[0], ry[0], rx[1], ry[1]};
;       }
;   DI u32x2 pack(int m, int n, float a, float b, float c, float d, float& ss) const {
;     if (n < q_end) { a *= qscale; b *= qscale; c *= qscale; d *= qscale; }
;     else if (n >= z_start) { a = silu_f(a); b = silu_f(b); c = silu_f(c); d = silu_f(d); }
;     ss += a * a + b * b + c * c + d * d;
;     u32x2 v; v.x = pack2(a, b); v.y = pack2(c, d);
;     return v;
.Lfe_D_not_plain:
	s_cmpk_lt_u32 s99, 0x400
	s_cbranch_scc0 .Lfe_D_not_q
	s_load_dwordx2 s[100:101], s[56:57], 0x130
	v_and_b32_e32 v152, 1, v83
	v_mul_u32_u24_e32 v152, 12, v152
	v_lshl_add_u32 v152, v83, 2, v152
	v_add_u32_e32 v152, v152, v68
	v_lshl_add_u32 v152, v66, 12, v152
	v_lshlrev_b32_e32 v152, 1, v152
	v_add_u32_e32 v153, 0x20000, v152
	v_add_u32_e32 v154, 0x40000, v152
	v_add_u32_e32 v155, 0x60000, v152
	s_mov_b32 s98, 0x3e000000
	s_nop 3
	v_pk_mul_f32 v[60:61], v[60:61], s[98:99] op_sel_hi:[1,0]
	v_pk_mul_f32 v[62:63], v[62:63], s[98:99] op_sel_hi:[1,0]
	v_pk_mul_f32 v[56:57], v[56:57], s[98:99] op_sel_hi:[1,0]
	v_pk_mul_f32 v[58:59], v[58:59], s[98:99] op_sel_hi:[1,0]
	v_pk_mul_f32 v[52:53], v[52:53], s[98:99] op_sel_hi:[1,0]
	v_pk_mul_f32 v[54:55], v[54:55], s[98:99] op_sel_hi:[1,0]
	v_pk_mul_f32 v[48:49], v[48:49], s[98:99] op_sel_hi:[1,0]
	v_pk_mul_f32 v[50:51], v[50:51], s[98:99] op_sel_hi:[1,0]
	v_cvt_pk_bf16_f32 v120, v60, v61
	v_cvt_pk_bf16_f32 v121, v62, v63
	v_cvt_pk_bf16_f32 v122, v56, v57
	v_cvt_pk_bf16_f32 v123, v58, v59
	v_cvt_pk_bf16_f32 v124, v52, v53
	v_cvt_pk_bf16_f32 v125, v54, v55
	v_cvt_pk_bf16_f32 v126, v48, v49
	v_cvt_pk_bf16_f32 v127, v50, v51
	s_nop 1
	v_permlane16_swap_b32_e32 v120, v122
	v_permlane16_swap_b32_e32 v121, v123
	v_permlane16_swap_b32_e32 v124, v126
	v_permlane16_swap_b32_e32 v125, v127
	s_waitcnt lgkmcnt(0)
	global_store_dwordx4 v152, v[120:123], s[100:101] sc0 sc1
	global_store_dwordx4 v152, v[124:127], s[100:101] offset:64 sc0 sc1
	v_pk_mul_f32 v[44:45], v[44:45], s[98:99] op_sel_hi:[1,0]
	v_pk_mul_f32 v[46:47], v[46:47], s[98:99] op_sel_hi:[1,0]
	v_pk_mul_f32 v[40:41], v[40:41], s[98:99] op_sel_hi:[1,0]
	v_pk_mul_f32 v[42:43], v[42:43], s[98:99] op_sel_hi:[1,0]
	v_pk_mul_f32 v[36:37], v[36:37], s[98:99] op_sel_hi:[1,0]
	v_pk_mul_f32 v[38:39], v[38:39], s[98:99] op_sel_hi:[1,0]
	v_pk_mul_f32 v[32:33], v[32:33], s[98:99] op_sel_hi:[1,0]
	v_pk_mul_f32 v[34:35], v[34:35], s[98:99] op_sel_hi:[1,0]
	v_cvt_pk_bf16_f32 v128, v44, v45
	v_cvt_pk_bf16_f32 v129, v46, v47
	v_cvt_pk_bf16_f32 v130, v40, v41
	v_cvt_pk_bf16_f32 v131, v42, v43
	v_cvt_pk_bf16_f32 v132, v36, v37
	v_cvt_pk_bf16_f32 v133, v38, v39
	v_cvt_pk_bf16_f32 v134, v32, v33
	v_cvt_pk_bf16_f32 v135, v34, v35
	s_nop 1
	v_permlane16_swap_b32_e32 v128, v130
	v_permlane16_swap_b32_e32 v129, v131
	v_permlane16_swap_b32_e32 v132, v134
	v_permlane16_swap_b32_e32 v133, v135
	global_store_dwordx4 v153, v[128:131], s[100:101] sc0 sc1
	global_store_dwordx4 v153, v[132:135], s[100:101] offset:64 sc0 sc1
	v_pk_mul_f32 v[28:29], v[28:29], s[98:99] op_sel_hi:[1,0]
	v_pk_mul_f32 v[30:31], v[30:31], s[98:99] op_sel_hi:[1,0]
	v_pk_mul_f32 v[24:25], v[24:25], s[98:99] op_sel_hi:[1,0]
	v_pk_mul_f32 v[26:27], v[26:27], s[98:99] op_sel_hi:[1,0]
	v_pk_mul_f32 v[20:21], v[20:21], s[98:99] op_sel_hi:[1,0]
	v_pk_mul_f32 v[22:23], v[22:23], s[98:99] op_sel_hi:[1,0]
	v_pk_mul_f32 v[16:17], v[16:17], s[98:99] op_sel_hi:[1,0]
	v_pk_mul_f32 v[18:19], v[18:19], s[98:99] op_sel_hi:[1,0]
	v_cvt_pk_bf16_f32 v136, v28, v29
	v_cvt_pk_bf16_f32 v137, v30, v31
	v_cvt_pk_bf16_f32 v138, v24, v25
	v_cvt_pk_bf16_f32 v139, v26, v27
	v_cvt_pk_bf16_f32 v140, v20, v21
	v_cvt_pk_bf16_f32 v141, v22, v23
	v_cvt_pk_bf16_f32 v142, v16, v17
	v_cvt_pk_bf16_f32 v143, v18, v19
	s_nop 1
	v_permlane16_swap_b32_e32 v136, v138
	v_permlane16_swap_b32_e32 v137, v139
	v_permlane16_swap_b32_e32 v140, v142
	v_permlane16_swap_b32_e32 v141, v143
	global_store_dwordx4 v154, v[136:139], s[100:101] sc0 sc1
	global_store_dwordx4 v154, v[140:143], s[100:101] offset:64 sc0 sc1
	v_pk_mul_f32 v[12:13], v[12:13], s[98:99] op_sel_hi:[1,0]
	v_pk_mul_f32 v[14:15], v[14:15], s[98:99] op_sel_hi:[1,0]
	v_pk_mul_f32 v[8:9], v[8:9], s[98:99] op_sel_hi:[1,0]
	v_pk_mul_f32 v[10:11], v[10:11], s[98:99] op_sel_hi:[1,0]
	v_pk_mul_f32 v[4:5], v[4:5], s[98:99] op_sel_hi:[1,0]
	v_pk_mul_f32 v[6:7], v[6:7], s[98:99] op_sel_hi:[1,0]
	v_pk_mul_f32 v[0:1], v[0:1], s[98:99] op_sel_hi:[1,0]
	v_pk_mul_f32 v[2:3], v[2:3], s[98:99] op_sel_hi:[1,0]
	v_cvt_pk_bf16_f32 v144, v12, v13
	v_cvt_pk_bf16_f32 v145, v14, v15
	v_cvt_pk_bf16_f32 v146, v8, v9
	v_cvt_pk_bf16_f32 v147, v10, v11
	v_cvt_pk_bf16_f32 v148, v4, v5
	v_cvt_pk_bf16_f32 v149, v6, v7
	v_cvt_pk_bf16_f32 v150, v0, v1
	v_cvt_pk_bf16_f32 v151, v2, v3
	s_nop 1
	v_permlane16_swap_b32_e32 v144, v146
	v_permlane16_swap_b32_e32 v145, v147
	v_permlane16_swap_b32_e32 v148, v150
	v_permlane16_swap_b32_e32 v149, v151
	global_store_dwordx4 v155, v[144:147], s[100:101] sc0 sc1
	global_store_dwordx4 v155, v[148:151], s[100:101] offset:64 sc0 sc1
	s_branch .Lfe_join_D
; DI unsigned pack2(float a, float b) { v2f f = {a, b}; return __builtin_bit_cast(unsigned, __builtin_convertvector(f, v2bf)); }
; DI float silu_f(float v) { return v / (1.f + fexp(-v)); }
;   DI u32x2 pack(int, int, float a, float b, float c, float d, float&) const { u32x2 v; v.x = pack2(a, b); v.y = pack2(c, d); return v; }
; template <class ARow, class Epi>
; DI void gemm_tile(const ARow& arow, long a_kstride, const u16* __restrict__ Bt, long ldb, int K, int m0, int n0,
;                   const Epi& epi, char* smem) {
;     ...
;     for (int mi = 0; mi < 4; ++mi) {
;       const int m = m0 + wm * 64 + mi * 16 + fr;
;       float ss = 0.f;
;       u32x2 pk[4];
; #pragma unroll
;       for (int ni = 0; ni < 4; ++ni) pk[ni] = epi.pack(m, nh + ni * 16 + fq * 4, acc[ni][mi][0], acc[ni][mi][1], acc[ni][mi][2], acc[ni][mi][3], ss);
;       epi.finish16(m, nh, ss);
;       u16* rp = epi.rowp(m) + nh;
; #pragma unroll
;       for (int pp = 0; pp < 2; ++pp) {
;         u32x2 a = pk[2 * pp], b = pk[2 * pp + 1];
;         const u32x2 rx = __builtin_amdgcn_permlane16_swap(a.x, b.x, false, false);
;         const u32x2 ry = __builtin_amdgcn_permlane16_swap(a.y, b.y, false, false);
;         const int nst = (fq & 1) ? ((2 * pp + 1) * 16 + (fq - 1) * 4) : ((2 * pp) * 16 + fq * 4);
;         *(u32x4*)(rp + nst) = (u32x4){rx[0], ry[0], rx[1], ry[1]};
;       }
;   DI u32x2 pack(int m, int n, float a, float b, float c, float d, float& ss) const {
;     if (n < q_end) { a *= qscale; b *= qscale; c *= qscale; d *= qscale; }
;     else if (n >= z_start) { a = silu_f(a); b = silu_f(b); c = silu_f(c); d = silu_f(d); }
;     ss += a * a + b * b + c * c + d * d;
;     u32x2 v; v.x = pack2(a, b); v.y = pack2(c, d);
;     return v;
.Lfe_D_not_q:
	s_cmpk_ge_u32 s99, 0xc00
	s_cbranch_scc0 .Lfe_D_not_z
	s_cmpk_lt_u32 s99, 0x1000
	s_cbranch_scc0 .Lfe_D_not_z
	s_load_dwordx2 s[100:101], s[56:57], 0x130
	v_and_b32_e32 v152, 1, v83
	v_mul_u32_u24_e32 v152, 12, v152
	v_lshl_add_u32 v152, v83, 2, v152
	v_add_u32_e32 v152, v152, v68
	v_lshl_add_u32 v152, v66, 12, v152
	v_lshlrev_b32_e32 v152, 1, v152
	v_add_u32_e32 v153, 0x20000, v152
	v_add_u32_e32 v154, 0x40000, v152
	v_add_u32_e32 v155, 0x60000, v152
	s_nop 3
	v_mul_f32_e32 v156, 0xbfb8aa3b, v60
	v_mul_f32_e32 v157, 0xbfb8aa3b, v61
	v_mul_f32_e32 v158, 0xbfb8aa3b, v62
	v_mul_f32_e32 v159, 0xbfb8aa3b, v63
	v_mul_f32_e32 v160, 0xbfb8aa3b, v56
	v_mul_f32_e32 v161, 0xbfb8aa3b, v57
	v_mul_f32_e32 v162, 0xbfb8aa3b, v58
	v_mul_f32_e32 v163, 0xbfb8aa3b, v59
	v_exp_f32_e32 v156, v156
	v_exp_f32_e32 v157, v157
	v_exp_f32_e32 v158, v158
	v_exp_f32_e32 v159, v159
	v_exp_f32_e32 v160, v160
	v_exp_f32_e32 v161, v161
	v_exp_f32_e32 v162, v162
	v_exp_f32_e32 v163, v163
	v_add_f32_e32 v156, 1.0, v156
	v_add_f32_e32 v157, 1.0, v157
	v_add_f32_e32 v158, 1.0, v158
	v_add_f32_e32 v159, 1.0, v159
	v_add_f32_e32 v160, 1.0, v160
	v_add_f32_e32 v161, 1.0, v161
	v_add_f32_e32 v162, 1.0, v162
	v_add_f32_e32 v163, 1.0, v163
	v_rcp_f32_e32 v156, v156
	v_rcp_f32_e32 v157, v157
	v_rcp_f32_e32 v158, v158
	v_rcp_f32_e32 v159, v159
	v_rcp_f32_e32 v160, v160
	v_rcp_f32_e32 v161, v161
	v_rcp_f32_e32 v162, v162
	v_rcp_f32_e32 v163, v163
	v_mul_f32_e32 v60, v60, v156
	v_mul_f32_e32 v61, v61, v157
	v_mul_f32_e32 v62, v62, v158
	v_mul_f32_e32 v63, v63, v159
	v_mul_f32_e32 v56, v56, v160
	v_mul_f32_e32 v57, v57, v161
	v_mul_f32_e32 v58, v58, v162
	v_mul_f32_e32 v59, v59, v163
	v_mul_f32_e32 v156, 0xbfb8aa3b, v52
	v_mul_f32_e32 v157, 0xbfb8aa3b, v53
	v_mul_f32_e32 v158, 0xbfb8aa3b, v54
	v_mul_f32_e32 v159, 0xbfb8aa3b, v55
	v_mul_f32_e32 v160, 0xbfb8aa3b, v48
	v_mul_f32_e32 v161, 0xbfb8aa3b, v49
	v_mul_f32_e32 v162, 0xbfb8aa3b, v50
	v_mul_f32_e32 v163, 0xbfb8aa3b, v51
	v_exp_f32_e32 v156, v156
	v_exp_f32_e32 v157, v157
	v_exp_f32_e32 v158, v158
	v_exp_f32_e32 v159, v159
	v_exp_f32_e32 v160, v160
	v_exp_f32_e32 v161, v161
	v_exp_f32_e32 v162, v162
	v_exp_f32_e32 v163, v163
	v_add_f32_e32 v156, 1.0, v156
	v_add_f32_e32 v157, 1.0, v157
	v_add_f32_e32 v158, 1.0, v158
	v_add_f32_e32 v159, 1.0, v159
	v_add_f32_e32 v160, 1.0, v160
	v_add_f32_e32 v161, 1.0, v161
	v_add_f32_e32 v162, 1.0, v162
	v_add_f32_e32 v163, 1.0, v163
	v_rcp_f32_e32 v156, v156
	v_rcp_f32_e32 v157, v157
	v_rcp_f32_e32 v158, v158
	v_rcp_f32_e32 v159, v159
	v_rcp_f32_e32 v160, v160
	v_rcp_f32_e32 v161, v161
	v_rcp_f32_e32 v162, v162
	v_rcp_f32_e32 v163, v163
	v_mul_f32_e32 v52, v52, v156
	v_mul_f32_e32 v53, v53, v157
	v_mul_f32_e32 v54, v54, v158
	v_mul_f32_e32 v55, v55, v159
	v_mul_f32_e32 v48, v48, v160
	v_mul_f32_e32 v49, v49, v161
	v_mul_f32_e32 v50, v50, v162
	v_mul_f32_e32 v51, v51, v163
	v_cvt_pk_bf16_f32 v120, v60, v61
	v_cvt_pk_bf16_f32 v121, v62, v63
	v_cvt_pk_bf16_f32 v122, v56, v57
	v_cvt_pk_bf16_f32 v123, v58, v59
	v_cvt_pk_bf16_f32 v124, v52, v53
	v_cvt_pk_bf16_f32 v125, v54, v55
	v_cvt_pk_bf16_f32 v126, v48, v49
	v_cvt_pk_bf16_f32 v127, v50, v51
	s_nop 1
	v_permlane16_swap_b32_e32 v120, v122
	v_permlane16_swap_b32_e32 v121, v123
	v_permlane16_swap_b32_e32 v124, v126
	v_permlane16_swap_b32_e32 v125, v127
	s_waitcnt lgkmcnt(0)
	global_store_dwordx4 v152, v[120:123], s[100:101] sc0 sc1
	global_store_dwordx4 v152, v[124:127], s[100:101] offset:64 sc0 sc1
	v_mul_f32_e32 v156, 0xbfb8aa3b, v44
	v_mul_f32_e32 v157, 0xbfb8aa3b, v45
	v_mul_f32_e32 v158, 0xbfb8aa3b, v46
	v_mul_f32_e32 v159, 0xbfb8aa3b, v47
	v_mul_f32_e32 v160, 0xbfb8aa3b, v40
	v_mul_f32_e32 v161, 0xbfb8aa3b, v41
	v_mul_f32_e32 v162, 0xbfb8aa3b, v42
	v_mul_f32_e32 v163, 0xbfb8aa3b, v43
	v_exp_f32_e32 v156, v156
	v_exp_f32_e32 v157, v157
	v_exp_f32_e32 v158, v158
	v_exp_f32_e32 v159, v159
	v_exp_f32_e32 v160, v160
	v_exp_f32_e32 v161, v161
	v_exp_f32_e32 v162, v162
	v_exp_f32_e32 v163, v163
	v_add_f32_e32 v156, 1.0, v156
	v_add_f32_e32 v157, 1.0, v157
	v_add_f32_e32 v158, 1.0, v158
	v_add_f32_e32 v159, 1.0, v159
	v_add_f32_e32 v160, 1.0, v160
	v_add_f32_e32 v161, 1.0, v161
	v_add_f32_e32 v162, 1.0, v162
	v_add_f32_e32 v163, 1.0, v163
	v_rcp_f32_e32 v156, v156
	v_rcp_f32_e32 v157, v157
	v_rcp_f32_e32 v158, v158
	v_rcp_f32_e32 v159, v159
	v_rcp_f32_e32 v160, v160
	v_rcp_f32_e32 v161, v161
	v_rcp_f32_e32 v162, v162
	v_rcp_f32_e32 v163, v163
	v_mul_f32_e32 v44, v44, v156
	v_mul_f32_e32 v45, v45, v157
	v_mul_f32_e32 v46, v46, v158
	v_mul_f32_e32 v47, v47, v159
	v_mul_f32_e32 v40, v40, v160
	v_mul_f32_e32 v41, v41, v161
	v_mul_f32_e32 v42, v42, v162
	v_mul_f32_e32 v43, v43, v163
	v_mul_f32_e32 v156, 0xbfb8aa3b, v36
	v_mul_f32_e32 v157, 0xbfb8aa3b, v37
	v_mul_f32_e32 v158, 0xbfb8aa3b, v38
	v_mul_f32_e32 v159, 0xbfb8aa3b, v39
	v_mul_f32_e32 v160, 0xbfb8aa3b, v32
	v_mul_f32_e32 v161, 0xbfb8aa3b, v33
	v_mul_f32_e32 v162, 0xbfb8aa3b, v34
	v_mul_f32_e32 v163, 0xbfb8aa3b, v35
	v_exp_f32_e32 v156, v156
	v_exp_f32_e32 v157, v157
	v_exp_f32_e32 v158, v158
	v_exp_f32_e32 v159, v159
	v_exp_f32_e32 v160, v160
	v_exp_f32_e32 v161, v161
	v_exp_f32_e32 v162, v162
	v_exp_f32_e32 v163, v163
	v_add_f32_e32 v156, 1.0, v156
	v_add_f32_e32 v157, 1.0, v157
	v_add_f32_e32 v158, 1.0, v158
	v_add_f32_e32 v159, 1.0, v159
	v_add_f32_e32 v160, 1.0, v160
	v_add_f32_e32 v161, 1.0, v161
	v_add_f32_e32 v162, 1.0, v162
	v_add_f32_e32 v163, 1.0, v163
	v_rcp_f32_e32 v156, v156
	v_rcp_f32_e32 v157, v157
	v_rcp_f32_e32 v158, v158
	v_rcp_f32_e32 v159, v159
	v_rcp_f32_e32 v160, v160
	v_rcp_f32_e32 v161, v161
	v_rcp_f32_e32 v162, v162
	v_rcp_f32_e32 v163, v163
	v_mul_f32_e32 v36, v36, v156
; DI unsigned pack2(float a, float b) { v2f f = {a, b}; return __builtin_bit_cast(unsigned, __builtin_convertvector(f, v2bf)); }
; DI float silu_f(float v) { return v / (1.f + fexp(-v)); }
;   DI u32x2 pack(int, int, float a, float b, float c, float d, float&) const { u32x2 v; v.x = pack2(a, b); v.y = pack2(c, d); return v; }
; template <class ARow, class Epi>
; DI void gemm_tile(const ARow& arow, long a_kstride, const u16* __restrict__ Bt, long ldb, int K, int m0, int n0,
;                   const Epi& epi, char* smem) {
;     ...
;     for (int mi = 0; mi < 4; ++mi) {
;       const int m = m0 + wm * 64 + mi * 16 + fr;
;       float ss = 0.f;
;       u32x2 pk[4];
; #pragma unroll
;       for (int ni = 0; ni < 4; ++ni) pk[ni] = epi.pack(m, nh + ni * 16 + fq * 4, acc[ni][mi][0], acc[ni][mi][1], acc[ni][mi][2], acc[ni][mi][3], ss);
;       epi.finish16(m, nh, ss);
;       u16* rp = epi.rowp(m) + nh;
; #pragma unroll
;       for (int pp = 0; pp < 2; ++pp) {
;         u32x2 a = pk[2 * pp], b = pk[2 * pp + 1];
;         const u32x2 rx = __builtin_amdgcn_permlane16_swap(a.x, b.x, false, false);
;         const u32x2 ry = __builtin_amdgcn_permlane16_swap(a.y, b.y, false, false);
;         const int nst = (fq & 1) ? ((2 * pp + 1) * 16 + (fq - 1) * 4) : ((2 * pp) * 16 + fq * 4);
;         *(u32x4*)(rp + nst) = (u32x4){rx[0], ry[0], rx[1], ry[1]};
;       }
;   DI u32x2 pack(int m, int n, float a, float b, float c, float d, float& ss) const {
;     if (n < q_end) { a *= qscale; b *= qscale; c *= qscale; d *= qscale; }
;     else if (n >= z_start) { a = silu_f(a); b = silu_f(b); c = silu_f(c); d = silu_f(d); }
;     ss += a * a + b * b + c * c + d * d;
;     u32x2 v; v.x = pack2(a, b); v.y = pack2(c, d);
;     return v;
	v_mul_f32_e32 v37, v37, v157
	v_mul_f32_e32 v38, v38, v158
	v_mul_f32_e32 v39, v39, v159
	v_mul_f32_e32 v32, v32, v160
	v_mul_f32_e32 v33, v33, v161
	v_mul_f32_e32 v34, v34, v162
	v_mul_f32_e32 v35, v35, v163
	v_cvt_pk_bf16_f32 v128, v44, v45
	v_cvt_pk_bf16_f32 v129, v46, v47
	v_cvt_pk_bf16_f32 v130, v40, v41
	v_cvt_pk_bf16_f32 v131, v42, v43
	v_cvt_pk_bf16_f32 v132, v36, v37
	v_cvt_pk_bf16_f32 v133, v38, v39
	v_cvt_pk_bf16_f32 v134, v32, v33
	v_cvt_pk_bf16_f32 v135, v34, v35
	s_nop 1
	v_permlane16_swap_b32_e32 v128, v130
	v_permlane16_swap_b32_e32 v129, v131
	v_permlane16_swap_b32_e32 v132, v134
	v_permlane16_swap_b32_e32 v133, v135
	global_store_dwordx4 v153, v[128:131], s[100:101] sc0 sc1
	global_store_dwordx4 v153, v[132:135], s[100:101] offset:64 sc0 sc1
	v_mul_f32_e32 v156, 0xbfb8aa3b, v28
	v_mul_f32_e32 v157, 0xbfb8aa3b, v29
	v_mul_f32_e32 v158, 0xbfb8aa3b, v30
	v_mul_f32_e32 v159, 0xbfb8aa3b, v31
	v_mul_f32_e32 v160, 0xbfb8aa3b, v24
	v_mul_f32_e32 v161, 0xbfb8aa3b, v25
	v_mul_f32_e32 v162, 0xbfb8aa3b, v26
	v_mul_f32_e32 v163, 0xbfb8aa3b, v27
	v_exp_f32_e32 v156, v156
	v_exp_f32_e32 v157, v157
	v_exp_f32_e32 v158, v158
	v_exp_f32_e32 v159, v159
	v_exp_f32_e32 v160, v160
	v_exp_f32_e32 v161, v161
	v_exp_f32_e32 v162, v162
	v_exp_f32_e32 v163, v163
	v_add_f32_e32 v156, 1.0, v156
	v_add_f32_e32 v157, 1.0, v157
	v_add_f32_e32 v158, 1.0, v158
	v_add_f32_e32 v159, 1.0, v159
	v_add_f32_e32 v160, 1.0, v160
	v_add_f32_e32 v161, 1.0, v161
	v_add_f32_e32 v162, 1.0, v162
	v_add_f32_e32 v163, 1.0, v163
	v_rcp_f32_e32 v156, v156
	v_rcp_f32_e32 v157, v157
	v_rcp_f32_e32 v158, v158
	v_rcp_f32_e32 v159, v159
	v_rcp_f32_e32 v160, v160
	v_rcp_f32_e32 v161, v161
	v_rcp_f32_e32 v162, v162
	v_rcp_f32_e32 v163, v163
	v_mul_f32_e32 v28, v28, v156
	v_mul_f32_e32 v29, v29, v157
	v_mul_f32_e32 v30, v30, v158
	v_mul_f32_e32 v31, v31, v159
	v_mul_f32_e32 v24, v24, v160
	v_mul_f32_e32 v25, v25, v161
	v_mul_f32_e32 v26, v26, v162
	v_mul_f32_e32 v27, v27, v163
	v_mul_f32_e32 v156, 0xbfb8aa3b, v20
	v_mul_f32_e32 v157, 0xbfb8aa3b, v21
	v_mul_f32_e32 v158, 0xbfb8aa3b, v22
	v_mul_f32_e32 v159, 0xbfb8aa3b, v23
	v_mul_f32_e32 v160, 0xbfb8aa3b, v16
	v_mul_f32_e32 v161, 0xbfb8aa3b, v17
	v_mul_f32_e32 v162, 0xbfb8aa3b, v18
	v_mul_f32_e32 v163, 0xbfb8aa3b, v19
	v_exp_f32_e32 v156, v156
	v_exp_f32_e32 v157, v157
	v_exp_f32_e32 v158, v158
	v_exp_f32_e32 v159, v159
	v_exp_f32_e32 v160, v160
	v_exp_f32_e32 v161, v161
	v_exp_f32_e32 v162, v162
	v_exp_f32_e32 v163, v163
	v_add_f32_e32 v156, 1.0, v156
	v_add_f32_e32 v157, 1.0, v157
	v_add_f32_e32 v158, 1.0, v158
	v_add_f32_e32 v159, 1.0, v159
	v_add_f32_e32 v160, 1.0, v160
	v_add_f32_e32 v161, 1.0, v161
	v_add_f32_e32 v162, 1.0, v162
	v_add_f32_e32 v163, 1.0, v163
	v_rcp_f32_e32 v156, v156
	v_rcp_f32_e32 v157, v157
	v_rcp_f32_e32 v158, v158
	v_rcp_f32_e32 v159, v159
	v_rcp_f32_e32 v160, v160
	v_rcp_f32_e32 v161, v161
	v_rcp_f32_e32 v162, v162
	v_rcp_f32_e32 v163, v163
	v_mul_f32_e32 v20, v20, v156
	v_mul_f32_e32 v21, v21, v157
	v_mul_f32_e32 v22, v22, v158
	v_mul_f32_e32 v23, v23, v159
	v_mul_f32_e32 v16, v16, v160
	v_mul_f32_e32 v17, v17, v161
	v_mul_f32_e32 v18, v18, v162
	v_mul_f32_e32 v19, v19, v163
	v_cvt_pk_bf16_f32 v136, v28, v29
	v_cvt_pk_bf16_f32 v137, v30, v31
	v_cvt_pk_bf16_f32 v138, v24, v25
	v_cvt_pk_bf16_f32 v139, v26, v27
	v_cvt_pk_bf16_f32 v140, v20, v21
	v_cvt_pk_bf16_f32 v141, v22, v23
	v_cvt_pk_bf16_f32 v142, v16, v17
	v_cvt_pk_bf16_f32 v143, v18, v19
	s_nop 1
	v_permlane16_swap_b32_e32 v136, v138
	v_permlane16_swap_b32_e32 v137, v139
	v_permlane16_swap_b32_e32 v140, v142
	v_permlane16_swap_b32_e32 v141, v143
	global_store_dwordx4 v154, v[136:139], s[100:101] sc0 sc1
	global_store_dwordx4 v154, v[140:143], s[100:101] offset:64 sc0 sc1
	v_mul_f32_e32 v156, 0xbfb8aa3b, v12
	v_mul_f32_e32 v157, 0xbfb8aa3b, v13
	v_mul_f32_e32 v158, 0xbfb8aa3b, v14
	v_mul_f32_e32 v159, 0xbfb8aa3b, v15
	v_mul_f32_e32 v160, 0xbfb8aa3b, v8
	v_mul_f32_e32 v161, 0xbfb8aa3b, v9
	v_mul_f32_e32 v162, 0xbfb8aa3b, v10
	v_mul_f32_e32 v163, 0xbfb8aa3b, v11
	v_exp_f32_e32 v156, v156
	v_exp_f32_e32 v157, v157
	v_exp_f32_e32 v158, v158
	v_exp_f32_e32 v159, v159
	v_exp_f32_e32 v160, v160
	v_exp_f32_e32 v161, v161
	v_exp_f32_e32 v162, v162
	v_exp_f32_e32 v163, v163
	v_add_f32_e32 v156, 1.0, v156
	v_add_f32_e32 v157, 1.0, v157
	v_add_f32_e32 v158, 1.0, v158
	v_add_f32_e32 v159, 1.0, v159
	v_add_f32_e32 v160, 1.0, v160
	v_add_f32_e32 v161, 1.0, v161
	v_add_f32_e32 v162, 1.0, v162
	v_add_f32_e32 v163, 1.0, v163
	v_rcp_f32_e32 v156, v156
	v_rcp_f32_e32 v157, v157
	v_rcp_f32_e32 v158, v158
	v_rcp_f32_e32 v159, v159
	v_rcp_f32_e32 v160, v160
	v_rcp_f32_e32 v161, v161
	v_rcp_f32_e32 v162, v162
	v_rcp_f32_e32 v163, v163
	v_mul_f32_e32 v12, v12, v156
	v_mul_f32_e32 v13, v13, v157
	v_mul_f32_e32 v14, v14, v158
	v_mul_f32_e32 v15, v15, v159
	v_mul_f32_e32 v8, v8, v160
	v_mul_f32_e32 v9, v9, v161
	v_mul_f32_e32 v10, v10, v162
	v_mul_f32_e32 v11, v11, v163
	v_mul_f32_e32 v156, 0xbfb8aa3b, v4
	v_mul_f32_e32 v157, 0xbfb8aa3b, v5
	v_mul_f32_e32 v158, 0xbfb8aa3b, v6
	v_mul_f32_e32 v159, 0xbfb8aa3b, v7
	v_mul_f32_e32 v160, 0xbfb8aa3b, v0
	v_mul_f32_e32 v161, 0xbfb8aa3b, v1
	v_mul_f32_e32 v162, 0xbfb8aa3b, v2
	v_mul_f32_e32 v163, 0xbfb8aa3b, v3
	v_exp_f32_e32 v156, v156
	v_exp_f32_e32 v157, v157
	v_exp_f32_e32 v158, v158
	v_exp_f32_e32 v159, v159
	v_exp_f32_e32 v160, v160
	v_exp_f32_e32 v161, v161
	v_exp_f32_e32 v162, v162
	v_exp_f32_e32 v163, v163
	v_add_f32_e32 v156, 1.0, v156
	v_add_f32_e32 v157, 1.0, v157
	v_add_f32_e32 v158, 1.0, v158
	v_add_f32_e32 v159, 1.0, v159
	v_add_f32_e32 v160, 1.0, v160
	v_add_f32_e32 v161, 1.0, v161
	v_add_f32_e32 v162, 1.0, v162
	v_add_f32_e32 v163, 1.0, v163
	v_rcp_f32_e32 v156, v156
	v_rcp_f32_e32 v157, v157
	v_rcp_f32_e32 v158, v158
	v_rcp_f32_e32 v159, v159
	v_rcp_f32_e32 v160, v160
	v_rcp_f32_e32 v161, v161
	v_rcp_f32_e32 v162, v162
	v_rcp_f32_e32 v163, v163
	v_mul_f32_e32 v4, v4, v156
	v_mul_f32_e32 v5, v5, v157
	v_mul_f32_e32 v6, v6, v158
	v_mul_f32_e32 v7, v7, v159
	v_mul_f32_e32 v0, v0, v160
	v_mul_f32_e32 v1, v1, v161
	v_mul_f32_e32 v2, v2, v162
	v_mul_f32_e32 v3, v3, v163
	v_cvt_pk_bf16_f32 v144, v12, v13
	v_cvt_pk_bf16_f32 v145, v14, v15
	v_cvt_pk_bf16_f32 v146, v8, v9
	v_cvt_pk_bf16_f32 v147, v10, v11
	v_cvt_pk_bf16_f32 v148, v4, v5
	v_cvt_pk_bf16_f32 v149, v6, v7
	v_cvt_pk_bf16_f32 v150, v0, v1
	v_cvt_pk_bf16_f32 v151, v2, v3
	s_nop 1
	v_permlane16_swap_b32_e32 v144, v146
	v_permlane16_swap_b32_e32 v145, v147
	v_permlane16_swap_b32_e32 v148, v150
	v_permlane16_swap_b32_e32 v149, v151
	global_store_dwordx4 v155, v[144:147], s[100:101] sc0 sc1
	global_store_dwordx4 v155, v[148:151], s[100:101] offset:64 sc0 sc1
	s_branch .Lfe_join_D

; DI unsigned pack2(float a, float b) { v2f f = {a, b}; return __builtin_bit_cast(unsigned, __builtin_convertvector(f, v2bf)); }
; DI float silu_f(float v) { return v / (1.f + fexp(-v)); }
;   DI u32x2 pack(int, int, float a, float b, float c, float d, float&) const { u32x2 v; v.x = pack2(a, b); v.y = pack2(c, d); return v; }
; template <class ARow, class Epi>
; DI void gemm_tile(const ARow& arow, long a_kstride, const u16* __restrict__ Bt, long ldb, int K, int m0, int n0,
;                   const Epi& epi, char* smem) {
;     ...
;     for (int mi = 0; mi < 4; ++mi) {
;       const int m = m0 + wm * 64 + mi * 16 + fr;
;       float ss = 0.f;
;       u32x2 pk[4];
; #pragma unroll
;       for (int ni = 0; ni < 4; ++ni) pk[ni] = epi.pack(m, nh + ni * 16 + fq * 4, acc[ni][mi][0], acc[ni][mi][1], acc[ni][mi][2], acc[ni][mi][3], ss);
;       epi.finish16(m, nh, ss);
;       u16* rp = epi.rowp(m) + nh;
; #pragma unroll
;       for (int pp = 0; pp < 2; ++pp) {
;         u32x2 a = pk[2 * pp], b = pk[2 * pp + 1];
;         const u32x2 rx = __builtin_amdgcn_permlane16_swap(a.x, b.x, false, false);
;         const u32x2 ry = __builtin_amdgcn_permlane16_swap(a.y, b.y, false, false);
;         const int nst = (fq & 1) ? ((2 * pp + 1) * 16 + (fq - 1) * 4) : ((2 * pp) * 16 + fq * 4);
;         *(u32x4*)(rp + nst) = (u32x4){rx[0], ry[0], rx[1], ry[1]};
;       }
;   DI u32x2 pack(int m, int n, float a, float b, float c, float d, float& ss) const {
;     if (n < q_end) { a *= qscale; b *= qscale; c *= qscale; d *= qscale; }
;     else if (n >= z_start) { a = silu_f(a); b = silu_f(b); c = silu_f(c); d = silu_f(d); }
;     ss += a * a + b * b + c * c + d * d;
;     u32x2 v; v.x = pack2(a, b); v.y = pack2(c, d);
;     return v;
.LBB0_2480:
	s_andn2_saveexec_b64 s[0:1], s[0:1]
	v_pk_mul_f32 v[48:49], v[48:49], s[24:25] op_sel_hi:[1,0]
	v_pk_mul_f32 v[50:51], v[50:51], s[24:25] op_sel_hi:[1,0]
	s_or_b64 exec, exec, s[0:1]
	v_ashrrev_i32_e32 v67, 31, v66
	v_cvt_pk_bf16_f32 v52, v52, v53
	v_cvt_pk_bf16_f32 v53, v54, v55
	v_cvt_pk_bf16_f32 v54, v48, v49
	v_lshlrev_b64 v[48:49], 13, v[66:67]
	v_cvt_pk_bf16_f32 v74, v56, v57
	v_ashrrev_i32_e32 v69, 31, v68
	v_and_b32_e32 v56, 16, v82
	v_lshl_add_u64 v[48:49], s[14:15], 0, v[48:49]
	v_cvt_pk_bf16_f32 v55, v50, v51
	v_lshl_add_u64 v[50:51], v[68:69], 1, v[48:49]
	v_add_u32_e32 v48, 12, v70
	v_cmp_eq_u32_e32 vcc, 0, v56
	v_cvt_pk_bf16_f32 v75, v58, v59
	v_cvt_pk_bf16_f32 v72, v60, v61
	v_cndmask_b32_e32 v48, v48, v70, vcc
	v_cvt_pk_bf16_f32 v73, v62, v63
	v_lshlrev_b32_e32 v64, 1, v48
	v_permlane16_swap_b32_e32 v72, v74
	v_permlane16_swap_b32_e32 v73, v75
	v_lshl_add_u64 v[48:49], v[50:51], 0, v[64:65]
	global_store_dwordx4 v[48:49], v[72:75], off sc0 sc1
	v_add_u32_e32 v48, 44, v70
	v_or_b32_e32 v49, 32, v70
	v_cndmask_b32_e32 v48, v48, v49, vcc
	v_lshlrev_b32_e32 v48, 1, v48
	v_mov_b32_e32 v49, v65
	v_permlane16_swap_b32_e32 v52, v54
	v_permlane16_swap_b32_e32 v53, v55
	v_lshl_add_u64 v[50:51], v[50:51], 0, v[48:49]
	global_store_dwordx4 v[50:51], v[52:55], off sc0 sc1
	s_and_saveexec_b64 s[0:1], s[4:5]
	s_xor_b64 s[0:1], exec, s[0:1]
	s_cbranch_execz .LBB0_2485
	s_cmpk_lt_u32 s34, 0xc00
	s_cbranch_scc1 .LBB0_2485
	v_mul_f32_e32 v49, 0xbfb8aa3b, v44
	v_exp_f32_e32 v50, v49
	v_mul_f32_e32 v49, 0xbfb8aa3b, v45
	v_exp_f32_e32 v51, v49
	s_nop 0
	v_pk_add_f32 v[50:51], v[50:51], 1.0 op_sel_hi:[1,0]
	s_nop 0
	v_rcp_f32_e32 v49, v50
	v_mul_f32_e32 v52, 0xbfb8aa3b, v46
	v_mul_f32_e32 v53, 0xbfb8aa3b, v47
	v_exp_f32_e32 v52, v52
	v_exp_f32_e32 v53, v53
	v_mul_f32_e32 v44, v44, v49
	v_pk_add_f32 v[52:53], v[52:53], 1.0 op_sel_hi:[1,0]
	v_rcp_f32_e32 v49, v51
	s_nop 0
	v_mul_f32_e32 v45, v45, v49
	v_rcp_f32_e32 v49, v52
	s_nop 0
	v_mul_f32_e32 v46, v46, v49
	v_rcp_f32_e32 v49, v53
	s_nop 0
	v_mul_f32_e32 v47, v47, v49

; DI unsigned pack2(float a, float b) { v2f f = {a, b}; return __builtin_bit_cast(unsigned, __builtin_convertvector(f, v2bf)); }
; DI float silu_f(float v) { return v / (1.f + fexp(-v)); }
;   DI u32x2 pack(int, int, float a, float b, float c, float d, float&) const { u32x2 v; v.x = pack2(a, b); v.y = pack2(c, d); return v; }
; template <class ARow, class Epi>
; DI void gemm_tile(const ARow& arow, long a_kstride, const u16* __restrict__ Bt, long ldb, int K, int m0, int n0,
;                   const Epi& epi, char* smem) {
;     ...
;     for (int mi = 0; mi < 4; ++mi) {
;       const int m = m0 + wm * 64 + mi * 16 + fr;
;       float ss = 0.f;
;       u32x2 pk[4];
; #pragma unroll
;       for (int ni = 0; ni < 4; ++ni) pk[ni] = epi.pack(m, nh + ni * 16 + fq * 4, acc[ni][mi][0], acc[ni][mi][1], acc[ni][mi][2], acc[ni][mi][3], ss);
;       epi.finish16(m, nh, ss);
;       u16* rp = epi.rowp(m) + nh;
; #pragma unroll
;       for (int pp = 0; pp < 2; ++pp) {
;         u32x2 a = pk[2 * pp], b = pk[2 * pp + 1];
;         const u32x2 rx = __builtin_amdgcn_permlane16_swap(a.x, b.x, false, false);
;         const u32x2 ry = __builtin_amdgcn_permlane16_swap(a.y, b.y, false, false);
;         const int nst = (fq & 1) ? ((2 * pp + 1) * 16 + (fq - 1) * 4) : ((2 * pp) * 16 + fq * 4);
;         *(u32x4*)(rp + nst) = (u32x4){rx[0], ry[0], rx[1], ry[1]};
;       }
;   DI u32x2 pack(int m, int n, float a, float b, float c, float d, float& ss) const {
;     if (n < q_end) { a *= qscale; b *= qscale; c *= qscale; d *= qscale; }
;     else if (n >= z_start) { a = silu_f(a); b = silu_f(b); c = silu_f(c); d = silu_f(d); }
;     ss += a * a + b * b + c * c + d * d;
;     u32x2 v; v.x = pack2(a, b); v.y = pack2(c, d);
;     return v;
.LBB0_2500:
	s_andn2_saveexec_b64 s[0:1], s[0:1]
	v_pk_mul_f32 v[32:33], v[32:33], s[24:25] op_sel_hi:[1,0]
	v_pk_mul_f32 v[34:35], v[34:35], s[24:25] op_sel_hi:[1,0]
	s_or_b64 exec, exec, s[0:1]
	v_cvt_pk_bf16_f32 v36, v36, v37
	v_cvt_pk_bf16_f32 v37, v38, v39
	v_cvt_pk_bf16_f32 v38, v32, v33
	v_or_b32_e32 v32, 16, v66
	v_ashrrev_i32_e32 v33, 31, v32
	v_lshlrev_b64 v[32:33], 13, v[32:33]
	v_lshl_add_u64 v[32:33], s[14:15], 0, v[32:33]
	v_cvt_pk_bf16_f32 v52, v40, v41
	v_cvt_pk_bf16_f32 v53, v42, v43
	v_cvt_pk_bf16_f32 v50, v44, v45
	v_cvt_pk_bf16_f32 v51, v46, v47
	v_cvt_pk_bf16_f32 v39, v34, v35
	v_lshl_add_u64 v[32:33], v[68:69], 1, v[32:33]
	v_mov_b32_e32 v49, v65
	v_permlane16_swap_b32_e32 v50, v52
	v_permlane16_swap_b32_e32 v51, v53
	v_lshl_add_u64 v[34:35], v[32:33], 0, v[64:65]
	v_permlane16_swap_b32_e32 v36, v38
	v_permlane16_swap_b32_e32 v37, v39
	v_lshl_add_u64 v[32:33], v[32:33], 0, v[48:49]
	global_store_dwordx4 v[34:35], v[50:53], off sc0 sc1
	global_store_dwordx4 v[32:33], v[36:39], off sc0 sc1
	s_and_saveexec_b64 s[0:1], s[4:5]
	s_xor_b64 s[0:1], exec, s[0:1]
	s_cbranch_execz .LBB0_2505
	s_cmpk_lt_u32 s34, 0xc00
	s_cbranch_scc1 .LBB0_2505
	v_mul_f32_e32 v32, 0xbfb8aa3b, v28
	v_mul_f32_e32 v33, 0xbfb8aa3b, v29
	v_exp_f32_e32 v32, v32
	v_exp_f32_e32 v33, v33
	s_nop 0
	v_pk_add_f32 v[32:33], v[32:33], 1.0 op_sel_hi:[1,0]
	s_nop 0
	v_rcp_f32_e32 v34, v32
	s_nop 0
	v_mul_f32_e32 v28, v28, v34
	v_mul_f32_e32 v34, 0xbfb8aa3b, v30
	v_mul_f32_e32 v35, 0xbfb8aa3b, v31
	v_exp_f32_e32 v34, v34
	v_exp_f32_e32 v35, v35
	s_nop 0
	v_pk_add_f32 v[34:35], v[34:35], 1.0 op_sel_hi:[1,0]
	v_rcp_f32_e32 v32, v33
	s_nop 0
	v_mul_f32_e32 v29, v29, v32
	v_rcp_f32_e32 v32, v34
	s_nop 0
	v_mul_f32_e32 v30, v30, v32
	v_rcp_f32_e32 v32, v35
	s_nop 0
	v_mul_f32_e32 v31, v31, v32

; DI unsigned pack2(float a, float b) { v2f f = {a, b}; return __builtin_bit_cast(unsigned, __builtin_convertvector(f, v2bf)); }
; DI float silu_f(float v) { return v / (1.f + fexp(-v)); }
;   DI u32x2 pack(int, int, float a, float b, float c, float d, float&) const { u32x2 v; v.x = pack2(a, b); v.y = pack2(c, d); return v; }
; template <class ARow, class Epi>
; DI void gemm_tile(const ARow& arow, long a_kstride, const u16* __restrict__ Bt, long ldb, int K, int m0, int n0,
;                   const Epi& epi, char* smem) {
;     ...
;     for (int mi = 0; mi < 4; ++mi) {
;       const int m = m0 + wm * 64 + mi * 16 + fr;
;       float ss = 0.f;
;       u32x2 pk[4];
; #pragma unroll
;       for (int ni = 0; ni < 4; ++ni) pk[ni] = epi.pack(m, nh + ni * 16 + fq * 4, acc[ni][mi][0], acc[ni][mi][1], acc[ni][mi][2], acc[ni][mi][3], ss);
;       epi.finish16(m, nh, ss);
;       u16* rp = epi.rowp(m) + nh;
; #pragma unroll
;       for (int pp = 0; pp < 2; ++pp) {
;         u32x2 a = pk[2 * pp], b = pk[2 * pp + 1];
;         const u32x2 rx = __builtin_amdgcn_permlane16_swap(a.x, b.x, false, false);
;         const u32x2 ry = __builtin_amdgcn_permlane16_swap(a.y, b.y, false, false);
;         const int nst = (fq & 1) ? ((2 * pp + 1) * 16 + (fq - 1) * 4) : ((2 * pp) * 16 + fq * 4);
;         *(u32x4*)(rp + nst) = (u32x4){rx[0], ry[0], rx[1], ry[1]};
;       }
;   DI u32x2 pack(int m, int n, float a, float b, float c, float d, float& ss) const {
;     if (n < q_end) { a *= qscale; b *= qscale; c *= qscale; d *= qscale; }
;     else if (n >= z_start) { a = silu_f(a); b = silu_f(b); c = silu_f(c); d = silu_f(d); }
;     ss += a * a + b * b + c * c + d * d;
;     u32x2 v; v.x = pack2(a, b); v.y = pack2(c, d);
;     return v;
.LBB0_2520:
	s_andn2_saveexec_b64 s[0:1], s[0:1]
	v_pk_mul_f32 v[16:17], v[16:17], s[24:25] op_sel_hi:[1,0]
	v_pk_mul_f32 v[18:19], v[18:19], s[24:25] op_sel_hi:[1,0]
	s_or_b64 exec, exec, s[0:1]
	v_cvt_pk_bf16_f32 v20, v20, v21
	v_cvt_pk_bf16_f32 v21, v22, v23
	v_cvt_pk_bf16_f32 v22, v16, v17
	v_or_b32_e32 v16, 32, v66
	v_ashrrev_i32_e32 v17, 31, v16
	v_lshlrev_b64 v[16:17], 13, v[16:17]
	v_lshl_add_u64 v[16:17], s[14:15], 0, v[16:17]
	v_cvt_pk_bf16_f32 v34, v24, v25
	v_cvt_pk_bf16_f32 v35, v26, v27
	v_cvt_pk_bf16_f32 v32, v28, v29
	v_cvt_pk_bf16_f32 v33, v30, v31
	v_cvt_pk_bf16_f32 v23, v18, v19
	v_lshl_add_u64 v[16:17], v[68:69], 1, v[16:17]
	v_mov_b32_e32 v49, v65
	v_permlane16_swap_b32_e32 v32, v34
	v_permlane16_swap_b32_e32 v33, v35
	v_lshl_add_u64 v[18:19], v[16:17], 0, v[64:65]
	v_permlane16_swap_b32_e32 v20, v22
	v_permlane16_swap_b32_e32 v21, v23
	v_lshl_add_u64 v[16:17], v[16:17], 0, v[48:49]
	global_store_dwordx4 v[18:19], v[32:35], off sc0 sc1
	global_store_dwordx4 v[16:17], v[20:23], off sc0 sc1
	s_and_saveexec_b64 s[0:1], s[4:5]
	s_xor_b64 s[0:1], exec, s[0:1]
	s_cbranch_execz .LBB0_2525
	s_cmpk_lt_u32 s34, 0xc00
	s_cbranch_scc1 .LBB0_2525
	v_mul_f32_e32 v16, 0xbfb8aa3b, v12
	v_mul_f32_e32 v17, 0xbfb8aa3b, v13
	v_exp_f32_e32 v16, v16
	v_exp_f32_e32 v17, v17
	s_nop 0
	v_pk_add_f32 v[16:17], v[16:17], 1.0 op_sel_hi:[1,0]
	s_nop 0
	v_rcp_f32_e32 v18, v16
	s_nop 0
	v_mul_f32_e32 v12, v12, v18
	v_mul_f32_e32 v18, 0xbfb8aa3b, v14
	v_mul_f32_e32 v19, 0xbfb8aa3b, v15
	v_exp_f32_e32 v18, v18
	v_exp_f32_e32 v19, v19
	s_nop 0
	v_pk_add_f32 v[18:19], v[18:19], 1.0 op_sel_hi:[1,0]
	v_rcp_f32_e32 v16, v17
	s_nop 0
	v_mul_f32_e32 v13, v13, v16
	v_rcp_f32_e32 v16, v18
	s_nop 0
	v_mul_f32_e32 v14, v14, v16
	v_rcp_f32_e32 v16, v19
	s_nop 0
	v_mul_f32_e32 v15, v15, v16

; DI unsigned pack2(float a, float b) { v2f f = {a, b}; return __builtin_bit_cast(unsigned, __builtin_convertvector(f, v2bf)); }
; template <bool HI_BF, bool HO_BF>
; DI void post_phase(const u16* __restrict__ y, const void* hin_, void* hout_,
;                    const float* __restrict__ gpost, const float* __restrict__ gpre, u16* __restrict__ uout) {
;     ...
;     if (hout_) {
; #pragma unroll
;       for (int j = 0; j < 4; ++j) {
;         if (HO_BF) { u32x2 v; v.x = pack2(hv[j].x, hv[j].y); v.y = pack2(hv[j].z, hv[j].w); *(u32x2*)((u16*)hout_ + (long)row * 1024 + 4 * lane + 256 * j) = v; }
;         else *(float4*)(hout + (long)row * 1024 + 4 * lane + 256 * j) = hv[j];
;       }
;     }
.LBB0_2739:
	s_and_b64 vcc, exec, s[2:3]
	s_cbranch_vccnz .LBB0_2736
	global_store_dwordx4 v[20:21], v[12:15], off sc0 sc1
	global_store_dwordx4 v[20:21], v[8:11], off offset:1024 sc0 sc1
	global_store_dwordx4 v[20:21], v[4:7], off offset:2048 sc0 sc1
	global_store_dwordx4 v[20:21], v[0:3], off offset:3072 sc0 sc1
	s_branch .LBB0_2736
